# placement: PEER u-phase code moved 8 bytes (start at 60 mod 64), act and v-phase placements kept
# baseline (speedup 1.0000x reference)
; #define LAS __attribute__((address_space(3)))
; #define MFMA32(a, b, c) __builtin_amdgcn_mfma_f32_32x32x16_bf16((a), (b), (c), 0, 0, 0)
; __device__ __forceinline__ void route_task(int task, int tl0, const bf16* QP  , const LAS bf16* KHL, LAS unsigned short* EL, LAS float* GL, int lane) {
;     const int r = lane & 31, hi = lane >> 5, t = 4 * task + (r >> 3), head = r & 7;
;     int top[2][16]; bf16x8 qa[2][4];
;     { unsigned qo = (unsigned)t * (unsigned)D + (unsigned)(head * 128 + 8 * hi); asm volatile("" : "+v"(qo)); const bf16* qp = QP + qo;
; #pragma unroll
;       for (int hf = 0; hf < 2; ++hf)
; #pragma unroll
;         for (int ks = 0; ks < 4; ++ks) qa[hf][ks] = ldg8(qp + 64 * hf + 16 * ks); }
; #pragma unroll
;     for (int half = 0; half < 2; ++half) {
;         int cur[16];
; #pragma unroll
;         for (int kt = 0; kt < 4; ++kt) {
;             f32x16 X;
; #pragma unroll
;             for (int i = 0; i < 16; ++i) X[i] = 8.f;
;             const LAS bf16* khp = KHL + (half * 128 + 32 * kt + r) * 72 + 8 * hi;
; #pragma unroll
;             for (int ks = 0; ks < 4; ++ks) {
;                 const bf16x8 kh = lds8(khp + 16 * ks);
;                 X = MFMA32(kh, qa[half][ks], X);
;             }
;             int grp[16];
; #pragma unroll
;             for (int i = 0; i < 16; ++i) grp[i] = (int)((__float_as_uint(X[i]) | 127u) - (unsigned)(32 * kt + (i & 3) + 8 * (i >> 2)));
;             sort16_desc(grp);
;             if (kt == 0) {
; #pragma unroll
;                 for (int i = 0; i < 16; ++i) cur[i] = grp[i];
;             } else merge16_desc(cur, grp);
.LBB0_666:
	s_or_b64 exec, exec, s[10:11]
	s_lshl_b32 s10, s2, 4
	s_add_i32 s10, s10, s95
	s_lshl_b32 s10, s10, 12
	v_or_b32_e32 v82, s10, v88
	s_waitcnt lgkmcnt(0)
	s_barrier
	s_add_i32 s11, 0, 0x12000
	v_lshl_add_u64 v[70:71], v[82:83], 1, s[80:81]
	global_load_dwordx4 v[62:65], v[70:71], off
	global_load_dwordx4 v[54:57], v[70:71], off offset:32
	global_load_dwordx4 v[58:61], v[70:71], off offset:64
	global_load_dwordx4 v[50:53], v[70:71], off offset:96
	ds_read_b128 v[34:37], v94
	ds_read_b128 v[38:41], v94 offset:32
	s_add_i32 s10, s10, 0x8000
	s_mov_b32 s41, 0
	s_waitcnt vmcnt(3) lgkmcnt(1)
	v_mfma_f32_32x32x16_bf16 v[18:33], v[34:37], v[62:65], v[2:17]
	ds_read_b128 v[34:37], v94 offset:64
	ds_read_b128 v[66:69], v94 offset:96
	s_waitcnt vmcnt(2) lgkmcnt(2)
	v_mfma_f32_32x32x16_bf16 v[18:33], v[38:41], v[54:57], v[18:33]
	v_and_b32_e32 v38, 64, v112
	v_add_u32_e32 v122, 64, v38
	v_cmp_lt_i32_e32 vcc, v113, v122
	s_waitcnt vmcnt(1) lgkmcnt(1)
	v_mfma_f32_32x32x16_bf16 v[18:33], v[34:37], v[58:61], v[18:33]
	v_cndmask_b32_e32 v34, v112, v113, vcc
	v_lshlrev_b32_e32 v123, 2, v34
	global_load_dwordx4 v[46:49], v[70:71], off offset:128
	global_load_dwordx4 v[42:45], v[70:71], off offset:160
	global_load_dwordx4 v[38:41], v[70:71], off offset:192
	global_load_dwordx4 v[34:37], v[70:71], off offset:224
	s_waitcnt vmcnt(4) lgkmcnt(0)
	v_mfma_f32_32x32x16_bf16 v[18:33], v[66:69], v[50:53], v[18:33]
	s_nop 11
	s_movk_i32 s42, 0x7f
	s_movk_i32 s43, 0xff80
	v_bitop3_b32 v21, v21, s42, 3 bitop3:0x56
	v_bitop3_b32 v32, v32, s42, 26 bitop3:0x56
	v_bitop3_b32 v22, v22, s42, 8 bitop3:0x56
	v_bitop3_b32 v26, v26, s42, 16 bitop3:0x56
	v_bitop3_b32 v31, v31, s42, 25 bitop3:0x56
	v_bitop3_b32 v23, v23, s42, 9 bitop3:0x56
	v_bitop3_b32 v24, v24, s42, 10 bitop3:0x56
	v_bitop3_b32 v27, v27, s42, 17 bitop3:0x56
	v_bitop3_b32 v28, v28, s42, 18 bitop3:0x56
	v_bitop3_b32 v20, v20, s42, 2 bitop3:0x56
	v_bitop3_b32 v33, v33, s42, 27 bitop3:0x56
	v_bitop3_b32 v25, v25, s42, 11 bitop3:0x56
	v_bitop3_b32 v29, v29, s42, 19 bitop3:0x56
	v_bitop3_b32 v19, v19, s42, 1 bitop3:0x56
	v_bitop3_b32 v30, v30, s42, 24 bitop3:0x56
	v_or_b32_e32 v18, 0x7f, v18
	v_max_i32_e32 v66, v21, v32
	v_max_i32_e32 v67, v22, v26
	v_max_i32_e32 v68, v18, v31
	v_max_i32_e32 v69, v23, v24
	v_min_i32_e32 v70, v27, v28
	v_min_i32_e32 v71, v20, v33
	v_min_i32_e32 v72, v25, v29
	v_min_i32_e32 v73, v19, v30
	v_min_i32_e32 v23, v23, v24
	v_min_i32_e32 v18, v18, v31
	v_min_i32_e32 v22, v22, v26
	v_min_i32_e32 v21, v21, v32
	v_max_i32_e32 v19, v19, v30
	v_max_i32_e32 v24, v25, v29
	v_max_i32_e32 v20, v20, v33
	v_max_i32_e32 v25, v27, v28
	v_min_i32_e32 v26, v66, v67
	v_min_i32_e32 v27, v68, v69
	v_max_i32_e32 v28, v70, v71
	v_max_i32_e32 v29, v72, v73
	v_max_i32_e32 v30, v23, v18
	v_max_i32_e32 v31, v22, v21
	v_min_i32_e32 v32, v19, v24
	v_min_i32_e32 v33, v20, v25
	v_min_i32_e32 v18, v23, v18
	v_min_i32_e32 v21, v22, v21
	v_min_i32_e32 v22, v70, v71
	v_max_i32_e32 v23, v68, v69
	v_max_i32_e32 v19, v19, v24
	v_max_i32_e32 v20, v20, v25
	v_max_i32_e32 v24, v66, v67
	v_min_i32_e32 v25, v26, v27
	v_max_i32_e32 v67, v30, v31
	v_min_i32_e32 v30, v30, v31
	v_min_i32_e32 v31, v32, v33
	v_max_i32_e32 v26, v26, v27
	v_max_i32_e32 v27, v28, v29
	v_min_i32_e32 v66, v28, v29
	v_max_i32_e32 v68, v32, v33
	v_min_i32_e32 v75, v21, v22
	v_max_i32_e32 v21, v21, v22
	v_min_i32_e32 v22, v23, v19
	v_min_i32_e32 v28, v20, v24
	v_max_i32_e32 v33, v30, v31
	v_min_i32_e32 v69, v26, v27
	v_max_i32_e32 v29, v25, v66
	v_min_i32_e32 v32, v67, v68
	v_min_i32_e32 v77, v25, v66
	v_min_i32_e32 v25, v22, v28
	v_max_i32_e32 v80, v22, v28
	v_min_i32_e32 v22, v33, v69
	v_max_i32_e32 v125, v20, v24
	v_max_i32_e32 v129, v67, v68
	v_max_i32_e32 v24, v33, v69
	ds_read_b128 v[66:69], v95
	v_min_i32_e32 v72, v72, v73
	v_min_i32_e32 v74, v72, v18
	v_max_i32_e32 v18, v72, v18
	v_max_i32_e32 v124, v23, v19
	v_min_i32_e32 v76, v30, v31
	v_max_i32_e32 v78, v74, v75
	v_min_i32_e32 v79, v18, v21
	v_min_i32_e32 v126, v124, v125
	v_max_i32_e32 v128, v26, v27
	v_max_i32_e32 v18, v18, v21
	v_max_i32_e32 v81, v76, v77
	v_max_i32_e32 v82, v78, v79
	v_min_i32_e32 v127, v80, v126
	v_min_i32_e32 v130, v128, v129
	v_min_i32_e32 v21, v29, v32
	v_min_i32_e32 v28, v25, v18
	v_max_i32_e32 v18, v25, v18
	v_max_i32_e32 v30, v81, v82
	v_min_i32_e32 v19, v127, v130
	v_max_i32_e32 v23, v29, v32
	v_max_i32_e32 v25, v21, v22
	v_max_i32_e32 v31, v30, v28
	v_min_i32_e32 v20, v18, v19
	v_min_i32_e32 v26, v23, v24
	v_max_i32_e32 v70, v25, v31
	v_min_i32_e32 v27, v20, v26
	v_min_i32_e32 v131, v70, v27
	v_max_i32_e32 v143, v70, v27
	ds_read_b128 v[70:73], v95 offset:32
	v_min_i32_e32 v132, v25, v31
	v_min_i32_e32 v133, v21, v22
	v_min_i32_e32 v134, v30, v28
	v_max_i32_e32 v138, v18, v19
	v_max_i32_e32 v139, v23, v24
	v_max_i32_e32 v141, v20, v26
	s_waitcnt lgkmcnt(1)
	v_mfma_f32_32x32x16_bf16 v[18:33], v[66:69], v[62:65], v[2:17]
	ds_read_b128 v[66:69], v95 offset:64
	v_max_i32_e32 v135, v133, v134
	v_max_i32_e32 v136, v132, v135
	v_min_i32_e32 v76, v76, v77
	v_min_i32_e32 v77, v78, v79
	v_min_i32_e32 v132, v132, v135
	v_max_i32_e32 v127, v127, v130
	s_waitcnt lgkmcnt(1)
	v_mfma_f32_32x32x16_bf16 v[18:33], v[70:73], v[54:57], v[18:33]
	ds_read_b128 v[70:73], v95 offset:96
	v_max_i32_e32 v80, v80, v126
	v_min_i32_e32 v74, v74, v75
	v_min_i32_e32 v140, v138, v139
	v_max_i32_e32 v78, v76, v77
	v_min_i32_e32 v79, v81, v82
	v_min_i32_e32 v82, v133, v134
	s_waitcnt lgkmcnt(1)
	v_mfma_f32_32x32x16_bf16 v[18:33], v[66:69], v[58:61], v[18:33]
	v_max_i32_e32 v66, v128, v129
	v_max_i32_e32 v134, v138, v139
	v_min_i32_e32 v76, v76, v77
	v_max_i32_e32 v81, v78, v79
	v_min_i32_e32 v78, v78, v79
	v_min_i32_e32 v67, v80, v66
	v_min_i32_e32 v142, v140, v141
	s_waitcnt lgkmcnt(0)
; #define LAS __attribute__((address_space(3)))
; #define MFMA32(a, b, c) __builtin_amdgcn_mfma_f32_32x32x16_bf16((a), (b), (c), 0, 0, 0)
; __device__ __forceinline__ void route_task(int task, int tl0, const bf16* QP  , const LAS bf16* KHL, LAS unsigned short* EL, LAS float* GL, int lane) {
;     ...
;         for (int kt = 0; kt < 4; ++kt) {
;             f32x16 X;
; #pragma unroll
;             for (int i = 0; i < 16; ++i) X[i] = 8.f;
;             const LAS bf16* khp = KHL + (half * 128 + 32 * kt + r) * 72 + 8 * hi;
; #pragma unroll
;             for (int ks = 0; ks < 4; ++ks) {
;                 const bf16x8 kh = lds8(khp + 16 * ks);
;                 X = MFMA32(kh, qa[half][ks], X);
;             }
;             int grp[16];
; #pragma unroll
;             for (int i = 0; i < 16; ++i) grp[i] = (int)((__float_as_uint(X[i]) | 127u) - (unsigned)(32 * kt + (i & 3) + 8 * (i >> 2)));
;             sort16_desc(grp);
;             if (kt == 0) {
; #pragma unroll
;                 for (int i = 0; i < 16; ++i) cur[i] = grp[i];
;             } else merge16_desc(cur, grp);
	v_mfma_f32_32x32x16_bf16 v[18:33], v[70:73], v[50:53], v[18:33]
	v_min_i32_e32 v68, v127, v67
	v_min_i32_e32 v137, v131, v136
	v_min_i32_e32 v144, v142, v143
	v_min_i32_e32 v133, v81, v82
	v_min_i32_e32 v69, v134, v68
	s_nop 6
	v_bitop3_b32 v21, v21, s42, 35 bitop3:0x56
	v_bitop3_b32 v32, v32, s42, 58 bitop3:0x56
	v_bitop3_b32 v22, v22, s42, 40 bitop3:0x56
	v_bitop3_b32 v26, v26, s42, 48 bitop3:0x56
	v_bitop3_b32 v18, v18, s42, 32 bitop3:0x56
	v_bitop3_b32 v31, v31, s42, 57 bitop3:0x56
	v_bitop3_b32 v23, v23, s42, 41 bitop3:0x56
	v_bitop3_b32 v24, v24, s42, 42 bitop3:0x56
	v_bitop3_b32 v27, v27, s42, 49 bitop3:0x56
	v_bitop3_b32 v28, v28, s42, 50 bitop3:0x56
	v_bitop3_b32 v20, v20, s42, 34 bitop3:0x56
	v_bitop3_b32 v33, v33, s42, 59 bitop3:0x56
	v_bitop3_b32 v25, v25, s42, 43 bitop3:0x56
	v_bitop3_b32 v29, v29, s42, 51 bitop3:0x56
	v_bitop3_b32 v19, v19, s42, 33 bitop3:0x56
	v_bitop3_b32 v30, v30, s42, 56 bitop3:0x56
	v_max_i32_e32 v70, v21, v32
	v_max_i32_e32 v71, v22, v26
	v_max_i32_e32 v73, v18, v31
	v_max_i32_e32 v75, v23, v24
	v_min_i32_e32 v126, v27, v28
	v_min_i32_e32 v128, v20, v33
	v_min_i32_e32 v130, v25, v29
	v_min_i32_e32 v135, v19, v30
	v_min_i32_e32 v23, v23, v24
	v_min_i32_e32 v18, v18, v31
	v_min_i32_e32 v22, v22, v26
	v_min_i32_e32 v21, v21, v32
	v_max_i32_e32 v19, v19, v30
	v_max_i32_e32 v25, v25, v29
	v_max_i32_e32 v20, v20, v33
	v_max_i32_e32 v27, v27, v28
	v_min_i32_e32 v72, v70, v71
	v_min_i32_e32 v77, v73, v75
	v_max_i32_e32 v129, v126, v128
	v_max_i32_e32 v138, v130, v135
	v_max_i32_e32 v24, v23, v18
	v_max_i32_e32 v26, v22, v21
	v_min_i32_e32 v29, v19, v25
	v_min_i32_e32 v28, v20, v27
	v_min_i32_e32 v130, v130, v135
	v_min_i32_e32 v18, v23, v18
	v_min_i32_e32 v21, v22, v21
	v_min_i32_e32 v22, v126, v128
	v_max_i32_e32 v73, v73, v75
	v_max_i32_e32 v19, v19, v25
	v_max_i32_e32 v20, v20, v27
	v_max_i32_e32 v27, v70, v71
	v_min_i32_e32 v79, v72, v77
	v_min_i32_e32 v139, v129, v138
	v_max_i32_e32 v31, v24, v26
	v_max_i32_e32 v30, v29, v28
	v_min_i32_e32 v24, v24, v26
	v_min_i32_e32 v26, v29, v28
	v_max_i32_e32 v29, v72, v77
	v_max_i32_e32 v72, v129, v138
	v_min_i32_e32 v23, v130, v18
	v_min_i32_e32 v126, v21, v22
	v_max_i32_e32 v18, v130, v18
	v_max_i32_e32 v21, v21, v22
	v_min_i32_e32 v25, v73, v19
	v_min_i32_e32 v70, v20, v27
	v_max_i32_e32 v19, v73, v19
	v_max_i32_e32 v20, v20, v27
	v_min_i32_e32 v32, v31, v30
	v_max_i32_e32 v28, v24, v26
	v_min_i32_e32 v77, v29, v72
	v_min_i32_e32 v24, v24, v26
	v_min_i32_e32 v26, v79, v139
	v_max_i32_e32 v128, v23, v126
	v_min_i32_e32 v22, v18, v21
	v_min_i32_e32 v71, v25, v70
	v_max_i32_e32 v25, v25, v70
	v_min_i32_e32 v27, v19, v20
	v_max_i32_e32 v29, v29, v72
	v_max_i32_e32 v30, v31, v30
	v_max_i32_e32 v145, v79, v139
	v_max_i32_e32 v79, v24, v26
	v_max_i32_e32 v130, v128, v22
	v_max_i32_e32 v18, v18, v21
	v_min_i32_e32 v70, v25, v27
	v_min_i32_e32 v31, v29, v30
	v_min_i32_e32 v33, v145, v32
	v_min_i32_e32 v129, v28, v77
	v_max_i32_e32 v135, v79, v130
	v_min_i32_e32 v21, v71, v18
	v_max_i32_e32 v18, v71, v18
	v_min_i32_e32 v71, v70, v31
	v_max_i32_e32 v32, v145, v32
	v_max_i32_e32 v28, v28, v77
	v_max_i32_e32 v138, v33, v129
	v_max_i32_e32 v75, v135, v21
	v_min_i32_e32 v72, v18, v71
	v_min_i32_e32 v73, v32, v28
	v_min_i32_e32 v33, v33, v129
	v_min_i32_e32 v21, v135, v21
	v_max_i32_e32 v18, v18, v71
	v_max_i32_e32 v28, v32, v28
	v_min_i32_e32 v24, v24, v26
	v_min_i32_e32 v22, v128, v22
	v_max_i32_e32 v25, v25, v27
	v_max_i32_e32 v27, v29, v30
	v_max_i32_e32 v139, v138, v75
	v_min_i32_e32 v77, v72, v73
	v_min_i32_e32 v75, v138, v75
	v_max_i32_e32 v129, v33, v21
	v_min_i32_e32 v32, v18, v28
	v_max_i32_e32 v71, v72, v73
	v_max_i32_e32 v26, v24, v22
	v_min_i32_e32 v79, v79, v130
	v_max_i32_e32 v18, v18, v28
	v_max_i32_e32 v28, v70, v31
	v_min_i32_e32 v29, v25, v27
	v_min_i32_e32 v145, v139, v77
	v_max_i32_e32 v135, v75, v129
	v_min_i32_e32 v72, v32, v71
	v_max_i32_e32 v73, v139, v77
	v_max_i32_e32 v128, v26, v79
	v_min_i32_e32 v21, v33, v21
	v_min_i32_e32 v30, v28, v29
	v_min_i32_e32 v138, v145, v135
	v_min_i32_e32 v77, v72, v73
	v_min_i32_e32 v33, v128, v21
	v_min_i32_e32 v75, v75, v129
	v_min_i32_e32 v31, v18, v30
	v_min_i32_e32 v26, v26, v79
	v_min_i32_e32 v22, v24, v22
	v_min_i32_e32 v23, v23, v126
	v_max3_i32 v23, v124, v125, v23
	v_max3_i32 v22, v80, v66, v22
	v_max3_i32 v24, v127, v67, v26
	v_max3_i32 v26, v134, v68, v33
	v_max3_i32 v21, v69, v128, v21
	v_max3_i32 v33, v140, v141, v75
	v_max3_i32 v66, v142, v143, v138
	v_max3_i32 v67, v144, v145, v135
	v_max3_i32 v68, v131, v136, v77
	v_max3_i32 v69, v137, v72, v73
	v_max3_i32 v32, v132, v32, v71
	v_max3_i32 v31, v81, v82, v31
	v_max3_i32 v18, v133, v18, v30
	v_max3_i32 v28, v78, v28, v29
	v_max3_i32 v25, v76, v25, v27
	v_max3_i32 v19, v74, v19, v20
	v_max_i32_e32 v20, v23, v68
	v_min_i32_e32 v23, v23, v68
	v_max_i32_e32 v27, v22, v69
	v_min_i32_e32 v22, v22, v69
	v_max_i32_e32 v29, v24, v32
	v_min_i32_e32 v24, v24, v32
	v_max_i32_e32 v30, v26, v31
	v_min_i32_e32 v26, v26, v31
	v_max_i32_e32 v31, v21, v18
	v_min_i32_e32 v18, v21, v18
	v_max_i32_e32 v21, v33, v28
	v_min_i32_e32 v28, v33, v28
	v_max_i32_e32 v32, v66, v25
	v_min_i32_e32 v25, v66, v25
	v_max_i32_e32 v33, v67, v19
	v_min_i32_e32 v19, v67, v19
	ds_read_b128 v[66:69], v94 offset:9216
	v_max_i32_e32 v70, v20, v31
	v_min_i32_e32 v74, v20, v31
	v_max_i32_e32 v20, v27, v21
	v_min_i32_e32 v75, v27, v21
	v_max_i32_e32 v21, v29, v32
	v_max_i32_e32 v27, v30, v33
	v_max_i32_e32 v127, v70, v21
	v_min_i32_e32 v128, v70, v21
	ds_read_b128 v[70:73], v94 offset:9248
	v_min_i32_e32 v76, v29, v32
	v_min_i32_e32 v77, v30, v33
	v_max_i32_e32 v78, v23, v18
	v_min_i32_e32 v79, v23, v18
	v_max_i32_e32 v80, v22, v28
	v_min_i32_e32 v81, v22, v28
	v_max_i32_e32 v82, v24, v25
	v_min_i32_e32 v124, v24, v25
	v_max_i32_e32 v125, v26, v19
	v_min_i32_e32 v126, v26, v19
	v_max_i32_e32 v129, v20, v27
	v_min_i32_e32 v130, v20, v27
	s_waitcnt lgkmcnt(1)
; #define LAS __attribute__((address_space(3)))
; #define MFMA32(a, b, c) __builtin_amdgcn_mfma_f32_32x32x16_bf16((a), (b), (c), 0, 0, 0)
; __device__ __forceinline__ void route_task(int task, int tl0, const bf16* QP  , const LAS bf16* KHL, LAS unsigned short* EL, LAS float* GL, int lane) {
;     ...
;         for (int kt = 0; kt < 4; ++kt) {
;             f32x16 X;
; #pragma unroll
;             for (int i = 0; i < 16; ++i) X[i] = 8.f;
;             const LAS bf16* khp = KHL + (half * 128 + 32 * kt + r) * 72 + 8 * hi;
; #pragma unroll
;             for (int ks = 0; ks < 4; ++ks) {
;                 const bf16x8 kh = lds8(khp + 16 * ks);
;                 X = MFMA32(kh, qa[half][ks], X);
;             }
;             int grp[16];
; #pragma unroll
;             for (int i = 0; i < 16; ++i) grp[i] = (int)((__float_as_uint(X[i]) | 127u) - (unsigned)(32 * kt + (i & 3) + 8 * (i >> 2)));
;             sort16_desc(grp);
;             if (kt == 0) {
; #pragma unroll
;                 for (int i = 0; i < 16; ++i) cur[i] = grp[i];
;             } else merge16_desc(cur, grp);
	v_mfma_f32_32x32x16_bf16 v[18:33], v[66:69], v[62:65], v[2:17]
	ds_read_b128 v[66:69], v94 offset:9280
	v_max_i32_e32 v131, v74, v76
	v_min_i32_e32 v74, v74, v76
	v_max_i32_e32 v76, v75, v77
	v_min_i32_e32 v75, v75, v77
	v_max_i32_e32 v77, v78, v82
	v_min_i32_e32 v78, v78, v82
	s_waitcnt lgkmcnt(1)
	v_mfma_f32_32x32x16_bf16 v[18:33], v[70:73], v[54:57], v[18:33]
	ds_read_b128 v[70:73], v94 offset:9312
	v_max_i32_e32 v82, v80, v125
	v_min_i32_e32 v80, v80, v125
	v_max_i32_e32 v125, v79, v124
	v_min_i32_e32 v79, v79, v124
	v_max_i32_e32 v124, v81, v126
	v_min_i32_e32 v81, v81, v126
	s_waitcnt lgkmcnt(1)
	v_mfma_f32_32x32x16_bf16 v[18:33], v[66:69], v[58:61], v[18:33]
	v_min_i32_e32 v126, v127, v129
	v_min_i32_e32 v66, v128, v130
	v_min_i32_e32 v67, v131, v76
	v_min_i32_e32 v69, v77, v82
	v_min_i32_e32 v132, v78, v80
	v_min_i32_e32 v133, v125, v124
	v_min_i32_e32 v68, v74, v75
	s_waitcnt lgkmcnt(0)
	v_mfma_f32_32x32x16_bf16 v[18:33], v[70:73], v[50:53], v[18:33]
	v_min_i32_e32 v134, v79, v81
	s_nop 10
	v_and_or_b32 v21, v21, s43, 60
	v_and_or_b32 v32, v32, s43, 37
	v_and_or_b32 v22, v22, s43, 55
	v_and_or_b32 v26, v26, s43, 47
	v_bitop3_b32 v18, v18, s42, 64 bitop3:0x56
	v_and_or_b32 v31, v31, s43, 38
	v_and_or_b32 v23, v23, s43, 54
	v_and_or_b32 v24, v24, s43, 53
	v_and_or_b32 v27, v27, s43, 46
	v_and_or_b32 v28, v28, s43, 45
	v_and_or_b32 v20, v20, s43, 61
	v_and_or_b32 v33, v33, s43, 36
	v_and_or_b32 v25, v25, s43, 52
	v_and_or_b32 v29, v29, s43, 44
	v_and_or_b32 v19, v19, s43, 62
	v_and_or_b32 v30, v30, s43, 39
	v_max_i32_e32 v70, v21, v32
	v_max_i32_e32 v71, v22, v26
	v_max_i32_e32 v73, v18, v31
	v_max_i32_e32 v135, v23, v24
	v_min_i32_e32 v138, v27, v28
	v_min_i32_e32 v139, v20, v33
	v_min_i32_e32 v141, v25, v29
	v_min_i32_e32 v142, v19, v30
	v_min_i32_e32 v23, v23, v24
	v_min_i32_e32 v18, v18, v31
	v_min_i32_e32 v22, v22, v26
	v_min_i32_e32 v21, v21, v32
	v_max_i32_e32 v19, v19, v30
	v_max_i32_e32 v25, v25, v29
	v_max_i32_e32 v20, v20, v33
	v_max_i32_e32 v27, v27, v28
	v_min_i32_e32 v72, v70, v71
	v_min_i32_e32 v136, v73, v135
	v_max_i32_e32 v140, v138, v139
	v_max_i32_e32 v143, v141, v142
	v_max_i32_e32 v24, v23, v18
	v_max_i32_e32 v26, v22, v21
	v_min_i32_e32 v29, v19, v25
	v_min_i32_e32 v28, v20, v27
	v_min_i32_e32 v141, v141, v142
	v_min_i32_e32 v18, v23, v18
	v_min_i32_e32 v21, v22, v21
	v_min_i32_e32 v22, v138, v139
	v_max_i32_e32 v73, v73, v135
	v_max_i32_e32 v19, v19, v25
	v_max_i32_e32 v20, v20, v27
	v_max_i32_e32 v27, v70, v71
	v_min_i32_e32 v137, v72, v136
	v_min_i32_e32 v144, v140, v143
	v_max_i32_e32 v31, v24, v26
	v_max_i32_e32 v30, v29, v28
	v_min_i32_e32 v24, v24, v26
	v_min_i32_e32 v26, v29, v28
	v_max_i32_e32 v29, v72, v136
	v_max_i32_e32 v72, v140, v143
	v_min_i32_e32 v23, v141, v18
	v_min_i32_e32 v138, v21, v22
	v_max_i32_e32 v18, v141, v18
	v_max_i32_e32 v21, v21, v22
	v_min_i32_e32 v25, v73, v19
	v_min_i32_e32 v70, v20, v27
	v_max_i32_e32 v19, v73, v19
	v_max_i32_e32 v20, v20, v27
	v_min_i32_e32 v32, v31, v30
	v_max_i32_e32 v28, v24, v26
	v_min_i32_e32 v136, v29, v72
	v_min_i32_e32 v24, v24, v26
	v_min_i32_e32 v26, v137, v144
	v_max_i32_e32 v139, v23, v138
	v_min_i32_e32 v22, v18, v21
	v_min_i32_e32 v71, v25, v70
	v_max_i32_e32 v25, v25, v70
	v_min_i32_e32 v27, v19, v20
	v_max_i32_e32 v29, v29, v72
	v_max_i32_e32 v30, v31, v30
	v_max_i32_e32 v145, v137, v144
	v_max_i32_e32 v137, v24, v26
	v_max_i32_e32 v141, v139, v22
	v_max_i32_e32 v18, v18, v21
	v_min_i32_e32 v70, v25, v27
	v_min_i32_e32 v31, v29, v30
	v_min_i32_e32 v33, v145, v32
	v_min_i32_e32 v140, v28, v136
	v_max_i32_e32 v142, v137, v141
	v_min_i32_e32 v21, v71, v18
	v_max_i32_e32 v18, v71, v18
	v_min_i32_e32 v71, v70, v31
	v_max_i32_e32 v32, v145, v32
	v_max_i32_e32 v28, v28, v136
	v_max_i32_e32 v143, v33, v140
	v_max_i32_e32 v135, v142, v21
	v_min_i32_e32 v72, v18, v71
	v_min_i32_e32 v73, v32, v28
	v_min_i32_e32 v33, v33, v140
	v_min_i32_e32 v21, v142, v21
	v_max_i32_e32 v18, v18, v71
	v_max_i32_e32 v28, v32, v28
	v_min_i32_e32 v24, v24, v26
	v_min_i32_e32 v22, v139, v22
	v_max_i32_e32 v25, v25, v27
	v_max_i32_e32 v27, v29, v30
	v_max_i32_e32 v144, v143, v135
	v_min_i32_e32 v136, v72, v73
	v_min_i32_e32 v135, v143, v135
	v_max_i32_e32 v140, v33, v21
	v_min_i32_e32 v32, v18, v28
	v_max_i32_e32 v71, v72, v73
	v_max_i32_e32 v26, v24, v22
	v_min_i32_e32 v137, v137, v141
	v_max_i32_e32 v18, v18, v28
	v_max_i32_e32 v28, v70, v31
	v_min_i32_e32 v29, v25, v27
	v_min_i32_e32 v145, v144, v136
	v_max_i32_e32 v142, v135, v140
	v_min_i32_e32 v72, v32, v71
	v_max_i32_e32 v73, v144, v136
	v_max_i32_e32 v139, v26, v137
	v_min_i32_e32 v21, v33, v21
	v_min_i32_e32 v30, v28, v29
	v_min_i32_e32 v143, v145, v142
	v_min_i32_e32 v136, v72, v73
	v_min_i32_e32 v33, v139, v21
	v_max_i32_e32 v21, v139, v21
	v_min_i32_e32 v135, v135, v140
	v_max_i32_e32 v32, v32, v71
	v_min_i32_e32 v31, v18, v30
	v_max_i32_e32 v18, v18, v30
	v_min_i32_e32 v26, v26, v137
	v_min_i32_e32 v22, v24, v22
	v_max_i32_e32 v24, v25, v27
	v_min_i32_e32 v23, v23, v138
	v_max3_i32 v23, v127, v129, v23
	v_max_i32_e32 v22, v126, v22
	v_max3_i32 v25, v128, v130, v26
	v_max_i32_e32 v26, v66, v33
	v_max3_i32 v21, v131, v76, v21
	v_max_i32_e32 v27, v67, v135
	v_max3_i32 v30, v74, v75, v143
	v_max3_i32 v66, v77, v82, v136
	v_max3_i32 v67, v69, v72, v73
	v_max3_i32 v32, v78, v80, v32
	v_max_i32_e32 v31, v132, v31
	v_max3_i32 v18, v125, v124, v18
	v_max3_i32 v28, v133, v28, v29
	v_max3_i32 v24, v79, v81, v24
	v_max3_i32 v33, v68, v145, v142
	v_max3_i32 v19, v134, v19, v20
	v_max_i32_e32 v20, v23, v66
	v_min_i32_e32 v23, v23, v66
	v_max_i32_e32 v29, v22, v67
	v_max_i32_e32 v66, v25, v32
	v_min_i32_e32 v25, v25, v32
	v_max_i32_e32 v32, v26, v31
	v_min_i32_e32 v26, v26, v31
	v_max_i32_e32 v31, v21, v18
	v_min_i32_e32 v18, v21, v18
	v_max_i32_e32 v21, v27, v28
	v_min_i32_e32 v27, v27, v28
	v_max_i32_e32 v28, v30, v24
	v_min_i32_e32 v22, v22, v67
	v_min_i32_e32 v24, v30, v24
	v_max_i32_e32 v30, v33, v19
	v_min_i32_e32 v19, v33, v19
	v_max_i32_e32 v33, v20, v31
	v_min_i32_e32 v74, v20, v31
	v_max_i32_e32 v20, v29, v21
	v_min_i32_e32 v75, v29, v21
	v_max_i32_e32 v21, v66, v28
	v_min_i32_e32 v76, v66, v28
	ds_read_b128 v[66:69], v96
	ds_read_b128 v[70:73], v96 offset:32
	v_max_i32_e32 v28, v32, v30
	v_min_i32_e32 v77, v32, v30
	v_max_i32_e32 v78, v23, v18
	v_min_i32_e32 v79, v23, v18
	v_max_i32_e32 v80, v22, v27
	v_min_i32_e32 v81, v22, v27
	v_max_i32_e32 v82, v25, v24
	v_min_i32_e32 v124, v25, v24
	v_max_i32_e32 v125, v26, v19
	v_min_i32_e32 v126, v26, v19
	v_max_i32_e32 v127, v33, v21
	v_min_i32_e32 v128, v33, v21
	v_max_i32_e32 v129, v20, v28
	v_min_i32_e32 v130, v20, v28
	s_waitcnt lgkmcnt(1)
; #define LAS __attribute__((address_space(3)))
; #define MFMA32(a, b, c) __builtin_amdgcn_mfma_f32_32x32x16_bf16((a), (b), (c), 0, 0, 0)
; __device__ __forceinline__ void route_task(int task, int tl0, const bf16* QP  , const LAS bf16* KHL, LAS unsigned short* EL, LAS float* GL, int lane) {
;     ...
;         for (int kt = 0; kt < 4; ++kt) {
;             f32x16 X;
; #pragma unroll
;             for (int i = 0; i < 16; ++i) X[i] = 8.f;
;             const LAS bf16* khp = KHL + (half * 128 + 32 * kt + r) * 72 + 8 * hi;
; #pragma unroll
;             for (int ks = 0; ks < 4; ++ks) {
;                 const bf16x8 kh = lds8(khp + 16 * ks);
;                 X = MFMA32(kh, qa[half][ks], X);
;             }
;             int grp[16];
; #pragma unroll
;             for (int i = 0; i < 16; ++i) grp[i] = (int)((__float_as_uint(X[i]) | 127u) - (unsigned)(32 * kt + (i & 3) + 8 * (i >> 2)));
;             sort16_desc(grp);
;             if (kt == 0) {
; #pragma unroll
;                 for (int i = 0; i < 16; ++i) cur[i] = grp[i];
;             } else merge16_desc(cur, grp);
	v_mfma_f32_32x32x16_bf16 v[18:33], v[66:69], v[62:65], v[2:17]
	ds_read_b128 v[62:65], v96 offset:64
	v_max_i32_e32 v67, v75, v77
	v_min_i32_e32 v68, v75, v77
	v_max_i32_e32 v75, v80, v125
	v_max_i32_e32 v131, v74, v76
	v_min_i32_e32 v66, v74, v76
	v_max_i32_e32 v69, v78, v82
	s_waitcnt lgkmcnt(1)
	v_mfma_f32_32x32x16_bf16 v[18:33], v[70:73], v[54:57], v[18:33]
	ds_read_b128 v[54:57], v96 offset:96
	v_min_i32_e32 v70, v80, v125
	v_max_i32_e32 v71, v79, v124
	v_min_i32_e32 v72, v79, v124
	v_min_i32_e32 v74, v78, v82
	v_max_i32_e32 v73, v81, v126
	v_min_i32_e32 v76, v81, v126
	s_waitcnt lgkmcnt(1)
	v_mfma_f32_32x32x16_bf16 v[18:33], v[62:65], v[58:61], v[18:33]
	v_min_i32_e32 v77, v127, v129
	v_min_i32_e32 v58, v128, v130
	v_min_i32_e32 v59, v131, v67
	v_min_i32_e32 v60, v66, v68
	v_min_i32_e32 v61, v69, v75
	v_min_i32_e32 v62, v74, v70
	v_min_i32_e32 v63, v71, v73
	s_waitcnt lgkmcnt(0)
	v_mfma_f32_32x32x16_bf16 v[18:33], v[54:57], v[50:53], v[18:33]
	v_min_i32_e32 v64, v72, v76
	s_nop 10
	v_and_or_b32 v25, v25, s43, 20
	v_and_or_b32 v29, v29, s43, 12
	v_and_or_b32 v19, v19, s43, 30
	v_and_or_b32 v30, v30, s43, 7
	v_and_or_b32 v23, v23, s43, 22
	v_and_or_b32 v24, v24, s43, 21
	v_and_or_b32 v18, v18, s43, 31
	v_and_or_b32 v31, v31, s43, 6
	v_and_or_b32 v22, v22, s43, 23
	v_and_or_b32 v26, v26, s43, 15
	v_and_or_b32 v21, v21, s43, 28
	v_and_or_b32 v32, v32, s43, 5
	v_and_or_b32 v27, v27, s43, 14
	v_and_or_b32 v28, v28, s43, 13
	v_and_or_b32 v20, v20, s43, 29
	v_and_or_b32 v33, v33, s43, 4
	v_min_i32_e32 v50, v25, v29
	v_min_i32_e32 v51, v19, v30
	v_min_i32_e32 v53, v23, v24
	v_min_i32_e32 v54, v18, v31
	v_min_i32_e32 v57, v22, v26
	v_min_i32_e32 v65, v21, v32
	v_min_i32_e32 v79, v27, v28
	v_min_i32_e32 v80, v20, v33
	v_max_i32_e32 v18, v18, v31
	v_max_i32_e32 v23, v23, v24
	v_max_i32_e32 v19, v19, v30
	v_max_i32_e32 v25, v25, v29
	v_max_i32_e32 v20, v20, v33
	v_max_i32_e32 v27, v27, v28
	v_max_i32_e32 v21, v21, v32
	v_max_i32_e32 v22, v22, v26
	v_max_i32_e32 v24, v18, v23
	v_max_i32_e32 v29, v19, v25
	v_max_i32_e32 v28, v20, v27
	v_max_i32_e32 v26, v21, v22
	v_min_i32_e32 v30, v24, v29
	v_min_i32_e32 v31, v28, v26
	v_min_i32_e32 v55, v53, v54
	v_min_i32_e32 v32, v30, v31
	v_max_i32_e32 v30, v30, v31
	v_min_i32_e32 v21, v21, v22
	v_min_i32_e32 v18, v18, v23
	v_max_i32_e32 v23, v79, v80
	v_max_i32_e32 v31, v50, v51
	v_max_i32_e32 v53, v53, v54
	v_max_i32_e32 v54, v57, v65
	v_min_i32_e32 v19, v19, v25
	v_min_i32_e32 v20, v20, v27
	v_min_i32_e32 v52, v50, v51
	v_min_i32_e32 v78, v57, v65
	v_min_i32_e32 v81, v79, v80
	v_max_i32_e32 v22, v21, v18
	v_max_i32_e32 v57, v53, v54
	v_max_i32_e32 v25, v19, v20
	v_min_i32_e32 v18, v21, v18
	v_min_i32_e32 v21, v23, v31
	v_min_i32_e32 v56, v52, v55
	v_min_i32_e32 v82, v78, v81
	v_max_i32_e32 v33, v52, v55
	v_max_i32_e32 v52, v78, v81
	v_max_i32_e32 v24, v24, v29
	v_max_i32_e32 v26, v28, v26
	v_max_i32_e32 v50, v23, v31
	v_max_i32_e32 v27, v57, v25
	v_max_i32_e32 v23, v18, v21
	v_min_i32_e32 v25, v57, v25
	v_min_i32_e32 v53, v53, v54
	v_min_i32_e32 v19, v19, v20
	v_max_i32_e32 v55, v33, v52
	v_min_i32_e32 v28, v24, v26
	v_max_i32_e32 v51, v22, v50
	v_max_i32_e32 v31, v23, v25
	v_max_i32_e32 v20, v53, v19
	v_min_i32_e32 v23, v23, v25
	v_min_i32_e32 v19, v53, v19
	v_min_i32_e32 v18, v18, v21
	v_max_i32_e32 v25, v56, v82
	v_min_i32_e32 v33, v33, v52
	v_min_i32_e32 v29, v30, v28
	v_min_i32_e32 v65, v51, v27
	v_min_i32_e32 v22, v22, v50
	v_max_i32_e32 v21, v19, v18
	v_max_i32_e32 v52, v25, v33
	v_max_i32_e32 v78, v32, v55
	v_min_i32_e32 v79, v29, v65
	v_max_i32_e32 v50, v20, v22
	v_min_i32_e32 v20, v20, v22
	v_max_i32_e32 v53, v21, v52
	v_min_i32_e32 v32, v32, v55
	v_max_i32_e32 v80, v78, v79
	v_max_i32_e32 v54, v31, v50
	v_min_i32_e32 v78, v78, v79
	v_min_i32_e32 v31, v31, v50
	v_max_i32_e32 v22, v23, v20
	v_max_i32_e32 v55, v53, v32
	v_min_i32_e32 v18, v19, v18
	v_min_i32_e32 v19, v25, v33
	v_min_i32_e32 v20, v23, v20
	v_min_i32_e32 v23, v53, v32
	v_max_i32_e32 v28, v30, v28
	v_max_i32_e32 v27, v51, v27
	v_min_i32_e32 v124, v56, v82
	v_min_i32_e32 v57, v80, v54
	v_max_i32_e32 v50, v78, v31
	v_max_i32_e32 v56, v22, v55
	v_min_i32_e32 v31, v78, v31
	v_max_i32_e32 v25, v18, v19
	v_min_i32_e32 v21, v21, v52
	v_min_i32_e32 v32, v20, v23
	v_max_i32_e32 v29, v29, v65
	v_min_i32_e32 v30, v28, v27
	v_min_i32_e32 v22, v22, v55
	v_max_i32_e32 v20, v20, v23
	v_min_i32_e32 v79, v57, v50
	v_max_i32_e32 v78, v56, v31
	v_max_i32_e32 v33, v25, v21
	v_max_i32_e32 v53, v80, v54
	v_min_i32_e32 v51, v29, v30
	v_min_i32_e32 v31, v56, v31
	v_max_i32_e32 v23, v22, v20
	v_min_i32_e32 v81, v79, v78
	v_max_i32_e32 v52, v33, v32
	v_max_i32_e32 v54, v53, v51
	v_min_i32_e32 v21, v25, v21
	v_max_i32_e32 v25, v57, v50
	v_min_i32_e32 v55, v31, v23
	v_max_i32_e32 v27, v28, v27
	v_min_i32_e32 v18, v18, v19
	v_min_i32_e32 v20, v22, v20
	v_min_i32_e32 v32, v33, v32
	v_min_i32_e32 v33, v53, v51
	v_max3_i32 v124, v127, v129, v124
	v_max3_i32 v69, v69, v75, v81
	v_max3_i32 v52, v131, v67, v52
	v_max3_i32 v54, v71, v73, v54
	v_max3_i32 v21, v128, v130, v21
	v_max3_i32 v25, v74, v70, v25
	v_max3_i32 v55, v66, v68, v55
	v_max3_i32 v27, v72, v76, v27
	v_max_i32_e32 v18, v77, v18
	v_max3_i32 v19, v61, v79, v78
	v_max_i32_e32 v20, v59, v20
	v_max3_i32 v22, v63, v29, v30
	v_max_i32_e32 v32, v58, v32
	v_max_i32_e32 v33, v62, v33
	v_max3_i32 v23, v60, v31, v23
	v_max3_i32 v24, v64, v24, v26
	v_min_i32_e32 v65, v52, v54
	v_min_i32_e32 v50, v21, v25
	v_min_i32_e32 v61, v18, v19
	v_min_i32_e32 v29, v20, v22
	v_min_i32_e32 v26, v23, v24
	v_max_i32_e32 v59, v124, v69
	v_max_i32_e32 v52, v52, v54
	v_max_i32_e32 v21, v21, v25
	v_max_i32_e32 v25, v55, v27
; __device__ __forceinline__ void route_task(int task, int tl0, const bf16* QP  , const LAS bf16* KHL, LAS unsigned short* EL, LAS float* GL, int lane) {
;     ...
;             } else merge16_desc(cur, grp);
;         }
;         { const unsigned h4 = 4u * (unsigned)hi;
; #pragma unroll
;           for (int i = 0; i < 16; ++i) cur[i] -= (int)h4; }
;         int oth[16];
; #pragma unroll
;         for (int i = 0; i < 16; ++i) oth[i] = __shfl_xor(cur[i], 32);
;         merge16_desc(cur, oth);
; #pragma unroll
	v_max_i32_e32 v18, v18, v19
	v_max_i32_e32 v19, v20, v22
	v_max_i32_e32 v22, v32, v33
	v_max_i32_e32 v23, v23, v24
	v_min_i32_e32 v28, v55, v27
	v_max_i32_e32 v54, v59, v52
	v_max_i32_e32 v27, v21, v25
	v_max_i32_e32 v20, v18, v19
	v_max_i32_e32 v24, v22, v23
	v_min_i32_e32 v51, v32, v33
	v_max_i32_e32 v55, v54, v27
	v_max_i32_e32 v32, v20, v24
	v_min_i32_e32 v27, v54, v27
	v_min_i32_e32 v20, v20, v24
	v_max_i32_e32 v24, v27, v20
	v_min_i32_e32 v20, v27, v20
	v_min_i32_e32 v27, v59, v52
	v_min_i32_e32 v21, v21, v25
	v_min_i32_e32 v18, v18, v19
	v_min_i32_e32 v19, v22, v23
	v_min_i32_e32 v75, v124, v69
	v_max_i32_e32 v25, v27, v21
	v_max_i32_e32 v22, v18, v19
	v_min_i32_e32 v21, v27, v21
	v_min_i32_e32 v18, v18, v19
	v_min_i32_e32 v56, v50, v28
	v_min_i32_e32 v31, v51, v26
	v_max_i32_e32 v23, v25, v22
	v_min_i32_e32 v22, v25, v22
	v_max_i32_e32 v19, v21, v18
	v_min_i32_e32 v18, v21, v18
	v_max_i32_e32 v21, v75, v65
	v_max_i32_e32 v25, v50, v28
	v_max_i32_e32 v28, v61, v29
	v_max_i32_e32 v26, v51, v26
	v_min_i32_e32 v67, v75, v65
	v_min_i32_e32 v30, v61, v29
	v_max_i32_e32 v27, v21, v25
	v_min_i32_e32 v21, v21, v25
	v_min_i32_e32 v25, v28, v26
	v_min_i32_e32 v57, v67, v56
	v_min_i32_e32 v53, v30, v31
	v_max_i32_e32 v29, v28, v26
	v_max_i32_e32 v26, v21, v25
	v_min_i32_e32 v21, v21, v25
	v_max_i32_e32 v25, v67, v56
	v_max_i32_e32 v28, v30, v31
	v_min_i32_e32 v58, v57, v53
	v_max_i32_e32 v33, v55, v32
	v_min_i32_e32 v32, v55, v32
	v_max_i32_e32 v50, v27, v29
	v_min_i32_e32 v27, v27, v29
	v_max_i32_e32 v29, v25, v28
	v_min_i32_e32 v25, v25, v28
	v_max_i32_e32 v28, v57, v53
	v_sub_u32_e32 v30, v33, v87
	v_sub_u32_e32 v31, v32, v87
	v_sub_u32_e32 v24, v24, v87
	v_sub_u32_e32 v20, v20, v87
	v_sub_u32_e32 v23, v23, v87
	v_sub_u32_e32 v22, v22, v87
	v_sub_u32_e32 v19, v19, v87
	v_sub_u32_e32 v18, v18, v87
	v_sub_u32_e32 v32, v50, v87
	v_sub_u32_e32 v27, v27, v87
	v_sub_u32_e32 v26, v26, v87
	v_sub_u32_e32 v21, v21, v87
	v_sub_u32_e32 v29, v29, v87
	v_sub_u32_e32 v25, v25, v87
	v_sub_u32_e32 v28, v28, v87
	v_sub_u32_e32 v33, v58, v87
	ds_bpermute_b32 v50, v123, v30
	ds_bpermute_b32 v51, v123, v31
	ds_bpermute_b32 v52, v123, v24
	ds_bpermute_b32 v53, v123, v20
	ds_bpermute_b32 v54, v123, v23
	ds_bpermute_b32 v55, v123, v22
	ds_bpermute_b32 v56, v123, v19
	ds_bpermute_b32 v57, v123, v18
	ds_bpermute_b32 v58, v123, v32
	ds_bpermute_b32 v59, v123, v27
	ds_bpermute_b32 v60, v123, v26
	ds_bpermute_b32 v61, v123, v33
	ds_bpermute_b32 v62, v123, v28
	ds_bpermute_b32 v63, v123, v25
	ds_bpermute_b32 v64, v123, v29
	ds_bpermute_b32 v65, v123, v21
	s_waitcnt lgkmcnt(4)
	v_max_i32_e32 v30, v30, v61
	s_waitcnt lgkmcnt(3)
	v_max_i32_e32 v31, v31, v62
	s_waitcnt lgkmcnt(2)
	v_max_i32_e32 v24, v24, v63
	s_waitcnt lgkmcnt(1)
	v_max_i32_e32 v20, v20, v64
	s_waitcnt lgkmcnt(0)
	v_max_i32_e32 v23, v23, v65
	v_max_i32_e32 v22, v22, v60
	v_max_i32_e32 v19, v19, v59
	v_max_i32_e32 v18, v18, v58
	v_max_i32_e32 v32, v32, v57
	v_max_i32_e32 v27, v27, v56
	v_max_i32_e32 v26, v26, v55
	v_max_i32_e32 v21, v21, v54
	v_max_i32_e32 v29, v29, v53
	v_max_i32_e32 v25, v25, v52
	v_max_i32_e32 v28, v28, v51
	v_max_i32_e32 v33, v33, v50
	v_max_i32_e32 v50, v30, v32
	v_min_i32_e32 v30, v30, v32
	v_max_i32_e32 v32, v31, v27
	v_min_i32_e32 v27, v31, v27
	v_max_i32_e32 v31, v24, v26
	v_min_i32_e32 v24, v24, v26
	v_max_i32_e32 v26, v20, v21
	v_min_i32_e32 v20, v20, v21
	v_max_i32_e32 v21, v23, v29
	v_min_i32_e32 v23, v23, v29
	v_max_i32_e32 v29, v22, v25
	v_min_i32_e32 v22, v22, v25
	v_max_i32_e32 v25, v19, v28
	v_min_i32_e32 v19, v19, v28
	v_max_i32_e32 v28, v18, v33
	v_min_i32_e32 v18, v18, v33
	v_max_i32_e32 v33, v50, v21
	v_min_i32_e32 v21, v50, v21
	v_max_i32_e32 v50, v32, v29
	v_min_i32_e32 v29, v32, v29
	v_max_i32_e32 v32, v31, v25
	v_min_i32_e32 v25, v31, v25
	v_max_i32_e32 v31, v26, v28
	v_max_i32_e32 v64, v50, v31
	v_min_i32_e32 v67, v50, v31
	ds_read_b128 v[50:53], v94 offset:18432
	ds_read_b128 v[54:57], v94 offset:18464
	v_min_i32_e32 v26, v26, v28
	v_max_i32_e32 v28, v30, v23
	v_min_i32_e32 v58, v30, v23
	v_max_i32_e32 v23, v27, v22
	v_min_i32_e32 v59, v27, v22
	v_max_i32_e32 v22, v24, v19
	v_min_i32_e32 v60, v24, v19
	v_max_i32_e32 v19, v20, v18
	v_min_i32_e32 v61, v20, v18
	v_max_i32_e32 v62, v33, v32
	v_min_i32_e32 v66, v33, v32
	v_max_i32_e32 v68, v21, v25
	v_min_i32_e32 v69, v21, v25
	v_max_i32_e32 v70, v29, v26
	v_min_i32_e32 v71, v29, v26
	v_max_i32_e32 v72, v28, v22
	v_min_i32_e32 v73, v28, v22
	v_max_i32_e32 v74, v23, v19
	v_min_i32_e32 v75, v23, v19
	s_waitcnt vmcnt(3) lgkmcnt(1)
	v_mfma_f32_32x32x16_bf16 v[18:33], v[50:53], v[46:49], v[2:17]
	ds_read_b128 v[50:53], v94 offset:18496
	v_max_i32_e32 v76, v58, v60
	v_min_i32_e32 v77, v58, v60
	v_max_i32_e32 v78, v59, v61
	v_min_i32_e32 v79, v59, v61
	v_max_i32_e32 v63, v62, v64
	v_min_i32_e32 v65, v62, v64
	s_waitcnt vmcnt(2) lgkmcnt(1)
	v_mfma_f32_32x32x16_bf16 v[18:33], v[54:57], v[42:45], v[18:33]
	v_max_i32_e32 v64, v66, v67
	v_min_i32_e32 v62, v66, v67
	v_max_i32_e32 v61, v68, v70
	v_min_i32_e32 v60, v68, v70
	v_max_i32_e32 v59, v69, v71
	v_min_i32_e32 v57, v69, v71
	ds_read_b128 v[66:69], v94 offset:18528
	s_waitcnt vmcnt(1) lgkmcnt(1)
	v_mfma_f32_32x32x16_bf16 v[18:33], v[50:53], v[38:41], v[18:33]
	v_max_i32_e32 v55, v72, v74
	v_min_i32_e32 v58, v72, v74
	v_max_i32_e32 v56, v73, v75
	v_min_i32_e32 v54, v73, v75
	v_max_i32_e32 v53, v76, v78
	v_min_i32_e32 v52, v76, v78
	v_max_i32_e32 v51, v77, v79
	s_waitcnt vmcnt(0) lgkmcnt(0)
; #define LAS __attribute__((address_space(3)))
; #define MFMA32(a, b, c) __builtin_amdgcn_mfma_f32_32x32x16_bf16((a), (b), (c), 0, 0, 0)
; __device__ __forceinline__ void route_task(int task, int tl0, const bf16* QP  , const LAS bf16* KHL, LAS unsigned short* EL, LAS float* GL, int lane) {
;     ...
;     { unsigned qo = (unsigned)t * (unsigned)D + (unsigned)(head * 128 + 8 * hi); asm volatile("" : "+v"(qo)); const bf16* qp = QP + qo;
; #pragma unroll
;       for (int hf = 0; hf < 2; ++hf)
; #pragma unroll
;         for (int ks = 0; ks < 4; ++ks) qa[hf][ks] = ldg8(qp + 64 * hf + 16 * ks); }
;     ...
;         for (int kt = 0; kt < 4; ++kt) {
;             f32x16 X;
; #pragma unroll
;             for (int i = 0; i < 16; ++i) X[i] = 8.f;
;             const LAS bf16* khp = KHL + (half * 128 + 32 * kt + r) * 72 + 8 * hi;
; #pragma unroll
;             for (int ks = 0; ks < 4; ++ks) {
;                 const bf16x8 kh = lds8(khp + 16 * ks);
;                 X = MFMA32(kh, qa[half][ks], X);
;             }
;             int grp[16];
; #pragma unroll
;             for (int i = 0; i < 16; ++i) grp[i] = (int)((__float_as_uint(X[i]) | 127u) - (unsigned)(32 * kt + (i & 3) + 8 * (i >> 2)));
;             sort16_desc(grp);
;             if (kt == 0) {
; #pragma unroll
;                 for (int i = 0; i < 16; ++i) cur[i] = grp[i];
;             } else merge16_desc(cur, grp);
	v_or_b32_e32 v146, s10, v88
	v_mov_b32_e32 v147, v83
	v_lshl_add_u64 v[148:149], v[146:147], 1, s[80:81]
	global_load_dwordx4 v[150:153], v[148:149], off
	global_load_dwordx4 v[154:157], v[148:149], off offset:32
	global_load_dwordx4 v[158:161], v[148:149], off offset:64
	global_load_dwordx4 v[162:165], v[148:149], off offset:96
	global_load_dwordx4 v[166:169], v[148:149], off offset:128
	global_load_dwordx4 v[170:173], v[148:149], off offset:160
	global_load_dwordx4 v[174:177], v[148:149], off offset:192
	global_load_dwordx4 v[178:181], v[148:149], off offset:224
	v_mfma_f32_32x32x16_bf16 v[18:33], v[66:69], v[34:37], v[18:33]
	v_min_i32_e32 v50, v77, v79
	s_nop 10
	v_bitop3_b32 v21, v21, s42, 3 bitop3:0x56
	v_bitop3_b32 v32, v32, s42, 26 bitop3:0x56
	v_bitop3_b32 v22, v22, s42, 8 bitop3:0x56
	v_bitop3_b32 v26, v26, s42, 16 bitop3:0x56
	v_bitop3_b32 v31, v31, s42, 25 bitop3:0x56
	v_bitop3_b32 v23, v23, s42, 9 bitop3:0x56
	v_bitop3_b32 v24, v24, s42, 10 bitop3:0x56
	v_bitop3_b32 v27, v27, s42, 17 bitop3:0x56
	v_bitop3_b32 v28, v28, s42, 18 bitop3:0x56
	v_bitop3_b32 v20, v20, s42, 2 bitop3:0x56
	v_bitop3_b32 v33, v33, s42, 27 bitop3:0x56
	v_bitop3_b32 v25, v25, s42, 11 bitop3:0x56
	v_bitop3_b32 v29, v29, s42, 19 bitop3:0x56
	v_bitop3_b32 v19, v19, s42, 1 bitop3:0x56
	v_bitop3_b32 v30, v30, s42, 24 bitop3:0x56
	v_or_b32_e32 v18, 0x7f, v18
	v_max_i32_e32 v66, v21, v32
	v_max_i32_e32 v67, v22, v26
	v_max_i32_e32 v69, v18, v31
	v_max_i32_e32 v70, v23, v24
	v_min_i32_e32 v73, v27, v28
	v_min_i32_e32 v74, v20, v33
	v_min_i32_e32 v76, v25, v29
	v_min_i32_e32 v77, v19, v30
	v_min_i32_e32 v23, v23, v24
	v_min_i32_e32 v18, v18, v31
	v_min_i32_e32 v22, v22, v26
	v_min_i32_e32 v21, v21, v32
	v_max_i32_e32 v19, v19, v30
	v_max_i32_e32 v25, v25, v29
	v_max_i32_e32 v20, v20, v33
	v_max_i32_e32 v27, v27, v28
	v_max_i32_e32 v24, v23, v18
	v_max_i32_e32 v26, v22, v21
	v_min_i32_e32 v29, v19, v25
	v_min_i32_e32 v28, v20, v27
	v_max_i32_e32 v31, v24, v26
	v_min_i32_e32 v24, v24, v26
	v_min_i32_e32 v26, v29, v28
	v_min_i32_e32 v68, v66, v67
	v_min_i32_e32 v71, v69, v70
	v_max_i32_e32 v75, v73, v74
	v_max_i32_e32 v78, v76, v77
	v_max_i32_e32 v30, v29, v28
	v_max_i32_e32 v28, v24, v26
	v_min_i32_e32 v81, v24, v26
	v_min_i32_e32 v24, v76, v77
	v_min_i32_e32 v18, v23, v18
	v_min_i32_e32 v21, v22, v21
	v_min_i32_e32 v22, v73, v74
	v_min_i32_e32 v72, v68, v71
	v_min_i32_e32 v79, v75, v78
	v_min_i32_e32 v76, v24, v18
	v_min_i32_e32 v74, v21, v22
	v_max_i32_e32 v18, v24, v18
	v_max_i32_e32 v21, v21, v22
	v_max_i32_e32 v23, v69, v70
	v_max_i32_e32 v19, v19, v25
	v_max_i32_e32 v20, v20, v27
	v_max_i32_e32 v25, v66, v67
	v_max_i32_e32 v80, v72, v79
	v_max_i32_e32 v29, v68, v71
	v_max_i32_e32 v68, v75, v78
	v_min_i32_e32 v79, v72, v79
	v_max_i32_e32 v77, v76, v74
	v_min_i32_e32 v124, v18, v21
	v_min_i32_e32 v24, v23, v19
	v_min_i32_e32 v26, v20, v25
	v_min_i32_e32 v32, v31, v30
	v_min_i32_e32 v71, v29, v68
	v_max_i32_e32 v82, v81, v79
	v_max_i32_e32 v125, v77, v124
	v_min_i32_e32 v27, v24, v26
	v_max_i32_e32 v18, v18, v21
	v_min_i32_e32 v33, v80, v32
	v_min_i32_e32 v75, v28, v71
	v_max_i32_e32 v22, v82, v125
	v_min_i32_e32 v21, v27, v18
	v_max_i32_e32 v78, v33, v75
	v_max_i32_e32 v66, v22, v21
	v_max_i32_e32 v70, v78, v66
	v_max_i32_e32 v131, v29, v68
	v_min_i32_e32 v78, v78, v66
	ds_read_b128 v[66:69], v97
	v_max_i32_e32 v127, v23, v19
	v_max_i32_e32 v128, v20, v25
	v_max_i32_e32 v126, v24, v26
	v_min_i32_e32 v129, v127, v128
	v_max_i32_e32 v132, v31, v30
	v_min_i32_e32 v130, v126, v129
	v_min_i32_e32 v133, v131, v132
	v_max_i32_e32 v18, v27, v18
	v_min_i32_e32 v19, v130, v133
	v_max_i32_e32 v23, v80, v32
	v_max_i32_e32 v24, v28, v71
	v_min_i32_e32 v20, v18, v19
	v_min_i32_e32 v25, v23, v24
	v_min_i32_e32 v26, v20, v25
	v_min_i32_e32 v80, v70, v26
	v_max_i32_e32 v143, v70, v26
	ds_read_b128 v[70:73], v97 offset:32
	v_min_i32_e32 v75, v33, v75
	v_min_i32_e32 v134, v22, v21
	v_max_i32_e32 v138, v18, v19
	v_max_i32_e32 v139, v23, v24
	v_max_i32_e32 v141, v20, v25
	s_waitcnt lgkmcnt(1)
	v_mfma_f32_32x32x16_bf16 v[18:33], v[66:69], v[46:49], v[2:17]
	ds_read_b128 v[66:69], v97 offset:64
	v_max_i32_e32 v135, v75, v134
	v_max_i32_e32 v136, v78, v135
	v_min_i32_e32 v79, v81, v79
	v_min_i32_e32 v77, v77, v124
	v_min_i32_e32 v78, v78, v135
	v_max_i32_e32 v130, v130, v133
	s_waitcnt lgkmcnt(1)
	v_mfma_f32_32x32x16_bf16 v[18:33], v[70:73], v[42:45], v[18:33]
	ds_read_b128 v[70:73], v97 offset:96
	v_max_i32_e32 v126, v126, v129
	v_min_i32_e32 v74, v76, v74
	v_min_i32_e32 v140, v138, v139
	v_max_i32_e32 v81, v79, v77
	v_min_i32_e32 v82, v82, v125
	v_min_i32_e32 v75, v75, v134
	s_waitcnt lgkmcnt(1)
	v_mfma_f32_32x32x16_bf16 v[18:33], v[66:69], v[38:41], v[18:33]
	v_max_i32_e32 v66, v131, v132
	v_max_i32_e32 v134, v138, v139
	v_min_i32_e32 v77, v79, v77
	v_max_i32_e32 v124, v81, v82
	v_min_i32_e32 v81, v81, v82
	v_min_i32_e32 v67, v126, v66
	v_min_i32_e32 v142, v140, v141
	s_waitcnt lgkmcnt(0)
; #define LAS __attribute__((address_space(3)))
; #define MFMA32(a, b, c) __builtin_amdgcn_mfma_f32_32x32x16_bf16((a), (b), (c), 0, 0, 0)
; __device__ __forceinline__ void route_task(int task, int tl0, const bf16* QP  , const LAS bf16* KHL, LAS unsigned short* EL, LAS float* GL, int lane) {
;     ...
;         for (int kt = 0; kt < 4; ++kt) {
;             f32x16 X;
; #pragma unroll
;             for (int i = 0; i < 16; ++i) X[i] = 8.f;
;             const LAS bf16* khp = KHL + (half * 128 + 32 * kt + r) * 72 + 8 * hi;
; #pragma unroll
;             for (int ks = 0; ks < 4; ++ks) {
;                 const bf16x8 kh = lds8(khp + 16 * ks);
;                 X = MFMA32(kh, qa[half][ks], X);
;             }
;             int grp[16];
; #pragma unroll
;             for (int i = 0; i < 16; ++i) grp[i] = (int)((__float_as_uint(X[i]) | 127u) - (unsigned)(32 * kt + (i & 3) + 8 * (i >> 2)));
;             sort16_desc(grp);
;             if (kt == 0) {
; #pragma unroll
;                 for (int i = 0; i < 16; ++i) cur[i] = grp[i];
;             } else merge16_desc(cur, grp);
	v_mfma_f32_32x32x16_bf16 v[18:33], v[70:73], v[34:37], v[18:33]
	v_min_i32_e32 v68, v130, v67
	v_min_i32_e32 v137, v80, v136
	v_min_i32_e32 v144, v142, v143
	v_min_i32_e32 v125, v124, v75
	v_min_i32_e32 v69, v134, v68
	s_nop 6
	v_bitop3_b32 v21, v21, s42, 35 bitop3:0x56
	v_bitop3_b32 v32, v32, s42, 58 bitop3:0x56
	v_bitop3_b32 v22, v22, s42, 40 bitop3:0x56
	v_bitop3_b32 v26, v26, s42, 48 bitop3:0x56
	v_bitop3_b32 v18, v18, s42, 32 bitop3:0x56
	v_bitop3_b32 v31, v31, s42, 57 bitop3:0x56
	v_bitop3_b32 v23, v23, s42, 41 bitop3:0x56
	v_bitop3_b32 v24, v24, s42, 42 bitop3:0x56
	v_bitop3_b32 v27, v27, s42, 49 bitop3:0x56
	v_bitop3_b32 v28, v28, s42, 50 bitop3:0x56
	v_bitop3_b32 v20, v20, s42, 34 bitop3:0x56
	v_bitop3_b32 v33, v33, s42, 59 bitop3:0x56
	v_bitop3_b32 v25, v25, s42, 43 bitop3:0x56
	v_bitop3_b32 v29, v29, s42, 51 bitop3:0x56
	v_bitop3_b32 v19, v19, s42, 33 bitop3:0x56
	v_bitop3_b32 v30, v30, s42, 56 bitop3:0x56
	v_max_i32_e32 v70, v21, v32
	v_max_i32_e32 v71, v22, v26
	v_max_i32_e32 v73, v18, v31
	v_max_i32_e32 v76, v23, v24
	v_min_i32_e32 v129, v27, v28
	v_min_i32_e32 v131, v20, v33
	v_min_i32_e32 v133, v25, v29
	v_min_i32_e32 v135, v19, v30
	v_min_i32_e32 v23, v23, v24
	v_min_i32_e32 v18, v18, v31
	v_min_i32_e32 v22, v22, v26
	v_min_i32_e32 v21, v21, v32
	v_max_i32_e32 v19, v19, v30
	v_max_i32_e32 v25, v25, v29
	v_max_i32_e32 v20, v20, v33
	v_max_i32_e32 v27, v27, v28
	v_min_i32_e32 v72, v70, v71
	v_min_i32_e32 v79, v73, v76
	v_max_i32_e32 v132, v129, v131
	v_max_i32_e32 v138, v133, v135
	v_max_i32_e32 v24, v23, v18
	v_max_i32_e32 v26, v22, v21
	v_min_i32_e32 v29, v19, v25
	v_min_i32_e32 v28, v20, v27
	v_min_i32_e32 v133, v133, v135
	v_min_i32_e32 v18, v23, v18
	v_min_i32_e32 v21, v22, v21
	v_min_i32_e32 v22, v129, v131
	v_max_i32_e32 v73, v73, v76
	v_max_i32_e32 v19, v19, v25
	v_max_i32_e32 v20, v20, v27
	v_max_i32_e32 v27, v70, v71
	v_min_i32_e32 v82, v72, v79
	v_min_i32_e32 v139, v132, v138
	v_max_i32_e32 v31, v24, v26
	v_max_i32_e32 v30, v29, v28
	v_min_i32_e32 v24, v24, v26
	v_min_i32_e32 v26, v29, v28
	v_max_i32_e32 v29, v72, v79
	v_max_i32_e32 v72, v132, v138
	v_min_i32_e32 v23, v133, v18
	v_min_i32_e32 v129, v21, v22
	v_max_i32_e32 v18, v133, v18
	v_max_i32_e32 v21, v21, v22
	v_min_i32_e32 v25, v73, v19
	v_min_i32_e32 v70, v20, v27
	v_max_i32_e32 v19, v73, v19
	v_max_i32_e32 v20, v20, v27
	v_min_i32_e32 v32, v31, v30
	v_max_i32_e32 v28, v24, v26
	v_min_i32_e32 v79, v29, v72
	v_min_i32_e32 v24, v24, v26
	v_min_i32_e32 v26, v82, v139
	v_max_i32_e32 v131, v23, v129
	v_min_i32_e32 v22, v18, v21
	v_min_i32_e32 v71, v25, v70
	v_max_i32_e32 v25, v25, v70
	v_min_i32_e32 v27, v19, v20
	v_max_i32_e32 v29, v29, v72
	v_max_i32_e32 v30, v31, v30
	v_max_i32_e32 v145, v82, v139
	v_max_i32_e32 v82, v24, v26
	v_max_i32_e32 v133, v131, v22
	v_max_i32_e32 v18, v18, v21
	v_min_i32_e32 v70, v25, v27
	v_min_i32_e32 v31, v29, v30
	v_min_i32_e32 v33, v145, v32
	v_min_i32_e32 v132, v28, v79
	v_max_i32_e32 v135, v82, v133
	v_min_i32_e32 v21, v71, v18
	v_max_i32_e32 v18, v71, v18
	v_min_i32_e32 v71, v70, v31
	v_max_i32_e32 v32, v145, v32
	v_max_i32_e32 v28, v28, v79
	v_max_i32_e32 v138, v33, v132
	v_max_i32_e32 v76, v135, v21
	v_min_i32_e32 v72, v18, v71
	v_min_i32_e32 v73, v32, v28
	v_min_i32_e32 v33, v33, v132
	v_min_i32_e32 v21, v135, v21
	v_max_i32_e32 v18, v18, v71
	v_max_i32_e32 v28, v32, v28
	v_min_i32_e32 v24, v24, v26
	v_min_i32_e32 v22, v131, v22
	v_max_i32_e32 v25, v25, v27
	v_max_i32_e32 v27, v29, v30
	v_max_i32_e32 v139, v138, v76
	v_min_i32_e32 v79, v72, v73
	v_min_i32_e32 v76, v138, v76
	v_max_i32_e32 v132, v33, v21
	v_min_i32_e32 v32, v18, v28
	v_max_i32_e32 v71, v72, v73
	v_max_i32_e32 v26, v24, v22
	v_min_i32_e32 v82, v82, v133
	v_max_i32_e32 v18, v18, v28
	v_max_i32_e32 v28, v70, v31
	v_min_i32_e32 v29, v25, v27
	v_min_i32_e32 v145, v139, v79
	v_max_i32_e32 v135, v76, v132
	v_min_i32_e32 v72, v32, v71
	v_max_i32_e32 v73, v139, v79
	v_max_i32_e32 v131, v26, v82
	v_min_i32_e32 v21, v33, v21
	v_min_i32_e32 v30, v28, v29
	v_min_i32_e32 v138, v145, v135
	v_min_i32_e32 v79, v72, v73
	v_min_i32_e32 v33, v131, v21
	v_min_i32_e32 v76, v76, v132
	v_min_i32_e32 v31, v18, v30
	v_min_i32_e32 v26, v26, v82
	v_min_i32_e32 v22, v24, v22
	v_min_i32_e32 v23, v23, v129
	v_max3_i32 v23, v127, v128, v23
	v_max3_i32 v22, v126, v66, v22
	v_max3_i32 v24, v130, v67, v26
	v_max3_i32 v26, v134, v68, v33
	v_max3_i32 v21, v69, v131, v21
	v_max3_i32 v33, v140, v141, v76
	v_max3_i32 v66, v142, v143, v138
	v_max3_i32 v67, v144, v145, v135
	v_max3_i32 v68, v80, v136, v79
	v_max3_i32 v69, v137, v72, v73
	v_max3_i32 v32, v78, v32, v71
	v_max3_i32 v31, v124, v75, v31
	v_max3_i32 v18, v125, v18, v30
	v_max3_i32 v28, v81, v28, v29
	v_max3_i32 v25, v77, v25, v27
	v_max3_i32 v19, v74, v19, v20
	v_max_i32_e32 v20, v23, v68
	v_min_i32_e32 v23, v23, v68
	v_max_i32_e32 v27, v22, v69
	v_min_i32_e32 v22, v22, v69
	v_max_i32_e32 v29, v24, v32
	v_min_i32_e32 v24, v24, v32
	v_max_i32_e32 v30, v26, v31
	v_min_i32_e32 v26, v26, v31
	v_max_i32_e32 v31, v21, v18
	v_min_i32_e32 v18, v21, v18
	v_max_i32_e32 v21, v33, v28
	v_min_i32_e32 v28, v33, v28
	v_max_i32_e32 v32, v66, v25
	v_min_i32_e32 v25, v66, v25
	v_max_i32_e32 v33, v67, v19
	v_min_i32_e32 v19, v67, v19
	ds_read_b128 v[66:69], v94 offset:27648
	v_max_i32_e32 v70, v20, v31
	v_min_i32_e32 v74, v20, v31
	v_max_i32_e32 v20, v27, v21
	v_min_i32_e32 v75, v27, v21
	v_max_i32_e32 v21, v29, v32
	v_max_i32_e32 v27, v30, v33
	v_max_i32_e32 v127, v70, v21
	v_min_i32_e32 v128, v70, v21
	ds_read_b128 v[70:73], v94 offset:27680
	v_min_i32_e32 v76, v29, v32
	v_min_i32_e32 v77, v30, v33
	v_max_i32_e32 v78, v23, v18
	v_min_i32_e32 v79, v23, v18
	v_max_i32_e32 v80, v22, v28
	v_min_i32_e32 v81, v22, v28
	v_max_i32_e32 v82, v24, v25
	v_min_i32_e32 v124, v24, v25
	v_max_i32_e32 v125, v26, v19
	v_min_i32_e32 v126, v26, v19
	v_max_i32_e32 v129, v20, v27
	v_min_i32_e32 v130, v20, v27
	s_waitcnt lgkmcnt(1)
; #define LAS __attribute__((address_space(3)))
; #define MFMA32(a, b, c) __builtin_amdgcn_mfma_f32_32x32x16_bf16((a), (b), (c), 0, 0, 0)
; __device__ __forceinline__ void route_task(int task, int tl0, const bf16* QP  , const LAS bf16* KHL, LAS unsigned short* EL, LAS float* GL, int lane) {
;     ...
;         for (int kt = 0; kt < 4; ++kt) {
;             f32x16 X;
; #pragma unroll
;             for (int i = 0; i < 16; ++i) X[i] = 8.f;
;             const LAS bf16* khp = KHL + (half * 128 + 32 * kt + r) * 72 + 8 * hi;
; #pragma unroll
;             for (int ks = 0; ks < 4; ++ks) {
;                 const bf16x8 kh = lds8(khp + 16 * ks);
;                 X = MFMA32(kh, qa[half][ks], X);
;             }
;             int grp[16];
; #pragma unroll
;             for (int i = 0; i < 16; ++i) grp[i] = (int)((__float_as_uint(X[i]) | 127u) - (unsigned)(32 * kt + (i & 3) + 8 * (i >> 2)));
;             sort16_desc(grp);
;             if (kt == 0) {
; #pragma unroll
;                 for (int i = 0; i < 16; ++i) cur[i] = grp[i];
;             } else merge16_desc(cur, grp);
	v_mfma_f32_32x32x16_bf16 v[18:33], v[66:69], v[46:49], v[2:17]
	ds_read_b128 v[66:69], v94 offset:27712
	v_max_i32_e32 v131, v74, v76
	v_min_i32_e32 v74, v74, v76
	v_max_i32_e32 v76, v75, v77
	v_min_i32_e32 v75, v75, v77
	v_max_i32_e32 v77, v78, v82
	v_min_i32_e32 v78, v78, v82
	s_waitcnt lgkmcnt(1)
	v_mfma_f32_32x32x16_bf16 v[18:33], v[70:73], v[42:45], v[18:33]
	ds_read_b128 v[70:73], v94 offset:27744
	v_max_i32_e32 v82, v80, v125
	v_min_i32_e32 v80, v80, v125
	v_max_i32_e32 v125, v79, v124
	v_min_i32_e32 v79, v79, v124
	v_max_i32_e32 v124, v81, v126
	v_min_i32_e32 v81, v81, v126
	s_waitcnt lgkmcnt(1)
	v_mfma_f32_32x32x16_bf16 v[18:33], v[66:69], v[38:41], v[18:33]
	v_min_i32_e32 v126, v127, v129
	v_min_i32_e32 v66, v128, v130
	v_min_i32_e32 v67, v131, v76
	v_min_i32_e32 v69, v77, v82
	v_min_i32_e32 v132, v78, v80
	v_min_i32_e32 v133, v125, v124
	v_min_i32_e32 v68, v74, v75
	s_waitcnt lgkmcnt(0)
	v_mfma_f32_32x32x16_bf16 v[18:33], v[70:73], v[34:37], v[18:33]
	v_min_i32_e32 v134, v79, v81
	s_nop 10
	v_and_or_b32 v21, v21, s43, 60
	v_and_or_b32 v32, v32, s43, 37
	v_and_or_b32 v22, v22, s43, 55
	v_and_or_b32 v26, v26, s43, 47
	v_bitop3_b32 v18, v18, s42, 64 bitop3:0x56
	v_and_or_b32 v31, v31, s43, 38
	v_and_or_b32 v23, v23, s43, 54
	v_and_or_b32 v24, v24, s43, 53
	v_and_or_b32 v27, v27, s43, 46
	v_and_or_b32 v28, v28, s43, 45
	v_and_or_b32 v20, v20, s43, 61
	v_and_or_b32 v33, v33, s43, 36
	v_and_or_b32 v25, v25, s43, 52
	v_and_or_b32 v29, v29, s43, 44
	v_and_or_b32 v19, v19, s43, 62
	v_and_or_b32 v30, v30, s43, 39
	v_max_i32_e32 v70, v21, v32
	v_max_i32_e32 v71, v22, v26
	v_max_i32_e32 v73, v18, v31
	v_max_i32_e32 v135, v23, v24
	v_min_i32_e32 v138, v27, v28
	v_min_i32_e32 v139, v20, v33
	v_min_i32_e32 v141, v25, v29
	v_min_i32_e32 v142, v19, v30
	v_min_i32_e32 v23, v23, v24
	v_min_i32_e32 v18, v18, v31
	v_min_i32_e32 v22, v22, v26
	v_min_i32_e32 v21, v21, v32
	v_max_i32_e32 v19, v19, v30
	v_max_i32_e32 v25, v25, v29
	v_max_i32_e32 v20, v20, v33
	v_max_i32_e32 v27, v27, v28
	v_min_i32_e32 v72, v70, v71
	v_min_i32_e32 v136, v73, v135
	v_max_i32_e32 v140, v138, v139
	v_max_i32_e32 v143, v141, v142
	v_max_i32_e32 v24, v23, v18
	v_max_i32_e32 v26, v22, v21
	v_min_i32_e32 v29, v19, v25
	v_min_i32_e32 v28, v20, v27
	v_min_i32_e32 v141, v141, v142
	v_min_i32_e32 v18, v23, v18
	v_min_i32_e32 v21, v22, v21
	v_min_i32_e32 v22, v138, v139
	v_max_i32_e32 v73, v73, v135
	v_max_i32_e32 v19, v19, v25
	v_max_i32_e32 v20, v20, v27
	v_max_i32_e32 v27, v70, v71
	v_min_i32_e32 v137, v72, v136
	v_min_i32_e32 v144, v140, v143
	v_max_i32_e32 v31, v24, v26
	v_max_i32_e32 v30, v29, v28
	v_min_i32_e32 v24, v24, v26
	v_min_i32_e32 v26, v29, v28
	v_max_i32_e32 v29, v72, v136
	v_max_i32_e32 v72, v140, v143
	v_min_i32_e32 v23, v141, v18
	v_min_i32_e32 v138, v21, v22
	v_max_i32_e32 v18, v141, v18
	v_max_i32_e32 v21, v21, v22
	v_min_i32_e32 v25, v73, v19
	v_min_i32_e32 v70, v20, v27
	v_max_i32_e32 v19, v73, v19
	v_max_i32_e32 v20, v20, v27
	v_min_i32_e32 v32, v31, v30
	v_max_i32_e32 v28, v24, v26
	v_min_i32_e32 v136, v29, v72
	v_min_i32_e32 v24, v24, v26
	v_min_i32_e32 v26, v137, v144
	v_max_i32_e32 v139, v23, v138
	v_min_i32_e32 v22, v18, v21
	v_min_i32_e32 v71, v25, v70
	v_max_i32_e32 v25, v25, v70
	v_min_i32_e32 v27, v19, v20
	v_max_i32_e32 v29, v29, v72
	v_max_i32_e32 v30, v31, v30
	v_max_i32_e32 v145, v137, v144
	v_max_i32_e32 v137, v24, v26
	v_max_i32_e32 v141, v139, v22
	v_max_i32_e32 v18, v18, v21
	v_min_i32_e32 v70, v25, v27
	v_min_i32_e32 v31, v29, v30
	v_min_i32_e32 v33, v145, v32
	v_min_i32_e32 v140, v28, v136
	v_max_i32_e32 v142, v137, v141
	v_min_i32_e32 v21, v71, v18
	v_max_i32_e32 v18, v71, v18
	v_min_i32_e32 v71, v70, v31
	v_max_i32_e32 v32, v145, v32
	v_max_i32_e32 v28, v28, v136
	v_max_i32_e32 v143, v33, v140
	v_max_i32_e32 v135, v142, v21
	v_min_i32_e32 v72, v18, v71
	v_min_i32_e32 v73, v32, v28
	v_min_i32_e32 v33, v33, v140
	v_min_i32_e32 v21, v142, v21
	v_max_i32_e32 v18, v18, v71
	v_max_i32_e32 v28, v32, v28
	v_min_i32_e32 v24, v24, v26
	v_min_i32_e32 v22, v139, v22
	v_max_i32_e32 v25, v25, v27
	v_max_i32_e32 v27, v29, v30
	v_max_i32_e32 v144, v143, v135
	v_min_i32_e32 v136, v72, v73
	v_min_i32_e32 v135, v143, v135
	v_max_i32_e32 v140, v33, v21
	v_min_i32_e32 v32, v18, v28
	v_max_i32_e32 v71, v72, v73
	v_max_i32_e32 v26, v24, v22
	v_min_i32_e32 v137, v137, v141
	v_max_i32_e32 v18, v18, v28
	v_max_i32_e32 v28, v70, v31
	v_min_i32_e32 v29, v25, v27
	v_min_i32_e32 v145, v144, v136
	v_max_i32_e32 v142, v135, v140
	v_min_i32_e32 v72, v32, v71
	v_max_i32_e32 v73, v144, v136
	v_max_i32_e32 v139, v26, v137
	v_min_i32_e32 v21, v33, v21
	v_min_i32_e32 v30, v28, v29
	v_min_i32_e32 v143, v145, v142
	v_min_i32_e32 v136, v72, v73
	v_min_i32_e32 v33, v139, v21
	v_max_i32_e32 v21, v139, v21
	v_min_i32_e32 v135, v135, v140
	v_max_i32_e32 v32, v32, v71
	v_min_i32_e32 v31, v18, v30
	v_max_i32_e32 v18, v18, v30
	v_min_i32_e32 v26, v26, v137
	v_min_i32_e32 v22, v24, v22
	v_max_i32_e32 v24, v25, v27
	v_min_i32_e32 v23, v23, v138
	v_max3_i32 v23, v127, v129, v23
	v_max_i32_e32 v22, v126, v22
	v_max3_i32 v25, v128, v130, v26
	v_max_i32_e32 v26, v66, v33
	v_max3_i32 v21, v131, v76, v21
	v_max_i32_e32 v27, v67, v135
	v_max3_i32 v30, v74, v75, v143
	v_max3_i32 v66, v77, v82, v136
	v_max3_i32 v67, v69, v72, v73
	v_max3_i32 v32, v78, v80, v32
	v_max_i32_e32 v31, v132, v31
	v_max3_i32 v18, v125, v124, v18
	v_max3_i32 v28, v133, v28, v29
	v_max3_i32 v24, v79, v81, v24
	v_max3_i32 v33, v68, v145, v142
	v_max3_i32 v19, v134, v19, v20
	v_max_i32_e32 v20, v23, v66
	v_min_i32_e32 v23, v23, v66
	v_max_i32_e32 v29, v22, v67
	v_max_i32_e32 v66, v25, v32
	v_min_i32_e32 v25, v25, v32
	v_max_i32_e32 v32, v26, v31
	v_min_i32_e32 v26, v26, v31
	v_max_i32_e32 v31, v21, v18
	v_min_i32_e32 v18, v21, v18
	v_max_i32_e32 v21, v27, v28
	v_min_i32_e32 v27, v27, v28
	v_max_i32_e32 v28, v30, v24
	v_min_i32_e32 v22, v22, v67
	v_min_i32_e32 v24, v30, v24
	v_max_i32_e32 v30, v33, v19
	v_min_i32_e32 v19, v33, v19
	v_max_i32_e32 v33, v20, v31
	v_min_i32_e32 v74, v20, v31
	v_max_i32_e32 v20, v29, v21
	v_min_i32_e32 v75, v29, v21
	v_max_i32_e32 v21, v66, v28
	v_min_i32_e32 v76, v66, v28
	ds_read_b128 v[66:69], v98
	ds_read_b128 v[70:73], v98 offset:32
	v_max_i32_e32 v28, v32, v30
	v_min_i32_e32 v77, v32, v30
	v_max_i32_e32 v78, v23, v18
	v_min_i32_e32 v79, v23, v18
	v_max_i32_e32 v80, v22, v27
	v_min_i32_e32 v81, v22, v27
	v_max_i32_e32 v82, v25, v24
	v_min_i32_e32 v124, v25, v24
	v_max_i32_e32 v125, v26, v19
	v_min_i32_e32 v126, v26, v19
	v_max_i32_e32 v127, v33, v21
	v_min_i32_e32 v128, v33, v21
	v_max_i32_e32 v129, v20, v28
	v_min_i32_e32 v130, v20, v28
	s_waitcnt lgkmcnt(1)
; #define LAS __attribute__((address_space(3)))
; #define MFMA32(a, b, c) __builtin_amdgcn_mfma_f32_32x32x16_bf16((a), (b), (c), 0, 0, 0)
; __device__ __forceinline__ void route_task(int task, int tl0, const bf16* QP  , const LAS bf16* KHL, LAS unsigned short* EL, LAS float* GL, int lane) {
;     ...
;         for (int kt = 0; kt < 4; ++kt) {
;             f32x16 X;
; #pragma unroll
;             for (int i = 0; i < 16; ++i) X[i] = 8.f;
;             const LAS bf16* khp = KHL + (half * 128 + 32 * kt + r) * 72 + 8 * hi;
; #pragma unroll
;             for (int ks = 0; ks < 4; ++ks) {
;                 const bf16x8 kh = lds8(khp + 16 * ks);
;                 X = MFMA32(kh, qa[half][ks], X);
;             }
;             int grp[16];
; #pragma unroll
;             for (int i = 0; i < 16; ++i) grp[i] = (int)((__float_as_uint(X[i]) | 127u) - (unsigned)(32 * kt + (i & 3) + 8 * (i >> 2)));
;             sort16_desc(grp);
;             if (kt == 0) {
; #pragma unroll
;                 for (int i = 0; i < 16; ++i) cur[i] = grp[i];
;             } else merge16_desc(cur, grp);
	v_mfma_f32_32x32x16_bf16 v[18:33], v[66:69], v[46:49], v[2:17]
	ds_read_b128 v[46:49], v98 offset:64
	v_max_i32_e32 v67, v75, v77
	v_min_i32_e32 v68, v75, v77
	v_max_i32_e32 v75, v80, v125
	v_max_i32_e32 v131, v74, v76
	v_min_i32_e32 v66, v74, v76
	v_max_i32_e32 v69, v78, v82
	s_waitcnt lgkmcnt(1)
	v_mfma_f32_32x32x16_bf16 v[18:33], v[70:73], v[42:45], v[18:33]
	ds_read_b128 v[42:45], v98 offset:96
	v_min_i32_e32 v70, v80, v125
	v_max_i32_e32 v71, v79, v124
	v_min_i32_e32 v72, v79, v124
	v_min_i32_e32 v74, v78, v82
	v_max_i32_e32 v73, v81, v126
	v_min_i32_e32 v76, v81, v126
	s_waitcnt lgkmcnt(1)
	v_mfma_f32_32x32x16_bf16 v[18:33], v[46:49], v[38:41], v[18:33]
	v_min_i32_e32 v77, v127, v129
	v_min_i32_e32 v38, v128, v130
	v_min_i32_e32 v39, v131, v67
	v_min_i32_e32 v40, v66, v68
	v_min_i32_e32 v41, v69, v75
	v_min_i32_e32 v46, v74, v70
	v_min_i32_e32 v47, v71, v73
	s_waitcnt lgkmcnt(0)
	v_mfma_f32_32x32x16_bf16 v[18:33], v[42:45], v[34:37], v[18:33]
	v_min_i32_e32 v48, v72, v76
	s_nop 10
	v_and_or_b32 v25, v25, s43, 20
	v_and_or_b32 v29, v29, s43, 12
	v_and_or_b32 v19, v19, s43, 30
	v_and_or_b32 v30, v30, s43, 7
	v_and_or_b32 v23, v23, s43, 22
	v_and_or_b32 v24, v24, s43, 21
	v_and_or_b32 v18, v18, s43, 31
	v_and_or_b32 v31, v31, s43, 6
	v_and_or_b32 v22, v22, s43, 23
	v_and_or_b32 v26, v26, s43, 15
	v_and_or_b32 v21, v21, s43, 28
	v_and_or_b32 v32, v32, s43, 5
	v_and_or_b32 v27, v27, s43, 14
	v_and_or_b32 v28, v28, s43, 13
	v_and_or_b32 v20, v20, s43, 29
	v_and_or_b32 v33, v33, s43, 4
	v_min_i32_e32 v34, v25, v29
	v_min_i32_e32 v35, v19, v30
	v_min_i32_e32 v37, v23, v24
	v_min_i32_e32 v42, v18, v31
	v_min_i32_e32 v45, v22, v26
	v_min_i32_e32 v49, v21, v32
	v_min_i32_e32 v79, v27, v28
	v_min_i32_e32 v80, v20, v33
	v_max_i32_e32 v18, v18, v31
	v_max_i32_e32 v23, v23, v24
	v_max_i32_e32 v19, v19, v30
	v_max_i32_e32 v25, v25, v29
	v_max_i32_e32 v20, v20, v33
	v_max_i32_e32 v27, v27, v28
	v_max_i32_e32 v21, v21, v32
	v_max_i32_e32 v22, v22, v26
	v_max_i32_e32 v24, v18, v23
	v_max_i32_e32 v29, v19, v25
	v_max_i32_e32 v28, v20, v27
	v_max_i32_e32 v26, v21, v22
	v_min_i32_e32 v30, v24, v29
	v_min_i32_e32 v31, v28, v26
	v_min_i32_e32 v43, v37, v42
	v_min_i32_e32 v32, v30, v31
	v_max_i32_e32 v30, v30, v31
	v_min_i32_e32 v21, v21, v22
	v_min_i32_e32 v18, v18, v23
	v_max_i32_e32 v23, v79, v80
	v_max_i32_e32 v31, v34, v35
	v_max_i32_e32 v37, v37, v42
	v_max_i32_e32 v42, v45, v49
	v_min_i32_e32 v19, v19, v25
	v_min_i32_e32 v20, v20, v27
	v_min_i32_e32 v36, v34, v35
	v_min_i32_e32 v78, v45, v49
	v_min_i32_e32 v81, v79, v80
	v_max_i32_e32 v22, v21, v18
	v_max_i32_e32 v45, v37, v42
	v_max_i32_e32 v25, v19, v20
	v_min_i32_e32 v18, v21, v18
	v_min_i32_e32 v21, v23, v31
	v_min_i32_e32 v44, v36, v43
	v_min_i32_e32 v82, v78, v81
	v_max_i32_e32 v33, v36, v43
	v_max_i32_e32 v36, v78, v81
	v_max_i32_e32 v24, v24, v29
	v_max_i32_e32 v26, v28, v26
	v_max_i32_e32 v34, v23, v31
	v_max_i32_e32 v27, v45, v25
	v_max_i32_e32 v23, v18, v21
	v_min_i32_e32 v25, v45, v25
	v_min_i32_e32 v37, v37, v42
	v_min_i32_e32 v19, v19, v20
	v_max_i32_e32 v43, v33, v36
	v_min_i32_e32 v28, v24, v26
	v_max_i32_e32 v35, v22, v34
	v_max_i32_e32 v31, v23, v25
	v_max_i32_e32 v20, v37, v19
	v_min_i32_e32 v23, v23, v25
	v_min_i32_e32 v19, v37, v19
	v_min_i32_e32 v18, v18, v21
	v_max_i32_e32 v25, v44, v82
	v_min_i32_e32 v33, v33, v36
	v_min_i32_e32 v29, v30, v28
	v_min_i32_e32 v49, v35, v27
	v_min_i32_e32 v22, v22, v34
	v_max_i32_e32 v21, v19, v18
	v_max_i32_e32 v36, v25, v33
	v_max_i32_e32 v78, v32, v43
	v_min_i32_e32 v79, v29, v49
	v_max_i32_e32 v34, v20, v22
	v_min_i32_e32 v20, v20, v22
	v_max_i32_e32 v37, v21, v36
	v_min_i32_e32 v32, v32, v43
	v_max_i32_e32 v80, v78, v79
	v_max_i32_e32 v42, v31, v34
	v_min_i32_e32 v78, v78, v79
	v_min_i32_e32 v31, v31, v34
	v_max_i32_e32 v22, v23, v20
	v_max_i32_e32 v43, v37, v32
	v_min_i32_e32 v18, v19, v18
	v_min_i32_e32 v19, v25, v33
	v_min_i32_e32 v20, v23, v20
	v_min_i32_e32 v23, v37, v32
	v_max_i32_e32 v28, v30, v28
	v_max_i32_e32 v27, v35, v27
	v_min_i32_e32 v124, v44, v82
	v_min_i32_e32 v45, v80, v42
	v_max_i32_e32 v34, v78, v31
	v_max_i32_e32 v44, v22, v43
	v_min_i32_e32 v31, v78, v31
	v_max_i32_e32 v25, v18, v19
	v_min_i32_e32 v21, v21, v36
	v_min_i32_e32 v32, v20, v23
	v_max_i32_e32 v29, v29, v49
	v_min_i32_e32 v30, v28, v27
	v_min_i32_e32 v22, v22, v43
	v_max_i32_e32 v20, v20, v23
	v_min_i32_e32 v79, v45, v34
	v_max_i32_e32 v78, v44, v31
	v_max_i32_e32 v33, v25, v21
	v_max_i32_e32 v37, v80, v42
	v_min_i32_e32 v35, v29, v30
	v_min_i32_e32 v31, v44, v31
	v_max_i32_e32 v23, v22, v20
	v_min_i32_e32 v81, v79, v78
	v_max_i32_e32 v36, v33, v32
	v_max_i32_e32 v42, v37, v35
	v_min_i32_e32 v21, v25, v21
	v_max_i32_e32 v25, v45, v34
	v_min_i32_e32 v43, v31, v23
	v_max_i32_e32 v27, v28, v27
	v_min_i32_e32 v18, v18, v19
	v_min_i32_e32 v20, v22, v20
	v_min_i32_e32 v32, v33, v32
	v_min_i32_e32 v33, v37, v35
	v_max3_i32 v124, v127, v129, v124
	v_max3_i32 v69, v69, v75, v81
	v_max3_i32 v36, v131, v67, v36
	v_max3_i32 v42, v71, v73, v42
	v_max3_i32 v21, v128, v130, v21
	v_max3_i32 v25, v74, v70, v25
	v_max3_i32 v43, v66, v68, v43
	v_max3_i32 v27, v72, v76, v27
	v_max_i32_e32 v18, v77, v18
	v_max3_i32 v19, v41, v79, v78
	v_max_i32_e32 v20, v39, v20
	v_max3_i32 v22, v47, v29, v30
	v_max_i32_e32 v32, v38, v32
	v_max_i32_e32 v33, v46, v33
	v_max3_i32 v23, v40, v31, v23
	v_max3_i32 v24, v48, v24, v26
	v_min_i32_e32 v49, v36, v42
	v_min_i32_e32 v34, v21, v25
	v_min_i32_e32 v41, v18, v19
	v_min_i32_e32 v29, v20, v22
	v_min_i32_e32 v26, v23, v24
	v_max_i32_e32 v39, v124, v69
	v_max_i32_e32 v36, v36, v42
	v_max_i32_e32 v21, v21, v25
	v_max_i32_e32 v25, v43, v27
; __device__ __forceinline__ void route_task(int task, int tl0, const bf16* QP  , const LAS bf16* KHL, LAS unsigned short* EL, LAS float* GL, int lane) {
;     ...
;         { const unsigned h4 = 4u * (unsigned)hi;
; #pragma unroll
;           for (int i = 0; i < 16; ++i) cur[i] -= (int)h4; }
;         int oth[16];
; #pragma unroll
;         for (int i = 0; i < 16; ++i) oth[i] = __shfl_xor(cur[i], 32);
;         merge16_desc(cur, oth);
; #pragma unroll
;         for (int i = 0; i < 16; ++i) top[half][i] = cur[i];
;     }
;     unsigned P1[4], P2[4];
; #pragma unroll
;     for (int q = 0; q < 4; ++q) { P1[q] = 0u; P2[q] = 0u;
; #pragma unroll
;         for (int s = 0; s < 4; ++s) { P1[q] |= (127u - ((unsigned)top[0][4 * q + s] & 127u)) << (8 * s); P2[q] |= (127u - ((unsigned)top[1][4 * q + s] & 127u)) << (8 * s); } }
	v_max_i32_e32 v18, v18, v19
	v_max_i32_e32 v19, v20, v22
	v_max_i32_e32 v22, v32, v33
	v_max_i32_e32 v23, v23, v24
	v_min_i32_e32 v28, v43, v27
	v_max_i32_e32 v40, v39, v36
	v_max_i32_e32 v27, v21, v25
	v_max_i32_e32 v20, v18, v19
	v_max_i32_e32 v24, v22, v23
	v_min_i32_e32 v35, v32, v33
	v_max_i32_e32 v42, v40, v27
	v_max_i32_e32 v32, v20, v24
	v_min_i32_e32 v27, v40, v27
	v_min_i32_e32 v20, v20, v24
	v_max_i32_e32 v24, v27, v20
	v_min_i32_e32 v20, v27, v20
	v_min_i32_e32 v27, v39, v36
	v_min_i32_e32 v21, v21, v25
	v_min_i32_e32 v18, v18, v19
	v_min_i32_e32 v19, v22, v23
	v_min_i32_e32 v75, v124, v69
	v_max_i32_e32 v25, v27, v21
	v_max_i32_e32 v22, v18, v19
	v_min_i32_e32 v21, v27, v21
	v_min_i32_e32 v18, v18, v19
	v_min_i32_e32 v44, v34, v28
	v_min_i32_e32 v31, v35, v26
	v_max_i32_e32 v23, v25, v22
	v_min_i32_e32 v22, v25, v22
	v_max_i32_e32 v19, v21, v18
	v_min_i32_e32 v18, v21, v18
	v_max_i32_e32 v21, v75, v49
	v_max_i32_e32 v25, v34, v28
	v_max_i32_e32 v28, v41, v29
	v_max_i32_e32 v26, v35, v26
	v_min_i32_e32 v67, v75, v49
	v_min_i32_e32 v30, v41, v29
	v_max_i32_e32 v27, v21, v25
	v_min_i32_e32 v21, v21, v25
	v_min_i32_e32 v25, v28, v26
	v_min_i32_e32 v45, v67, v44
	v_min_i32_e32 v37, v30, v31
	v_max_i32_e32 v29, v28, v26
	v_max_i32_e32 v26, v21, v25
	v_min_i32_e32 v21, v21, v25
	v_max_i32_e32 v25, v67, v44
	v_max_i32_e32 v28, v30, v31
	v_min_i32_e32 v38, v45, v37
	v_max_i32_e32 v33, v42, v32
	v_min_i32_e32 v32, v42, v32
	v_max_i32_e32 v34, v27, v29
	v_min_i32_e32 v27, v27, v29
	v_max_i32_e32 v29, v25, v28
	v_min_i32_e32 v25, v25, v28
	v_max_i32_e32 v28, v45, v37
	v_sub_u32_e32 v30, v33, v87
	v_sub_u32_e32 v31, v32, v87
	v_sub_u32_e32 v24, v24, v87
	v_sub_u32_e32 v20, v20, v87
	v_sub_u32_e32 v23, v23, v87
	v_sub_u32_e32 v22, v22, v87
	v_sub_u32_e32 v19, v19, v87
	v_sub_u32_e32 v18, v18, v87
	v_sub_u32_e32 v32, v34, v87
	v_sub_u32_e32 v27, v27, v87
	v_sub_u32_e32 v26, v26, v87
	v_sub_u32_e32 v21, v21, v87
	v_sub_u32_e32 v29, v29, v87
	v_sub_u32_e32 v25, v25, v87
	v_sub_u32_e32 v28, v28, v87
	v_sub_u32_e32 v33, v38, v87
	ds_bpermute_b32 v34, v123, v30
	ds_bpermute_b32 v35, v123, v31
	ds_bpermute_b32 v36, v123, v24
	ds_bpermute_b32 v37, v123, v20
	ds_bpermute_b32 v38, v123, v23
	ds_bpermute_b32 v39, v123, v22
	ds_bpermute_b32 v40, v123, v19
	ds_bpermute_b32 v41, v123, v18
	ds_bpermute_b32 v42, v123, v32
	ds_bpermute_b32 v43, v123, v27
	ds_bpermute_b32 v44, v123, v26
	ds_bpermute_b32 v45, v123, v33
	ds_bpermute_b32 v46, v123, v28
	ds_bpermute_b32 v47, v123, v25
	ds_bpermute_b32 v48, v123, v29
	ds_bpermute_b32 v49, v123, v21
	s_waitcnt lgkmcnt(4)
	v_max_i32_e32 v30, v30, v45
	s_waitcnt lgkmcnt(3)
	v_max_i32_e32 v31, v31, v46
	s_waitcnt lgkmcnt(2)
	v_max_i32_e32 v24, v24, v47
	s_waitcnt lgkmcnt(1)
	v_max_i32_e32 v20, v20, v48
	s_waitcnt lgkmcnt(0)
	v_max_i32_e32 v23, v23, v49
	v_max_i32_e32 v22, v22, v44
	v_max_i32_e32 v19, v19, v43
	v_max_i32_e32 v18, v18, v42
	v_max_i32_e32 v32, v32, v41
	v_max_i32_e32 v27, v27, v40
	v_max_i32_e32 v26, v26, v39
	v_max_i32_e32 v21, v21, v38
	v_max_i32_e32 v29, v29, v37
	v_max_i32_e32 v25, v25, v36
	v_max_i32_e32 v28, v28, v35
	v_max_i32_e32 v33, v33, v34
	v_max_i32_e32 v34, v30, v32
	v_min_i32_e32 v30, v30, v32
	v_max_i32_e32 v32, v31, v27
	v_min_i32_e32 v27, v31, v27
	v_max_i32_e32 v31, v24, v26
	v_min_i32_e32 v24, v24, v26
	v_max_i32_e32 v26, v20, v21
	v_min_i32_e32 v20, v20, v21
	v_max_i32_e32 v21, v23, v29
	v_min_i32_e32 v23, v23, v29
	v_max_i32_e32 v29, v22, v25
	v_min_i32_e32 v22, v22, v25
	v_max_i32_e32 v25, v19, v28
	v_min_i32_e32 v19, v19, v28
	v_max_i32_e32 v28, v18, v33
	v_min_i32_e32 v18, v18, v33
	v_max_i32_e32 v33, v34, v21
	v_min_i32_e32 v21, v34, v21
	v_max_i32_e32 v34, v32, v29
	v_min_i32_e32 v29, v32, v29
	v_max_i32_e32 v32, v31, v25
	v_min_i32_e32 v25, v31, v25
	v_max_i32_e32 v31, v26, v28
	v_min_i32_e32 v26, v26, v28
	v_max_i32_e32 v28, v30, v23
	v_min_i32_e32 v23, v30, v23
	v_max_i32_e32 v30, v27, v22
	v_min_i32_e32 v22, v27, v22
	v_max_i32_e32 v27, v24, v19
	v_min_i32_e32 v19, v24, v19
	v_max_i32_e32 v24, v20, v18
	v_min_i32_e32 v18, v20, v18
	v_max_i32_e32 v20, v33, v32
	v_min_i32_e32 v32, v33, v32
	v_max_i32_e32 v33, v34, v31
	v_min_i32_e32 v31, v34, v31
	v_max_i32_e32 v34, v21, v25
	v_min_i32_e32 v21, v21, v25
	v_max_i32_e32 v25, v29, v26
	v_min_i32_e32 v29, v29, v26
	v_max_i32_e32 v35, v28, v27
	v_min_i32_e32 v27, v28, v27
	v_max_i32_e32 v28, v30, v24
	v_min_i32_e32 v24, v30, v24
	v_max_i32_e32 v30, v23, v19
	v_min_i32_e32 v19, v23, v19
	v_max_i32_e32 v23, v22, v18
	v_min_i32_e32 v18, v22, v18
	v_max_i32_e32 v26, v20, v33
	v_min_i32_e32 v33, v20, v33
	v_lshlrev_b32_e32 v20, 8, v65
	v_lshlrev_b32_e32 v22, 16, v64
	v_max_i32_e32 v36, v32, v31
	v_max_i32_e32 v40, v19, v18
	v_min_i32_e32 v41, v19, v18
	v_and_b32_e32 v18, 0x7f, v63
	v_and_b32_e32 v20, 0x7f00, v20
	v_and_b32_e32 v22, 0x7f0000, v22
	v_max_i32_e32 v37, v21, v29
	v_min_i32_e32 v29, v21, v29
	v_lshlrev_b32_e32 v21, 8, v33
	v_or3_b32 v18, v20, v18, v22
	v_lshlrev_b32_e32 v20, 16, v36
	v_and_b32_e32 v19, 0x7f, v26
	v_and_b32_e32 v21, 0x7f00, v21
	v_and_b32_e32 v20, 0x7f0000, v20
	v_or3_b32 v20, v21, v19, v20
	v_lshlrev_b32_e32 v19, 24, v62
	v_min_i32_e32 v31, v32, v31
	v_and_b32_e32 v19, 0x7f000000, v19
	v_bitop3_b32 v19, v18, s68, v19 bitop3:0x36
	v_lshlrev_b32_e32 v18, 24, v31
	v_max_i32_e32 v38, v35, v28
	v_min_i32_e32 v28, v35, v28
	v_max_i32_e32 v35, v27, v24
	v_min_i32_e32 v27, v27, v24
	v_and_b32_e32 v18, 0x7f000000, v18
	v_lshlrev_b32_e32 v22, 8, v60
	v_lshlrev_b32_e32 v24, 16, v59
	v_max_i32_e32 v32, v34, v25
	v_min_i32_e32 v34, v34, v25
	v_bitop3_b32 v18, v20, s68, v18 bitop3:0x36
	v_and_b32_e32 v20, 0x7f, v61
; __device__ __forceinline__ void route_task(int task, int tl0, const bf16* QP  , const LAS bf16* KHL, LAS unsigned short* EL, LAS float* GL, int lane) {
;     ...
;     unsigned P1[4], P2[4];
; #pragma unroll
;     for (int q = 0; q < 4; ++q) { P1[q] = 0u; P2[q] = 0u;
; #pragma unroll
;         for (int s = 0; s < 4; ++s) { P1[q] |= (127u - ((unsigned)top[0][4 * q + s] & 127u)) << (8 * s); P2[q] |= (127u - ((unsigned)top[1][4 * q + s] & 127u)) << (8 * s); } }
;     int bk[16];
;     {
;         int hi2 = hi; asm volatile("" : "+v"(hi2));
;         const bool h1 = hi2 != 0;
;         constexpr int A1[16] = {1, 1, 1, 1, 1, 1, 1, 1, 2, 2, 2, 2, 2, 3, 3, 3}, B1[16] = {0, 1, 2, 3, 4, 5, 6, 7, 0, 1, 2, 3, 4, 0, 1, 2};
; #pragma unroll
;         for (int i = 0; i < 16; ++i) { const float ta = __int_as_float(h1 ? top[0][A1[i]] : top[0][0]), tb = __int_as_float(h1 ? top[1][B1[i]] : top[1][i]); const unsigned code = h1 ? (unsigned)(A1[i] * 16 + B1[i]) : (unsigned)i;
;             bk[i] = (int)((__float_as_uint(ta + tb) | 255u) - code); }
;         sort16_desc(bk);
	v_and_b32_e32 v22, 0x7f00, v22
	v_and_b32_e32 v24, 0x7f0000, v24
	v_max_i32_e32 v39, v30, v23
	v_min_i32_e32 v30, v30, v23
	v_lshlrev_b32_e32 v23, 8, v34
	v_or3_b32 v20, v22, v20, v24
	v_lshlrev_b32_e32 v22, 16, v37
	v_and_b32_e32 v21, 0x7f, v32
	v_and_b32_e32 v23, 0x7f00, v23
	v_and_b32_e32 v22, 0x7f0000, v22
	v_or3_b32 v22, v23, v21, v22
	v_lshlrev_b32_e32 v21, 24, v57
	v_and_b32_e32 v21, 0x7f000000, v21
	v_bitop3_b32 v21, v20, s68, v21 bitop3:0x36
	v_lshlrev_b32_e32 v20, 24, v29
	v_and_b32_e32 v20, 0x7f000000, v20
	v_lshlrev_b32_e32 v24, 8, v58
	v_lshlrev_b32_e32 v42, 16, v56
	v_bitop3_b32 v20, v22, s68, v20 bitop3:0x36
	v_and_b32_e32 v22, 0x7f, v55
	v_and_b32_e32 v24, 0x7f00, v24
	v_and_b32_e32 v42, 0x7f0000, v42
	v_lshlrev_b32_e32 v25, 8, v28
	v_or3_b32 v22, v24, v22, v42
	v_lshlrev_b32_e32 v24, 16, v35
	v_and_b32_e32 v23, 0x7f, v38
	v_and_b32_e32 v25, 0x7f00, v25
	v_and_b32_e32 v24, 0x7f0000, v24
	v_or3_b32 v24, v25, v23, v24
	v_lshlrev_b32_e32 v23, 24, v54
	v_and_b32_e32 v23, 0x7f000000, v23
	v_bitop3_b32 v23, v22, s68, v23 bitop3:0x36
	v_lshlrev_b32_e32 v22, 24, v27
	v_and_b32_e32 v22, 0x7f000000, v22
	v_lshlrev_b32_e32 v42, 8, v52
	v_lshlrev_b32_e32 v44, 16, v51
	v_bitop3_b32 v22, v24, s68, v22 bitop3:0x36
	v_and_b32_e32 v24, 0x7f, v53
	v_and_b32_e32 v42, 0x7f00, v42
	v_and_b32_e32 v44, 0x7f0000, v44
	v_lshlrev_b32_e32 v43, 8, v30
	v_or3_b32 v24, v42, v24, v44
	v_lshlrev_b32_e32 v42, 16, v40
	v_and_b32_e32 v25, 0x7f, v39
	v_and_b32_e32 v43, 0x7f00, v43
	v_and_b32_e32 v42, 0x7f0000, v42
	v_or3_b32 v42, v43, v25, v42
	v_lshlrev_b32_e32 v25, 24, v50
	v_and_b32_e32 v25, 0x7f000000, v25
	v_bitop3_b32 v25, v24, s68, v25 bitop3:0x36
	v_lshlrev_b32_e32 v24, 24, v41
	v_and_b32_e32 v24, 0x7f000000, v24
	v_bitop3_b32 v24, v42, s68, v24 bitop3:0x36
	v_mov_b32_e32 v42, v86
	v_add_f32_e32 v55, v55, v26
	v_cmp_eq_u32_e32 vcc, 0, v42
	v_add_f32_e32 v56, v56, v26
	v_add_f32_e32 v54, v54, v26
	v_cndmask_b32_e32 v42, v65, v63, vcc
	v_add_f32_e32 v44, v42, v26
	v_cndmask_b32_e64 v43, -16, 0, vcc
	v_or_b32_e32 v44, 0xff, v44
	v_add_f32_e32 v45, v42, v33
	v_add_u32_e32 v43, v44, v43
	v_cndmask_b32_e64 v44, v99, -1, vcc
	v_or_b32_e32 v45, 0xff, v45
	v_add_f32_e32 v46, v42, v36
	v_add_u32_e32 v44, v45, v44
	v_cndmask_b32_e64 v45, v100, -2, vcc
	v_or_b32_e32 v46, 0xff, v46
	v_add_f32_e32 v47, v42, v31
	v_add_u32_e32 v45, v46, v45
	v_cndmask_b32_e64 v46, v101, -3, vcc
	v_or_b32_e32 v47, 0xff, v47
	v_add_f32_e32 v48, v42, v32
	v_add_u32_e32 v46, v47, v46
	v_cndmask_b32_e64 v47, v102, -4, vcc
	v_or_b32_e32 v48, 0xff, v48
	v_add_f32_e32 v34, v42, v34
	v_add_f32_e32 v37, v42, v37
	v_add_f32_e32 v29, v42, v29
	v_cndmask_b32_e32 v42, v64, v63, vcc
	v_cndmask_b32_e32 v32, v32, v39, vcc
	v_add_u32_e32 v47, v48, v47
	v_cndmask_b32_e64 v48, v103, -5, vcc
	v_or_b32_e32 v34, 0xff, v34
	v_add_f32_e32 v32, v42, v32
	v_add_u32_e32 v34, v34, v48
	v_cndmask_b32_e64 v48, v104, -6, vcc
	v_or_b32_e32 v37, 0xff, v37
	v_cndmask_b32_e32 v38, v26, v38, vcc
	v_cndmask_b32_e64 v39, v116, -12, vcc
	v_or_b32_e32 v32, 0xff, v32
	v_add_u32_e32 v37, v37, v48
	v_cndmask_b32_e64 v48, v105, -7, vcc
	v_or_b32_e32 v29, 0xff, v29
	v_add_f32_e32 v38, v42, v38
	v_cndmask_b32_e32 v28, v33, v28, vcc
	v_add_u32_e32 v32, v32, v39
	v_cndmask_b32_e32 v39, v62, v63, vcc
	v_cndmask_b32_e32 v30, v26, v30, vcc
	v_add_u32_e32 v29, v29, v48
	v_cndmask_b32_e64 v48, v106, -8, vcc
	v_or_b32_e32 v38, 0xff, v38
	v_add_f32_e32 v28, v42, v28
	v_cndmask_b32_e32 v35, v36, v35, vcc
	v_cndmask_b32_e32 v27, v31, v27, vcc
	v_add_f32_e32 v30, v39, v30
	v_cndmask_b32_e32 v40, v33, v40, vcc
	v_add_u32_e32 v38, v38, v48
	v_cndmask_b32_e64 v48, v107, -9, vcc
	v_or_b32_e32 v28, 0xff, v28
	v_add_f32_e32 v35, v42, v35
	v_add_f32_e32 v27, v42, v27
	v_cndmask_b32_e64 v42, v117, -13, vcc
	v_or_b32_e32 v30, 0xff, v30
	v_add_f32_e32 v40, v39, v40
	v_cndmask_b32_e32 v41, v36, v41, vcc
	v_add_u32_e32 v28, v28, v48
	v_cndmask_b32_e64 v48, v114, -10, vcc
	v_or_b32_e32 v35, 0xff, v35
	v_add_u32_e32 v30, v30, v42
	v_cndmask_b32_e64 v42, v118, -14, vcc
	v_or_b32_e32 v40, 0xff, v40
	v_add_f32_e32 v39, v39, v41
	v_add_u32_e32 v35, v35, v48
	v_cndmask_b32_e64 v48, v115, -11, vcc
	v_or_b32_e32 v27, 0xff, v27
	v_add_u32_e32 v40, v40, v42
	v_cndmask_b32_e64 v42, v119, -15, vcc
	v_or_b32_e32 v39, 0xff, v39
	v_add_u32_e32 v27, v27, v48
	v_add_u32_e32 v39, v39, v42
	v_max_i32_e32 v41, v43, v30
	v_min_i32_e32 v30, v43, v30
	v_max_i32_e32 v42, v44, v32
	v_min_i32_e32 v32, v44, v32
	v_max_i32_e32 v43, v45, v39
	v_min_i32_e32 v39, v45, v39
	v_max_i32_e32 v44, v46, v40
	v_min_i32_e32 v40, v46, v40
	v_max_i32_e32 v45, v47, v38
	v_min_i32_e32 v38, v47, v38
	v_max_i32_e32 v46, v34, v37
	v_min_i32_e32 v34, v34, v37
	v_max_i32_e32 v37, v29, v27
	v_min_i32_e32 v27, v29, v27
	v_max_i32_e32 v29, v28, v35
	v_min_i32_e32 v28, v28, v35
	v_max_i32_e32 v35, v41, v46
	v_min_i32_e32 v41, v41, v46
	v_max_i32_e32 v46, v42, v37
	v_min_i32_e32 v37, v42, v37
	v_max_i32_e32 v42, v43, v29
	v_min_i32_e32 v29, v43, v29
	v_max_i32_e32 v43, v44, v45
	v_min_i32_e32 v44, v44, v45
	v_max_i32_e32 v45, v34, v30
	v_min_i32_e32 v30, v34, v30
	v_max_i32_e32 v34, v38, v40
	v_min_i32_e32 v38, v38, v40
	v_max_i32_e32 v40, v28, v39
	v_min_i32_e32 v28, v28, v39
	v_max_i32_e32 v39, v27, v32
	v_min_i32_e32 v27, v27, v32
	v_max_i32_e32 v32, v35, v46
	v_min_i32_e32 v35, v35, v46
	v_max_i32_e32 v46, v42, v43
	v_min_i32_e32 v42, v42, v43
	v_max_i32_e32 v43, v44, v41
	v_min_i32_e32 v41, v44, v41
	v_max_i32_e32 v44, v45, v34
	v_min_i32_e32 v34, v45, v34
	v_max_i32_e32 v45, v37, v29
	v_min_i32_e32 v29, v37, v29
	v_max_i32_e32 v37, v40, v39
	v_min_i32_e32 v39, v40, v39
	v_max_i32_e32 v40, v27, v30
; #define CAND(a, b) (int)((__float_as_uint(__int_as_float(top[0][a]) + __int_as_float(top[1][b])) | 255u) - (unsigned)((a) * 16 + (b)))
; __device__ __forceinline__ void route_task(int task, int tl0, const bf16* QP  , const LAS bf16* KHL, LAS unsigned short* EL, LAS float* GL, int lane) {
;     ...
;         sort16_desc(bk);
;         int oth[16];
; #pragma unroll
;         for (int i = 0; i < 16; ++i) oth[i] = __shfl_xor(bk[i], 32);
;         merge16_desc(bk, oth);
;     }
;     ...
;     {
;         int gk[16];
;         gk[0] = CAND(3, 3); gk[1] = CAND(4, 0); gk[2] = CAND(4, 1); gk[3] = CAND(4, 2); gk[4] = CAND(5, 0); gk[5] = CAND(5, 1); gk[6] = CAND(6, 0); gk[7] = CAND(6, 1);
;         gk[8] = CAND(7, 0); gk[9] = CAND(7, 1); gk[10] = CAND(8, 0); gk[11] = CAND(9, 0); gk[12] = CAND(10, 0); gk[13] = CAND(11, 0); gk[14] = CAND(12, 0); gk[15] = CAND(13, 0);
;         sort16_desc(gk);
	v_min_i32_e32 v27, v27, v30
	v_max_i32_e32 v30, v38, v28
	v_min_i32_e32 v28, v38, v28
	v_max_i32_e32 v38, v32, v46
	v_min_i32_e32 v32, v32, v46
	v_max_i32_e32 v46, v35, v42
	v_min_i32_e32 v35, v35, v42
	v_max_i32_e32 v42, v43, v37
	v_min_i32_e32 v37, v43, v37
	v_max_i32_e32 v43, v41, v39
	v_min_i32_e32 v39, v41, v39
	v_max_i32_e32 v41, v44, v45
	v_min_i32_e32 v44, v44, v45
	v_max_i32_e32 v45, v34, v29
	v_min_i32_e32 v29, v34, v29
	v_max_i32_e32 v34, v40, v30
	v_min_i32_e32 v30, v40, v30
	v_max_i32_e32 v40, v27, v28
	v_min_i32_e32 v27, v27, v28
	v_max_i32_e32 v28, v46, v32
	v_min_i32_e32 v32, v46, v32
	v_max_i32_e32 v46, v35, v34
	v_min_i32_e32 v34, v35, v34
	v_max_i32_e32 v35, v42, v41
	v_min_i32_e32 v41, v42, v41
	v_max_i32_e32 v42, v43, v44
	v_min_i32_e32 v43, v43, v44
	v_max_i32_e32 v44, v45, v37
	v_min_i32_e32 v37, v45, v37
	v_max_i32_e32 v45, v29, v39
	v_min_i32_e32 v29, v29, v39
	v_max_i32_e32 v39, v40, v30
	v_min_i32_e32 v30, v40, v30
	v_max_i32_e32 v40, v28, v35
	v_min_i32_e32 v28, v28, v35
	v_max_i32_e32 v35, v32, v41
	v_min_i32_e32 v32, v32, v41
	v_max_i32_e32 v41, v42, v44
	v_min_i32_e32 v42, v42, v44
	v_max_i32_e32 v44, v43, v37
	v_min_i32_e32 v37, v43, v37
	v_max_i32_e32 v43, v45, v39
	v_min_i32_e32 v39, v45, v39
	v_max_i32_e32 v45, v29, v30
	v_min_i32_e32 v29, v29, v30
	v_max_i32_e32 v30, v35, v28
	v_min_i32_e32 v28, v35, v28
	v_max_i32_e32 v35, v46, v32
	v_min_i32_e32 v32, v46, v32
	v_max_i32_e32 v46, v43, v34
	v_min_i32_e32 v34, v43, v34
	v_max_i32_e32 v43, v45, v39
	v_min_i32_e32 v39, v45, v39
	v_max_i32_e32 v45, v35, v41
	v_min_i32_e32 v35, v35, v41
	v_max_i32_e32 v41, v32, v42
	v_min_i32_e32 v32, v32, v42
	v_max_i32_e32 v42, v44, v46
	v_min_i32_e32 v44, v44, v46
	v_max_i32_e32 v46, v37, v34
	v_min_i32_e32 v34, v37, v34
	v_max_i32_e32 v37, v45, v28
	v_min_i32_e32 v28, v45, v28
	v_max_i32_e32 v45, v35, v41
	v_min_i32_e32 v35, v35, v41
	v_max_i32_e32 v41, v42, v32
	v_min_i32_e32 v32, v42, v32
	v_max_i32_e32 v42, v44, v46
	v_min_i32_e32 v44, v44, v46
	v_max_i32_e32 v46, v43, v34
	v_min_i32_e32 v34, v43, v34
	v_max_i32_e32 v43, v35, v41
	v_min_i32_e32 v35, v35, v41
	v_max_i32_e32 v41, v32, v42
	v_min_i32_e32 v32, v32, v42
	ds_bpermute_b32 v67, v123, v41
	ds_bpermute_b32 v68, v123, v32
	ds_bpermute_b32 v69, v123, v44
	ds_bpermute_b32 v64, v123, v45
	ds_bpermute_b32 v65, v123, v43
	ds_bpermute_b32 v66, v123, v35
	s_waitcnt lgkmcnt(4)
	v_max_i32_e32 v43, v43, v68
	s_waitcnt lgkmcnt(3)
	v_max_i32_e32 v45, v45, v69
	v_max_i32_e32 v35, v35, v67
	v_add_f32_e32 v31, v62, v31
	v_add_f32_e32 v62, v61, v26
	v_add_f32_e32 v67, v61, v33
	v_add_f32_e32 v36, v61, v36
	v_add_f32_e32 v61, v60, v26
	v_add_f32_e32 v60, v60, v33
	v_add_f32_e32 v68, v59, v26
	v_add_f32_e32 v59, v59, v33
	v_add_f32_e32 v69, v57, v26
	v_add_f32_e32 v33, v57, v33
	v_add_f32_e32 v57, v58, v26
	v_add_f32_e32 v53, v53, v26
	v_add_f32_e32 v52, v52, v26
	ds_bpermute_b32 v70, v123, v27
	v_or_b32_e32 v31, 0xff, v31
	v_or_b32_e32 v62, 0xff, v62
	v_or_b32_e32 v67, 0xff, v67
	v_or_b32_e32 v36, 0xff, v36
	v_or_b32_e32 v61, 0xff, v61
	v_or_b32_e32 v60, 0xff, v60
	v_or_b32_e32 v68, 0xff, v68
	v_or_b32_e32 v59, 0xff, v59
	v_or_b32_e32 v69, 0xff, v69
	v_or_b32_e32 v33, 0xff, v33
	v_or_b32_e32 v55, 0xff, v55
	v_or_b32_e32 v57, 0xff, v57
	v_or_b32_e32 v56, 0xff, v56
	v_or_b32_e32 v54, 0xff, v54
	v_or_b32_e32 v53, 0xff, v53
	v_or_b32_e32 v52, 0xff, v52
	v_subrev_u32_e32 v31, 51, v31
	v_subrev_u32_e32 v62, 64, v62
	v_add_u32_e32 v67, 0xffffffbf, v67
	v_add_u32_e32 v36, 0xffffffbe, v36
	v_add_u32_e32 v61, 0xffffffb0, v61
	v_add_u32_e32 v60, 0xffffffaf, v60
	v_add_u32_e32 v68, 0xffffffa0, v68
	v_add_u32_e32 v59, 0xffffff9f, v59
	v_add_u32_e32 v69, 0xffffff90, v69
	v_add_u32_e32 v33, 0xffffff8f, v33
	v_add_u32_e32 v55, 0xffffff80, v55
	v_add_u32_e32 v57, 0xffffff70, v57
	v_add_u32_e32 v56, 0xffffff60, v56
	v_add_u32_e32 v54, 0xffffff50, v54
	v_add_u32_e32 v53, 0xffffff40, v53
	v_add_u32_e32 v52, 0xffffff30, v52
	ds_bpermute_b32 v42, v123, v38
	ds_bpermute_b32 v47, v123, v40
	ds_bpermute_b32 v48, v123, v30
	ds_bpermute_b32 v49, v123, v37
	ds_bpermute_b32 v63, v123, v28
	ds_bpermute_b32 v71, v123, v29
	ds_bpermute_b32 v72, v123, v39
	ds_bpermute_b32 v73, v123, v34
	ds_bpermute_b32 v74, v123, v46
	v_max_i32_e32 v58, v31, v54
	v_min_i32_e32 v31, v31, v54
	v_max_i32_e32 v54, v62, v56
	v_min_i32_e32 v56, v62, v56
	v_max_i32_e32 v62, v67, v52
	v_min_i32_e32 v52, v67, v52
	v_max_i32_e32 v67, v36, v53
	v_min_i32_e32 v36, v36, v53
	v_max_i32_e32 v53, v61, v69
	v_min_i32_e32 v61, v61, v69
	v_max_i32_e32 v69, v60, v68
	v_min_i32_e32 v60, v60, v68
	v_max_i32_e32 v68, v59, v57
	v_min_i32_e32 v57, v59, v57
	v_max_i32_e32 v59, v33, v55
	v_min_i32_e32 v33, v33, v55
	v_max_i32_e32 v55, v58, v69
	v_min_i32_e32 v58, v58, v69
	v_max_i32_e32 v69, v54, v68
	v_min_i32_e32 v54, v54, v68
	v_max_i32_e32 v68, v62, v59
	v_min_i32_e32 v59, v62, v59
	v_max_i32_e32 v62, v67, v53
	v_min_i32_e32 v53, v67, v53
	v_max_i32_e32 v67, v60, v31
	v_min_i32_e32 v31, v60, v31
	v_max_i32_e32 v60, v61, v36
	v_min_i32_e32 v36, v61, v36
	v_max_i32_e32 v61, v33, v52
	v_min_i32_e32 v33, v33, v52
	v_max_i32_e32 v52, v57, v56
	v_min_i32_e32 v56, v57, v56
	v_max_i32_e32 v57, v55, v69
	v_min_i32_e32 v55, v55, v69
	v_max_i32_e32 v69, v68, v62
	v_min_i32_e32 v62, v68, v62
	v_max_i32_e32 v68, v53, v58
	v_min_i32_e32 v53, v53, v58
	v_max_i32_e32 v58, v67, v60
	v_min_i32_e32 v60, v67, v60
	v_max_i32_e32 v67, v54, v59
	v_min_i32_e32 v54, v54, v59
	v_max_i32_e32 v59, v61, v52
	v_min_i32_e32 v52, v61, v52
	v_max_i32_e32 v61, v56, v31
	v_min_i32_e32 v31, v56, v31
	v_max_i32_e32 v56, v36, v33
	v_min_i32_e32 v33, v36, v33
	s_waitcnt lgkmcnt(9)
; #define CE_(a, b) ce_desc(v[a], v[b])
; #define CAND(a, b) (int)((__float_as_uint(__int_as_float(top[0][a]) + __int_as_float(top[1][b])) | 255u) - (unsigned)((a) * 16 + (b)))
; __device__ __forceinline__ void sort16_desc(int (&v)[16]) {
;     ...
;     CE_(0,13); CE_(1,12); CE_(2,15); CE_(3,14); CE_(4,8); CE_(5,6); CE_(7,11); CE_(9,10);
;     CE_(0,5); CE_(1,7); CE_(2,9); CE_(3,4); CE_(6,13); CE_(8,14); CE_(10,15); CE_(11,12);
;     CE_(0,1); CE_(2,3); CE_(4,5); CE_(6,8); CE_(7,9); CE_(10,11); CE_(12,13); CE_(14,15);
;     CE_(0,2); CE_(1,3); CE_(4,10); CE_(5,11); CE_(6,7); CE_(8,9); CE_(12,14); CE_(13,15);
;     CE_(1,2); CE_(3,12); CE_(4,6); CE_(5,7); CE_(8,10); CE_(9,11); CE_(13,14);
;     CE_(1,4); CE_(2,6); CE_(5,8); CE_(7,10); CE_(9,13); CE_(11,14);
;     CE_(2,4); CE_(3,6); CE_(9,12); CE_(11,13);
;     CE_(3,5); CE_(6,8); CE_(7,9); CE_(10,12);
;     CE_(3,4); CE_(5,6); CE_(7,8); CE_(9,10); CE_(11,12);
;     CE_(6,7); CE_(8,9);
;     ...
; }
; __device__ __forceinline__ void merge16_desc(int (&a)[16], const int (&b)[16]) {
; #pragma unroll
;     for (int i = 0; i < 16; ++i) a[i] = a[i] > b[15 - i] ? a[i] : b[15 - i];
; #pragma unroll
;     for (int j = 8; j > 0; j >>= 1)
; #pragma unroll
;         for (int i = 0; i < 16; ++i) { const int l = i ^ j; if (l > i) ce_desc(a[i], a[l]); }
; }
; __device__ __forceinline__ void route_task(int task, int tl0, const bf16* QP  , const LAS bf16* KHL, LAS unsigned short* EL, LAS float* GL, int lane) {
;     ...
;         sort16_desc(bk);
;         int oth[16];
; #pragma unroll
;         for (int i = 0; i < 16; ++i) oth[i] = __shfl_xor(bk[i], 32);
;         merge16_desc(bk, oth);
;     }
;     ...
;     {
;         int gk[16];
;         gk[0] = CAND(3, 3); gk[1] = CAND(4, 0); gk[2] = CAND(4, 1); gk[3] = CAND(4, 2); gk[4] = CAND(5, 0); gk[5] = CAND(5, 1); gk[6] = CAND(6, 0); gk[7] = CAND(6, 1);
;         gk[8] = CAND(7, 0); gk[9] = CAND(7, 1); gk[10] = CAND(8, 0); gk[11] = CAND(9, 0); gk[12] = CAND(10, 0); gk[13] = CAND(11, 0); gk[14] = CAND(12, 0); gk[15] = CAND(13, 0);
;         sort16_desc(gk);
;         merge16_desc(bk, gk);
	v_max_i32_e32 v38, v38, v70
	v_min_i32_e32 v36, v57, v69
	v_max_i32_e32 v70, v55, v62
	v_min_i32_e32 v55, v55, v62
	v_max_i32_e32 v62, v68, v59
	v_min_i32_e32 v59, v68, v59
	v_max_i32_e32 v68, v53, v52
	v_min_i32_e32 v52, v53, v52
	v_max_i32_e32 v53, v58, v67
	v_min_i32_e32 v58, v58, v67
	v_max_i32_e32 v67, v60, v54
	v_min_i32_e32 v54, v60, v54
	v_max_i32_e32 v60, v61, v56
	v_min_i32_e32 v56, v61, v56
	v_max_i32_e32 v61, v31, v33
	v_min_i32_e32 v31, v31, v33
	v_max_i32_e32 v33, v70, v36
	v_min_i32_e32 v36, v70, v36
	v_max_i32_e32 v70, v55, v60
	v_min_i32_e32 v55, v55, v60
	v_max_i32_e32 v60, v62, v53
	v_min_i32_e32 v53, v62, v53
	v_max_i32_e32 v62, v68, v58
	v_min_i32_e32 v58, v68, v58
	v_max_i32_e32 v68, v67, v59
	v_min_i32_e32 v59, v67, v59
	v_max_i32_e32 v67, v54, v52
	v_min_i32_e32 v52, v54, v52
	v_max_i32_e32 v54, v61, v56
	s_waitcnt lgkmcnt(3)
	v_max_i32_e32 v40, v40, v71
	s_waitcnt lgkmcnt(2)
	v_max_i32_e32 v30, v30, v72
	s_waitcnt lgkmcnt(1)
	v_max_i32_e32 v37, v37, v73
	s_waitcnt lgkmcnt(0)
	v_max_i32_e32 v28, v28, v74
	v_max_i32_e32 v41, v41, v66
	v_max_i32_e32 v32, v32, v65
	v_max_i32_e32 v44, v44, v64
	v_max_i32_e32 v46, v46, v63
	v_max_i32_e32 v34, v34, v49
	v_max_i32_e32 v39, v39, v48
	v_max_i32_e32 v29, v29, v47
	v_max_i32_e32 v27, v27, v42
	v_min_i32_e32 v56, v61, v56
	v_max_i32_e32 v61, v33, v60
	v_min_i32_e32 v33, v33, v60
	v_max_i32_e32 v60, v36, v53
	v_min_i32_e32 v36, v36, v53
	v_max_i32_e32 v53, v62, v68
	v_min_i32_e32 v62, v62, v68
	v_max_i32_e32 v68, v58, v59
	v_min_i32_e32 v58, v58, v59
	v_max_i32_e32 v59, v67, v54
	v_max_i32_e32 v42, v38, v41
	v_min_i32_e32 v38, v38, v41
	v_max_i32_e32 v41, v40, v32
	v_min_i32_e32 v32, v40, v32
	v_max_i32_e32 v40, v30, v44
	v_min_i32_e32 v30, v30, v44
	v_max_i32_e32 v44, v37, v46
	v_min_i32_e32 v37, v37, v46
	v_max_i32_e32 v46, v28, v34
	v_min_i32_e32 v28, v28, v34
	v_max_i32_e32 v34, v45, v39
	v_min_i32_e32 v39, v45, v39
	v_max_i32_e32 v45, v43, v29
	v_min_i32_e32 v29, v43, v29
	v_max_i32_e32 v43, v35, v27
	v_min_i32_e32 v27, v35, v27
	v_min_i32_e32 v54, v67, v54
	v_max_i32_e32 v67, v52, v56
	v_max_i32_e32 v71, v70, v36
	v_min_i32_e32 v36, v70, v36
	v_max_i32_e32 v70, v59, v55
	v_min_i32_e32 v55, v59, v55
	v_max_i32_e32 v35, v42, v46
	v_min_i32_e32 v42, v42, v46
	v_max_i32_e32 v46, v41, v34
	v_min_i32_e32 v34, v41, v34
	v_max_i32_e32 v41, v40, v45
	v_min_i32_e32 v40, v40, v45
	v_max_i32_e32 v45, v44, v43
	v_min_i32_e32 v43, v44, v43
	v_max_i32_e32 v44, v38, v28
	v_min_i32_e32 v28, v38, v28
	v_max_i32_e32 v38, v32, v39
	v_min_i32_e32 v32, v32, v39
	v_max_i32_e32 v39, v30, v29
	v_min_i32_e32 v29, v30, v29
	v_max_i32_e32 v30, v37, v27
	v_min_i32_e32 v27, v37, v27
	v_min_i32_e32 v52, v52, v56
	v_min_i32_e32 v56, v60, v33
	v_max_i32_e32 v59, v67, v54
	v_min_i32_e32 v54, v67, v54
	v_max_i32_e32 v67, v71, v53
	v_min_i32_e32 v53, v71, v53
	v_max_i32_e32 v71, v36, v62
	v_min_i32_e32 v36, v36, v62
	v_max_i32_e32 v62, v68, v70
	v_min_i32_e32 v68, v68, v70
	v_max_i32_e32 v70, v58, v55
	v_max_i32_e32 v37, v35, v41
	v_min_i32_e32 v35, v35, v41
	v_max_i32_e32 v41, v46, v45
	v_min_i32_e32 v45, v46, v45
	v_max_i32_e32 v46, v42, v40
	v_min_i32_e32 v40, v42, v40
	v_max_i32_e32 v42, v34, v43
	v_min_i32_e32 v34, v34, v43
	v_max_i32_e32 v43, v44, v39
	v_min_i32_e32 v39, v44, v39
	v_max_i32_e32 v44, v38, v30
	v_min_i32_e32 v30, v38, v30
	v_max_i32_e32 v38, v28, v29
	v_min_i32_e32 v28, v28, v29
	v_max_i32_e32 v29, v32, v27
	v_min_i32_e32 v27, v32, v27
	v_min_i32_e32 v55, v58, v55
	v_max_i32_e32 v58, v67, v56
	v_min_i32_e32 v56, v67, v56
	v_max_i32_e32 v67, v53, v71
	v_min_i32_e32 v53, v53, v71
	v_max_i32_e32 v71, v62, v36
	v_min_i32_e32 v36, v62, v36
	v_max_i32_e32 v62, v68, v70
	v_min_i32_e32 v32, v37, v41
	v_min_i32_e32 v47, v35, v45
	v_min_i32_e32 v48, v46, v42
	v_min_i32_e32 v49, v40, v34
	v_min_i32_e32 v63, v43, v44
	v_min_i32_e32 v64, v39, v30
	v_min_i32_e32 v65, v38, v29
	v_min_i32_e32 v66, v28, v27
	v_min_i32_e32 v68, v68, v70
	v_max_i32_e32 v70, v59, v55
	v_min_i32_e32 v55, v59, v55
	v_min_i32_e32 v59, v53, v71
	v_min_i32_e32 v72, v36, v62
	v_max3_i32 v31, v37, v41, v31
	v_max_i32_e32 v32, v32, v52
	v_max3_i32 v35, v35, v45, v54
	v_max_i32_e32 v37, v47, v55
	v_max3_i32 v41, v46, v42, v70
	v_max_i32_e32 v42, v48, v68
	v_max3_i32 v34, v40, v34, v72
	v_max3_i32 v36, v49, v36, v62
	v_max3_i32 v40, v43, v44, v59
	v_max3_i32 v43, v63, v53, v71
	v_max3_i32 v30, v39, v30, v67
	v_max_i32_e32 v39, v64, v56
	v_max3_i32 v29, v38, v29, v58
	v_max3_i32 v33, v65, v60, v33
	v_max3_i32 v27, v28, v27, v61
	v_max3_i32 v28, v66, v57, v69
	v_max_i32_e32 v38, v31, v40
	v_min_i32_e32 v31, v31, v40
	v_max_i32_e32 v40, v32, v43
	v_min_i32_e32 v32, v32, v43
	v_max_i32_e32 v43, v35, v30
	v_min_i32_e32 v30, v35, v30
	v_max_i32_e32 v35, v37, v39
	v_min_i32_e32 v37, v37, v39
	v_max_i32_e32 v39, v41, v29
	v_min_i32_e32 v29, v41, v29
	v_max_i32_e32 v41, v42, v33
	v_min_i32_e32 v33, v42, v33
	v_max_i32_e32 v42, v34, v27
	v_min_i32_e32 v27, v34, v27
	v_max_i32_e32 v34, v36, v28
	v_min_i32_e32 v28, v36, v28
	v_max_i32_e32 v36, v38, v39
	v_min_i32_e32 v38, v38, v39
	v_max_i32_e32 v39, v40, v41
	v_min_i32_e32 v40, v40, v41
	v_max_i32_e32 v41, v43, v42
	v_min_i32_e32 v42, v43, v42
	v_max_i32_e32 v43, v35, v34
	v_min_i32_e32 v34, v35, v34
	v_max_i32_e32 v35, v31, v29
	v_min_i32_e32 v29, v31, v29
	v_max_i32_e32 v31, v32, v33
	v_min_i32_e32 v32, v32, v33
	v_max_i32_e32 v33, v30, v27
	v_min_i32_e32 v27, v30, v27
	v_max_i32_e32 v30, v37, v28
	v_min_i32_e32 v28, v37, v28
	v_max_i32_e32 v37, v36, v41
	v_min_i32_e32 v36, v36, v41
	v_max_i32_e32 v41, v39, v43
	v_min_i32_e32 v39, v39, v43
	v_max_i32_e32 v43, v38, v42
	v_min_i32_e32 v38, v38, v42
; #define CAND(a, b) (int)((__float_as_uint(__int_as_float(top[0][a]) + __int_as_float(top[1][b])) | 255u) - (unsigned)((a) * 16 + (b)))
; __device__ __forceinline__ void route_task(int task, int tl0, const bf16* QP  , const LAS bf16* KHL, LAS unsigned short* EL, LAS float* GL, int lane) {
;     ...
;     {
;         const int c14 = CAND(14, 0), c15 = CAND(15, 0);
;         const int n14 = max(bk[14], c14), n15 = max(min(bk[14], c14), max(bk[15], c15));
;         bk[14] = n14; bk[15] = n15;
;     }
;     ...
;     int my[8];
; #pragma unroll
;     for (int i = 0; i < 8; ++i) { int lo_ = bk[i], hi_ = bk[8 + i]; asm volatile("" : "+v"(lo_), "+v"(hi_)); my[i] = hi ? hi_ : lo_; }
;     int bv[8];
; #pragma unroll
;     for (int i = 0; i < 8; ++i) {
;         const unsigned cd = 255u - ((unsigned)my[i] & 255u), ca = cd >> 4, cb = cd & 15u;
;         const unsigned wa = (ca >> 2) == 0u ? P1[0] : (ca >> 2) == 1u ? P1[1] : (ca >> 2) == 2u ? P1[2] : P1[3];
;         const unsigned wb = (cb >> 2) == 0u ? P2[0] : (cb >> 2) == 1u ? P2[1] : (cb >> 2) == 2u ? P2[2] : P2[3];
;         bv[i] = (int)((((wa >> (8u * (ca & 3u))) & 255u) << 7) | ((wb >> (8u * (cb & 3u))) & 255u));
;     }
	v_max_i32_e32 v42, v40, v34
	v_min_i32_e32 v34, v40, v34
	v_max_i32_e32 v40, v35, v33
	v_min_i32_e32 v33, v35, v33
	v_max_i32_e32 v35, v31, v30
	v_min_i32_e32 v30, v31, v30
	v_max_i32_e32 v31, v29, v27
	v_min_i32_e32 v27, v29, v27
	v_max_i32_e32 v29, v32, v28
	v_min_i32_e32 v28, v32, v28
	v_max_i32_e32 v32, v37, v41
	v_min_i32_e32 v37, v37, v41
	v_max_i32_e32 v41, v36, v39
	v_min_i32_e32 v36, v36, v39
	v_max_i32_e32 v39, v43, v42
	v_min_i32_e32 v42, v43, v42
	v_max_i32_e32 v43, v38, v34
	v_min_i32_e32 v34, v38, v34
	v_max_i32_e32 v38, v40, v35
	v_min_i32_e32 v35, v40, v35
	v_max_i32_e32 v40, v33, v30
	v_min_i32_e32 v30, v33, v30
	v_max_i32_e32 v33, v31, v29
	v_min_i32_e32 v29, v31, v29
	v_max_i32_e32 v31, v27, v28
	v_min_i32_e32 v27, v27, v28
	v_add_f32_e32 v28, v51, v26
	v_or_b32_e32 v28, 0xff, v28
	v_add_f32_e32 v26, v50, v26
	v_add_u32_e32 v28, 0xffffff20, v28
	v_or_b32_e32 v26, 0xff, v26
	v_add_u32_e32 v26, 0xffffff10, v26
	v_max_i32_e32 v44, v31, v28
	v_min_i32_e32 v28, v31, v28
	v_max3_i32 v26, v28, v27, v26
	v_mov_b32_e32 v27, v32
	s_nop 0
	v_cndmask_b32_e64 v27, v38, v27, s[6:7]
	v_not_b32_e32 v28, v27
	v_bfe_u32 v45, v28, 6, 2
	v_cmp_eq_u32_e32 vcc, 2, v45
	v_cndmask_b32_e64 v34, v26, v34, s[6:7]
	v_bitop3_b32 v26, v27, s3, v27 bitop3:0xc
	v_cndmask_b32_e32 v46, v25, v23, vcc
	v_cmp_eq_u32_e32 vcc, 1, v45
	v_cndmask_b32_e64 v31, v35, v37, s[6:7]
	v_not_b32_e32 v35, v31
	v_cndmask_b32_e32 v45, v46, v21, vcc
	v_cmp_gt_u32_e32 vcc, 64, v26
	v_cndmask_b32_e64 v37, v40, v41, s[6:7]
	v_cndmask_b32_e64 v41, v44, v43, s[6:7]
	v_cndmask_b32_e32 v26, v45, v19, vcc
	v_bfe_u32 v45, v28, 2, 2
	v_cmp_eq_u32_e32 vcc, 2, v45
	v_bitop3_b32 v44, v27, 15, v27 bitop3:0xc
	v_bfe_u32 v47, v35, 6, 2
	v_cndmask_b32_e32 v46, v24, v22, vcc
	v_cmp_eq_u32_e32 vcc, 1, v45
	v_not_b32_e32 v38, v37
	v_bfe_u32 v49, v38, 6, 2
	v_cndmask_b32_e32 v45, v46, v20, vcc
	v_cmp_gt_u32_e32 vcc, 4, v44
	v_bitop3_b32 v46, v31, 15, v31 bitop3:0xc
	v_cndmask_b32_e64 v30, v30, v36, s[6:7]
	v_cndmask_b32_e32 v44, v45, v18, vcc
	v_cmp_eq_u32_e32 vcc, 2, v47
	v_bitop3_b32 v45, v31, s3, v31 bitop3:0xc
	v_not_b32_e32 v36, v30
	v_cndmask_b32_e32 v48, v25, v23, vcc
	v_cmp_eq_u32_e32 vcc, 1, v47
	v_bfe_u32 v51, v36, 6, 2
	v_cndmask_b32_e64 v33, v33, v39, s[6:7]
	v_cndmask_b32_e32 v47, v48, v21, vcc
	v_cmp_gt_u32_e32 vcc, 64, v45
	v_not_b32_e32 v39, v33
	v_bfe_u32 v53, v39, 6, 2
	v_cndmask_b32_e32 v45, v47, v19, vcc
	v_bfe_u32 v47, v35, 2, 2
	v_cmp_eq_u32_e32 vcc, 2, v47
	v_cndmask_b32_e64 v29, v29, v42, s[6:7]
	v_not_b32_e32 v40, v29
	v_cndmask_b32_e32 v48, v24, v22, vcc
	v_cmp_eq_u32_e32 vcc, 1, v47
	v_bfe_u32 v55, v40, 6, 2
	v_not_b32_e32 v42, v41
	v_cndmask_b32_e32 v47, v48, v20, vcc
	v_cmp_gt_u32_e32 vcc, 4, v46
	v_bitop3_b32 v48, v37, 15, v37 bitop3:0xc
	v_bfe_u32 v57, v42, 6, 2
	v_cndmask_b32_e32 v46, v47, v18, vcc
	v_cmp_eq_u32_e32 vcc, 2, v49
	v_bitop3_b32 v47, v37, s3, v37 bitop3:0xc
	v_not_b32_e32 v43, v34
	v_cndmask_b32_e32 v50, v25, v23, vcc
	v_cmp_eq_u32_e32 vcc, 1, v49
	v_bfe_u32 v59, v43, 6, 2
	v_or_b32_e32 v82, s10, v88
	v_cndmask_b32_e32 v49, v50, v21, vcc
	v_cmp_gt_u32_e32 vcc, 64, v47
	s_nop 1
	v_cndmask_b32_e32 v47, v49, v19, vcc
	v_bfe_u32 v49, v38, 2, 2
	v_cmp_eq_u32_e32 vcc, 2, v49
	s_nop 1
	v_cndmask_b32_e32 v50, v24, v22, vcc
	v_cmp_eq_u32_e32 vcc, 1, v49
	s_nop 1
	v_cndmask_b32_e32 v49, v50, v20, vcc
	v_cmp_gt_u32_e32 vcc, 4, v48
	v_bitop3_b32 v50, v30, 15, v30 bitop3:0xc
	s_nop 0
	v_cndmask_b32_e32 v48, v49, v18, vcc
	v_cmp_eq_u32_e32 vcc, 2, v51
	v_bitop3_b32 v49, v30, s3, v30 bitop3:0xc
	s_nop 0
	v_cndmask_b32_e32 v52, v25, v23, vcc
	v_cmp_eq_u32_e32 vcc, 1, v51
	s_nop 1
	v_cndmask_b32_e32 v51, v52, v21, vcc
	v_cmp_gt_u32_e32 vcc, 64, v49
	s_nop 1
	v_cndmask_b32_e32 v49, v51, v19, vcc
	v_bfe_u32 v51, v36, 2, 2
	v_cmp_eq_u32_e32 vcc, 2, v51
	s_nop 1
	v_cndmask_b32_e32 v52, v24, v22, vcc
	v_cmp_eq_u32_e32 vcc, 1, v51
	s_nop 1
	v_cndmask_b32_e32 v51, v52, v20, vcc
	v_cmp_gt_u32_e32 vcc, 4, v50
	v_bitop3_b32 v52, v33, 15, v33 bitop3:0xc
	s_nop 0
	v_cndmask_b32_e32 v50, v51, v18, vcc
	v_cmp_eq_u32_e32 vcc, 2, v53
	v_bitop3_b32 v51, v33, s3, v33 bitop3:0xc
	s_nop 0
	v_cndmask_b32_e32 v54, v25, v23, vcc
	v_cmp_eq_u32_e32 vcc, 1, v53
	s_nop 1
	v_cndmask_b32_e32 v53, v54, v21, vcc
	v_cmp_gt_u32_e32 vcc, 64, v51
	s_nop 1
	v_cndmask_b32_e32 v51, v53, v19, vcc
	v_bfe_u32 v53, v39, 2, 2
	v_cmp_eq_u32_e32 vcc, 2, v53
	s_nop 1
	v_cndmask_b32_e32 v54, v24, v22, vcc
	v_cmp_eq_u32_e32 vcc, 1, v53
	s_nop 1
	v_cndmask_b32_e32 v53, v54, v20, vcc
	v_cmp_gt_u32_e32 vcc, 4, v52
	v_bitop3_b32 v54, v29, 15, v29 bitop3:0xc
	s_nop 0
	v_cndmask_b32_e32 v52, v53, v18, vcc
	v_cmp_eq_u32_e32 vcc, 2, v55
	v_bitop3_b32 v53, v29, s3, v29 bitop3:0xc
	s_nop 0
	v_cndmask_b32_e32 v56, v25, v23, vcc
	v_cmp_eq_u32_e32 vcc, 1, v55
	s_nop 1
	v_cndmask_b32_e32 v55, v56, v21, vcc
	v_cmp_gt_u32_e32 vcc, 64, v53
	s_nop 1
	v_cndmask_b32_e32 v53, v55, v19, vcc
	v_bfe_u32 v55, v40, 2, 2
	v_cmp_eq_u32_e32 vcc, 2, v55
	s_nop 1
	v_cndmask_b32_e32 v56, v24, v22, vcc
	v_cmp_eq_u32_e32 vcc, 1, v55
	s_nop 1
	v_cndmask_b32_e32 v55, v56, v20, vcc
	v_cmp_gt_u32_e32 vcc, 4, v54
	v_bitop3_b32 v56, v41, 15, v41 bitop3:0xc
	s_nop 0
	v_cndmask_b32_e32 v54, v55, v18, vcc
	v_cmp_eq_u32_e32 vcc, 2, v57
	v_bitop3_b32 v55, v41, s3, v41 bitop3:0xc
	s_nop 0
	v_cndmask_b32_e32 v58, v25, v23, vcc
	v_cmp_eq_u32_e32 vcc, 1, v57
	s_nop 1
	v_cndmask_b32_e32 v57, v58, v21, vcc
	v_cmp_gt_u32_e32 vcc, 64, v55
	s_nop 1
	v_cndmask_b32_e32 v55, v57, v19, vcc
	v_bfe_u32 v57, v42, 2, 2
	v_cmp_eq_u32_e32 vcc, 2, v57
	s_nop 1
	v_cndmask_b32_e32 v58, v24, v22, vcc
	v_cmp_eq_u32_e32 vcc, 1, v57
	s_nop 1
	v_cndmask_b32_e32 v57, v58, v20, vcc
; #define LAS __attribute__((address_space(3)))
; #define MFMA32(a, b, c) __builtin_amdgcn_mfma_f32_32x32x16_bf16((a), (b), (c), 0, 0, 0)
; __device__ __forceinline__ void route_task(int task, int tl0, const bf16* QP  , const LAS bf16* KHL, LAS unsigned short* EL, LAS float* GL, int lane) {
;     const int r = lane & 31, hi = lane >> 5, t = 4 * task + (r >> 3), head = r & 7;
;     int top[2][16]; bf16x8 qa[2][4];
;     { unsigned qo = (unsigned)t * (unsigned)D + (unsigned)(head * 128 + 8 * hi); asm volatile("" : "+v"(qo)); const bf16* qp = QP + qo;
; #pragma unroll
;       for (int hf = 0; hf < 2; ++hf)
; #pragma unroll
;         for (int ks = 0; ks < 4; ++ks) qa[hf][ks] = ldg8(qp + 64 * hf + 16 * ks); }
; #pragma unroll
;     for (int half = 0; half < 2; ++half) {
;         int cur[16];
; #pragma unroll
;         for (int kt = 0; kt < 4; ++kt) {
;             f32x16 X;
; #pragma unroll
;             for (int i = 0; i < 16; ++i) X[i] = 8.f;
;             const LAS bf16* khp = KHL + (half * 128 + 32 * kt + r) * 72 + 8 * hi;
; #pragma unroll
;             for (int ks = 0; ks < 4; ++ks) {
;                 const bf16x8 kh = lds8(khp + 16 * ks);
;                 X = MFMA32(kh, qa[half][ks], X);
;     ...
;     float e[8], se = 0.f;
; #pragma unroll
;     for (int i = 0; i < 8; ++i) { e[i] = __expf(__int_as_float(my[i]) - __int_as_float(bk[0])); se += e[i]; }
;     se += __shfl_xor(se, 32);
;     const float inv = 1.f / se;
;     {
;         int l2 = lane; asm volatile("" : "+v"(l2));
;         const int o2 = (tl0 + ((l2 & 31) >> 3)) * 128 + (l2 & 7) * 16 + 8 * (l2 >> 5);
;         LAS v4u* ip = (LAS v4u*)(EL + o2); typedef float f4v __attribute__((ext_vector_type(4))); LAS f4v* gp = (LAS f4v*)(GL + o2);
;         ip[0] = (v4u){(unsigned)bv[0] | ((unsigned)bv[1] << 16), (unsigned)bv[2] | ((unsigned)bv[3] << 16), (unsigned)bv[4] | ((unsigned)bv[5] << 16), (unsigned)bv[6] | ((unsigned)bv[7] << 16)};
;         gp[0] = (f4v){e[0] * inv, e[1] * inv, e[2] * inv, e[3] * inv}; gp[1] = (f4v){e[4] * inv, e[5] * inv, e[6] * inv, e[7] * inv};
;     }
	v_cmp_gt_u32_e32 vcc, 4, v56
	v_bitop3_b32 v58, v34, 15, v34 bitop3:0xc
	s_nop 0
	v_cndmask_b32_e32 v56, v57, v18, vcc
	v_cmp_eq_u32_e32 vcc, 2, v59
	v_bitop3_b32 v57, v34, s3, v34 bitop3:0xc
	s_nop 0
	v_cndmask_b32_e32 v23, v25, v23, vcc
	v_cmp_eq_u32_e32 vcc, 1, v59
	v_sub_f32_e32 v25, v30, v32
	v_mul_f32_e32 v25, 0x3fb8aa3b, v25
	v_cndmask_b32_e32 v21, v23, v21, vcc
	v_cmp_gt_u32_e32 vcc, 64, v57
	v_lshrrev_b32_e32 v23, 1, v39
	v_and_b32_e32 v23, 24, v23
	v_cndmask_b32_e32 v19, v21, v19, vcc
	v_bfe_u32 v21, v43, 2, 2
	v_cmp_eq_u32_e32 vcc, 2, v21
	v_lshrrev_b32_e32 v23, v23, v51
	v_lshlrev_b32_e32 v23, 7, v23
	v_cndmask_b32_e32 v22, v24, v22, vcc
	v_cmp_eq_u32_e32 vcc, 1, v21
	v_lshrrev_b32_e32 v21, 1, v42
	v_and_b32_e32 v21, 24, v21
	v_cndmask_b32_e32 v20, v22, v20, vcc
	v_cmp_gt_u32_e32 vcc, 4, v58
	v_lshrrev_b32_e32 v21, v21, v55
	v_lshrrev_b32_e32 v22, 1, v40
	v_cndmask_b32_e32 v18, v20, v18, vcc
	v_lshlrev_b32_e32 v20, 3, v42
	v_lshlrev_b32_e32 v21, 7, v21
	v_and_b32_e32 v22, 24, v22
	v_lshrrev_b32_e32 v20, v20, v56
	v_and_b32_e32 v21, 0x7f80, v21
	v_lshrrev_b32_e32 v22, v22, v53
	v_and_or_b32 v21, v20, s3, v21
	v_lshlrev_b32_e32 v20, 3, v40
	v_lshlrev_b32_e32 v22, 7, v22
	v_lshrrev_b32_e32 v20, v20, v54
	v_and_b32_e32 v22, 0x7f80, v22
	v_and_or_b32 v20, v20, s3, v22
	v_lshlrev_b32_e32 v22, 3, v39
	v_lshrrev_b32_e32 v22, v22, v52
	v_and_b32_e32 v23, 0x7f80, v23
	v_and_or_b32 v39, v22, s3, v23
	v_lshrrev_b32_e32 v23, 1, v36
	v_and_b32_e32 v23, 24, v23
	v_lshrrev_b32_e32 v23, v23, v49
	v_lshlrev_b32_e32 v22, 3, v36
	v_lshlrev_b32_e32 v23, 7, v23
	v_lshrrev_b32_e32 v22, v22, v50
	v_and_b32_e32 v23, 0x7f80, v23
	v_and_or_b32 v36, v22, s3, v23
	v_lshrrev_b32_e32 v23, 1, v38
	v_and_b32_e32 v23, 24, v23
	v_lshrrev_b32_e32 v23, v23, v47
	v_lshlrev_b32_e32 v22, 3, v38
	v_lshlrev_b32_e32 v23, 7, v23
	v_lshrrev_b32_e32 v22, v22, v48
	v_and_b32_e32 v23, 0x7f80, v23
	v_and_or_b32 v38, v22, s3, v23
	v_lshrrev_b32_e32 v23, 1, v35
	v_and_b32_e32 v23, 24, v23
	v_lshrrev_b32_e32 v23, v23, v45
	v_lshlrev_b32_e32 v22, 3, v35
	v_lshlrev_b32_e32 v23, 7, v23
	v_lshrrev_b32_e32 v22, v22, v46
	v_and_b32_e32 v23, 0x7f80, v23
	v_and_or_b32 v35, v22, s3, v23
	v_lshrrev_b32_e32 v23, 1, v28
	v_and_b32_e32 v23, 24, v23
	v_lshrrev_b32_e32 v23, v23, v26
	v_lshlrev_b32_e32 v22, 3, v28
	v_lshlrev_b32_e32 v23, 7, v23
	v_lshrrev_b32_e32 v22, v22, v44
	v_and_b32_e32 v23, 0x7f80, v23
	v_and_or_b32 v40, v22, s3, v23
	v_sub_f32_e32 v22, v27, v32
	v_mul_f32_e32 v22, 0x3fb8aa3b, v22
	v_sub_f32_e32 v23, v31, v32
	v_exp_f32_e32 v22, v22
	v_mul_f32_e32 v23, 0x3fb8aa3b, v23
	v_sub_f32_e32 v24, v37, v32
	v_exp_f32_e32 v23, v23
	v_mul_f32_e32 v24, 0x3fb8aa3b, v24
	v_exp_f32_e32 v24, v24
	v_exp_f32_e32 v25, v25
	v_add_f32_e32 v26, 0, v22
	v_add_f32_e32 v26, v23, v26
	v_add_f32_e32 v26, v24, v26
	v_add_f32_e32 v30, v25, v26
	v_sub_f32_e32 v26, v33, v32
	v_mul_f32_e32 v26, 0x3fb8aa3b, v26
	v_sub_f32_e32 v27, v29, v32
	v_exp_f32_e32 v26, v26
	v_mul_f32_e32 v27, 0x3fb8aa3b, v27
	v_sub_f32_e32 v28, v41, v32
	v_exp_f32_e32 v27, v27
	v_mul_f32_e32 v28, 0x3fb8aa3b, v28
	v_sub_f32_e32 v29, v34, v32
	v_exp_f32_e32 v28, v28
	v_mul_f32_e32 v29, 0x3fb8aa3b, v29
	v_exp_f32_e32 v29, v29
	v_add_f32_e32 v30, v26, v30
	v_add_f32_e32 v30, v27, v30
	v_add_f32_e32 v30, v28, v30
	v_add_f32_e32 v30, v29, v30
	ds_bpermute_b32 v31, v123, v30
	v_lshrrev_b32_e32 v42, 1, v43
	v_and_b32_e32 v32, 24, v42
	v_lshrrev_b32_e32 v19, v32, v19
	v_lshlrev_b32_e32 v19, 7, v19
	s_waitcnt lgkmcnt(0)
	v_add_f32_e32 v30, v30, v31
	v_div_scale_f32 v31, s[12:13], v30, v30, 1.0
	v_rcp_f32_e32 v32, v31
	v_lshlrev_b32_e32 v33, 3, v43
	v_and_b32_e32 v19, 0x7f80, v19
	v_lshrrev_b32_e32 v18, v33, v18
	v_and_or_b32 v33, v18, s3, v19
	v_fma_f32 v18, -v31, v32, 1.0
	v_fmac_f32_e32 v32, v18, v32
	v_div_scale_f32 v18, vcc, 1.0, v30, 1.0
	v_mul_f32_e32 v19, v18, v32
	v_fma_f32 v34, -v31, v19, v18
	v_fmac_f32_e32 v19, v34, v32
	v_fma_f32 v18, -v31, v19, v18
	v_div_fmas_f32 v18, v18, v32, v19
	v_div_fixup_f32 v30, v18, v30, 1.0
	v_mov_b32_e32 v18, v1
	v_lshl_or_b32 v20, v20, 16, v39
	v_lshrrev_b32_e32 v19, 3, v18
	v_and_or_b32 v19, v19, 3, s55
	v_lshlrev_b32_e32 v31, 4, v18
	v_ashrrev_i32_e32 v18, 2, v18
	v_lshlrev_b32_e32 v19, 7, v19
	v_and_b32_e32 v31, 0x70, v31
	v_and_b32_e32 v18, -8, v18
	v_add3_u32 v18, v18, v31, v19
	v_lshl_add_u32 v31, v18, 1, s11
	v_lshl_add_u32 v32, v18, 2, s69
	v_lshl_or_b32 v18, v35, 16, v40
	v_lshl_or_b32 v19, v36, 16, v38
	v_lshl_or_b32 v21, v33, 16, v21
	ds_write_b128 v31, v[18:21]
	v_pk_mul_f32 v[20:21], v[24:25], v[30:31] op_sel_hi:[1,0]
	v_pk_mul_f32 v[18:19], v[22:23], v[30:31] op_sel_hi:[1,0]
	ds_write_b128 v32, v[18:21]
	v_pk_mul_f32 v[20:21], v[28:29], v[30:31] op_sel_hi:[1,0]
	v_pk_mul_f32 v[18:19], v[26:27], v[30:31] op_sel_hi:[1,0]
	ds_write_b128 v32, v[18:21] offset:16
	v_mov_b64_e32 v[32:33], s[30:31]
	v_lshl_add_u64 v[128:129], v[82:83], 1, s[80:81]
	s_waitcnt vmcnt(4)
	v_mov_b32_e32 v78, v150
	v_mov_b32_e32 v79, v151
	v_mov_b32_e32 v80, v152
	v_mov_b32_e32 v81, v153
	v_mov_b32_e32 v74, v154
	v_mov_b32_e32 v75, v155
	v_mov_b32_e32 v76, v156
	v_mov_b32_e32 v77, v157
	v_mov_b32_e32 v70, v158
	v_mov_b32_e32 v71, v159
	v_mov_b32_e32 v72, v160
	v_mov_b32_e32 v73, v161
	v_mov_b32_e32 v66, v162
	v_mov_b32_e32 v67, v163
	v_mov_b32_e32 v68, v164
	v_mov_b32_e32 v69, v165
	ds_read_b128 v[50:53], v94
	ds_read_b128 v[54:57], v94 offset:32
	v_mov_b64_e32 v[30:31], s[28:29]
	v_mov_b64_e32 v[28:29], s[26:27]
	v_mov_b64_e32 v[26:27], s[24:25]
	v_mov_b64_e32 v[24:25], s[22:23]
	v_mov_b64_e32 v[22:23], s[20:21]
	v_mov_b64_e32 v[20:21], s[18:19]
	v_mov_b64_e32 v[18:19], s[16:17]
	s_waitcnt vmcnt(3) lgkmcnt(1)
; #define LAS __attribute__((address_space(3)))
; #define MFMA32(a, b, c) __builtin_amdgcn_mfma_f32_32x32x16_bf16((a), (b), (c), 0, 0, 0)
; #define CE_(a, b) ce_desc(v[a], v[b])
; __device__ __forceinline__ void sort16_desc(int (&v)[16]) {
;     ...
;     CE_(0,13); CE_(1,12); CE_(2,15); CE_(3,14); CE_(4,8); CE_(5,6); CE_(7,11); CE_(9,10);
;     CE_(0,5); CE_(1,7); CE_(2,9); CE_(3,4); CE_(6,13); CE_(8,14); CE_(10,15); CE_(11,12);
;     CE_(0,1); CE_(2,3); CE_(4,5); CE_(6,8); CE_(7,9); CE_(10,11); CE_(12,13); CE_(14,15);
;     CE_(0,2); CE_(1,3); CE_(4,10); CE_(5,11); CE_(6,7); CE_(8,9); CE_(12,14); CE_(13,15);
;     CE_(1,2); CE_(3,12); CE_(4,6); CE_(5,7); CE_(8,10); CE_(9,11); CE_(13,14);
;     CE_(1,4); CE_(2,6); CE_(5,8); CE_(7,10); CE_(9,13); CE_(11,14);
;     CE_(2,4); CE_(3,6); CE_(9,12); CE_(11,13);
;     CE_(3,5); CE_(6,8); CE_(7,9); CE_(10,12);
;     CE_(3,4); CE_(5,6); CE_(7,8); CE_(9,10); CE_(11,12);
;     CE_(6,7); CE_(8,9);
;     ...
; }
; __device__ __forceinline__ void route_task(int task, int tl0, const bf16* QP  , const LAS bf16* KHL, LAS unsigned short* EL, LAS float* GL, int lane) {
;     ...
;         for (int kt = 0; kt < 4; ++kt) {
;             f32x16 X;
; #pragma unroll
;             for (int i = 0; i < 16; ++i) X[i] = 8.f;
;             const LAS bf16* khp = KHL + (half * 128 + 32 * kt + r) * 72 + 8 * hi;
; #pragma unroll
;             for (int ks = 0; ks < 4; ++ks) {
;                 const bf16x8 kh = lds8(khp + 16 * ks);
;                 X = MFMA32(kh, qa[half][ks], X);
;             }
;             int grp[16];
; #pragma unroll
;             for (int i = 0; i < 16; ++i) grp[i] = (int)((__float_as_uint(X[i]) | 127u) - (unsigned)(32 * kt + (i & 3) + 8 * (i >> 2)));
;             sort16_desc(grp);
;             if (kt == 0) {
; #pragma unroll
;                 for (int i = 0; i < 16; ++i) cur[i] = grp[i];
;             } else merge16_desc(cur, grp);
	s_nop 0
	v_mfma_f32_32x32x16_bf16 v[34:49], v[50:53], v[78:81], v[18:33]
	ds_read_b128 v[50:53], v94 offset:64
	ds_read_b128 v[124:127], v94 offset:96
	s_waitcnt vmcnt(2) lgkmcnt(2)
	v_mfma_f32_32x32x16_bf16 v[34:49], v[54:57], v[74:77], v[34:49]
	s_waitcnt vmcnt(1) lgkmcnt(1)
	v_mfma_f32_32x32x16_bf16 v[34:49], v[50:53], v[70:73], v[34:49]
	s_waitcnt vmcnt(0)
	v_mov_b32_e32 v62, v166
	v_mov_b32_e32 v63, v167
	v_mov_b32_e32 v64, v168
	v_mov_b32_e32 v65, v169
	v_mov_b32_e32 v58, v170
	v_mov_b32_e32 v59, v171
	v_mov_b32_e32 v60, v172
	v_mov_b32_e32 v61, v173
	v_mov_b32_e32 v54, v174
	v_mov_b32_e32 v55, v175
	v_mov_b32_e32 v56, v176
	v_mov_b32_e32 v57, v177
	v_mov_b32_e32 v50, v178
	v_mov_b32_e32 v51, v179
	v_mov_b32_e32 v52, v180
	v_mov_b32_e32 v53, v181
	s_waitcnt vmcnt(4) lgkmcnt(0)
	v_mfma_f32_32x32x16_bf16 v[34:49], v[124:127], v[66:69], v[34:49]
	s_nop 11
	v_bitop3_b32 v37, v37, s42, 3 bitop3:0x56
	v_bitop3_b32 v48, v48, s42, 26 bitop3:0x56
	v_bitop3_b32 v38, v38, s42, 8 bitop3:0x56
	v_bitop3_b32 v42, v42, s42, 16 bitop3:0x56
	v_bitop3_b32 v47, v47, s42, 25 bitop3:0x56
	v_bitop3_b32 v39, v39, s42, 9 bitop3:0x56
	v_bitop3_b32 v40, v40, s42, 10 bitop3:0x56
	v_bitop3_b32 v43, v43, s42, 17 bitop3:0x56
	v_bitop3_b32 v44, v44, s42, 18 bitop3:0x56
	v_bitop3_b32 v36, v36, s42, 2 bitop3:0x56
	v_bitop3_b32 v49, v49, s42, 27 bitop3:0x56
	v_bitop3_b32 v41, v41, s42, 11 bitop3:0x56
	v_bitop3_b32 v45, v45, s42, 19 bitop3:0x56
	v_bitop3_b32 v35, v35, s42, 1 bitop3:0x56
	v_bitop3_b32 v46, v46, s42, 24 bitop3:0x56
	v_or_b32_e32 v34, 0x7f, v34
	v_max_i32_e32 v82, v37, v48
	v_max_i32_e32 v124, v38, v42
	v_max_i32_e32 v126, v34, v47
	v_max_i32_e32 v127, v39, v40
	v_min_i32_e32 v130, v43, v44
	v_min_i32_e32 v131, v36, v49
	v_min_i32_e32 v133, v41, v45
	v_min_i32_e32 v134, v35, v46
	v_min_i32_e32 v39, v39, v40
	v_min_i32_e32 v34, v34, v47
	v_min_i32_e32 v38, v38, v42
	v_min_i32_e32 v37, v37, v48
	v_max_i32_e32 v35, v35, v46
	v_max_i32_e32 v41, v41, v45
	v_max_i32_e32 v36, v36, v49
	v_max_i32_e32 v43, v43, v44
	v_min_i32_e32 v125, v82, v124
	v_min_i32_e32 v128, v126, v127
	v_max_i32_e32 v132, v130, v131
	v_max_i32_e32 v135, v133, v134
	v_max_i32_e32 v40, v39, v34
	v_max_i32_e32 v42, v38, v37
	v_min_i32_e32 v45, v35, v41
	v_min_i32_e32 v44, v36, v43
	v_min_i32_e32 v129, v125, v128
	v_max_i32_e32 v47, v40, v42
	v_max_i32_e32 v46, v45, v44
	v_min_i32_e32 v40, v40, v42
	v_min_i32_e32 v42, v45, v44
	v_max_i32_e32 v45, v125, v128
	v_max_i32_e32 v125, v132, v135
	v_min_i32_e32 v128, v45, v125
	v_min_i32_e32 v34, v39, v34
	v_max_i32_e32 v39, v126, v127
	v_max_i32_e32 v35, v35, v41
	v_max_i32_e32 v41, v82, v124
	v_max_i32_e32 v148, v45, v125
	ds_read_b128 v[124:127], v95
	v_max_i32_e32 v44, v40, v42
	v_min_i32_e32 v138, v40, v42
	v_min_i32_e32 v40, v133, v134
	v_min_i32_e32 v37, v38, v37
	v_min_i32_e32 v38, v130, v131
	v_max_i32_e32 v36, v36, v43
	v_min_i32_e32 v136, v132, v135
	v_min_i32_e32 v133, v40, v34
	v_min_i32_e32 v134, v37, v38
	v_max_i32_e32 v34, v40, v34
	v_max_i32_e32 v37, v37, v38
	v_min_i32_e32 v40, v39, v35
	v_min_i32_e32 v42, v36, v41
	v_max_i32_e32 v144, v39, v35
	v_max_i32_e32 v145, v36, v41
	v_max_i32_e32 v137, v129, v136
	v_min_i32_e32 v136, v129, v136
	v_max_i32_e32 v140, v133, v134
	v_min_i32_e32 v141, v34, v37
	v_max_i32_e32 v143, v40, v42
	v_min_i32_e32 v146, v144, v145
	v_max_i32_e32 v149, v47, v46
	v_min_i32_e32 v48, v47, v46
	v_max_i32_e32 v139, v138, v136
	v_max_i32_e32 v142, v140, v141
	v_min_i32_e32 v43, v40, v42
	v_max_i32_e32 v34, v34, v37
	v_min_i32_e32 v147, v143, v146
	v_min_i32_e32 v150, v148, v149
	v_min_i32_e32 v49, v137, v48
	v_min_i32_e32 v132, v44, v128
	v_max_i32_e32 v38, v139, v142
	v_min_i32_e32 v37, v43, v34
	v_max_i32_e32 v34, v43, v34
	v_min_i32_e32 v35, v147, v150
	v_max_i32_e32 v39, v137, v48
	v_max_i32_e32 v40, v44, v128
	v_max_i32_e32 v135, v49, v132
	v_max_i32_e32 v82, v38, v37
	v_min_i32_e32 v36, v34, v35
	v_min_i32_e32 v41, v39, v40
	v_max_i32_e32 v129, v135, v82
	v_min_i32_e32 v42, v36, v41
	v_min_i32_e32 v137, v129, v42
	v_max_i32_e32 v159, v129, v42
	ds_read_b128 v[128:131], v95 offset:32
	v_min_i32_e32 v82, v135, v82
	v_min_i32_e32 v132, v49, v132
	v_min_i32_e32 v135, v38, v37
	v_max_i32_e32 v154, v34, v35
	v_max_i32_e32 v155, v39, v40
	v_max_i32_e32 v157, v36, v41
	s_waitcnt lgkmcnt(1)
	v_mfma_f32_32x32x16_bf16 v[34:49], v[124:127], v[78:81], v[18:33]
	ds_read_b128 v[124:127], v95 offset:64
	v_max_i32_e32 v151, v132, v135
	v_max_i32_e32 v152, v82, v151
	v_min_i32_e32 v136, v138, v136
	v_min_i32_e32 v138, v140, v141
	v_min_i32_e32 v82, v82, v151
	v_max_i32_e32 v147, v147, v150
	s_waitcnt lgkmcnt(1)
	v_mfma_f32_32x32x16_bf16 v[34:49], v[128:131], v[74:77], v[34:49]
	ds_read_b128 v[128:131], v95 offset:96
	v_max_i32_e32 v143, v143, v146
	v_min_i32_e32 v133, v133, v134
	v_min_i32_e32 v156, v154, v155
	v_max_i32_e32 v140, v136, v138
	v_min_i32_e32 v139, v139, v142
	v_max_i32_e32 v142, v154, v155
	s_waitcnt lgkmcnt(1)
	v_mfma_f32_32x32x16_bf16 v[34:49], v[124:127], v[70:73], v[34:49]
	v_max_i32_e32 v124, v148, v149
	v_min_i32_e32 v136, v136, v138
	v_max_i32_e32 v141, v140, v139
	v_min_i32_e32 v139, v140, v139
	v_min_i32_e32 v125, v143, v124
	v_min_i32_e32 v158, v156, v157
	v_min_i32_e32 v132, v132, v135
	s_waitcnt lgkmcnt(0)
; #define LAS __attribute__((address_space(3)))
; #define MFMA32(a, b, c) __builtin_amdgcn_mfma_f32_32x32x16_bf16((a), (b), (c), 0, 0, 0)
; #define CE_(a, b) ce_desc(v[a], v[b])
; __device__ __forceinline__ void sort16_desc(int (&v)[16]) {
;     ...
;     CE_(0,13); CE_(1,12); CE_(2,15); CE_(3,14); CE_(4,8); CE_(5,6); CE_(7,11); CE_(9,10);
;     CE_(0,5); CE_(1,7); CE_(2,9); CE_(3,4); CE_(6,13); CE_(8,14); CE_(10,15); CE_(11,12);
;     CE_(0,1); CE_(2,3); CE_(4,5); CE_(6,8); CE_(7,9); CE_(10,11); CE_(12,13); CE_(14,15);
;     CE_(0,2); CE_(1,3); CE_(4,10); CE_(5,11); CE_(6,7); CE_(8,9); CE_(12,14); CE_(13,15);
;     CE_(1,2); CE_(3,12); CE_(4,6); CE_(5,7); CE_(8,10); CE_(9,11); CE_(13,14);
;     CE_(1,4); CE_(2,6); CE_(5,8); CE_(7,10); CE_(9,13); CE_(11,14);
;     CE_(2,4); CE_(3,6); CE_(9,12); CE_(11,13);
;     CE_(3,5); CE_(6,8); CE_(7,9); CE_(10,12);
;     CE_(3,4); CE_(5,6); CE_(7,8); CE_(9,10); CE_(11,12);
;     CE_(6,7); CE_(8,9);
;     ...
; }
; __device__ __forceinline__ void merge16_desc(int (&a)[16], const int (&b)[16]) {
; #pragma unroll
;     for (int i = 0; i < 16; ++i) a[i] = a[i] > b[15 - i] ? a[i] : b[15 - i];
; #pragma unroll
;     for (int j = 8; j > 0; j >>= 1)
; #pragma unroll
;         for (int i = 0; i < 16; ++i) { const int l = i ^ j; if (l > i) ce_desc(a[i], a[l]); }
; }
; __device__ __forceinline__ void route_task(int task, int tl0, const bf16* QP  , const LAS bf16* KHL, LAS unsigned short* EL, LAS float* GL, int lane) {
;     ...
;         for (int kt = 0; kt < 4; ++kt) {
;             f32x16 X;
; #pragma unroll
;             for (int i = 0; i < 16; ++i) X[i] = 8.f;
;             const LAS bf16* khp = KHL + (half * 128 + 32 * kt + r) * 72 + 8 * hi;
; #pragma unroll
;             for (int ks = 0; ks < 4; ++ks) {
;                 const bf16x8 kh = lds8(khp + 16 * ks);
;                 X = MFMA32(kh, qa[half][ks], X);
;             }
;             int grp[16];
; #pragma unroll
;             for (int i = 0; i < 16; ++i) grp[i] = (int)((__float_as_uint(X[i]) | 127u) - (unsigned)(32 * kt + (i & 3) + 8 * (i >> 2)));
;             sort16_desc(grp);
;             if (kt == 0) {
; #pragma unroll
;                 for (int i = 0; i < 16; ++i) cur[i] = grp[i];
;             } else merge16_desc(cur, grp);
	v_mfma_f32_32x32x16_bf16 v[34:49], v[128:131], v[66:69], v[34:49]
	v_min_i32_e32 v126, v147, v125
	v_min_i32_e32 v153, v137, v152
	v_min_i32_e32 v160, v158, v159
	v_min_i32_e32 v135, v141, v132
	v_min_i32_e32 v127, v142, v126
	s_nop 6
	v_bitop3_b32 v37, v37, s42, 35 bitop3:0x56
	v_bitop3_b32 v48, v48, s42, 58 bitop3:0x56
	v_bitop3_b32 v38, v38, s42, 40 bitop3:0x56
	v_bitop3_b32 v42, v42, s42, 48 bitop3:0x56
	v_bitop3_b32 v34, v34, s42, 32 bitop3:0x56
	v_bitop3_b32 v47, v47, s42, 57 bitop3:0x56
	v_bitop3_b32 v39, v39, s42, 41 bitop3:0x56
	v_bitop3_b32 v40, v40, s42, 42 bitop3:0x56
	v_bitop3_b32 v43, v43, s42, 49 bitop3:0x56
	v_bitop3_b32 v44, v44, s42, 50 bitop3:0x56
	v_bitop3_b32 v36, v36, s42, 34 bitop3:0x56
	v_bitop3_b32 v49, v49, s42, 59 bitop3:0x56
	v_bitop3_b32 v41, v41, s42, 43 bitop3:0x56
	v_bitop3_b32 v45, v45, s42, 51 bitop3:0x56
	v_bitop3_b32 v35, v35, s42, 33 bitop3:0x56
	v_bitop3_b32 v46, v46, s42, 56 bitop3:0x56
	v_max_i32_e32 v128, v37, v48
	v_max_i32_e32 v129, v38, v42
	v_max_i32_e32 v131, v34, v47
	v_max_i32_e32 v134, v39, v40
	v_min_i32_e32 v146, v43, v44
	v_min_i32_e32 v148, v36, v49
	v_min_i32_e32 v150, v41, v45
	v_min_i32_e32 v151, v35, v46
	v_min_i32_e32 v39, v39, v40
	v_min_i32_e32 v34, v34, v47
	v_min_i32_e32 v38, v38, v42
	v_min_i32_e32 v37, v37, v48
	v_max_i32_e32 v35, v35, v46
	v_max_i32_e32 v41, v41, v45
	v_max_i32_e32 v36, v36, v49
	v_max_i32_e32 v43, v43, v44
	v_min_i32_e32 v130, v128, v129
	v_min_i32_e32 v138, v131, v134
	v_max_i32_e32 v149, v146, v148
	v_max_i32_e32 v154, v150, v151
	v_max_i32_e32 v40, v39, v34
	v_max_i32_e32 v42, v38, v37
	v_min_i32_e32 v45, v35, v41
	v_min_i32_e32 v44, v36, v43
	v_min_i32_e32 v150, v150, v151
	v_min_i32_e32 v34, v39, v34
	v_min_i32_e32 v37, v38, v37
	v_min_i32_e32 v38, v146, v148
	v_max_i32_e32 v131, v131, v134
	v_max_i32_e32 v35, v35, v41
	v_max_i32_e32 v36, v36, v43
	v_max_i32_e32 v43, v128, v129
	v_min_i32_e32 v140, v130, v138
	v_min_i32_e32 v155, v149, v154
	v_max_i32_e32 v47, v40, v42
	v_max_i32_e32 v46, v45, v44
	v_min_i32_e32 v40, v40, v42
	v_min_i32_e32 v42, v45, v44
	v_max_i32_e32 v45, v130, v138
	v_max_i32_e32 v130, v149, v154
	v_min_i32_e32 v39, v150, v34
	v_min_i32_e32 v146, v37, v38
	v_max_i32_e32 v34, v150, v34
	v_max_i32_e32 v37, v37, v38
	v_min_i32_e32 v41, v131, v35
	v_min_i32_e32 v128, v36, v43
	v_max_i32_e32 v35, v131, v35
	v_max_i32_e32 v36, v36, v43
	v_min_i32_e32 v48, v47, v46
	v_max_i32_e32 v44, v40, v42
	v_min_i32_e32 v138, v45, v130
	v_min_i32_e32 v40, v40, v42
	v_min_i32_e32 v42, v140, v155
	v_max_i32_e32 v148, v39, v146
	v_min_i32_e32 v38, v34, v37
	v_min_i32_e32 v129, v41, v128
	v_max_i32_e32 v41, v41, v128
	v_min_i32_e32 v43, v35, v36
	v_max_i32_e32 v45, v45, v130
	v_max_i32_e32 v46, v47, v46
	v_max_i32_e32 v161, v140, v155
	v_max_i32_e32 v140, v40, v42
	v_max_i32_e32 v150, v148, v38
	v_max_i32_e32 v34, v34, v37
	v_min_i32_e32 v128, v41, v43
	v_min_i32_e32 v47, v45, v46
	v_min_i32_e32 v49, v161, v48
	v_min_i32_e32 v149, v44, v138
	v_max_i32_e32 v151, v140, v150
	v_min_i32_e32 v37, v129, v34
	v_max_i32_e32 v34, v129, v34
	v_min_i32_e32 v129, v128, v47
	v_max_i32_e32 v48, v161, v48
	v_max_i32_e32 v44, v44, v138
	v_max_i32_e32 v154, v49, v149
	v_max_i32_e32 v134, v151, v37
	v_min_i32_e32 v130, v34, v129
	v_min_i32_e32 v131, v48, v44
	v_min_i32_e32 v49, v49, v149
	v_min_i32_e32 v37, v151, v37
	v_max_i32_e32 v34, v34, v129
	v_max_i32_e32 v44, v48, v44
	v_min_i32_e32 v40, v40, v42
	v_min_i32_e32 v38, v148, v38
	v_max_i32_e32 v41, v41, v43
	v_max_i32_e32 v43, v45, v46
	v_max_i32_e32 v155, v154, v134
	v_min_i32_e32 v138, v130, v131
	v_min_i32_e32 v134, v154, v134
	v_max_i32_e32 v149, v49, v37
	v_min_i32_e32 v48, v34, v44
	v_max_i32_e32 v129, v130, v131
	v_max_i32_e32 v42, v40, v38
	v_min_i32_e32 v140, v140, v150
	v_max_i32_e32 v34, v34, v44
	v_max_i32_e32 v44, v128, v47
	v_min_i32_e32 v45, v41, v43
	v_min_i32_e32 v161, v155, v138
	v_max_i32_e32 v151, v134, v149
	v_min_i32_e32 v130, v48, v129
	v_max_i32_e32 v131, v155, v138
	v_max_i32_e32 v148, v42, v140
	v_min_i32_e32 v37, v49, v37
	v_min_i32_e32 v46, v44, v45
	v_min_i32_e32 v154, v161, v151
	v_min_i32_e32 v138, v130, v131
	v_min_i32_e32 v49, v148, v37
	v_min_i32_e32 v134, v134, v149
	v_min_i32_e32 v47, v34, v46
	v_min_i32_e32 v42, v42, v140
	v_min_i32_e32 v38, v40, v38
	v_min_i32_e32 v39, v39, v146
	v_max3_i32 v39, v144, v145, v39
	v_max3_i32 v38, v143, v124, v38
	v_max3_i32 v40, v147, v125, v42
	v_max3_i32 v42, v142, v126, v49
	v_max3_i32 v37, v127, v148, v37
	v_max3_i32 v49, v156, v157, v134
	v_max3_i32 v124, v158, v159, v154
	v_max3_i32 v125, v160, v161, v151
	v_max3_i32 v126, v137, v152, v138
	v_max3_i32 v127, v153, v130, v131
	v_max3_i32 v48, v82, v48, v129
	v_max3_i32 v47, v141, v132, v47
	v_max3_i32 v34, v135, v34, v46
	v_max3_i32 v44, v139, v44, v45
	v_max3_i32 v41, v136, v41, v43
	v_max3_i32 v35, v133, v35, v36
	v_max_i32_e32 v36, v39, v126
	v_min_i32_e32 v39, v39, v126
	v_max_i32_e32 v43, v38, v127
	v_min_i32_e32 v38, v38, v127
	v_max_i32_e32 v45, v40, v48
	v_min_i32_e32 v40, v40, v48
	v_max_i32_e32 v46, v42, v47
	v_min_i32_e32 v42, v42, v47
	v_max_i32_e32 v47, v37, v34
	v_min_i32_e32 v34, v37, v34
	v_max_i32_e32 v37, v49, v44
	v_min_i32_e32 v44, v49, v44
	v_max_i32_e32 v48, v124, v41
	v_min_i32_e32 v41, v124, v41
	v_max_i32_e32 v49, v125, v35
	v_min_i32_e32 v35, v125, v35
	ds_read_b128 v[124:127], v94 offset:9216
	ds_read_b128 v[128:131], v94 offset:9248
	v_max_i32_e32 v82, v36, v47
	v_min_i32_e32 v132, v36, v47
	v_max_i32_e32 v36, v43, v37
	v_min_i32_e32 v133, v43, v37
	v_max_i32_e32 v37, v45, v48
	v_max_i32_e32 v43, v46, v49
	v_min_i32_e32 v134, v45, v48
	v_min_i32_e32 v135, v46, v49
	v_max_i32_e32 v136, v39, v34
	v_min_i32_e32 v137, v39, v34
	v_max_i32_e32 v138, v38, v44
	v_min_i32_e32 v139, v38, v44
	v_max_i32_e32 v140, v40, v41
	v_min_i32_e32 v141, v40, v41
	v_max_i32_e32 v142, v42, v35
	v_min_i32_e32 v143, v42, v35
	v_max_i32_e32 v144, v82, v37
	v_min_i32_e32 v82, v82, v37
	v_max_i32_e32 v145, v36, v43
	v_min_i32_e32 v146, v36, v43
	s_waitcnt lgkmcnt(1)
; #define LAS __attribute__((address_space(3)))
; #define MFMA32(a, b, c) __builtin_amdgcn_mfma_f32_32x32x16_bf16((a), (b), (c), 0, 0, 0)
; #define CE_(a, b) ce_desc(v[a], v[b])
; __device__ __forceinline__ void sort16_desc(int (&v)[16]) {
;     ...
;     CE_(0,13); CE_(1,12); CE_(2,15); CE_(3,14); CE_(4,8); CE_(5,6); CE_(7,11); CE_(9,10);
;     CE_(0,5); CE_(1,7); CE_(2,9); CE_(3,4); CE_(6,13); CE_(8,14); CE_(10,15); CE_(11,12);
;     CE_(0,1); CE_(2,3); CE_(4,5); CE_(6,8); CE_(7,9); CE_(10,11); CE_(12,13); CE_(14,15);
;     CE_(0,2); CE_(1,3); CE_(4,10); CE_(5,11); CE_(6,7); CE_(8,9); CE_(12,14); CE_(13,15);
;     CE_(1,2); CE_(3,12); CE_(4,6); CE_(5,7); CE_(8,10); CE_(9,11); CE_(13,14);
;     CE_(1,4); CE_(2,6); CE_(5,8); CE_(7,10); CE_(9,13); CE_(11,14);
;     CE_(2,4); CE_(3,6); CE_(9,12); CE_(11,13);
;     CE_(3,5); CE_(6,8); CE_(7,9); CE_(10,12);
;     CE_(3,4); CE_(5,6); CE_(7,8); CE_(9,10); CE_(11,12);
;     CE_(6,7); CE_(8,9);
;     ...
; }
; __device__ __forceinline__ void merge16_desc(int (&a)[16], const int (&b)[16]) {
; #pragma unroll
;     for (int i = 0; i < 16; ++i) a[i] = a[i] > b[15 - i] ? a[i] : b[15 - i];
; #pragma unroll
;     for (int j = 8; j > 0; j >>= 1)
; #pragma unroll
;         for (int i = 0; i < 16; ++i) { const int l = i ^ j; if (l > i) ce_desc(a[i], a[l]); }
; }
; __device__ __forceinline__ void route_task(int task, int tl0, const bf16* QP  , const LAS bf16* KHL, LAS unsigned short* EL, LAS float* GL, int lane) {
;     ...
;         for (int kt = 0; kt < 4; ++kt) {
;             f32x16 X;
; #pragma unroll
;             for (int i = 0; i < 16; ++i) X[i] = 8.f;
;             const LAS bf16* khp = KHL + (half * 128 + 32 * kt + r) * 72 + 8 * hi;
; #pragma unroll
;             for (int ks = 0; ks < 4; ++ks) {
;                 const bf16x8 kh = lds8(khp + 16 * ks);
;                 X = MFMA32(kh, qa[half][ks], X);
;             }
;             int grp[16];
; #pragma unroll
;             for (int i = 0; i < 16; ++i) grp[i] = (int)((__float_as_uint(X[i]) | 127u) - (unsigned)(32 * kt + (i & 3) + 8 * (i >> 2)));
;             sort16_desc(grp);
;             if (kt == 0) {
; #pragma unroll
;                 for (int i = 0; i < 16; ++i) cur[i] = grp[i];
;             } else merge16_desc(cur, grp);
	v_mfma_f32_32x32x16_bf16 v[34:49], v[124:127], v[78:81], v[18:33]
	ds_read_b128 v[124:127], v94 offset:9280
	v_max_i32_e32 v147, v132, v134
	v_min_i32_e32 v132, v132, v134
	v_max_i32_e32 v134, v133, v135
	v_min_i32_e32 v133, v133, v135
	v_max_i32_e32 v135, v136, v140
	v_min_i32_e32 v136, v136, v140
	s_waitcnt lgkmcnt(1)
	v_mfma_f32_32x32x16_bf16 v[34:49], v[128:131], v[74:77], v[34:49]
	ds_read_b128 v[128:131], v94 offset:9312
	v_max_i32_e32 v140, v138, v142
	v_min_i32_e32 v138, v138, v142
	v_max_i32_e32 v142, v137, v141
	v_min_i32_e32 v137, v137, v141
	v_max_i32_e32 v141, v139, v143
	v_min_i32_e32 v139, v139, v143
	s_waitcnt lgkmcnt(1)
	v_mfma_f32_32x32x16_bf16 v[34:49], v[124:127], v[70:73], v[34:49]
	v_min_i32_e32 v143, v144, v145
	v_min_i32_e32 v124, v82, v146
	v_min_i32_e32 v127, v135, v140
	v_min_i32_e32 v125, v147, v134
	v_min_i32_e32 v126, v132, v133
	v_min_i32_e32 v149, v142, v141
	v_min_i32_e32 v148, v136, v138
	s_waitcnt lgkmcnt(0)
	v_mfma_f32_32x32x16_bf16 v[34:49], v[128:131], v[66:69], v[34:49]
	v_min_i32_e32 v150, v137, v139
	s_nop 10
	v_and_or_b32 v37, v37, s43, 60
	v_and_or_b32 v48, v48, s43, 37
	v_and_or_b32 v38, v38, s43, 55
	v_and_or_b32 v42, v42, s43, 47
	v_bitop3_b32 v34, v34, s42, 64 bitop3:0x56
	v_and_or_b32 v47, v47, s43, 38
	v_and_or_b32 v39, v39, s43, 54
	v_and_or_b32 v40, v40, s43, 53
	v_and_or_b32 v43, v43, s43, 46
	v_and_or_b32 v44, v44, s43, 45
	v_and_or_b32 v36, v36, s43, 61
	v_and_or_b32 v49, v49, s43, 36
	v_and_or_b32 v41, v41, s43, 52
	v_and_or_b32 v45, v45, s43, 44
	v_and_or_b32 v35, v35, s43, 62
	v_and_or_b32 v46, v46, s43, 39
	v_max_i32_e32 v128, v37, v48
	v_max_i32_e32 v129, v38, v42
	v_max_i32_e32 v131, v34, v47
	v_max_i32_e32 v151, v39, v40
	v_min_i32_e32 v154, v43, v44
	v_min_i32_e32 v155, v36, v49
	v_min_i32_e32 v157, v41, v45
	v_min_i32_e32 v158, v35, v46
	v_min_i32_e32 v39, v39, v40
	v_min_i32_e32 v34, v34, v47
	v_min_i32_e32 v38, v38, v42
	v_min_i32_e32 v37, v37, v48
	v_max_i32_e32 v35, v35, v46
	v_max_i32_e32 v41, v41, v45
	v_max_i32_e32 v36, v36, v49
	v_max_i32_e32 v43, v43, v44
	v_min_i32_e32 v130, v128, v129
	v_min_i32_e32 v152, v131, v151
	v_max_i32_e32 v156, v154, v155
	v_max_i32_e32 v159, v157, v158
	v_max_i32_e32 v40, v39, v34
	v_max_i32_e32 v42, v38, v37
	v_min_i32_e32 v45, v35, v41
	v_min_i32_e32 v44, v36, v43
	v_min_i32_e32 v157, v157, v158
	v_min_i32_e32 v34, v39, v34
	v_min_i32_e32 v37, v38, v37
	v_min_i32_e32 v38, v154, v155
	v_max_i32_e32 v131, v131, v151
	v_max_i32_e32 v35, v35, v41
	v_max_i32_e32 v36, v36, v43
	v_max_i32_e32 v43, v128, v129
	v_min_i32_e32 v153, v130, v152
	v_min_i32_e32 v160, v156, v159
	v_max_i32_e32 v47, v40, v42
	v_max_i32_e32 v46, v45, v44
	v_min_i32_e32 v40, v40, v42
	v_min_i32_e32 v42, v45, v44
	v_max_i32_e32 v45, v130, v152
	v_max_i32_e32 v130, v156, v159
	v_min_i32_e32 v39, v157, v34
	v_min_i32_e32 v154, v37, v38
	v_max_i32_e32 v34, v157, v34
	v_max_i32_e32 v37, v37, v38
	v_min_i32_e32 v41, v131, v35
	v_min_i32_e32 v128, v36, v43
	v_max_i32_e32 v35, v131, v35
	v_max_i32_e32 v36, v36, v43
	v_min_i32_e32 v48, v47, v46
	v_max_i32_e32 v44, v40, v42
	v_min_i32_e32 v152, v45, v130
	v_min_i32_e32 v40, v40, v42
	v_min_i32_e32 v42, v153, v160
	v_max_i32_e32 v155, v39, v154
	v_min_i32_e32 v38, v34, v37
	v_min_i32_e32 v129, v41, v128
	v_max_i32_e32 v41, v41, v128
	v_min_i32_e32 v43, v35, v36
	v_max_i32_e32 v45, v45, v130
	v_max_i32_e32 v46, v47, v46
	v_max_i32_e32 v161, v153, v160
	v_max_i32_e32 v153, v40, v42
	v_max_i32_e32 v157, v155, v38
	v_max_i32_e32 v34, v34, v37
	v_min_i32_e32 v128, v41, v43
	v_min_i32_e32 v47, v45, v46
	v_min_i32_e32 v49, v161, v48
	v_min_i32_e32 v156, v44, v152
	v_max_i32_e32 v158, v153, v157
	v_min_i32_e32 v37, v129, v34
	v_max_i32_e32 v34, v129, v34
	v_min_i32_e32 v129, v128, v47
	v_max_i32_e32 v48, v161, v48
	v_max_i32_e32 v44, v44, v152
	v_min_i32_e32 v40, v40, v42
	v_min_i32_e32 v38, v155, v38
	v_max_i32_e32 v159, v49, v156
	v_max_i32_e32 v151, v158, v37
	v_min_i32_e32 v130, v34, v129
	v_min_i32_e32 v131, v48, v44
	v_min_i32_e32 v49, v49, v156
	v_min_i32_e32 v37, v158, v37
	v_max_i32_e32 v34, v34, v129
	v_max_i32_e32 v44, v48, v44
	v_max_i32_e32 v42, v40, v38
	v_min_i32_e32 v153, v153, v157
	v_max_i32_e32 v160, v159, v151
	v_min_i32_e32 v152, v130, v131
	v_max_i32_e32 v156, v49, v37
	v_min_i32_e32 v48, v34, v44
	v_max_i32_e32 v129, v130, v131
	v_max_i32_e32 v155, v42, v153
	v_min_i32_e32 v37, v49, v37
	v_min_i32_e32 v151, v159, v151
	v_min_i32_e32 v130, v48, v129
	v_max_i32_e32 v131, v160, v152
	v_min_i32_e32 v49, v155, v37
	v_max_i32_e32 v41, v41, v43
	v_max_i32_e32 v43, v45, v46
	v_min_i32_e32 v42, v42, v153
	v_min_i32_e32 v38, v40, v38
	v_min_i32_e32 v161, v160, v152
	v_max_i32_e32 v158, v151, v156
	v_min_i32_e32 v151, v151, v156
	v_max_i32_e32 v34, v34, v44
	v_max_i32_e32 v44, v128, v47
	v_min_i32_e32 v45, v41, v43
	v_max_i32_e32 v40, v41, v43
	v_max_i32_e32 v38, v143, v38
	v_max3_i32 v41, v82, v146, v42
	v_max_i32_e32 v42, v124, v49
	v_max3_i32 v124, v127, v130, v131
	v_min_i32_e32 v46, v44, v45
	v_max_i32_e32 v43, v125, v151
	v_max3_i32 v49, v126, v161, v158
	v_max3_i32 v44, v149, v44, v45
	v_max_i32_e32 v45, v38, v124
	v_min_i32_e32 v38, v38, v124
	ds_read_b128 v[124:127], v96
	v_min_i32_e32 v159, v161, v158
	v_min_i32_e32 v152, v130, v131
	v_max_i32_e32 v37, v155, v37
	v_max_i32_e32 v48, v48, v129
	v_min_i32_e32 v47, v34, v46
	v_max_i32_e32 v34, v34, v46
	v_min_i32_e32 v39, v39, v154
	v_max3_i32 v39, v144, v145, v39
	v_max3_i32 v37, v147, v134, v37
	v_max3_i32 v46, v132, v133, v159
	v_max3_i32 v82, v135, v140, v152
	v_max3_i32 v48, v136, v138, v48
	v_max_i32_e32 v47, v148, v47
	v_max3_i32 v34, v142, v141, v34
	v_max3_i32 v40, v137, v139, v40
	v_max3_i32 v35, v150, v35, v36
	v_max_i32_e32 v36, v39, v82
	v_min_i32_e32 v39, v39, v82
	v_max_i32_e32 v82, v41, v48
	v_min_i32_e32 v41, v41, v48
	v_max_i32_e32 v48, v42, v47
	v_min_i32_e32 v42, v42, v47
	v_max_i32_e32 v47, v37, v34
	v_min_i32_e32 v34, v37, v34
	v_max_i32_e32 v37, v43, v44
	v_min_i32_e32 v43, v43, v44
	v_max_i32_e32 v44, v46, v40
	v_min_i32_e32 v40, v46, v40
	v_max_i32_e32 v46, v49, v35
	v_min_i32_e32 v35, v49, v35
	v_max_i32_e32 v49, v36, v47
	v_min_i32_e32 v132, v36, v47
	v_max_i32_e32 v36, v45, v37
	v_min_i32_e32 v133, v45, v37
	v_max_i32_e32 v37, v82, v44
	v_min_i32_e32 v82, v82, v44
	v_max_i32_e32 v44, v48, v46
	ds_read_b128 v[128:131], v96 offset:32
	v_min_i32_e32 v134, v48, v46
	v_max_i32_e32 v135, v39, v34
	v_min_i32_e32 v136, v39, v34
	v_max_i32_e32 v137, v38, v43
	v_min_i32_e32 v138, v38, v43
	v_max_i32_e32 v139, v41, v40
	v_min_i32_e32 v140, v41, v40
	v_max_i32_e32 v141, v42, v35
	v_min_i32_e32 v142, v42, v35
	v_max_i32_e32 v143, v49, v37
	v_min_i32_e32 v144, v49, v37
	v_max_i32_e32 v145, v36, v44
	v_min_i32_e32 v146, v36, v44
	s_waitcnt lgkmcnt(1)
; #define LAS __attribute__((address_space(3)))
; #define MFMA32(a, b, c) __builtin_amdgcn_mfma_f32_32x32x16_bf16((a), (b), (c), 0, 0, 0)
; #define CE_(a, b) ce_desc(v[a], v[b])
; __device__ __forceinline__ void sort16_desc(int (&v)[16]) {
;     ...
;     CE_(0,13); CE_(1,12); CE_(2,15); CE_(3,14); CE_(4,8); CE_(5,6); CE_(7,11); CE_(9,10);
;     CE_(0,5); CE_(1,7); CE_(2,9); CE_(3,4); CE_(6,13); CE_(8,14); CE_(10,15); CE_(11,12);
;     CE_(0,1); CE_(2,3); CE_(4,5); CE_(6,8); CE_(7,9); CE_(10,11); CE_(12,13); CE_(14,15);
;     CE_(0,2); CE_(1,3); CE_(4,10); CE_(5,11); CE_(6,7); CE_(8,9); CE_(12,14); CE_(13,15);
;     CE_(1,2); CE_(3,12); CE_(4,6); CE_(5,7); CE_(8,10); CE_(9,11); CE_(13,14);
;     CE_(1,4); CE_(2,6); CE_(5,8); CE_(7,10); CE_(9,13); CE_(11,14);
;     CE_(2,4); CE_(3,6); CE_(9,12); CE_(11,13);
;     CE_(3,5); CE_(6,8); CE_(7,9); CE_(10,12);
;     CE_(3,4); CE_(5,6); CE_(7,8); CE_(9,10); CE_(11,12);
;     CE_(6,7); CE_(8,9);
;     ...
; }
; __device__ __forceinline__ void merge16_desc(int (&a)[16], const int (&b)[16]) {
; #pragma unroll
;     for (int i = 0; i < 16; ++i) a[i] = a[i] > b[15 - i] ? a[i] : b[15 - i];
; #pragma unroll
;     for (int j = 8; j > 0; j >>= 1)
; #pragma unroll
;         for (int i = 0; i < 16; ++i) { const int l = i ^ j; if (l > i) ce_desc(a[i], a[l]); }
; }
; __device__ __forceinline__ void route_task(int task, int tl0, const bf16* QP  , const LAS bf16* KHL, LAS unsigned short* EL, LAS float* GL, int lane) {
;     ...
;         for (int kt = 0; kt < 4; ++kt) {
;             f32x16 X;
; #pragma unroll
;             for (int i = 0; i < 16; ++i) X[i] = 8.f;
;             const LAS bf16* khp = KHL + (half * 128 + 32 * kt + r) * 72 + 8 * hi;
; #pragma unroll
;             for (int ks = 0; ks < 4; ++ks) {
;                 const bf16x8 kh = lds8(khp + 16 * ks);
;                 X = MFMA32(kh, qa[half][ks], X);
;             }
;             int grp[16];
; #pragma unroll
;             for (int i = 0; i < 16; ++i) grp[i] = (int)((__float_as_uint(X[i]) | 127u) - (unsigned)(32 * kt + (i & 3) + 8 * (i >> 2)));
;             sort16_desc(grp);
;             if (kt == 0) {
; #pragma unroll
;                 for (int i = 0; i < 16; ++i) cur[i] = grp[i];
;             } else merge16_desc(cur, grp);
	v_mfma_f32_32x32x16_bf16 v[34:49], v[124:127], v[78:81], v[18:33]
	ds_read_b128 v[78:81], v96 offset:64
	v_max_i32_e32 v147, v132, v82
	v_min_i32_e32 v82, v132, v82
	v_max_i32_e32 v132, v137, v141
	v_max_i32_e32 v124, v133, v134
	v_min_i32_e32 v125, v133, v134
	v_max_i32_e32 v126, v135, v139
	s_waitcnt lgkmcnt(1)
	v_mfma_f32_32x32x16_bf16 v[34:49], v[128:131], v[74:77], v[34:49]
	ds_read_b128 v[74:77], v96 offset:96
	v_min_i32_e32 v128, v137, v141
	v_max_i32_e32 v129, v136, v140
	v_min_i32_e32 v130, v136, v140
	v_min_i32_e32 v127, v135, v139
	v_max_i32_e32 v131, v138, v142
	v_min_i32_e32 v133, v138, v142
	s_waitcnt lgkmcnt(1)
	v_mfma_f32_32x32x16_bf16 v[34:49], v[78:81], v[70:73], v[34:49]
	v_min_i32_e32 v134, v143, v145
	v_min_i32_e32 v70, v144, v146
	v_min_i32_e32 v71, v147, v124
	v_min_i32_e32 v72, v82, v125
	v_min_i32_e32 v73, v126, v132
	v_min_i32_e32 v78, v127, v128
	v_min_i32_e32 v79, v129, v131
	s_waitcnt lgkmcnt(0)
	v_mfma_f32_32x32x16_bf16 v[34:49], v[74:77], v[66:69], v[34:49]
	v_min_i32_e32 v80, v130, v133
	s_nop 10
	v_and_or_b32 v41, v41, s43, 20
	v_and_or_b32 v45, v45, s43, 12
	v_and_or_b32 v35, v35, s43, 30
	v_and_or_b32 v46, v46, s43, 7
	v_and_or_b32 v39, v39, s43, 22
	v_and_or_b32 v40, v40, s43, 21
	v_and_or_b32 v34, v34, s43, 31
	v_and_or_b32 v47, v47, s43, 6
	v_and_or_b32 v38, v38, s43, 23
	v_and_or_b32 v42, v42, s43, 15
	v_and_or_b32 v37, v37, s43, 28
	v_and_or_b32 v48, v48, s43, 5
	v_and_or_b32 v43, v43, s43, 14
	v_and_or_b32 v44, v44, s43, 13
	v_and_or_b32 v36, v36, s43, 29
	v_and_or_b32 v49, v49, s43, 4
	v_min_i32_e32 v66, v41, v45
	v_min_i32_e32 v67, v35, v46
	v_min_i32_e32 v69, v39, v40
	v_min_i32_e32 v74, v34, v47
	v_min_i32_e32 v77, v38, v42
	v_min_i32_e32 v81, v37, v48
	v_min_i32_e32 v136, v43, v44
	v_min_i32_e32 v137, v36, v49
	v_max_i32_e32 v34, v34, v47
	v_max_i32_e32 v39, v39, v40
	v_max_i32_e32 v35, v35, v46
	v_max_i32_e32 v41, v41, v45
	v_max_i32_e32 v36, v36, v49
	v_max_i32_e32 v43, v43, v44
	v_max_i32_e32 v37, v37, v48
	v_max_i32_e32 v38, v38, v42
	v_max_i32_e32 v40, v34, v39
	v_max_i32_e32 v45, v35, v41
	v_max_i32_e32 v44, v36, v43
	v_max_i32_e32 v42, v37, v38
	v_min_i32_e32 v46, v40, v45
	v_min_i32_e32 v47, v44, v42
	v_min_i32_e32 v75, v69, v74
	v_min_i32_e32 v48, v46, v47
	v_max_i32_e32 v46, v46, v47
	v_min_i32_e32 v37, v37, v38
	v_min_i32_e32 v34, v34, v39
	v_max_i32_e32 v39, v136, v137
	v_max_i32_e32 v47, v66, v67
	v_max_i32_e32 v69, v69, v74
	v_max_i32_e32 v74, v77, v81
	v_min_i32_e32 v35, v35, v41
	v_min_i32_e32 v36, v36, v43
	v_min_i32_e32 v68, v66, v67
	v_min_i32_e32 v135, v77, v81
	v_min_i32_e32 v138, v136, v137
	v_max_i32_e32 v38, v37, v34
	v_max_i32_e32 v77, v69, v74
	v_max_i32_e32 v41, v35, v36
	v_min_i32_e32 v34, v37, v34
	v_min_i32_e32 v37, v39, v47
	v_min_i32_e32 v76, v68, v75
	v_min_i32_e32 v139, v135, v138
	v_max_i32_e32 v49, v68, v75
	v_max_i32_e32 v68, v135, v138
	v_max_i32_e32 v40, v40, v45
	v_max_i32_e32 v42, v44, v42
	v_max_i32_e32 v66, v39, v47
	v_max_i32_e32 v43, v77, v41
	v_max_i32_e32 v39, v34, v37
	v_min_i32_e32 v41, v77, v41
	v_min_i32_e32 v69, v69, v74
	v_min_i32_e32 v35, v35, v36
	v_max_i32_e32 v75, v49, v68
	v_min_i32_e32 v44, v40, v42
	v_max_i32_e32 v67, v38, v66
	v_max_i32_e32 v47, v39, v41
	v_max_i32_e32 v36, v69, v35
	v_min_i32_e32 v39, v39, v41
	v_min_i32_e32 v35, v69, v35
	v_min_i32_e32 v34, v34, v37
	v_max_i32_e32 v41, v76, v139
	v_min_i32_e32 v49, v49, v68
	v_min_i32_e32 v45, v46, v44
	v_min_i32_e32 v81, v67, v43
	v_min_i32_e32 v38, v38, v66
	v_max_i32_e32 v37, v35, v34
	v_max_i32_e32 v68, v41, v49
	v_max_i32_e32 v135, v48, v75
	v_min_i32_e32 v136, v45, v81
	v_max_i32_e32 v66, v36, v38
	v_min_i32_e32 v36, v36, v38
	v_max_i32_e32 v69, v37, v68
	v_min_i32_e32 v48, v48, v75
	v_max_i32_e32 v137, v135, v136
	v_max_i32_e32 v74, v47, v66
	v_min_i32_e32 v135, v135, v136
	v_min_i32_e32 v47, v47, v66
	v_max_i32_e32 v38, v39, v36
	v_max_i32_e32 v75, v69, v48
	v_min_i32_e32 v34, v35, v34
	v_min_i32_e32 v35, v41, v49
	v_min_i32_e32 v36, v39, v36
	v_min_i32_e32 v39, v69, v48
	v_max_i32_e32 v44, v46, v44
	v_max_i32_e32 v43, v67, v43
	v_min_i32_e32 v140, v76, v139
	v_min_i32_e32 v77, v137, v74
	v_max_i32_e32 v66, v135, v47
	v_max_i32_e32 v76, v38, v75
	v_min_i32_e32 v47, v135, v47
	v_max_i32_e32 v41, v34, v35
	v_min_i32_e32 v37, v37, v68
	v_min_i32_e32 v48, v36, v39
	v_max_i32_e32 v45, v45, v81
	v_min_i32_e32 v46, v44, v43
	v_min_i32_e32 v38, v38, v75
	v_max_i32_e32 v36, v36, v39
	v_min_i32_e32 v136, v77, v66
	v_max_i32_e32 v135, v76, v47
	v_max_i32_e32 v49, v41, v37
	v_max_i32_e32 v69, v137, v74
	v_min_i32_e32 v67, v45, v46
	v_min_i32_e32 v47, v76, v47
	v_max_i32_e32 v39, v38, v36
	v_min_i32_e32 v138, v136, v135
	v_max_i32_e32 v68, v49, v48
	v_max_i32_e32 v74, v69, v67
	v_min_i32_e32 v37, v41, v37
	v_max_i32_e32 v41, v77, v66
	v_min_i32_e32 v75, v47, v39
	v_max_i32_e32 v43, v44, v43
	v_min_i32_e32 v34, v34, v35
	v_min_i32_e32 v36, v38, v36
	v_min_i32_e32 v48, v49, v48
	v_min_i32_e32 v49, v69, v67
	v_max3_i32 v140, v143, v145, v140
	v_max3_i32 v126, v126, v132, v138
	v_max3_i32 v68, v147, v124, v68
	v_max3_i32 v74, v129, v131, v74
	v_max3_i32 v37, v144, v146, v37
	v_max3_i32 v41, v127, v128, v41
	v_max3_i32 v75, v82, v125, v75
	v_max3_i32 v43, v130, v133, v43
	v_max_i32_e32 v34, v134, v34
	v_max3_i32 v35, v73, v136, v135
	v_max_i32_e32 v36, v71, v36
	v_max3_i32 v38, v79, v45, v46
	v_max_i32_e32 v48, v70, v48
	v_max_i32_e32 v49, v78, v49
	v_max3_i32 v39, v72, v47, v39
	v_max3_i32 v40, v80, v40, v42
	v_min_i32_e32 v81, v68, v74
	v_min_i32_e32 v66, v37, v41
	v_min_i32_e32 v73, v34, v35
	v_min_i32_e32 v45, v36, v38
	v_min_i32_e32 v42, v39, v40
	v_max_i32_e32 v71, v140, v126
; #define LAS __attribute__((address_space(3)))
; #define MFMA32(a, b, c) __builtin_amdgcn_mfma_f32_32x32x16_bf16((a), (b), (c), 0, 0, 0)
; __device__ __forceinline__ void route_task(int task, int tl0, const bf16* QP  , const LAS bf16* KHL, LAS unsigned short* EL, LAS float* GL, int lane) {
;     ...
;         for (int kt = 0; kt < 4; ++kt) {
;             f32x16 X;
; #pragma unroll
;             for (int i = 0; i < 16; ++i) X[i] = 8.f;
;             const LAS bf16* khp = KHL + (half * 128 + 32 * kt + r) * 72 + 8 * hi;
; #pragma unroll
;             for (int ks = 0; ks < 4; ++ks) {
;                 const bf16x8 kh = lds8(khp + 16 * ks);
;                 X = MFMA32(kh, qa[half][ks], X);
;     ...
;         { const unsigned h4 = 4u * (unsigned)hi;
; #pragma unroll
;           for (int i = 0; i < 16; ++i) cur[i] -= (int)h4; }
;         int oth[16];
; #pragma unroll
;         for (int i = 0; i < 16; ++i) oth[i] = __shfl_xor(cur[i], 32);
;         merge16_desc(cur, oth);
; #pragma unroll
	v_max_i32_e32 v68, v68, v74
	v_max_i32_e32 v37, v37, v41
	v_max_i32_e32 v41, v75, v43
	v_max_i32_e32 v34, v34, v35
	v_max_i32_e32 v35, v36, v38
	v_max_i32_e32 v38, v48, v49
	v_max_i32_e32 v39, v39, v40
	v_min_i32_e32 v44, v75, v43
	v_max_i32_e32 v72, v71, v68
	v_max_i32_e32 v43, v37, v41
	v_max_i32_e32 v36, v34, v35
	v_max_i32_e32 v40, v38, v39
	v_min_i32_e32 v67, v48, v49
	v_max_i32_e32 v74, v72, v43
	v_max_i32_e32 v48, v36, v40
	v_min_i32_e32 v43, v72, v43
	v_min_i32_e32 v36, v36, v40
	v_max_i32_e32 v40, v43, v36
	v_min_i32_e32 v36, v43, v36
	v_min_i32_e32 v43, v71, v68
	v_min_i32_e32 v37, v37, v41
	v_min_i32_e32 v34, v34, v35
	v_min_i32_e32 v35, v38, v39
	v_min_i32_e32 v132, v140, v126
	v_max_i32_e32 v41, v43, v37
	v_max_i32_e32 v38, v34, v35
	v_min_i32_e32 v37, v43, v37
	v_min_i32_e32 v34, v34, v35
	v_min_i32_e32 v76, v66, v44
	v_min_i32_e32 v47, v67, v42
	v_max_i32_e32 v39, v41, v38
	v_min_i32_e32 v38, v41, v38
	v_max_i32_e32 v35, v37, v34
	v_min_i32_e32 v34, v37, v34
	v_max_i32_e32 v37, v132, v81
	v_max_i32_e32 v41, v66, v44
	v_max_i32_e32 v44, v73, v45
	v_max_i32_e32 v42, v67, v42
	v_min_i32_e32 v124, v132, v81
	v_min_i32_e32 v46, v73, v45
	v_max_i32_e32 v43, v37, v41
	v_min_i32_e32 v37, v37, v41
	v_min_i32_e32 v41, v44, v42
	v_min_i32_e32 v77, v124, v76
	v_min_i32_e32 v69, v46, v47
	v_max_i32_e32 v45, v44, v42
	v_max_i32_e32 v42, v37, v41
	v_min_i32_e32 v37, v37, v41
	v_max_i32_e32 v41, v124, v76
	v_max_i32_e32 v44, v46, v47
	v_min_i32_e32 v70, v77, v69
	v_max_i32_e32 v49, v74, v48
	v_min_i32_e32 v48, v74, v48
	v_max_i32_e32 v66, v43, v45
	v_min_i32_e32 v43, v43, v45
	v_max_i32_e32 v45, v41, v44
	v_min_i32_e32 v41, v41, v44
	v_max_i32_e32 v44, v77, v69
	v_sub_u32_e32 v46, v49, v87
	v_sub_u32_e32 v47, v48, v87
	v_sub_u32_e32 v40, v40, v87
	v_sub_u32_e32 v36, v36, v87
	v_sub_u32_e32 v39, v39, v87
	v_sub_u32_e32 v38, v38, v87
	v_sub_u32_e32 v35, v35, v87
	v_sub_u32_e32 v34, v34, v87
	v_sub_u32_e32 v48, v66, v87
	v_sub_u32_e32 v43, v43, v87
	v_sub_u32_e32 v42, v42, v87
	v_sub_u32_e32 v37, v37, v87
	v_sub_u32_e32 v45, v45, v87
	v_sub_u32_e32 v41, v41, v87
	v_sub_u32_e32 v44, v44, v87
	v_sub_u32_e32 v49, v70, v87
	ds_bpermute_b32 v66, v123, v46
	ds_bpermute_b32 v67, v123, v47
	ds_bpermute_b32 v68, v123, v40
	ds_bpermute_b32 v69, v123, v36
	ds_bpermute_b32 v70, v123, v39
	ds_bpermute_b32 v71, v123, v38
	ds_bpermute_b32 v72, v123, v35
	ds_bpermute_b32 v73, v123, v34
	ds_bpermute_b32 v74, v123, v48
	ds_bpermute_b32 v75, v123, v43
	ds_bpermute_b32 v76, v123, v42
	ds_bpermute_b32 v77, v123, v49
	ds_bpermute_b32 v78, v123, v44
	ds_bpermute_b32 v79, v123, v41
	ds_bpermute_b32 v80, v123, v45
	ds_bpermute_b32 v81, v123, v37
	s_waitcnt lgkmcnt(4)
	v_max_i32_e32 v46, v46, v77
	s_waitcnt lgkmcnt(3)
	v_max_i32_e32 v47, v47, v78
	s_waitcnt lgkmcnt(2)
	v_max_i32_e32 v40, v40, v79
	s_waitcnt lgkmcnt(1)
	v_max_i32_e32 v36, v36, v80
	s_waitcnt lgkmcnt(0)
	v_max_i32_e32 v39, v39, v81
	v_max_i32_e32 v38, v38, v76
	v_max_i32_e32 v35, v35, v75
	v_max_i32_e32 v34, v34, v74
	v_max_i32_e32 v48, v48, v73
	v_max_i32_e32 v43, v43, v72
	v_max_i32_e32 v42, v42, v71
	v_max_i32_e32 v37, v37, v70
	v_max_i32_e32 v45, v45, v69
	v_max_i32_e32 v41, v41, v68
	v_max_i32_e32 v44, v44, v67
	v_max_i32_e32 v49, v49, v66
	v_max_i32_e32 v66, v46, v48
	v_min_i32_e32 v46, v46, v48
	v_max_i32_e32 v48, v47, v43
	v_min_i32_e32 v43, v47, v43
	v_max_i32_e32 v47, v40, v42
	v_min_i32_e32 v40, v40, v42
	v_max_i32_e32 v42, v36, v37
	v_min_i32_e32 v36, v36, v37
	v_max_i32_e32 v37, v39, v45
	v_min_i32_e32 v39, v39, v45
	v_max_i32_e32 v45, v38, v41
	v_min_i32_e32 v38, v38, v41
	v_max_i32_e32 v41, v35, v44
	v_min_i32_e32 v35, v35, v44
	v_max_i32_e32 v44, v34, v49
	v_min_i32_e32 v34, v34, v49
	v_max_i32_e32 v49, v66, v37
	v_min_i32_e32 v37, v66, v37
	v_max_i32_e32 v66, v48, v45
	v_min_i32_e32 v45, v48, v45
	v_max_i32_e32 v48, v47, v41
	v_min_i32_e32 v41, v47, v41
	v_max_i32_e32 v47, v42, v44
	v_max_i32_e32 v80, v66, v47
	v_min_i32_e32 v124, v66, v47
	ds_read_b128 v[66:69], v94 offset:18432
	ds_read_b128 v[70:73], v94 offset:18464
	v_min_i32_e32 v42, v42, v44
	v_max_i32_e32 v44, v46, v39
	v_min_i32_e32 v74, v46, v39
	v_max_i32_e32 v39, v43, v38
	v_min_i32_e32 v75, v43, v38
	v_max_i32_e32 v38, v40, v35
	v_min_i32_e32 v76, v40, v35
	v_max_i32_e32 v35, v36, v34
	v_min_i32_e32 v77, v36, v34
	v_max_i32_e32 v78, v49, v48
	v_min_i32_e32 v82, v49, v48
	v_max_i32_e32 v125, v37, v41
	v_min_i32_e32 v126, v37, v41
	v_max_i32_e32 v127, v45, v42
	v_min_i32_e32 v128, v45, v42
	v_max_i32_e32 v129, v44, v38
	v_min_i32_e32 v130, v44, v38
	v_max_i32_e32 v131, v39, v35
	v_min_i32_e32 v132, v39, v35
	s_waitcnt vmcnt(3) lgkmcnt(1)
	v_mfma_f32_32x32x16_bf16 v[34:49], v[66:69], v[62:65], v[18:33]
	ds_read_b128 v[66:69], v94 offset:18496
	v_max_i32_e32 v133, v74, v76
	v_min_i32_e32 v134, v74, v76
	v_max_i32_e32 v135, v75, v77
	v_min_i32_e32 v136, v75, v77
	v_max_i32_e32 v79, v78, v80
	v_min_i32_e32 v81, v78, v80
	s_waitcnt vmcnt(2) lgkmcnt(1)
	v_mfma_f32_32x32x16_bf16 v[34:49], v[70:73], v[58:61], v[34:49]
	v_max_i32_e32 v80, v82, v124
	v_min_i32_e32 v78, v82, v124
	v_max_i32_e32 v77, v125, v127
	v_min_i32_e32 v76, v125, v127
	v_max_i32_e32 v75, v126, v128
	v_min_i32_e32 v73, v126, v128
	ds_read_b128 v[124:127], v94 offset:18528
	s_waitcnt vmcnt(1) lgkmcnt(1)
	v_mfma_f32_32x32x16_bf16 v[34:49], v[66:69], v[54:57], v[34:49]
	v_max_i32_e32 v71, v129, v131
	v_min_i32_e32 v74, v129, v131
	v_max_i32_e32 v72, v130, v132
	v_min_i32_e32 v70, v130, v132
	v_max_i32_e32 v69, v133, v135
	v_min_i32_e32 v68, v133, v135
	v_max_i32_e32 v67, v134, v136
	s_waitcnt vmcnt(0) lgkmcnt(0)
; #define LAS __attribute__((address_space(3)))
; #define MFMA32(a, b, c) __builtin_amdgcn_mfma_f32_32x32x16_bf16((a), (b), (c), 0, 0, 0)
; #define CE_(a, b) ce_desc(v[a], v[b])
; __device__ __forceinline__ void sort16_desc(int (&v)[16]) {
;     ...
;     CE_(0,13); CE_(1,12); CE_(2,15); CE_(3,14); CE_(4,8); CE_(5,6); CE_(7,11); CE_(9,10);
;     CE_(0,5); CE_(1,7); CE_(2,9); CE_(3,4); CE_(6,13); CE_(8,14); CE_(10,15); CE_(11,12);
;     CE_(0,1); CE_(2,3); CE_(4,5); CE_(6,8); CE_(7,9); CE_(10,11); CE_(12,13); CE_(14,15);
;     CE_(0,2); CE_(1,3); CE_(4,10); CE_(5,11); CE_(6,7); CE_(8,9); CE_(12,14); CE_(13,15);
;     CE_(1,2); CE_(3,12); CE_(4,6); CE_(5,7); CE_(8,10); CE_(9,11); CE_(13,14);
;     CE_(1,4); CE_(2,6); CE_(5,8); CE_(7,10); CE_(9,13); CE_(11,14);
;     CE_(2,4); CE_(3,6); CE_(9,12); CE_(11,13);
;     CE_(3,5); CE_(6,8); CE_(7,9); CE_(10,12);
;     CE_(3,4); CE_(5,6); CE_(7,8); CE_(9,10); CE_(11,12);
;     CE_(6,7); CE_(8,9);
;     ...
; }
; __device__ __forceinline__ void route_task(int task, int tl0, const bf16* QP  , const LAS bf16* KHL, LAS unsigned short* EL, LAS float* GL, int lane) {
;     ...
;         for (int kt = 0; kt < 4; ++kt) {
;             f32x16 X;
; #pragma unroll
;             for (int i = 0; i < 16; ++i) X[i] = 8.f;
;             const LAS bf16* khp = KHL + (half * 128 + 32 * kt + r) * 72 + 8 * hi;
; #pragma unroll
;             for (int ks = 0; ks < 4; ++ks) {
;                 const bf16x8 kh = lds8(khp + 16 * ks);
;                 X = MFMA32(kh, qa[half][ks], X);
;             }
;             int grp[16];
; #pragma unroll
;             for (int i = 0; i < 16; ++i) grp[i] = (int)((__float_as_uint(X[i]) | 127u) - (unsigned)(32 * kt + (i & 3) + 8 * (i >> 2)));
;             sort16_desc(grp);
;             if (kt == 0) {
; #pragma unroll
;                 for (int i = 0; i < 16; ++i) cur[i] = grp[i];
;             } else merge16_desc(cur, grp);
	v_mfma_f32_32x32x16_bf16 v[34:49], v[124:127], v[50:53], v[34:49]
	v_min_i32_e32 v66, v134, v136
	s_nop 10
	v_bitop3_b32 v37, v37, s42, 3 bitop3:0x56
	v_bitop3_b32 v48, v48, s42, 26 bitop3:0x56
	v_bitop3_b32 v38, v38, s42, 8 bitop3:0x56
	v_bitop3_b32 v42, v42, s42, 16 bitop3:0x56
	v_bitop3_b32 v47, v47, s42, 25 bitop3:0x56
	v_bitop3_b32 v39, v39, s42, 9 bitop3:0x56
	v_bitop3_b32 v40, v40, s42, 10 bitop3:0x56
	v_bitop3_b32 v43, v43, s42, 17 bitop3:0x56
	v_bitop3_b32 v44, v44, s42, 18 bitop3:0x56
	v_bitop3_b32 v36, v36, s42, 2 bitop3:0x56
	v_bitop3_b32 v49, v49, s42, 27 bitop3:0x56
	v_bitop3_b32 v41, v41, s42, 11 bitop3:0x56
	v_bitop3_b32 v45, v45, s42, 19 bitop3:0x56
	v_bitop3_b32 v35, v35, s42, 1 bitop3:0x56
	v_bitop3_b32 v46, v46, s42, 24 bitop3:0x56
	v_or_b32_e32 v34, 0x7f, v34
	v_max_i32_e32 v82, v37, v48
	v_max_i32_e32 v124, v38, v42
	v_max_i32_e32 v126, v34, v47
	v_max_i32_e32 v127, v39, v40
	v_min_i32_e32 v130, v43, v44
	v_min_i32_e32 v131, v36, v49
	v_min_i32_e32 v133, v41, v45
	v_min_i32_e32 v134, v35, v46
	v_min_i32_e32 v39, v39, v40
	v_min_i32_e32 v34, v34, v47
	v_min_i32_e32 v38, v38, v42
	v_min_i32_e32 v37, v37, v48
	v_max_i32_e32 v35, v35, v46
	v_max_i32_e32 v41, v41, v45
	v_max_i32_e32 v36, v36, v49
	v_max_i32_e32 v43, v43, v44
	v_min_i32_e32 v125, v82, v124
	v_min_i32_e32 v128, v126, v127
	v_max_i32_e32 v132, v130, v131
	v_max_i32_e32 v135, v133, v134
	v_max_i32_e32 v40, v39, v34
	v_max_i32_e32 v42, v38, v37
	v_min_i32_e32 v45, v35, v41
	v_min_i32_e32 v44, v36, v43
	v_min_i32_e32 v129, v125, v128
	v_max_i32_e32 v47, v40, v42
	v_max_i32_e32 v46, v45, v44
	v_min_i32_e32 v40, v40, v42
	v_min_i32_e32 v42, v45, v44
	v_max_i32_e32 v45, v125, v128
	v_max_i32_e32 v125, v132, v135
	v_min_i32_e32 v128, v45, v125
	v_min_i32_e32 v34, v39, v34
	v_max_i32_e32 v39, v126, v127
	v_max_i32_e32 v35, v35, v41
	v_max_i32_e32 v41, v82, v124
	v_max_i32_e32 v148, v45, v125
	ds_read_b128 v[124:127], v97
	v_max_i32_e32 v44, v40, v42
	v_min_i32_e32 v138, v40, v42
	v_min_i32_e32 v40, v133, v134
	v_min_i32_e32 v37, v38, v37
	v_min_i32_e32 v38, v130, v131
	v_max_i32_e32 v36, v36, v43
	v_min_i32_e32 v136, v132, v135
	v_min_i32_e32 v133, v40, v34
	v_min_i32_e32 v134, v37, v38
	v_max_i32_e32 v34, v40, v34
	v_max_i32_e32 v37, v37, v38
	v_min_i32_e32 v40, v39, v35
	v_min_i32_e32 v42, v36, v41
	v_max_i32_e32 v144, v39, v35
	v_max_i32_e32 v145, v36, v41
	v_max_i32_e32 v137, v129, v136
	v_min_i32_e32 v136, v129, v136
	v_max_i32_e32 v140, v133, v134
	v_min_i32_e32 v141, v34, v37
	v_max_i32_e32 v143, v40, v42
	v_min_i32_e32 v146, v144, v145
	v_max_i32_e32 v149, v47, v46
	v_min_i32_e32 v48, v47, v46
	v_max_i32_e32 v139, v138, v136
	v_max_i32_e32 v142, v140, v141
	v_min_i32_e32 v43, v40, v42
	v_max_i32_e32 v34, v34, v37
	v_min_i32_e32 v147, v143, v146
	v_min_i32_e32 v150, v148, v149
	v_min_i32_e32 v49, v137, v48
	v_min_i32_e32 v132, v44, v128
	v_max_i32_e32 v38, v139, v142
	v_min_i32_e32 v37, v43, v34
	v_max_i32_e32 v34, v43, v34
	v_min_i32_e32 v35, v147, v150
	v_max_i32_e32 v39, v137, v48
	v_max_i32_e32 v40, v44, v128
	v_max_i32_e32 v135, v49, v132
	v_max_i32_e32 v82, v38, v37
	v_min_i32_e32 v36, v34, v35
	v_min_i32_e32 v41, v39, v40
	v_max_i32_e32 v129, v135, v82
	v_min_i32_e32 v42, v36, v41
	v_min_i32_e32 v137, v129, v42
	v_max_i32_e32 v159, v129, v42
	ds_read_b128 v[128:131], v97 offset:32
	v_min_i32_e32 v82, v135, v82
	v_min_i32_e32 v132, v49, v132
	v_min_i32_e32 v135, v38, v37
	v_max_i32_e32 v154, v34, v35
	v_max_i32_e32 v155, v39, v40
	v_max_i32_e32 v157, v36, v41
	s_waitcnt lgkmcnt(1)
	v_mfma_f32_32x32x16_bf16 v[34:49], v[124:127], v[62:65], v[18:33]
	ds_read_b128 v[124:127], v97 offset:64
	v_max_i32_e32 v151, v132, v135
	v_max_i32_e32 v152, v82, v151
	v_min_i32_e32 v136, v138, v136
	v_min_i32_e32 v138, v140, v141
	v_min_i32_e32 v82, v82, v151
	v_max_i32_e32 v147, v147, v150
	s_waitcnt lgkmcnt(1)
	v_mfma_f32_32x32x16_bf16 v[34:49], v[128:131], v[58:61], v[34:49]
	ds_read_b128 v[128:131], v97 offset:96
	v_max_i32_e32 v143, v143, v146
	v_min_i32_e32 v133, v133, v134
	v_min_i32_e32 v156, v154, v155
	v_max_i32_e32 v140, v136, v138
	v_min_i32_e32 v139, v139, v142
	v_max_i32_e32 v142, v154, v155
	s_waitcnt lgkmcnt(1)
	v_mfma_f32_32x32x16_bf16 v[34:49], v[124:127], v[54:57], v[34:49]
	v_max_i32_e32 v124, v148, v149
	v_min_i32_e32 v136, v136, v138
	v_max_i32_e32 v141, v140, v139
	v_min_i32_e32 v139, v140, v139
	v_min_i32_e32 v125, v143, v124
	v_min_i32_e32 v158, v156, v157
	v_min_i32_e32 v132, v132, v135
	s_waitcnt lgkmcnt(0)
; #define LAS __attribute__((address_space(3)))
; #define MFMA32(a, b, c) __builtin_amdgcn_mfma_f32_32x32x16_bf16((a), (b), (c), 0, 0, 0)
; #define CE_(a, b) ce_desc(v[a], v[b])
; __device__ __forceinline__ void sort16_desc(int (&v)[16]) {
;     ...
;     CE_(0,13); CE_(1,12); CE_(2,15); CE_(3,14); CE_(4,8); CE_(5,6); CE_(7,11); CE_(9,10);
;     CE_(0,5); CE_(1,7); CE_(2,9); CE_(3,4); CE_(6,13); CE_(8,14); CE_(10,15); CE_(11,12);
;     CE_(0,1); CE_(2,3); CE_(4,5); CE_(6,8); CE_(7,9); CE_(10,11); CE_(12,13); CE_(14,15);
;     CE_(0,2); CE_(1,3); CE_(4,10); CE_(5,11); CE_(6,7); CE_(8,9); CE_(12,14); CE_(13,15);
;     CE_(1,2); CE_(3,12); CE_(4,6); CE_(5,7); CE_(8,10); CE_(9,11); CE_(13,14);
;     CE_(1,4); CE_(2,6); CE_(5,8); CE_(7,10); CE_(9,13); CE_(11,14);
;     CE_(2,4); CE_(3,6); CE_(9,12); CE_(11,13);
;     CE_(3,5); CE_(6,8); CE_(7,9); CE_(10,12);
;     CE_(3,4); CE_(5,6); CE_(7,8); CE_(9,10); CE_(11,12);
;     CE_(6,7); CE_(8,9);
;     ...
; }
; __device__ __forceinline__ void merge16_desc(int (&a)[16], const int (&b)[16]) {
; #pragma unroll
;     for (int i = 0; i < 16; ++i) a[i] = a[i] > b[15 - i] ? a[i] : b[15 - i];
; #pragma unroll
;     for (int j = 8; j > 0; j >>= 1)
; #pragma unroll
;         for (int i = 0; i < 16; ++i) { const int l = i ^ j; if (l > i) ce_desc(a[i], a[l]); }
; }
; __device__ __forceinline__ void route_task(int task, int tl0, const bf16* QP  , const LAS bf16* KHL, LAS unsigned short* EL, LAS float* GL, int lane) {
;     ...
;         for (int kt = 0; kt < 4; ++kt) {
;             f32x16 X;
; #pragma unroll
;             for (int i = 0; i < 16; ++i) X[i] = 8.f;
;             const LAS bf16* khp = KHL + (half * 128 + 32 * kt + r) * 72 + 8 * hi;
; #pragma unroll
;             for (int ks = 0; ks < 4; ++ks) {
;                 const bf16x8 kh = lds8(khp + 16 * ks);
;                 X = MFMA32(kh, qa[half][ks], X);
;             }
;             int grp[16];
; #pragma unroll
;             for (int i = 0; i < 16; ++i) grp[i] = (int)((__float_as_uint(X[i]) | 127u) - (unsigned)(32 * kt + (i & 3) + 8 * (i >> 2)));
;             sort16_desc(grp);
;             if (kt == 0) {
; #pragma unroll
;                 for (int i = 0; i < 16; ++i) cur[i] = grp[i];
;             } else merge16_desc(cur, grp);
	v_mfma_f32_32x32x16_bf16 v[34:49], v[128:131], v[50:53], v[34:49]
	v_min_i32_e32 v126, v147, v125
	v_min_i32_e32 v153, v137, v152
	v_min_i32_e32 v160, v158, v159
	v_min_i32_e32 v135, v141, v132
	v_min_i32_e32 v127, v142, v126
	s_nop 6
	v_bitop3_b32 v37, v37, s42, 35 bitop3:0x56
	v_bitop3_b32 v48, v48, s42, 58 bitop3:0x56
	v_bitop3_b32 v38, v38, s42, 40 bitop3:0x56
	v_bitop3_b32 v42, v42, s42, 48 bitop3:0x56
	v_bitop3_b32 v34, v34, s42, 32 bitop3:0x56
	v_bitop3_b32 v47, v47, s42, 57 bitop3:0x56
	v_bitop3_b32 v39, v39, s42, 41 bitop3:0x56
	v_bitop3_b32 v40, v40, s42, 42 bitop3:0x56
	v_bitop3_b32 v43, v43, s42, 49 bitop3:0x56
	v_bitop3_b32 v44, v44, s42, 50 bitop3:0x56
	v_bitop3_b32 v36, v36, s42, 34 bitop3:0x56
	v_bitop3_b32 v49, v49, s42, 59 bitop3:0x56
	v_bitop3_b32 v41, v41, s42, 43 bitop3:0x56
	v_bitop3_b32 v45, v45, s42, 51 bitop3:0x56
	v_bitop3_b32 v35, v35, s42, 33 bitop3:0x56
	v_bitop3_b32 v46, v46, s42, 56 bitop3:0x56
	v_max_i32_e32 v128, v37, v48
	v_max_i32_e32 v129, v38, v42
	v_max_i32_e32 v131, v34, v47
	v_max_i32_e32 v134, v39, v40
	v_min_i32_e32 v146, v43, v44
	v_min_i32_e32 v148, v36, v49
	v_min_i32_e32 v150, v41, v45
	v_min_i32_e32 v151, v35, v46
	v_min_i32_e32 v39, v39, v40
	v_min_i32_e32 v34, v34, v47
	v_min_i32_e32 v38, v38, v42
	v_min_i32_e32 v37, v37, v48
	v_max_i32_e32 v35, v35, v46
	v_max_i32_e32 v41, v41, v45
	v_max_i32_e32 v36, v36, v49
	v_max_i32_e32 v43, v43, v44
	v_min_i32_e32 v130, v128, v129
	v_min_i32_e32 v138, v131, v134
	v_max_i32_e32 v149, v146, v148
	v_max_i32_e32 v154, v150, v151
	v_max_i32_e32 v40, v39, v34
	v_max_i32_e32 v42, v38, v37
	v_min_i32_e32 v45, v35, v41
	v_min_i32_e32 v44, v36, v43
	v_min_i32_e32 v150, v150, v151
	v_min_i32_e32 v34, v39, v34
	v_min_i32_e32 v37, v38, v37
	v_min_i32_e32 v38, v146, v148
	v_max_i32_e32 v131, v131, v134
	v_max_i32_e32 v35, v35, v41
	v_max_i32_e32 v36, v36, v43
	v_max_i32_e32 v43, v128, v129
	v_min_i32_e32 v140, v130, v138
	v_min_i32_e32 v155, v149, v154
	v_max_i32_e32 v47, v40, v42
	v_max_i32_e32 v46, v45, v44
	v_min_i32_e32 v40, v40, v42
	v_min_i32_e32 v42, v45, v44
	v_max_i32_e32 v45, v130, v138
	v_max_i32_e32 v130, v149, v154
	v_min_i32_e32 v39, v150, v34
	v_min_i32_e32 v146, v37, v38
	v_max_i32_e32 v34, v150, v34
	v_max_i32_e32 v37, v37, v38
	v_min_i32_e32 v41, v131, v35
	v_min_i32_e32 v128, v36, v43
	v_max_i32_e32 v35, v131, v35
	v_max_i32_e32 v36, v36, v43
	v_min_i32_e32 v48, v47, v46
	v_max_i32_e32 v44, v40, v42
	v_min_i32_e32 v138, v45, v130
	v_min_i32_e32 v40, v40, v42
	v_min_i32_e32 v42, v140, v155
	v_max_i32_e32 v148, v39, v146
	v_min_i32_e32 v38, v34, v37
	v_min_i32_e32 v129, v41, v128
	v_max_i32_e32 v41, v41, v128
	v_min_i32_e32 v43, v35, v36
	v_max_i32_e32 v45, v45, v130
	v_max_i32_e32 v46, v47, v46
	v_max_i32_e32 v161, v140, v155
	v_max_i32_e32 v140, v40, v42
	v_max_i32_e32 v150, v148, v38
	v_max_i32_e32 v34, v34, v37
	v_min_i32_e32 v128, v41, v43
	v_min_i32_e32 v47, v45, v46
	v_min_i32_e32 v49, v161, v48
	v_min_i32_e32 v149, v44, v138
	v_max_i32_e32 v151, v140, v150
	v_min_i32_e32 v37, v129, v34
	v_max_i32_e32 v34, v129, v34
	v_min_i32_e32 v129, v128, v47
	v_max_i32_e32 v48, v161, v48
	v_max_i32_e32 v44, v44, v138
	v_max_i32_e32 v154, v49, v149
	v_max_i32_e32 v134, v151, v37
	v_min_i32_e32 v130, v34, v129
	v_min_i32_e32 v131, v48, v44
	v_min_i32_e32 v49, v49, v149
	v_min_i32_e32 v37, v151, v37
	v_max_i32_e32 v34, v34, v129
	v_max_i32_e32 v44, v48, v44
	v_min_i32_e32 v40, v40, v42
	v_min_i32_e32 v38, v148, v38
	v_max_i32_e32 v41, v41, v43
	v_max_i32_e32 v43, v45, v46
	v_max_i32_e32 v155, v154, v134
	v_min_i32_e32 v138, v130, v131
	v_min_i32_e32 v134, v154, v134
	v_max_i32_e32 v149, v49, v37
	v_min_i32_e32 v48, v34, v44
	v_max_i32_e32 v129, v130, v131
	v_max_i32_e32 v42, v40, v38
	v_min_i32_e32 v140, v140, v150
	v_max_i32_e32 v34, v34, v44
	v_max_i32_e32 v44, v128, v47
	v_min_i32_e32 v45, v41, v43
	v_min_i32_e32 v161, v155, v138
	v_max_i32_e32 v151, v134, v149
	v_min_i32_e32 v130, v48, v129
	v_max_i32_e32 v131, v155, v138
	v_max_i32_e32 v148, v42, v140
	v_min_i32_e32 v37, v49, v37
	v_min_i32_e32 v46, v44, v45
	v_min_i32_e32 v154, v161, v151
	v_min_i32_e32 v138, v130, v131
	v_min_i32_e32 v49, v148, v37
	v_min_i32_e32 v134, v134, v149
	v_min_i32_e32 v47, v34, v46
	v_min_i32_e32 v42, v42, v140
	v_min_i32_e32 v38, v40, v38
	v_min_i32_e32 v39, v39, v146
	v_max3_i32 v39, v144, v145, v39
	v_max3_i32 v38, v143, v124, v38
	v_max3_i32 v40, v147, v125, v42
	v_max3_i32 v42, v142, v126, v49
	v_max3_i32 v37, v127, v148, v37
	v_max3_i32 v49, v156, v157, v134
	v_max3_i32 v124, v158, v159, v154
	v_max3_i32 v125, v160, v161, v151
	v_max3_i32 v126, v137, v152, v138
	v_max3_i32 v127, v153, v130, v131
	v_max3_i32 v48, v82, v48, v129
	v_max3_i32 v47, v141, v132, v47
	v_max3_i32 v34, v135, v34, v46
	v_max3_i32 v44, v139, v44, v45
	v_max3_i32 v41, v136, v41, v43
	v_max3_i32 v35, v133, v35, v36
	v_max_i32_e32 v36, v39, v126
	v_min_i32_e32 v39, v39, v126
	v_max_i32_e32 v43, v38, v127
	v_min_i32_e32 v38, v38, v127
	v_max_i32_e32 v45, v40, v48
	v_min_i32_e32 v40, v40, v48
	v_max_i32_e32 v46, v42, v47
	v_min_i32_e32 v42, v42, v47
	v_max_i32_e32 v47, v37, v34
	v_min_i32_e32 v34, v37, v34
	v_max_i32_e32 v37, v49, v44
	v_min_i32_e32 v44, v49, v44
	v_max_i32_e32 v48, v124, v41
	v_min_i32_e32 v41, v124, v41
	v_max_i32_e32 v49, v125, v35
	v_min_i32_e32 v35, v125, v35
	ds_read_b128 v[124:127], v94 offset:27648
	ds_read_b128 v[128:131], v94 offset:27680
	v_max_i32_e32 v82, v36, v47
	v_min_i32_e32 v132, v36, v47
	v_max_i32_e32 v36, v43, v37
	v_min_i32_e32 v133, v43, v37
	v_max_i32_e32 v37, v45, v48
	v_max_i32_e32 v43, v46, v49
	v_min_i32_e32 v134, v45, v48
	v_min_i32_e32 v135, v46, v49
	v_max_i32_e32 v136, v39, v34
	v_min_i32_e32 v137, v39, v34
	v_max_i32_e32 v138, v38, v44
	v_min_i32_e32 v139, v38, v44
	v_max_i32_e32 v140, v40, v41
	v_min_i32_e32 v141, v40, v41
	v_max_i32_e32 v142, v42, v35
	v_min_i32_e32 v143, v42, v35
	v_max_i32_e32 v144, v82, v37
	v_min_i32_e32 v82, v82, v37
	v_max_i32_e32 v145, v36, v43
	v_min_i32_e32 v146, v36, v43
	s_waitcnt lgkmcnt(1)
; #define LAS __attribute__((address_space(3)))
; #define MFMA32(a, b, c) __builtin_amdgcn_mfma_f32_32x32x16_bf16((a), (b), (c), 0, 0, 0)
; #define CE_(a, b) ce_desc(v[a], v[b])
; __device__ __forceinline__ void sort16_desc(int (&v)[16]) {
;     ...
;     CE_(0,13); CE_(1,12); CE_(2,15); CE_(3,14); CE_(4,8); CE_(5,6); CE_(7,11); CE_(9,10);
;     CE_(0,5); CE_(1,7); CE_(2,9); CE_(3,4); CE_(6,13); CE_(8,14); CE_(10,15); CE_(11,12);
;     CE_(0,1); CE_(2,3); CE_(4,5); CE_(6,8); CE_(7,9); CE_(10,11); CE_(12,13); CE_(14,15);
;     CE_(0,2); CE_(1,3); CE_(4,10); CE_(5,11); CE_(6,7); CE_(8,9); CE_(12,14); CE_(13,15);
;     CE_(1,2); CE_(3,12); CE_(4,6); CE_(5,7); CE_(8,10); CE_(9,11); CE_(13,14);
;     CE_(1,4); CE_(2,6); CE_(5,8); CE_(7,10); CE_(9,13); CE_(11,14);
;     CE_(2,4); CE_(3,6); CE_(9,12); CE_(11,13);
;     CE_(3,5); CE_(6,8); CE_(7,9); CE_(10,12);
;     CE_(3,4); CE_(5,6); CE_(7,8); CE_(9,10); CE_(11,12);
;     CE_(6,7); CE_(8,9);
;     ...
; }
; __device__ __forceinline__ void merge16_desc(int (&a)[16], const int (&b)[16]) {
; #pragma unroll
;     for (int i = 0; i < 16; ++i) a[i] = a[i] > b[15 - i] ? a[i] : b[15 - i];
; #pragma unroll
;     for (int j = 8; j > 0; j >>= 1)
; #pragma unroll
;         for (int i = 0; i < 16; ++i) { const int l = i ^ j; if (l > i) ce_desc(a[i], a[l]); }
; }
; __device__ __forceinline__ void route_task(int task, int tl0, const bf16* QP  , const LAS bf16* KHL, LAS unsigned short* EL, LAS float* GL, int lane) {
;     ...
;         for (int kt = 0; kt < 4; ++kt) {
;             f32x16 X;
; #pragma unroll
;             for (int i = 0; i < 16; ++i) X[i] = 8.f;
;             const LAS bf16* khp = KHL + (half * 128 + 32 * kt + r) * 72 + 8 * hi;
; #pragma unroll
;             for (int ks = 0; ks < 4; ++ks) {
;                 const bf16x8 kh = lds8(khp + 16 * ks);
;                 X = MFMA32(kh, qa[half][ks], X);
;             }
;             int grp[16];
; #pragma unroll
;             for (int i = 0; i < 16; ++i) grp[i] = (int)((__float_as_uint(X[i]) | 127u) - (unsigned)(32 * kt + (i & 3) + 8 * (i >> 2)));
;             sort16_desc(grp);
;             if (kt == 0) {
; #pragma unroll
;                 for (int i = 0; i < 16; ++i) cur[i] = grp[i];
;             } else merge16_desc(cur, grp);
	v_mfma_f32_32x32x16_bf16 v[34:49], v[124:127], v[62:65], v[18:33]
	ds_read_b128 v[124:127], v94 offset:27712
	v_max_i32_e32 v147, v132, v134
	v_min_i32_e32 v132, v132, v134
	v_max_i32_e32 v134, v133, v135
	v_min_i32_e32 v133, v133, v135
	v_max_i32_e32 v135, v136, v140
	v_min_i32_e32 v136, v136, v140
	s_waitcnt lgkmcnt(1)
	v_mfma_f32_32x32x16_bf16 v[34:49], v[128:131], v[58:61], v[34:49]
	ds_read_b128 v[128:131], v94 offset:27744
	v_max_i32_e32 v140, v138, v142
	v_min_i32_e32 v138, v138, v142
	v_max_i32_e32 v142, v137, v141
	v_min_i32_e32 v137, v137, v141
	v_max_i32_e32 v141, v139, v143
	v_min_i32_e32 v139, v139, v143
	s_waitcnt lgkmcnt(1)
	v_mfma_f32_32x32x16_bf16 v[34:49], v[124:127], v[54:57], v[34:49]
	v_min_i32_e32 v143, v144, v145
	v_min_i32_e32 v124, v82, v146
	v_min_i32_e32 v127, v135, v140
	v_min_i32_e32 v125, v147, v134
	v_min_i32_e32 v126, v132, v133
	v_min_i32_e32 v149, v142, v141
	v_min_i32_e32 v148, v136, v138
	s_waitcnt lgkmcnt(0)
	v_mfma_f32_32x32x16_bf16 v[34:49], v[128:131], v[50:53], v[34:49]
	v_min_i32_e32 v150, v137, v139
	s_nop 10
	v_and_or_b32 v37, v37, s43, 60
	v_and_or_b32 v48, v48, s43, 37
	v_and_or_b32 v38, v38, s43, 55
	v_and_or_b32 v42, v42, s43, 47
	v_bitop3_b32 v34, v34, s42, 64 bitop3:0x56
	v_and_or_b32 v47, v47, s43, 38
	v_and_or_b32 v39, v39, s43, 54
	v_and_or_b32 v40, v40, s43, 53
	v_and_or_b32 v43, v43, s43, 46
	v_and_or_b32 v44, v44, s43, 45
	v_and_or_b32 v36, v36, s43, 61
	v_and_or_b32 v49, v49, s43, 36
	v_and_or_b32 v41, v41, s43, 52
	v_and_or_b32 v45, v45, s43, 44
	v_and_or_b32 v35, v35, s43, 62
	v_and_or_b32 v46, v46, s43, 39
	v_max_i32_e32 v128, v37, v48
	v_max_i32_e32 v129, v38, v42
	v_max_i32_e32 v131, v34, v47
	v_max_i32_e32 v151, v39, v40
	v_min_i32_e32 v154, v43, v44
	v_min_i32_e32 v155, v36, v49
	v_min_i32_e32 v157, v41, v45
	v_min_i32_e32 v158, v35, v46
	v_min_i32_e32 v39, v39, v40
	v_min_i32_e32 v34, v34, v47
	v_min_i32_e32 v38, v38, v42
	v_min_i32_e32 v37, v37, v48
	v_max_i32_e32 v35, v35, v46
	v_max_i32_e32 v41, v41, v45
	v_max_i32_e32 v36, v36, v49
	v_max_i32_e32 v43, v43, v44
	v_min_i32_e32 v130, v128, v129
	v_min_i32_e32 v152, v131, v151
	v_max_i32_e32 v156, v154, v155
	v_max_i32_e32 v159, v157, v158
	v_max_i32_e32 v40, v39, v34
	v_max_i32_e32 v42, v38, v37
	v_min_i32_e32 v45, v35, v41
	v_min_i32_e32 v44, v36, v43
	v_min_i32_e32 v157, v157, v158
	v_min_i32_e32 v34, v39, v34
	v_min_i32_e32 v37, v38, v37
	v_min_i32_e32 v38, v154, v155
	v_max_i32_e32 v131, v131, v151
	v_max_i32_e32 v35, v35, v41
	v_max_i32_e32 v36, v36, v43
	v_max_i32_e32 v43, v128, v129
	v_min_i32_e32 v153, v130, v152
	v_min_i32_e32 v160, v156, v159
	v_max_i32_e32 v47, v40, v42
	v_max_i32_e32 v46, v45, v44
	v_min_i32_e32 v40, v40, v42
	v_min_i32_e32 v42, v45, v44
	v_max_i32_e32 v45, v130, v152
	v_max_i32_e32 v130, v156, v159
	v_min_i32_e32 v39, v157, v34
	v_min_i32_e32 v154, v37, v38
	v_max_i32_e32 v34, v157, v34
	v_max_i32_e32 v37, v37, v38
	v_min_i32_e32 v41, v131, v35
	v_min_i32_e32 v128, v36, v43
	v_max_i32_e32 v35, v131, v35
	v_max_i32_e32 v36, v36, v43
	v_min_i32_e32 v48, v47, v46
	v_max_i32_e32 v44, v40, v42
	v_min_i32_e32 v152, v45, v130
	v_min_i32_e32 v40, v40, v42
	v_min_i32_e32 v42, v153, v160
	v_max_i32_e32 v155, v39, v154
	v_min_i32_e32 v38, v34, v37
	v_min_i32_e32 v129, v41, v128
	v_max_i32_e32 v41, v41, v128
	v_min_i32_e32 v43, v35, v36
	v_max_i32_e32 v45, v45, v130
	v_max_i32_e32 v46, v47, v46
	v_max_i32_e32 v161, v153, v160
	v_max_i32_e32 v153, v40, v42
	v_max_i32_e32 v157, v155, v38
	v_max_i32_e32 v34, v34, v37
	v_min_i32_e32 v128, v41, v43
	v_min_i32_e32 v47, v45, v46
	v_min_i32_e32 v49, v161, v48
	v_min_i32_e32 v156, v44, v152
	v_max_i32_e32 v158, v153, v157
	v_min_i32_e32 v37, v129, v34
	v_max_i32_e32 v34, v129, v34
	v_min_i32_e32 v129, v128, v47
	v_max_i32_e32 v48, v161, v48
	v_max_i32_e32 v44, v44, v152
	v_min_i32_e32 v40, v40, v42
	v_min_i32_e32 v38, v155, v38
	v_max_i32_e32 v159, v49, v156
	v_max_i32_e32 v151, v158, v37
	v_min_i32_e32 v130, v34, v129
	v_min_i32_e32 v131, v48, v44
	v_min_i32_e32 v49, v49, v156
	v_min_i32_e32 v37, v158, v37
	v_max_i32_e32 v34, v34, v129
	v_max_i32_e32 v44, v48, v44
	v_max_i32_e32 v42, v40, v38
	v_min_i32_e32 v153, v153, v157
	v_max_i32_e32 v160, v159, v151
	v_min_i32_e32 v152, v130, v131
	v_max_i32_e32 v156, v49, v37
	v_min_i32_e32 v48, v34, v44
	v_max_i32_e32 v129, v130, v131
	v_max_i32_e32 v155, v42, v153
	v_min_i32_e32 v37, v49, v37
	v_min_i32_e32 v151, v159, v151
	v_min_i32_e32 v130, v48, v129
	v_max_i32_e32 v131, v160, v152
	v_min_i32_e32 v49, v155, v37
	v_max_i32_e32 v41, v41, v43
	v_max_i32_e32 v43, v45, v46
	v_min_i32_e32 v42, v42, v153
	v_min_i32_e32 v38, v40, v38
	v_min_i32_e32 v161, v160, v152
	v_max_i32_e32 v158, v151, v156
	v_min_i32_e32 v151, v151, v156
	v_max_i32_e32 v34, v34, v44
	v_max_i32_e32 v44, v128, v47
	v_min_i32_e32 v45, v41, v43
	v_max_i32_e32 v40, v41, v43
	v_max_i32_e32 v38, v143, v38
	v_max3_i32 v41, v82, v146, v42
	v_max_i32_e32 v42, v124, v49
	v_max3_i32 v124, v127, v130, v131
	v_min_i32_e32 v46, v44, v45
	v_max_i32_e32 v43, v125, v151
	v_max3_i32 v49, v126, v161, v158
	v_max3_i32 v44, v149, v44, v45
	v_max_i32_e32 v45, v38, v124
	v_min_i32_e32 v38, v38, v124
	ds_read_b128 v[124:127], v98
	v_min_i32_e32 v159, v161, v158
	v_min_i32_e32 v152, v130, v131
	v_max_i32_e32 v37, v155, v37
	v_max_i32_e32 v48, v48, v129
	v_min_i32_e32 v47, v34, v46
	v_max_i32_e32 v34, v34, v46
	v_min_i32_e32 v39, v39, v154
	v_max3_i32 v39, v144, v145, v39
	v_max3_i32 v37, v147, v134, v37
	v_max3_i32 v46, v132, v133, v159
	v_max3_i32 v82, v135, v140, v152
	v_max3_i32 v48, v136, v138, v48
	v_max_i32_e32 v47, v148, v47
	v_max3_i32 v34, v142, v141, v34
	v_max3_i32 v40, v137, v139, v40
	v_max3_i32 v35, v150, v35, v36
	v_max_i32_e32 v36, v39, v82
	v_min_i32_e32 v39, v39, v82
	v_max_i32_e32 v82, v41, v48
	v_min_i32_e32 v41, v41, v48
	v_max_i32_e32 v48, v42, v47
	v_min_i32_e32 v42, v42, v47
	v_max_i32_e32 v47, v37, v34
	v_min_i32_e32 v34, v37, v34
	v_max_i32_e32 v37, v43, v44
	v_min_i32_e32 v43, v43, v44
	v_max_i32_e32 v44, v46, v40
	v_min_i32_e32 v40, v46, v40
	v_max_i32_e32 v46, v49, v35
	v_min_i32_e32 v35, v49, v35
	v_max_i32_e32 v49, v36, v47
	v_min_i32_e32 v132, v36, v47
	v_max_i32_e32 v36, v45, v37
	v_min_i32_e32 v133, v45, v37
	v_max_i32_e32 v37, v82, v44
	v_min_i32_e32 v82, v82, v44
	v_max_i32_e32 v44, v48, v46
	ds_read_b128 v[128:131], v98 offset:32
	v_min_i32_e32 v134, v48, v46
	v_max_i32_e32 v135, v39, v34
	v_min_i32_e32 v136, v39, v34
	v_max_i32_e32 v137, v38, v43
	v_min_i32_e32 v138, v38, v43
	v_max_i32_e32 v139, v41, v40
	v_min_i32_e32 v140, v41, v40
	v_max_i32_e32 v141, v42, v35
	v_min_i32_e32 v142, v42, v35
	v_max_i32_e32 v143, v49, v37
	v_min_i32_e32 v144, v49, v37
	v_max_i32_e32 v145, v36, v44
	v_min_i32_e32 v146, v36, v44
	s_waitcnt lgkmcnt(1)
; #define LAS __attribute__((address_space(3)))
; #define MFMA32(a, b, c) __builtin_amdgcn_mfma_f32_32x32x16_bf16((a), (b), (c), 0, 0, 0)
; #define CE_(a, b) ce_desc(v[a], v[b])
; __device__ __forceinline__ void sort16_desc(int (&v)[16]) {
;     ...
;     CE_(0,13); CE_(1,12); CE_(2,15); CE_(3,14); CE_(4,8); CE_(5,6); CE_(7,11); CE_(9,10);
;     CE_(0,5); CE_(1,7); CE_(2,9); CE_(3,4); CE_(6,13); CE_(8,14); CE_(10,15); CE_(11,12);
;     CE_(0,1); CE_(2,3); CE_(4,5); CE_(6,8); CE_(7,9); CE_(10,11); CE_(12,13); CE_(14,15);
;     CE_(0,2); CE_(1,3); CE_(4,10); CE_(5,11); CE_(6,7); CE_(8,9); CE_(12,14); CE_(13,15);
;     CE_(1,2); CE_(3,12); CE_(4,6); CE_(5,7); CE_(8,10); CE_(9,11); CE_(13,14);
;     CE_(1,4); CE_(2,6); CE_(5,8); CE_(7,10); CE_(9,13); CE_(11,14);
;     CE_(2,4); CE_(3,6); CE_(9,12); CE_(11,13);
;     CE_(3,5); CE_(6,8); CE_(7,9); CE_(10,12);
;     CE_(3,4); CE_(5,6); CE_(7,8); CE_(9,10); CE_(11,12);
;     CE_(6,7); CE_(8,9);
;     ...
; }
; __device__ __forceinline__ void merge16_desc(int (&a)[16], const int (&b)[16]) {
; #pragma unroll
;     for (int i = 0; i < 16; ++i) a[i] = a[i] > b[15 - i] ? a[i] : b[15 - i];
; #pragma unroll
;     for (int j = 8; j > 0; j >>= 1)
; #pragma unroll
;         for (int i = 0; i < 16; ++i) { const int l = i ^ j; if (l > i) ce_desc(a[i], a[l]); }
; }
; __device__ __forceinline__ void route_task(int task, int tl0, const bf16* QP  , const LAS bf16* KHL, LAS unsigned short* EL, LAS float* GL, int lane) {
;     ...
;         for (int kt = 0; kt < 4; ++kt) {
;             f32x16 X;
; #pragma unroll
;             for (int i = 0; i < 16; ++i) X[i] = 8.f;
;             const LAS bf16* khp = KHL + (half * 128 + 32 * kt + r) * 72 + 8 * hi;
; #pragma unroll
;             for (int ks = 0; ks < 4; ++ks) {
;                 const bf16x8 kh = lds8(khp + 16 * ks);
;                 X = MFMA32(kh, qa[half][ks], X);
;             }
;             int grp[16];
; #pragma unroll
;             for (int i = 0; i < 16; ++i) grp[i] = (int)((__float_as_uint(X[i]) | 127u) - (unsigned)(32 * kt + (i & 3) + 8 * (i >> 2)));
;             sort16_desc(grp);
;             if (kt == 0) {
; #pragma unroll
;                 for (int i = 0; i < 16; ++i) cur[i] = grp[i];
;             } else merge16_desc(cur, grp);
	v_mfma_f32_32x32x16_bf16 v[34:49], v[124:127], v[62:65], v[18:33]
	v_max_i32_e32 v147, v132, v82
	s_nop 5
	ds_read_b128 v[18:21], v98 offset:64
	ds_read_b128 v[22:25], v98 offset:96
	s_waitcnt lgkmcnt(2)
	v_mfma_f32_32x32x16_bf16 v[34:49], v[128:131], v[58:61], v[34:49]
	v_min_i32_e32 v26, v132, v82
	v_max_i32_e32 v27, v133, v134
	v_min_i32_e32 v30, v135, v139
	v_min_i32_e32 v32, v137, v141
	v_max_i32_e32 v33, v136, v140
	v_max_i32_e32 v59, v138, v142
	v_min_i32_e32 v28, v133, v134
	s_waitcnt lgkmcnt(1)
	v_mfma_f32_32x32x16_bf16 v[34:49], v[18:21], v[54:57], v[34:49]
	v_min_i32_e32 v19, v147, v27
	v_min_i32_e32 v54, v30, v32
	v_min_i32_e32 v55, v33, v59
	v_max_i32_e32 v29, v135, v139
	v_max_i32_e32 v31, v137, v141
	v_min_i32_e32 v58, v136, v140
	v_min_i32_e32 v60, v138, v142
	s_waitcnt lgkmcnt(0)
	v_mfma_f32_32x32x16_bf16 v[34:49], v[22:25], v[50:53], v[34:49]
	v_min_i32_e32 v18, v144, v146
	v_min_i32_e32 v61, v143, v145
	v_min_i32_e32 v20, v26, v28
	v_min_i32_e32 v21, v29, v31
	v_min_i32_e32 v56, v58, v60
	s_nop 6
	v_or_b32_e32 v22, 0x7f, v41
	v_or_b32_e32 v23, 0x7f, v45
	v_or_b32_e32 v25, 0x7f, v35
	v_or_b32_e32 v35, 0x7f, v46
	v_and_or_b32 v39, v39, s43, 22
	v_and_or_b32 v40, v40, s43, 21
	v_and_or_b32 v34, v34, s43, 31
	v_and_or_b32 v47, v47, s43, 6
	v_and_or_b32 v38, v38, s43, 23
	v_and_or_b32 v42, v42, s43, 15
	v_and_or_b32 v37, v37, s43, 28
	v_and_or_b32 v48, v48, s43, 5
	v_and_or_b32 v43, v43, s43, 14
	v_and_or_b32 v44, v44, s43, 13
	v_and_or_b32 v36, v36, s43, 29
	v_and_or_b32 v49, v49, s43, 4
	v_add_u32_e32 v22, 0xffffff95, v22
	v_add_u32_e32 v23, 0xffffff8d, v23
	v_add_u32_e32 v25, 0xffffff9f, v25
	v_add_u32_e32 v35, 0xffffff88, v35
	v_min_i32_e32 v24, v22, v23
	v_min_i32_e32 v41, v25, v35
	v_min_i32_e32 v46, v39, v40
	v_min_i32_e32 v50, v34, v47
	v_min_i32_e32 v53, v38, v42
	v_min_i32_e32 v57, v37, v48
	v_min_i32_e32 v63, v43, v44
	v_min_i32_e32 v64, v36, v49
	v_max_i32_e32 v34, v34, v47
	v_max_i32_e32 v39, v39, v40
	v_max_i32_e32 v25, v25, v35
	v_max_i32_e32 v22, v22, v23
	v_max_i32_e32 v36, v36, v49
	v_max_i32_e32 v43, v43, v44
	v_max_i32_e32 v37, v37, v48
	v_max_i32_e32 v38, v38, v42
	v_min_i32_e32 v45, v24, v41
	v_min_i32_e32 v51, v46, v50
	v_max_i32_e32 v40, v34, v39
	v_max_i32_e32 v23, v25, v22
	v_max_i32_e32 v44, v36, v43
	v_max_i32_e32 v42, v37, v38
	v_min_i32_e32 v37, v37, v38
	v_min_i32_e32 v34, v34, v39
	v_max_i32_e32 v39, v63, v64
	v_max_i32_e32 v24, v24, v41
	v_max_i32_e32 v46, v46, v50
	v_max_i32_e32 v50, v53, v57
	v_min_i32_e32 v22, v25, v22
	v_min_i32_e32 v25, v36, v43
	v_min_i32_e32 v62, v53, v57
	v_min_i32_e32 v65, v63, v64
	v_min_i32_e32 v35, v40, v23
	v_min_i32_e32 v47, v44, v42
	v_max_i32_e32 v23, v40, v23
	v_max_i32_e32 v40, v44, v42
	v_max_i32_e32 v38, v37, v34
	v_max_i32_e32 v41, v39, v24
	v_max_i32_e32 v53, v46, v50
	v_max_i32_e32 v36, v22, v25
	v_min_i32_e32 v46, v46, v50
	v_min_i32_e32 v22, v22, v25
	v_min_i32_e32 v52, v45, v51
	v_min_i32_e32 v82, v62, v65
	v_min_i32_e32 v48, v35, v47
	v_max_i32_e32 v45, v45, v51
	v_max_i32_e32 v49, v62, v65
	v_max_i32_e32 v35, v35, v47
	v_min_i32_e32 v42, v23, v40
	v_max_i32_e32 v47, v38, v41
	v_max_i32_e32 v43, v53, v36
	v_min_i32_e32 v34, v37, v34
	v_min_i32_e32 v24, v39, v24
	v_max_i32_e32 v25, v46, v22
	v_min_i32_e32 v38, v38, v41
	v_max_i32_e32 v51, v45, v49
	v_min_i32_e32 v44, v35, v42
	v_min_i32_e32 v57, v47, v43
	v_max_i32_e32 v37, v34, v24
	v_min_i32_e32 v36, v53, v36
	v_max_i32_e32 v41, v25, v38
	v_min_i32_e32 v25, v25, v38
	v_min_i32_e32 v22, v46, v22
	v_min_i32_e32 v24, v34, v24
	v_max_i32_e32 v38, v52, v82
	v_min_i32_e32 v45, v45, v49
	v_max_i32_e32 v62, v48, v51
	v_min_i32_e32 v63, v44, v57
	v_max_i32_e32 v39, v37, v36
	v_max_i32_e32 v34, v22, v24
	v_max_i32_e32 v46, v38, v45
	v_max_i32_e32 v64, v62, v63
	v_max_i32_e32 v50, v39, v41
	v_min_i32_e32 v62, v62, v63
	v_min_i32_e32 v39, v39, v41
	v_min_i32_e32 v36, v37, v36
	v_max_i32_e32 v49, v34, v46
	v_min_i32_e32 v48, v48, v51
	v_min_i32_e32 v22, v22, v24
	v_min_i32_e32 v24, v38, v45
	v_min_i32_e32 v53, v64, v50
	v_max_i32_e32 v41, v62, v39
	v_max_i32_e32 v37, v36, v25
	v_max_i32_e32 v51, v49, v48
	v_max_i32_e32 v38, v22, v24
	v_min_i32_e32 v34, v34, v46
	v_min_i32_e32 v25, v36, v25
	v_min_i32_e32 v36, v49, v48
	v_min_i32_e32 v124, v52, v82
	v_max_i32_e32 v52, v37, v51
	v_min_i32_e32 v39, v62, v39
	v_max_i32_e32 v45, v38, v34
	v_min_i32_e32 v46, v25, v36
	v_max_i32_e32 v35, v35, v42
	v_max_i32_e32 v42, v47, v43
	v_min_i32_e32 v34, v38, v34
	v_max_i32_e32 v38, v53, v41
	v_min_i32_e32 v37, v37, v51
	v_max_i32_e32 v25, v25, v36
	v_max_i32_e32 v48, v45, v46
	v_max_i32_e32 v44, v44, v57
	v_min_i32_e32 v43, v35, v42
	v_max3_i32 v30, v30, v32, v38
	v_min_i32_e32 v38, v52, v39
	v_max_i32_e32 v36, v37, v25
	v_min_i32_e32 v25, v37, v25
	v_min_i32_e32 v63, v53, v41
	v_max_i32_e32 v62, v52, v39
	v_max3_i32 v27, v147, v27, v48
	v_max_i32_e32 v48, v64, v50
	v_min_i32_e32 v47, v44, v43
	v_min_i32_e32 v39, v38, v36
	v_max_i32_e32 v19, v19, v25
	v_max3_i32 v25, v55, v44, v43
	v_min_i32_e32 v43, v45, v46
	v_min_i32_e32 v65, v63, v62
	v_max_i32_e32 v49, v48, v47
	v_max3_i32 v26, v26, v28, v39
	v_max_i32_e32 v28, v35, v42
	v_min_i32_e32 v22, v22, v24
	v_max_i32_e32 v18, v18, v43
	v_min_i32_e32 v43, v48, v47
	v_max3_i32 v124, v143, v145, v124
	v_max3_i32 v29, v29, v31, v65
	v_max3_i32 v33, v33, v59, v49
	v_max3_i32 v34, v144, v146, v34
	v_max3_i32 v28, v58, v60, v28
	v_max_i32_e32 v22, v61, v22
	v_max3_i32 v21, v21, v63, v62
	v_max_i32_e32 v43, v54, v43
	v_max3_i32 v20, v20, v38, v36
	v_max3_i32 v23, v56, v23, v40
	v_min_i32_e32 v31, v124, v29
	v_min_i32_e32 v49, v27, v33
	v_min_i32_e32 v32, v34, v30
	v_min_i32_e32 v35, v26, v28
; __device__ __forceinline__ void route_task(int task, int tl0, const bf16* QP  , const LAS bf16* KHL, LAS unsigned short* EL, LAS float* GL, int lane) {
;     ...
;         { const unsigned h4 = 4u * (unsigned)hi;
; #pragma unroll
;           for (int i = 0; i < 16; ++i) cur[i] -= (int)h4; }
;         int oth[16];
; #pragma unroll
;         for (int i = 0; i < 16; ++i) oth[i] = __shfl_xor(cur[i], 32);
;         merge16_desc(cur, oth);
; #pragma unroll
;         for (int i = 0; i < 16; ++i) top[half][i] = cur[i];
;     }
;     unsigned P1[4], P2[4];
; #pragma unroll
;     for (int q = 0; q < 4; ++q) { P1[q] = 0u; P2[q] = 0u;
; #pragma unroll
;         for (int s = 0; s < 4; ++s) { P1[q] |= (127u - ((unsigned)top[0][4 * q + s] & 127u)) << (8 * s); P2[q] |= (127u - ((unsigned)top[1][4 * q + s] & 127u)) << (8 * s); } }
	v_min_i32_e32 v24, v22, v21
	v_min_i32_e32 v37, v19, v25
	v_min_i32_e32 v44, v18, v43
	v_min_i32_e32 v36, v20, v23
	v_max_i32_e32 v29, v124, v29
	v_max_i32_e32 v27, v27, v33
	v_max_i32_e32 v30, v34, v30
	v_max_i32_e32 v26, v26, v28
	v_max_i32_e32 v21, v22, v21
	v_max_i32_e32 v19, v19, v25
	v_max_i32_e32 v18, v18, v43
	v_max_i32_e32 v20, v20, v23
	v_max_i32_e32 v33, v29, v27
	v_max_i32_e32 v28, v30, v26
	v_max_i32_e32 v22, v21, v19
	v_max_i32_e32 v23, v18, v20
	v_max_i32_e32 v34, v33, v28
	v_max_i32_e32 v25, v22, v23
	v_min_i32_e32 v28, v33, v28
	v_min_i32_e32 v22, v22, v23
	v_min_i32_e32 v27, v29, v27
	v_min_i32_e32 v26, v30, v26
	v_min_i32_e32 v19, v21, v19
	v_min_i32_e32 v18, v18, v20
	v_max_i32_e32 v23, v28, v22
	v_min_i32_e32 v22, v28, v22
	v_max_i32_e32 v28, v27, v26
	v_max_i32_e32 v20, v19, v18
	v_min_i32_e32 v26, v27, v26
	v_min_i32_e32 v18, v19, v18
	v_min_i32_e32 v42, v24, v37
	v_max_i32_e32 v19, v26, v18
	v_min_i32_e32 v18, v26, v18
	v_max_i32_e32 v26, v31, v49
	v_max_i32_e32 v27, v32, v35
	v_max_i32_e32 v24, v24, v37
	v_max_i32_e32 v29, v44, v36
	v_min_i32_e32 v50, v31, v49
	v_min_i32_e32 v39, v32, v35
	v_min_i32_e32 v38, v44, v36
	v_max_i32_e32 v21, v28, v20
	v_min_i32_e32 v20, v28, v20
	v_max_i32_e32 v28, v26, v27
	v_max_i32_e32 v30, v24, v29
	v_min_i32_e32 v26, v26, v27
	v_min_i32_e32 v24, v24, v29
	v_min_i32_e32 v41, v50, v39
	v_min_i32_e32 v40, v42, v38
	v_max_i32_e32 v27, v26, v24
	v_min_i32_e32 v24, v26, v24
	v_max_i32_e32 v26, v50, v39
	v_max_i32_e32 v29, v42, v38
	v_min_i32_e32 v45, v41, v40
	v_max_i32_e32 v43, v34, v25
	v_min_i32_e32 v25, v34, v25
	v_max_i32_e32 v31, v28, v30
	v_min_i32_e32 v28, v28, v30
	v_max_i32_e32 v30, v26, v29
	v_min_i32_e32 v26, v26, v29
	v_max_i32_e32 v29, v41, v40
	v_sub_u32_e32 v32, v43, v87
	v_sub_u32_e32 v25, v25, v87
	v_sub_u32_e32 v23, v23, v87
	v_sub_u32_e32 v22, v22, v87
	v_sub_u32_e32 v21, v21, v87
	v_sub_u32_e32 v20, v20, v87
	v_sub_u32_e32 v19, v19, v87
	v_sub_u32_e32 v18, v18, v87
	v_sub_u32_e32 v31, v31, v87
	v_sub_u32_e32 v28, v28, v87
	v_sub_u32_e32 v27, v27, v87
	v_sub_u32_e32 v24, v24, v87
	v_sub_u32_e32 v30, v30, v87
	v_sub_u32_e32 v26, v26, v87
	v_sub_u32_e32 v29, v29, v87
	v_sub_u32_e32 v33, v45, v87
	ds_bpermute_b32 v34, v123, v32
	ds_bpermute_b32 v35, v123, v25
	ds_bpermute_b32 v36, v123, v23
	ds_bpermute_b32 v37, v123, v22
	ds_bpermute_b32 v38, v123, v21
	ds_bpermute_b32 v39, v123, v20
	ds_bpermute_b32 v40, v123, v19
	ds_bpermute_b32 v41, v123, v18
	ds_bpermute_b32 v42, v123, v31
	ds_bpermute_b32 v43, v123, v28
	ds_bpermute_b32 v44, v123, v27
	ds_bpermute_b32 v45, v123, v33
	ds_bpermute_b32 v46, v123, v29
	ds_bpermute_b32 v47, v123, v26
	ds_bpermute_b32 v48, v123, v30
	ds_bpermute_b32 v49, v123, v24
	s_waitcnt lgkmcnt(4)
	v_max_i32_e32 v32, v32, v45
	s_waitcnt lgkmcnt(3)
	v_max_i32_e32 v25, v25, v46
	s_waitcnt lgkmcnt(2)
	v_max_i32_e32 v23, v23, v47
	s_waitcnt lgkmcnt(1)
	v_max_i32_e32 v22, v22, v48
	s_waitcnt lgkmcnt(0)
	v_max_i32_e32 v21, v21, v49
	v_max_i32_e32 v20, v20, v44
	v_max_i32_e32 v19, v19, v43
	v_max_i32_e32 v18, v18, v42
	v_max_i32_e32 v31, v31, v41
	v_max_i32_e32 v28, v28, v40
	v_max_i32_e32 v27, v27, v39
	v_max_i32_e32 v24, v24, v38
	v_max_i32_e32 v30, v30, v37
	v_max_i32_e32 v26, v26, v36
	v_max_i32_e32 v29, v29, v35
	v_max_i32_e32 v33, v33, v34
	v_max_i32_e32 v34, v32, v31
	v_min_i32_e32 v31, v32, v31
	v_max_i32_e32 v32, v25, v28
	v_min_i32_e32 v25, v25, v28
	v_max_i32_e32 v28, v23, v27
	v_min_i32_e32 v23, v23, v27
	v_max_i32_e32 v27, v22, v24
	v_min_i32_e32 v22, v22, v24
	v_max_i32_e32 v24, v21, v30
	v_min_i32_e32 v21, v21, v30
	v_max_i32_e32 v30, v20, v26
	v_min_i32_e32 v20, v20, v26
	v_max_i32_e32 v26, v19, v29
	v_min_i32_e32 v19, v19, v29
	v_max_i32_e32 v29, v18, v33
	v_min_i32_e32 v18, v18, v33
	v_max_i32_e32 v33, v34, v24
	v_min_i32_e32 v24, v34, v24
	v_max_i32_e32 v34, v32, v30
	v_min_i32_e32 v30, v32, v30
	v_max_i32_e32 v32, v28, v26
	v_min_i32_e32 v26, v28, v26
	v_max_i32_e32 v28, v27, v29
	v_min_i32_e32 v27, v27, v29
	v_max_i32_e32 v29, v31, v21
	v_min_i32_e32 v21, v31, v21
	v_max_i32_e32 v31, v25, v20
	v_min_i32_e32 v20, v25, v20
	v_max_i32_e32 v25, v23, v19
	v_min_i32_e32 v19, v23, v19
	v_max_i32_e32 v23, v22, v18
	v_min_i32_e32 v18, v22, v18
	v_max_i32_e32 v22, v33, v32
	v_min_i32_e32 v32, v33, v32
	v_max_i32_e32 v33, v34, v28
	v_min_i32_e32 v28, v34, v28
	v_max_i32_e32 v34, v24, v26
	v_min_i32_e32 v24, v24, v26
	v_max_i32_e32 v35, v30, v27
	v_min_i32_e32 v27, v30, v27
	v_max_i32_e32 v30, v29, v25
	v_min_i32_e32 v25, v29, v25
	v_max_i32_e32 v29, v31, v23
	v_min_i32_e32 v23, v31, v23
	v_max_i32_e32 v31, v21, v19
	v_min_i32_e32 v19, v21, v19
	v_max_i32_e32 v21, v20, v18
	v_min_i32_e32 v18, v20, v18
	v_max_i32_e32 v26, v22, v33
	v_min_i32_e32 v33, v22, v33
	v_lshlrev_b32_e32 v20, 8, v81
	v_lshlrev_b32_e32 v22, 16, v80
	v_max_i32_e32 v36, v32, v28
	v_max_i32_e32 v40, v19, v18
	v_min_i32_e32 v41, v19, v18
	v_and_b32_e32 v18, 0x7f, v79
	v_and_b32_e32 v20, 0x7f00, v20
	v_and_b32_e32 v22, 0x7f0000, v22
	v_max_i32_e32 v39, v31, v21
	v_min_i32_e32 v31, v31, v21
	v_lshlrev_b32_e32 v21, 8, v33
	v_or3_b32 v18, v20, v18, v22
	v_lshlrev_b32_e32 v20, 16, v36
	v_and_b32_e32 v19, 0x7f, v26
	v_and_b32_e32 v21, 0x7f00, v21
	v_and_b32_e32 v20, 0x7f0000, v20
	v_or3_b32 v20, v21, v19, v20
	v_lshlrev_b32_e32 v19, 24, v78
	v_min_i32_e32 v28, v32, v28
	v_and_b32_e32 v19, 0x7f000000, v19
	v_bitop3_b32 v19, v18, s68, v19 bitop3:0x36
	v_lshlrev_b32_e32 v18, 24, v28
	v_max_i32_e32 v32, v34, v35
	v_min_i32_e32 v34, v34, v35
	v_max_i32_e32 v35, v24, v27
	v_min_i32_e32 v27, v24, v27
	v_and_b32_e32 v18, 0x7f000000, v18
	v_lshlrev_b32_e32 v22, 8, v76
	v_lshlrev_b32_e32 v24, 16, v75
; __device__ __forceinline__ void route_task(int task, int tl0, const bf16* QP  , const LAS bf16* KHL, LAS unsigned short* EL, LAS float* GL, int lane) {
;     ...
;     unsigned P1[4], P2[4];
; #pragma unroll
;     for (int q = 0; q < 4; ++q) { P1[q] = 0u; P2[q] = 0u;
; #pragma unroll
;         for (int s = 0; s < 4; ++s) { P1[q] |= (127u - ((unsigned)top[0][4 * q + s] & 127u)) << (8 * s); P2[q] |= (127u - ((unsigned)top[1][4 * q + s] & 127u)) << (8 * s); } }
;     int bk[16];
;     {
;         int hi2 = hi; asm volatile("" : "+v"(hi2));
;         const bool h1 = hi2 != 0;
;         constexpr int A1[16] = {1, 1, 1, 1, 1, 1, 1, 1, 2, 2, 2, 2, 2, 3, 3, 3}, B1[16] = {0, 1, 2, 3, 4, 5, 6, 7, 0, 1, 2, 3, 4, 0, 1, 2};
; #pragma unroll
;         for (int i = 0; i < 16; ++i) { const float ta = __int_as_float(h1 ? top[0][A1[i]] : top[0][0]), tb = __int_as_float(h1 ? top[1][B1[i]] : top[1][i]); const unsigned code = h1 ? (unsigned)(A1[i] * 16 + B1[i]) : (unsigned)i;
;             bk[i] = (int)((__float_as_uint(ta + tb) | 255u) - code); }
;         sort16_desc(bk);
	v_bitop3_b32 v18, v20, s68, v18 bitop3:0x36
	v_and_b32_e32 v20, 0x7f, v77
	v_and_b32_e32 v22, 0x7f00, v22
	v_and_b32_e32 v24, 0x7f0000, v24
	v_max_i32_e32 v37, v30, v29
	v_min_i32_e32 v29, v30, v29
	v_max_i32_e32 v30, v25, v23
	v_min_i32_e32 v38, v25, v23
	v_lshlrev_b32_e32 v23, 8, v34
	v_or3_b32 v20, v22, v20, v24
	v_lshlrev_b32_e32 v22, 16, v35
	v_and_b32_e32 v21, 0x7f, v32
	v_and_b32_e32 v23, 0x7f00, v23
	v_and_b32_e32 v22, 0x7f0000, v22
	v_or3_b32 v22, v23, v21, v22
	v_lshlrev_b32_e32 v21, 24, v73
	v_and_b32_e32 v21, 0x7f000000, v21
	v_bitop3_b32 v21, v20, s68, v21 bitop3:0x36
	v_lshlrev_b32_e32 v20, 24, v27
	v_and_b32_e32 v20, 0x7f000000, v20
	v_lshlrev_b32_e32 v24, 8, v74
	v_lshlrev_b32_e32 v42, 16, v72
	v_bitop3_b32 v20, v22, s68, v20 bitop3:0x36
	v_and_b32_e32 v22, 0x7f, v71
	v_and_b32_e32 v24, 0x7f00, v24
	v_and_b32_e32 v42, 0x7f0000, v42
	v_lshlrev_b32_e32 v25, 8, v29
	v_or3_b32 v22, v24, v22, v42
	v_lshlrev_b32_e32 v24, 16, v30
	v_and_b32_e32 v23, 0x7f, v37
	v_and_b32_e32 v25, 0x7f00, v25
	v_and_b32_e32 v24, 0x7f0000, v24
	v_or3_b32 v24, v25, v23, v24
	v_lshlrev_b32_e32 v23, 24, v70
	v_and_b32_e32 v23, 0x7f000000, v23
	v_bitop3_b32 v23, v22, s68, v23 bitop3:0x36
	v_lshlrev_b32_e32 v22, 24, v38
	v_and_b32_e32 v22, 0x7f000000, v22
	v_lshlrev_b32_e32 v42, 8, v68
	v_lshlrev_b32_e32 v44, 16, v67
	v_bitop3_b32 v22, v24, s68, v22 bitop3:0x36
	v_and_b32_e32 v24, 0x7f, v69
	v_and_b32_e32 v42, 0x7f00, v42
	v_and_b32_e32 v44, 0x7f0000, v44
	v_lshlrev_b32_e32 v43, 8, v31
	v_or3_b32 v24, v42, v24, v44
	v_lshlrev_b32_e32 v42, 16, v40
	v_and_b32_e32 v25, 0x7f, v39
	v_and_b32_e32 v43, 0x7f00, v43
	v_and_b32_e32 v42, 0x7f0000, v42
	v_or3_b32 v42, v43, v25, v42
	v_lshlrev_b32_e32 v25, 24, v66
	v_and_b32_e32 v25, 0x7f000000, v25
	v_bitop3_b32 v25, v24, s68, v25 bitop3:0x36
	v_lshlrev_b32_e32 v24, 24, v41
	v_and_b32_e32 v24, 0x7f000000, v24
	v_bitop3_b32 v24, v42, s68, v24 bitop3:0x36
	v_mov_b32_e32 v42, v86
	v_add_f32_e32 v62, v74, v26
	v_cmp_eq_u32_e32 vcc, 0, v42
	v_add_f32_e32 v63, v72, v26
	v_add_f32_e32 v64, v70, v26
	v_cndmask_b32_e32 v42, v81, v79, vcc
	v_add_f32_e32 v44, v42, v26
	v_cndmask_b32_e64 v43, -16, 0, vcc
	v_or_b32_e32 v44, 0xff, v44
	v_add_f32_e32 v45, v42, v33
	v_add_u32_e32 v43, v44, v43
	v_cndmask_b32_e64 v44, v99, -1, vcc
	v_or_b32_e32 v45, 0xff, v45
	v_add_f32_e32 v46, v42, v36
	v_add_u32_e32 v44, v45, v44
	v_cndmask_b32_e64 v45, v100, -2, vcc
	v_or_b32_e32 v46, 0xff, v46
	v_add_f32_e32 v47, v42, v28
	v_add_u32_e32 v45, v46, v45
	v_cndmask_b32_e64 v46, v101, -3, vcc
	v_or_b32_e32 v47, 0xff, v47
	v_add_f32_e32 v48, v42, v32
	v_add_u32_e32 v46, v47, v46
	v_cndmask_b32_e64 v47, v102, -4, vcc
	v_or_b32_e32 v48, 0xff, v48
	v_add_f32_e32 v34, v42, v34
	v_add_f32_e32 v35, v42, v35
	v_add_f32_e32 v27, v42, v27
	v_cndmask_b32_e32 v42, v80, v79, vcc
	v_cndmask_b32_e32 v32, v32, v39, vcc
	v_add_u32_e32 v47, v48, v47
	v_cndmask_b32_e64 v48, v103, -5, vcc
	v_or_b32_e32 v34, 0xff, v34
	v_add_f32_e32 v32, v42, v32
	v_add_u32_e32 v34, v34, v48
	v_cndmask_b32_e64 v48, v104, -6, vcc
	v_or_b32_e32 v35, 0xff, v35
	v_cndmask_b32_e32 v37, v26, v37, vcc
	v_cndmask_b32_e64 v39, v116, -12, vcc
	v_or_b32_e32 v32, 0xff, v32
	v_add_u32_e32 v35, v35, v48
	v_cndmask_b32_e64 v48, v105, -7, vcc
	v_or_b32_e32 v27, 0xff, v27
	v_add_f32_e32 v37, v42, v37
	v_cndmask_b32_e32 v29, v33, v29, vcc
	v_add_u32_e32 v32, v32, v39
	v_cndmask_b32_e32 v39, v78, v79, vcc
	v_cndmask_b32_e32 v31, v26, v31, vcc
	v_add_u32_e32 v27, v27, v48
	v_cndmask_b32_e64 v48, v106, -8, vcc
	v_or_b32_e32 v37, 0xff, v37
	v_add_f32_e32 v29, v42, v29
	v_cndmask_b32_e32 v30, v36, v30, vcc
	v_cndmask_b32_e32 v38, v28, v38, vcc
	v_add_f32_e32 v31, v39, v31
	v_cndmask_b32_e32 v40, v33, v40, vcc
	v_add_u32_e32 v37, v37, v48
	v_cndmask_b32_e64 v48, v107, -9, vcc
	v_or_b32_e32 v29, 0xff, v29
	v_add_f32_e32 v30, v42, v30
	v_add_f32_e32 v38, v42, v38
	v_cndmask_b32_e64 v42, v117, -13, vcc
	v_or_b32_e32 v31, 0xff, v31
	v_add_f32_e32 v40, v39, v40
	v_cndmask_b32_e32 v41, v36, v41, vcc
	v_add_u32_e32 v29, v29, v48
	v_cndmask_b32_e64 v48, v114, -10, vcc
	v_or_b32_e32 v30, 0xff, v30
	v_add_u32_e32 v31, v31, v42
	v_cndmask_b32_e64 v42, v118, -14, vcc
	v_or_b32_e32 v40, 0xff, v40
	v_add_f32_e32 v39, v39, v41
	v_add_u32_e32 v30, v30, v48
	v_cndmask_b32_e64 v48, v115, -11, vcc
	v_or_b32_e32 v38, 0xff, v38
	v_add_u32_e32 v40, v40, v42
	v_cndmask_b32_e64 v42, v119, -15, vcc
	v_or_b32_e32 v39, 0xff, v39
	v_add_u32_e32 v38, v38, v48
	v_add_u32_e32 v39, v39, v42
	v_max_i32_e32 v41, v43, v31
	v_min_i32_e32 v31, v43, v31
	v_max_i32_e32 v42, v44, v32
	v_min_i32_e32 v32, v44, v32
	v_max_i32_e32 v43, v45, v39
	v_min_i32_e32 v39, v45, v39
	v_max_i32_e32 v44, v46, v40
	v_min_i32_e32 v40, v46, v40
	v_max_i32_e32 v45, v47, v37
	v_min_i32_e32 v37, v47, v37
	v_max_i32_e32 v46, v34, v35
	v_min_i32_e32 v34, v34, v35
	v_max_i32_e32 v35, v27, v38
	v_min_i32_e32 v27, v27, v38
	v_max_i32_e32 v38, v29, v30
	v_min_i32_e32 v29, v29, v30
	v_max_i32_e32 v30, v41, v46
	v_min_i32_e32 v41, v41, v46
	v_max_i32_e32 v46, v42, v35
	v_min_i32_e32 v35, v42, v35
	v_max_i32_e32 v42, v43, v38
	v_min_i32_e32 v38, v43, v38
	v_max_i32_e32 v43, v44, v45
	v_min_i32_e32 v44, v44, v45
	v_max_i32_e32 v45, v34, v31
	v_min_i32_e32 v31, v34, v31
	v_max_i32_e32 v34, v37, v40
	v_min_i32_e32 v37, v37, v40
	v_max_i32_e32 v40, v29, v39
	v_min_i32_e32 v29, v29, v39
	v_max_i32_e32 v39, v27, v32
	v_min_i32_e32 v27, v27, v32
	v_max_i32_e32 v32, v30, v46
	v_min_i32_e32 v30, v30, v46
	v_max_i32_e32 v46, v42, v43
	v_min_i32_e32 v42, v42, v43
	v_max_i32_e32 v43, v44, v41
	v_min_i32_e32 v41, v44, v41
	v_max_i32_e32 v44, v45, v34
	v_min_i32_e32 v34, v45, v34
; #define CE_(a, b) ce_desc(v[a], v[b])
; #define CAND(a, b) (int)((__float_as_uint(__int_as_float(top[0][a]) + __int_as_float(top[1][b])) | 255u) - (unsigned)((a) * 16 + (b)))
; __device__ __forceinline__ void sort16_desc(int (&v)[16]) {
;     ...
;     CE_(0,13); CE_(1,12); CE_(2,15); CE_(3,14); CE_(4,8); CE_(5,6); CE_(7,11); CE_(9,10);
;     CE_(0,5); CE_(1,7); CE_(2,9); CE_(3,4); CE_(6,13); CE_(8,14); CE_(10,15); CE_(11,12);
;     CE_(0,1); CE_(2,3); CE_(4,5); CE_(6,8); CE_(7,9); CE_(10,11); CE_(12,13); CE_(14,15);
;     CE_(0,2); CE_(1,3); CE_(4,10); CE_(5,11); CE_(6,7); CE_(8,9); CE_(12,14); CE_(13,15);
;     CE_(1,2); CE_(3,12); CE_(4,6); CE_(5,7); CE_(8,10); CE_(9,11); CE_(13,14);
;     CE_(1,4); CE_(2,6); CE_(5,8); CE_(7,10); CE_(9,13); CE_(11,14);
;     CE_(2,4); CE_(3,6); CE_(9,12); CE_(11,13);
;     CE_(3,5); CE_(6,8); CE_(7,9); CE_(10,12);
;     CE_(3,4); CE_(5,6); CE_(7,8); CE_(9,10); CE_(11,12);
;     CE_(6,7); CE_(8,9);
;     ...
; }
; __device__ __forceinline__ void route_task(int task, int tl0, const bf16* QP  , const LAS bf16* KHL, LAS unsigned short* EL, LAS float* GL, int lane) {
;     ...
;         sort16_desc(bk);
;         int oth[16];
; #pragma unroll
;         for (int i = 0; i < 16; ++i) oth[i] = __shfl_xor(bk[i], 32);
;         merge16_desc(bk, oth);
;     }
;     ...
;     {
;         int gk[16];
;         gk[0] = CAND(3, 3); gk[1] = CAND(4, 0); gk[2] = CAND(4, 1); gk[3] = CAND(4, 2); gk[4] = CAND(5, 0); gk[5] = CAND(5, 1); gk[6] = CAND(6, 0); gk[7] = CAND(6, 1);
;         gk[8] = CAND(7, 0); gk[9] = CAND(7, 1); gk[10] = CAND(8, 0); gk[11] = CAND(9, 0); gk[12] = CAND(10, 0); gk[13] = CAND(11, 0); gk[14] = CAND(12, 0); gk[15] = CAND(13, 0);
;         sort16_desc(gk);
	v_max_i32_e32 v45, v35, v38
	v_min_i32_e32 v35, v35, v38
	v_max_i32_e32 v38, v40, v39
	v_min_i32_e32 v39, v40, v39
	v_max_i32_e32 v40, v27, v31
	v_min_i32_e32 v27, v27, v31
	v_max_i32_e32 v31, v37, v29
	v_min_i32_e32 v29, v37, v29
	v_max_i32_e32 v37, v32, v46
	v_min_i32_e32 v32, v32, v46
	v_max_i32_e32 v46, v30, v42
	v_min_i32_e32 v30, v30, v42
	v_max_i32_e32 v42, v43, v38
	v_min_i32_e32 v38, v43, v38
	v_max_i32_e32 v43, v41, v39
	v_min_i32_e32 v39, v41, v39
	v_max_i32_e32 v41, v44, v45
	v_min_i32_e32 v44, v44, v45
	v_max_i32_e32 v45, v34, v35
	v_min_i32_e32 v34, v34, v35
	v_max_i32_e32 v35, v40, v31
	v_min_i32_e32 v31, v40, v31
	v_max_i32_e32 v40, v27, v29
	v_min_i32_e32 v27, v27, v29
	v_max_i32_e32 v29, v46, v32
	v_min_i32_e32 v32, v46, v32
	v_max_i32_e32 v46, v30, v35
	v_min_i32_e32 v30, v30, v35
	v_max_i32_e32 v35, v42, v41
	v_min_i32_e32 v41, v42, v41
	v_max_i32_e32 v42, v43, v44
	v_min_i32_e32 v43, v43, v44
	v_max_i32_e32 v44, v45, v38
	v_min_i32_e32 v38, v45, v38
	v_max_i32_e32 v45, v34, v39
	v_min_i32_e32 v34, v34, v39
	v_max_i32_e32 v39, v40, v31
	v_min_i32_e32 v31, v40, v31
	v_max_i32_e32 v40, v29, v35
	v_min_i32_e32 v29, v29, v35
	v_max_i32_e32 v35, v32, v41
	v_min_i32_e32 v32, v32, v41
	v_max_i32_e32 v41, v42, v44
	v_min_i32_e32 v42, v42, v44
	v_max_i32_e32 v44, v43, v38
	v_min_i32_e32 v38, v43, v38
	v_max_i32_e32 v43, v45, v39
	v_min_i32_e32 v39, v45, v39
	v_max_i32_e32 v45, v34, v31
	v_min_i32_e32 v31, v34, v31
	v_max_i32_e32 v34, v35, v29
	v_min_i32_e32 v29, v35, v29
	v_max_i32_e32 v35, v46, v32
	v_min_i32_e32 v32, v46, v32
	v_max_i32_e32 v46, v43, v30
	v_min_i32_e32 v30, v43, v30
	v_max_i32_e32 v43, v45, v39
	v_min_i32_e32 v39, v45, v39
	v_max_i32_e32 v45, v35, v41
	v_min_i32_e32 v35, v35, v41
	v_max_i32_e32 v41, v32, v42
	v_min_i32_e32 v32, v32, v42
	v_max_i32_e32 v42, v44, v46
	v_min_i32_e32 v44, v44, v46
	v_max_i32_e32 v46, v38, v30
	v_min_i32_e32 v30, v38, v30
	v_max_i32_e32 v38, v45, v29
	v_min_i32_e32 v29, v45, v29
	v_max_i32_e32 v45, v35, v41
	v_min_i32_e32 v35, v35, v41
	v_max_i32_e32 v41, v42, v32
	v_min_i32_e32 v32, v42, v32
	v_max_i32_e32 v42, v44, v46
	v_min_i32_e32 v44, v44, v46
	v_max_i32_e32 v46, v43, v30
	v_min_i32_e32 v30, v43, v30
	v_max_i32_e32 v43, v35, v41
	v_min_i32_e32 v35, v35, v41
	v_max_i32_e32 v41, v32, v42
	v_min_i32_e32 v32, v32, v42
	ds_bpermute_b32 v54, v123, v41
	ds_bpermute_b32 v55, v123, v32
	ds_bpermute_b32 v56, v123, v44
	ds_bpermute_b32 v57, v123, v27
	ds_bpermute_b32 v58, v123, v31
	ds_bpermute_b32 v59, v123, v39
	ds_bpermute_b32 v60, v123, v30
	ds_bpermute_b32 v61, v123, v46
	ds_bpermute_b32 v42, v123, v37
	ds_bpermute_b32 v47, v123, v40
	ds_bpermute_b32 v48, v123, v34
	ds_bpermute_b32 v49, v123, v38
	ds_bpermute_b32 v50, v123, v29
	ds_bpermute_b32 v51, v123, v45
	ds_bpermute_b32 v52, v123, v43
	ds_bpermute_b32 v53, v123, v35
	s_waitcnt lgkmcnt(12)
	v_max_i32_e32 v37, v37, v57
	s_waitcnt lgkmcnt(11)
	v_max_i32_e32 v40, v40, v58
	s_waitcnt lgkmcnt(10)
	v_max_i32_e32 v34, v34, v59
	s_waitcnt lgkmcnt(9)
	v_max_i32_e32 v38, v38, v60
	s_waitcnt lgkmcnt(8)
	v_max_i32_e32 v29, v29, v61
	v_max_i32_e32 v45, v45, v56
	v_max_i32_e32 v43, v43, v55
	v_max_i32_e32 v35, v35, v54
	v_add_f32_e32 v28, v78, v28
	v_add_f32_e32 v54, v77, v26
	v_add_f32_e32 v55, v77, v33
	v_add_f32_e32 v36, v77, v36
	v_add_f32_e32 v56, v76, v26
	v_add_f32_e32 v57, v76, v33
	v_add_f32_e32 v58, v75, v26
	v_add_f32_e32 v59, v75, v33
	v_add_f32_e32 v60, v73, v26
	v_add_f32_e32 v33, v73, v33
	v_add_f32_e32 v61, v71, v26
	v_add_f32_e32 v65, v69, v26
	v_add_f32_e32 v68, v68, v26
	v_or_b32_e32 v28, 0xff, v28
	v_or_b32_e32 v54, 0xff, v54
	v_or_b32_e32 v55, 0xff, v55
	v_or_b32_e32 v36, 0xff, v36
	v_or_b32_e32 v56, 0xff, v56
	v_or_b32_e32 v57, 0xff, v57
	v_or_b32_e32 v58, 0xff, v58
	v_or_b32_e32 v59, 0xff, v59
	v_or_b32_e32 v60, 0xff, v60
	v_or_b32_e32 v33, 0xff, v33
	v_or_b32_e32 v61, 0xff, v61
	v_or_b32_e32 v62, 0xff, v62
	v_or_b32_e32 v63, 0xff, v63
	v_or_b32_e32 v64, 0xff, v64
	v_or_b32_e32 v65, 0xff, v65
	v_or_b32_e32 v68, 0xff, v68
	v_subrev_u32_e32 v28, 51, v28
	v_subrev_u32_e32 v54, 64, v54
	v_add_u32_e32 v55, 0xffffffbf, v55
	v_add_u32_e32 v36, 0xffffffbe, v36
	v_add_u32_e32 v56, 0xffffffb0, v56
	v_add_u32_e32 v57, 0xffffffaf, v57
	v_add_u32_e32 v58, 0xffffffa0, v58
	v_add_u32_e32 v59, 0xffffff9f, v59
	v_add_u32_e32 v60, 0xffffff90, v60
	v_add_u32_e32 v33, 0xffffff8f, v33
	v_add_u32_e32 v61, 0xffffff80, v61
	v_add_u32_e32 v62, 0xffffff70, v62
	v_add_u32_e32 v63, 0xffffff60, v63
	v_add_u32_e32 v64, 0xffffff50, v64
	v_add_u32_e32 v65, 0xffffff40, v65
	v_add_u32_e32 v68, 0xffffff30, v68
	v_max_i32_e32 v69, v28, v64
	v_min_i32_e32 v28, v28, v64
	v_max_i32_e32 v64, v54, v63
	v_min_i32_e32 v54, v54, v63
	v_max_i32_e32 v63, v55, v68
	v_min_i32_e32 v55, v55, v68
	v_max_i32_e32 v68, v36, v65
	v_min_i32_e32 v36, v36, v65
	v_max_i32_e32 v65, v56, v60
	v_min_i32_e32 v56, v56, v60
	v_max_i32_e32 v60, v57, v58
	v_min_i32_e32 v57, v57, v58
	v_max_i32_e32 v58, v59, v62
	v_min_i32_e32 v59, v59, v62
	v_max_i32_e32 v62, v33, v61
	v_min_i32_e32 v33, v33, v61
	v_max_i32_e32 v61, v69, v60
	v_min_i32_e32 v60, v69, v60
	v_max_i32_e32 v69, v64, v58
	v_min_i32_e32 v58, v64, v58
	v_max_i32_e32 v64, v63, v62
	v_min_i32_e32 v62, v63, v62
	v_max_i32_e32 v63, v68, v65
	v_min_i32_e32 v65, v68, v65
	v_max_i32_e32 v68, v57, v28
	v_min_i32_e32 v28, v57, v28
	v_max_i32_e32 v57, v56, v36
	v_min_i32_e32 v36, v56, v36
	v_max_i32_e32 v56, v33, v55
	v_min_i32_e32 v33, v33, v55
	v_max_i32_e32 v55, v59, v54
	v_min_i32_e32 v54, v59, v54
	v_max_i32_e32 v59, v61, v69
	v_min_i32_e32 v61, v61, v69
	v_max_i32_e32 v69, v64, v63
	v_min_i32_e32 v63, v64, v63
	v_max_i32_e32 v64, v65, v60
	v_min_i32_e32 v60, v65, v60
	v_max_i32_e32 v65, v68, v57
	v_min_i32_e32 v57, v68, v57
	v_max_i32_e32 v68, v58, v62
	v_min_i32_e32 v58, v58, v62
	v_max_i32_e32 v62, v56, v55
	v_min_i32_e32 v55, v56, v55
	v_max_i32_e32 v56, v54, v28
	v_min_i32_e32 v28, v54, v28
	v_max_i32_e32 v54, v36, v33
	v_min_i32_e32 v33, v36, v33
	v_min_i32_e32 v36, v59, v69
	v_max_i32_e32 v70, v61, v63
	v_min_i32_e32 v61, v61, v63
	v_max_i32_e32 v63, v64, v62
	v_min_i32_e32 v62, v64, v62
	v_max_i32_e32 v64, v60, v55
	v_min_i32_e32 v55, v60, v55
	v_max_i32_e32 v60, v65, v68
	v_min_i32_e32 v65, v65, v68
	v_max_i32_e32 v68, v57, v58
	v_min_i32_e32 v57, v57, v58
	v_max_i32_e32 v58, v56, v54
	v_min_i32_e32 v54, v56, v54
	v_max_i32_e32 v56, v28, v33
	v_min_i32_e32 v28, v28, v33
	v_max_i32_e32 v33, v70, v36
	v_min_i32_e32 v36, v70, v36
	v_max_i32_e32 v70, v61, v58
	v_min_i32_e32 v58, v61, v58
	v_max_i32_e32 v61, v63, v60
	v_min_i32_e32 v60, v63, v60
	v_max_i32_e32 v63, v64, v65
	v_min_i32_e32 v64, v64, v65
	v_max_i32_e32 v65, v68, v62
	v_min_i32_e32 v62, v68, v62
	v_max_i32_e32 v68, v57, v55
	v_min_i32_e32 v55, v57, v55
	v_max_i32_e32 v57, v56, v54
	s_waitcnt lgkmcnt(0)
; #define CAND(a, b) (int)((__float_as_uint(__int_as_float(top[0][a]) + __int_as_float(top[1][b])) | 255u) - (unsigned)((a) * 16 + (b)))
; __device__ __forceinline__ void route_task(int task, int tl0, const bf16* QP  , const LAS bf16* KHL, LAS unsigned short* EL, LAS float* GL, int lane) {
;     ...
;         int oth[16];
; #pragma unroll
;         for (int i = 0; i < 16; ++i) oth[i] = __shfl_xor(bk[i], 32);
;         merge16_desc(bk, oth);
;     }
;     ...
;     {
;         int gk[16];
;         gk[0] = CAND(3, 3); gk[1] = CAND(4, 0); gk[2] = CAND(4, 1); gk[3] = CAND(4, 2); gk[4] = CAND(5, 0); gk[5] = CAND(5, 1); gk[6] = CAND(6, 0); gk[7] = CAND(6, 1);
;         gk[8] = CAND(7, 0); gk[9] = CAND(7, 1); gk[10] = CAND(8, 0); gk[11] = CAND(9, 0); gk[12] = CAND(10, 0); gk[13] = CAND(11, 0); gk[14] = CAND(12, 0); gk[15] = CAND(13, 0);
;         sort16_desc(gk);
;         merge16_desc(bk, gk);
;     }
;     {
;         const int c14 = CAND(14, 0), c15 = CAND(15, 0);
;         const int n14 = max(bk[14], c14), n15 = max(min(bk[14], c14), max(bk[15], c15));
;         bk[14] = n14; bk[15] = n15;
;     }
	v_max_i32_e32 v41, v41, v53
	v_max_i32_e32 v32, v32, v52
	v_max_i32_e32 v44, v44, v51
	v_max_i32_e32 v46, v46, v50
	v_max_i32_e32 v30, v30, v49
	v_max_i32_e32 v39, v39, v48
	v_max_i32_e32 v31, v31, v47
	v_max_i32_e32 v27, v27, v42
	v_min_i32_e32 v54, v56, v54
	v_max_i32_e32 v56, v33, v61
	v_min_i32_e32 v33, v33, v61
	v_max_i32_e32 v61, v36, v60
	v_min_i32_e32 v36, v36, v60
	v_max_i32_e32 v60, v63, v65
	v_min_i32_e32 v63, v63, v65
	v_max_i32_e32 v65, v64, v62
	v_min_i32_e32 v62, v64, v62
	v_max_i32_e32 v64, v68, v57
	v_max_i32_e32 v42, v37, v41
	v_min_i32_e32 v37, v37, v41
	v_max_i32_e32 v41, v40, v32
	v_min_i32_e32 v32, v40, v32
	v_max_i32_e32 v40, v34, v44
	v_min_i32_e32 v34, v34, v44
	v_max_i32_e32 v44, v38, v46
	v_min_i32_e32 v38, v38, v46
	v_max_i32_e32 v46, v29, v30
	v_min_i32_e32 v29, v29, v30
	v_max_i32_e32 v30, v45, v39
	v_min_i32_e32 v39, v45, v39
	v_max_i32_e32 v45, v43, v31
	v_min_i32_e32 v31, v43, v31
	v_max_i32_e32 v43, v35, v27
	v_min_i32_e32 v27, v35, v27
	v_min_i32_e32 v57, v68, v57
	v_max_i32_e32 v68, v55, v54
	v_max_i32_e32 v71, v70, v36
	v_min_i32_e32 v36, v70, v36
	v_max_i32_e32 v70, v64, v58
	v_min_i32_e32 v58, v64, v58
	v_max_i32_e32 v35, v42, v46
	v_min_i32_e32 v42, v42, v46
	v_max_i32_e32 v46, v41, v30
	v_min_i32_e32 v30, v41, v30
	v_max_i32_e32 v41, v40, v45
	v_min_i32_e32 v40, v40, v45
	v_max_i32_e32 v45, v44, v43
	v_min_i32_e32 v43, v44, v43
	v_max_i32_e32 v44, v37, v29
	v_min_i32_e32 v29, v37, v29
	v_max_i32_e32 v37, v32, v39
	v_min_i32_e32 v32, v32, v39
	v_max_i32_e32 v39, v34, v31
	v_min_i32_e32 v31, v34, v31
	v_max_i32_e32 v34, v38, v27
	v_min_i32_e32 v27, v38, v27
	v_min_i32_e32 v54, v55, v54
	v_min_i32_e32 v55, v61, v33
	v_max_i32_e32 v64, v68, v57
	v_min_i32_e32 v57, v68, v57
	v_max_i32_e32 v68, v71, v60
	v_min_i32_e32 v60, v71, v60
	v_max_i32_e32 v71, v36, v63
	v_min_i32_e32 v36, v36, v63
	v_max_i32_e32 v63, v65, v70
	v_min_i32_e32 v65, v65, v70
	v_max_i32_e32 v70, v62, v58
	v_max_i32_e32 v38, v35, v41
	v_min_i32_e32 v35, v35, v41
	v_max_i32_e32 v41, v46, v45
	v_min_i32_e32 v45, v46, v45
	v_max_i32_e32 v46, v42, v40
	v_min_i32_e32 v40, v42, v40
	v_max_i32_e32 v42, v30, v43
	v_min_i32_e32 v30, v30, v43
	v_max_i32_e32 v43, v44, v39
	v_min_i32_e32 v39, v44, v39
	v_max_i32_e32 v44, v37, v34
	v_min_i32_e32 v34, v37, v34
	v_max_i32_e32 v37, v29, v31
	v_min_i32_e32 v29, v29, v31
	v_max_i32_e32 v31, v32, v27
	v_min_i32_e32 v27, v32, v27
	v_min_i32_e32 v58, v62, v58
	v_max_i32_e32 v62, v68, v55
	v_min_i32_e32 v55, v68, v55
	v_max_i32_e32 v68, v60, v71
	v_min_i32_e32 v60, v60, v71
	v_max_i32_e32 v71, v63, v36
	v_min_i32_e32 v36, v63, v36
	v_max_i32_e32 v63, v65, v70
	v_min_i32_e32 v32, v38, v41
	v_min_i32_e32 v47, v35, v45
	v_min_i32_e32 v48, v46, v42
	v_min_i32_e32 v49, v40, v30
	v_min_i32_e32 v50, v43, v44
	v_min_i32_e32 v51, v39, v34
	v_min_i32_e32 v52, v37, v31
	v_min_i32_e32 v53, v29, v27
	v_min_i32_e32 v65, v65, v70
	v_max_i32_e32 v70, v64, v58
	v_min_i32_e32 v58, v64, v58
	v_min_i32_e32 v64, v60, v71
	v_min_i32_e32 v72, v36, v63
	v_max3_i32 v28, v38, v41, v28
	v_max_i32_e32 v32, v32, v54
	v_max3_i32 v35, v35, v45, v57
	v_max_i32_e32 v38, v47, v58
	v_max3_i32 v41, v46, v42, v70
	v_max_i32_e32 v42, v48, v65
	v_max3_i32 v30, v40, v30, v72
	v_max3_i32 v36, v49, v36, v63
	v_max3_i32 v40, v43, v44, v64
	v_max3_i32 v43, v50, v60, v71
	v_max3_i32 v34, v39, v34, v68
	v_max_i32_e32 v39, v51, v55
	v_max3_i32 v31, v37, v31, v62
	v_max3_i32 v33, v52, v61, v33
	v_max3_i32 v27, v29, v27, v56
	v_max3_i32 v29, v53, v59, v69
	v_max_i32_e32 v37, v28, v40
	v_min_i32_e32 v28, v28, v40
	v_max_i32_e32 v40, v32, v43
	v_min_i32_e32 v32, v32, v43
	v_max_i32_e32 v43, v35, v34
	v_min_i32_e32 v34, v35, v34
	v_max_i32_e32 v35, v38, v39
	v_min_i32_e32 v38, v38, v39
	v_max_i32_e32 v39, v41, v31
	v_min_i32_e32 v31, v41, v31
	v_max_i32_e32 v41, v42, v33
	v_min_i32_e32 v33, v42, v33
	v_max_i32_e32 v42, v30, v27
	v_min_i32_e32 v27, v30, v27
	v_max_i32_e32 v30, v36, v29
	v_min_i32_e32 v29, v36, v29
	v_max_i32_e32 v36, v37, v39
	v_min_i32_e32 v37, v37, v39
	v_max_i32_e32 v39, v40, v41
	v_min_i32_e32 v40, v40, v41
	v_max_i32_e32 v41, v43, v42
	v_min_i32_e32 v42, v43, v42
	v_max_i32_e32 v43, v35, v30
	v_min_i32_e32 v30, v35, v30
	v_max_i32_e32 v35, v28, v31
	v_min_i32_e32 v28, v28, v31
	v_max_i32_e32 v31, v32, v33
	v_min_i32_e32 v32, v32, v33
	v_max_i32_e32 v33, v34, v27
	v_min_i32_e32 v27, v34, v27
	v_max_i32_e32 v34, v38, v29
	v_min_i32_e32 v29, v38, v29
	v_max_i32_e32 v38, v36, v41
	v_min_i32_e32 v36, v36, v41
	v_max_i32_e32 v41, v39, v43
	v_min_i32_e32 v39, v39, v43
	v_max_i32_e32 v43, v37, v42
	v_min_i32_e32 v37, v37, v42
	v_max_i32_e32 v42, v40, v30
	v_min_i32_e32 v30, v40, v30
	v_max_i32_e32 v40, v35, v33
	v_min_i32_e32 v33, v35, v33
	v_max_i32_e32 v35, v31, v34
	v_min_i32_e32 v31, v31, v34
	v_max_i32_e32 v34, v28, v27
	v_min_i32_e32 v27, v28, v27
	v_max_i32_e32 v28, v32, v29
	v_min_i32_e32 v29, v32, v29
	v_max_i32_e32 v32, v38, v41
	v_min_i32_e32 v38, v38, v41
	v_max_i32_e32 v41, v36, v39
	v_min_i32_e32 v36, v36, v39
	v_max_i32_e32 v39, v43, v42
	v_min_i32_e32 v42, v43, v42
	v_max_i32_e32 v43, v37, v30
	v_min_i32_e32 v30, v37, v30
	v_max_i32_e32 v37, v40, v35
	v_min_i32_e32 v35, v40, v35
	v_max_i32_e32 v40, v33, v31
	v_min_i32_e32 v31, v33, v31
	v_max_i32_e32 v33, v34, v28
	v_min_i32_e32 v28, v34, v28
	v_max_i32_e32 v34, v27, v29
	v_min_i32_e32 v27, v27, v29
	v_add_f32_e32 v29, v67, v26
	v_or_b32_e32 v29, 0xff, v29
	v_add_f32_e32 v26, v66, v26
	v_add_u32_e32 v29, 0xffffff20, v29
	v_or_b32_e32 v26, 0xff, v26
	v_add_u32_e32 v26, 0xffffff10, v26
	v_max_i32_e32 v44, v34, v29
	v_min_i32_e32 v29, v34, v29
	v_max3_i32 v26, v29, v27, v26
; __device__ __forceinline__ void route_task(int task, int tl0, const bf16* QP  , const LAS bf16* KHL, LAS unsigned short* EL, LAS float* GL, int lane) {
;     ...
;     int my[8];
; #pragma unroll
;     for (int i = 0; i < 8; ++i) { int lo_ = bk[i], hi_ = bk[8 + i]; asm volatile("" : "+v"(lo_), "+v"(hi_)); my[i] = hi ? hi_ : lo_; }
;     int bv[8];
; #pragma unroll
;     for (int i = 0; i < 8; ++i) {
;         const unsigned cd = 255u - ((unsigned)my[i] & 255u), ca = cd >> 4, cb = cd & 15u;
;         const unsigned wa = (ca >> 2) == 0u ? P1[0] : (ca >> 2) == 1u ? P1[1] : (ca >> 2) == 2u ? P1[2] : P1[3];
;         const unsigned wb = (cb >> 2) == 0u ? P2[0] : (cb >> 2) == 1u ? P2[1] : (cb >> 2) == 2u ? P2[2] : P2[3];
;         bv[i] = (int)((((wa >> (8u * (ca & 3u))) & 255u) << 7) | ((wb >> (8u * (cb & 3u))) & 255u));
;     }
	v_mov_b32_e32 v27, v32
	s_nop 0
	v_cndmask_b32_e64 v27, v37, v27, s[6:7]
	v_not_b32_e32 v29, v27
	v_bfe_u32 v45, v29, 6, 2
	v_cmp_eq_u32_e32 vcc, 2, v45
	v_cndmask_b32_e64 v30, v26, v30, s[6:7]
	v_bitop3_b32 v26, v27, s3, v27 bitop3:0xc
	v_cndmask_b32_e32 v46, v25, v23, vcc
	v_cmp_eq_u32_e32 vcc, 1, v45
	v_cndmask_b32_e64 v34, v35, v38, s[6:7]
	v_not_b32_e32 v35, v34
	v_cndmask_b32_e32 v45, v46, v21, vcc
	v_cmp_gt_u32_e32 vcc, 64, v26
	v_cndmask_b32_e64 v37, v40, v41, s[6:7]
	v_cndmask_b32_e64 v41, v44, v43, s[6:7]
	v_cndmask_b32_e32 v26, v45, v19, vcc
	v_bfe_u32 v45, v29, 2, 2
	v_cmp_eq_u32_e32 vcc, 2, v45
	v_bitop3_b32 v44, v27, 15, v27 bitop3:0xc
	v_bfe_u32 v47, v35, 6, 2
	v_cndmask_b32_e32 v46, v24, v22, vcc
	v_cmp_eq_u32_e32 vcc, 1, v45
	v_not_b32_e32 v38, v37
	v_bfe_u32 v49, v38, 6, 2
	v_cndmask_b32_e32 v45, v46, v20, vcc
	v_cmp_gt_u32_e32 vcc, 4, v44
	v_bitop3_b32 v46, v34, 15, v34 bitop3:0xc
	v_cndmask_b32_e64 v31, v31, v36, s[6:7]
	v_cndmask_b32_e32 v44, v45, v18, vcc
	v_cmp_eq_u32_e32 vcc, 2, v47
	v_bitop3_b32 v45, v34, s3, v34 bitop3:0xc
	v_not_b32_e32 v36, v31
	v_cndmask_b32_e32 v48, v25, v23, vcc
	v_cmp_eq_u32_e32 vcc, 1, v47
	v_bfe_u32 v51, v36, 6, 2
	v_cndmask_b32_e64 v33, v33, v39, s[6:7]
	v_cndmask_b32_e32 v47, v48, v21, vcc
	v_cmp_gt_u32_e32 vcc, 64, v45
	v_not_b32_e32 v39, v33
	v_bfe_u32 v53, v39, 6, 2
	v_cndmask_b32_e32 v45, v47, v19, vcc
	v_bfe_u32 v47, v35, 2, 2
	v_cmp_eq_u32_e32 vcc, 2, v47
	v_cndmask_b32_e64 v28, v28, v42, s[6:7]
	v_not_b32_e32 v40, v28
	v_cndmask_b32_e32 v48, v24, v22, vcc
	v_cmp_eq_u32_e32 vcc, 1, v47
	v_bfe_u32 v55, v40, 6, 2
	v_not_b32_e32 v42, v41
	v_cndmask_b32_e32 v47, v48, v20, vcc
	v_cmp_gt_u32_e32 vcc, 4, v46
	v_bitop3_b32 v48, v37, 15, v37 bitop3:0xc
	v_bfe_u32 v57, v42, 6, 2
	v_cndmask_b32_e32 v46, v47, v18, vcc
	v_cmp_eq_u32_e32 vcc, 2, v49
	v_bitop3_b32 v47, v37, s3, v37 bitop3:0xc
	v_not_b32_e32 v43, v30
	v_cndmask_b32_e32 v50, v25, v23, vcc
	v_cmp_eq_u32_e32 vcc, 1, v49
	v_bfe_u32 v59, v43, 6, 2
	s_nop 0
	v_cndmask_b32_e32 v49, v50, v21, vcc
	v_cmp_gt_u32_e32 vcc, 64, v47
	s_nop 1
	v_cndmask_b32_e32 v47, v49, v19, vcc
	v_bfe_u32 v49, v38, 2, 2
	v_cmp_eq_u32_e32 vcc, 2, v49
	s_nop 1
	v_cndmask_b32_e32 v50, v24, v22, vcc
	v_cmp_eq_u32_e32 vcc, 1, v49
	s_nop 1
	v_cndmask_b32_e32 v49, v50, v20, vcc
	v_cmp_gt_u32_e32 vcc, 4, v48
	v_bitop3_b32 v50, v31, 15, v31 bitop3:0xc
	s_nop 0
	v_cndmask_b32_e32 v48, v49, v18, vcc
	v_cmp_eq_u32_e32 vcc, 2, v51
	v_bitop3_b32 v49, v31, s3, v31 bitop3:0xc
	s_nop 0
	v_cndmask_b32_e32 v52, v25, v23, vcc
	v_cmp_eq_u32_e32 vcc, 1, v51
	s_nop 1
	v_cndmask_b32_e32 v51, v52, v21, vcc
	v_cmp_gt_u32_e32 vcc, 64, v49
	s_nop 1
	v_cndmask_b32_e32 v49, v51, v19, vcc
	v_bfe_u32 v51, v36, 2, 2
	v_cmp_eq_u32_e32 vcc, 2, v51
	s_nop 1
	v_cndmask_b32_e32 v52, v24, v22, vcc
	v_cmp_eq_u32_e32 vcc, 1, v51
	s_nop 1
	v_cndmask_b32_e32 v51, v52, v20, vcc
	v_cmp_gt_u32_e32 vcc, 4, v50
	v_bitop3_b32 v52, v33, 15, v33 bitop3:0xc
	s_nop 0
	v_cndmask_b32_e32 v50, v51, v18, vcc
	v_cmp_eq_u32_e32 vcc, 2, v53
	v_bitop3_b32 v51, v33, s3, v33 bitop3:0xc
	s_nop 0
	v_cndmask_b32_e32 v54, v25, v23, vcc
	v_cmp_eq_u32_e32 vcc, 1, v53
	s_nop 1
	v_cndmask_b32_e32 v53, v54, v21, vcc
	v_cmp_gt_u32_e32 vcc, 64, v51
	s_nop 1
	v_cndmask_b32_e32 v51, v53, v19, vcc
	v_bfe_u32 v53, v39, 2, 2
	v_cmp_eq_u32_e32 vcc, 2, v53
	s_nop 1
	v_cndmask_b32_e32 v54, v24, v22, vcc
	v_cmp_eq_u32_e32 vcc, 1, v53
	s_nop 1
	v_cndmask_b32_e32 v53, v54, v20, vcc
	v_cmp_gt_u32_e32 vcc, 4, v52
	v_bitop3_b32 v54, v28, 15, v28 bitop3:0xc
	s_nop 0
	v_cndmask_b32_e32 v52, v53, v18, vcc
	v_cmp_eq_u32_e32 vcc, 2, v55
	v_bitop3_b32 v53, v28, s3, v28 bitop3:0xc
	s_nop 0
	v_cndmask_b32_e32 v56, v25, v23, vcc
	v_cmp_eq_u32_e32 vcc, 1, v55
	s_nop 1
	v_cndmask_b32_e32 v55, v56, v21, vcc
	v_cmp_gt_u32_e32 vcc, 64, v53
	s_nop 1
	v_cndmask_b32_e32 v53, v55, v19, vcc
	v_bfe_u32 v55, v40, 2, 2
	v_cmp_eq_u32_e32 vcc, 2, v55
	s_nop 1
	v_cndmask_b32_e32 v56, v24, v22, vcc
	v_cmp_eq_u32_e32 vcc, 1, v55
	s_nop 1
	v_cndmask_b32_e32 v55, v56, v20, vcc
	v_cmp_gt_u32_e32 vcc, 4, v54
	v_bitop3_b32 v56, v41, 15, v41 bitop3:0xc
	s_nop 0
	v_cndmask_b32_e32 v54, v55, v18, vcc
	v_cmp_eq_u32_e32 vcc, 2, v57
	v_bitop3_b32 v55, v41, s3, v41 bitop3:0xc
	s_nop 0
	v_cndmask_b32_e32 v58, v25, v23, vcc
	v_cmp_eq_u32_e32 vcc, 1, v57
	s_nop 1
	v_cndmask_b32_e32 v57, v58, v21, vcc
	v_cmp_gt_u32_e32 vcc, 64, v55
	s_nop 1
	v_cndmask_b32_e32 v55, v57, v19, vcc
	v_bfe_u32 v57, v42, 2, 2
	v_cmp_eq_u32_e32 vcc, 2, v57
	s_nop 1
	v_cndmask_b32_e32 v58, v24, v22, vcc
	v_cmp_eq_u32_e32 vcc, 1, v57
	s_nop 1
	v_cndmask_b32_e32 v57, v58, v20, vcc
	v_cmp_gt_u32_e32 vcc, 4, v56
	v_bitop3_b32 v58, v30, 15, v30 bitop3:0xc
	s_nop 0
	v_cndmask_b32_e32 v56, v57, v18, vcc
	v_cmp_eq_u32_e32 vcc, 2, v59
	v_bitop3_b32 v57, v30, s3, v30 bitop3:0xc
	s_nop 0
	v_cndmask_b32_e32 v23, v25, v23, vcc
	v_cmp_eq_u32_e32 vcc, 1, v59
	v_sub_f32_e32 v25, v31, v32
	v_mul_f32_e32 v25, 0x3fb8aa3b, v25
	v_cndmask_b32_e32 v21, v23, v21, vcc
	v_cmp_gt_u32_e32 vcc, 64, v57
	v_lshrrev_b32_e32 v23, 1, v39
	v_and_b32_e32 v23, 24, v23
	v_cndmask_b32_e32 v19, v21, v19, vcc
	v_bfe_u32 v21, v43, 2, 2
	v_cmp_eq_u32_e32 vcc, 2, v21
	v_lshrrev_b32_e32 v23, v23, v51
	v_lshlrev_b32_e32 v23, 7, v23
	v_cndmask_b32_e32 v22, v24, v22, vcc
	v_cmp_eq_u32_e32 vcc, 1, v21
	v_lshrrev_b32_e32 v21, 1, v42
	v_and_b32_e32 v21, 24, v21
	v_cndmask_b32_e32 v20, v22, v20, vcc
	v_cmp_gt_u32_e32 vcc, 4, v58
	v_lshrrev_b32_e32 v21, v21, v55
	v_lshrrev_b32_e32 v22, 1, v40
	v_cndmask_b32_e32 v18, v20, v18, vcc
	v_lshlrev_b32_e32 v20, 3, v42
	v_lshlrev_b32_e32 v21, 7, v21
	v_and_b32_e32 v22, 24, v22
	v_lshrrev_b32_e32 v20, v20, v56
; #define LAS __attribute__((address_space(3)))
; __device__ __forceinline__ void peer_u_item(int p, int j, const LAS unsigned short* EL  , const unsigned char* __restrict__ XQ, const unsigned char* __restrict__ U8, LAS int* ACC  , int lane, int wave) {
;     asm volatile("" : "+v"(lane));
;     const int gidx = lane >> 3; const unsigned coff = (unsigned)(p * 128 + (lane & 7) * 16), toff = (unsigned)(p * (16384 * 128) + (lane & 7) * 16);
; #pragma unroll 1
;     for (int it = 0; it < 8; ++it) {
;         const int t = j * 64 + it * 8 + wave;
;         unsigned E[8];
;         { const LAS v4u* ep = (const LAS v4u*)(EL + (it * 8 + wave) * 128 + 16 * gidx); const v4u e0 = ep[0], e1 = ep[1];
;           E[0] = e0.x; E[1] = e0.y; E[2] = e0.z; E[3] = e0.w; E[4] = e1.x; E[5] = e1.y; E[6] = e1.z; E[7] = e1.w; }
;         uint4 uu[16];
; #pragma unroll
;         for (int i = 0; i < 16; ++i) uu[i] = *(const uint4*)(U8 + (size_t)(PE_ID(E, i) * 128u + toff));
;         const uint4 xh = *(const uint4*)(XQ + (size_t)t * 512 + coff), xl = *(const uint4*)(XQ + 8 * MiB + (size_t)t * 512 + coff);
; __device__ __forceinline__ void route_task(int task, int tl0, const bf16* QP  , const LAS bf16* KHL, LAS unsigned short* EL, LAS float* GL, int lane) {
;     ...
;     float e[8], se = 0.f;
; #pragma unroll
;     for (int i = 0; i < 8; ++i) { e[i] = __expf(__int_as_float(my[i]) - __int_as_float(bk[0])); se += e[i]; }
;     se += __shfl_xor(se, 32);
;     const float inv = 1.f / se;
;     {
;         int l2 = lane; asm volatile("" : "+v"(l2));
;         const int o2 = (tl0 + ((l2 & 31) >> 3)) * 128 + (l2 & 7) * 16 + 8 * (l2 >> 5);
;         LAS v4u* ip = (LAS v4u*)(EL + o2); typedef float f4v __attribute__((ext_vector_type(4))); LAS f4v* gp = (LAS f4v*)(GL + o2);
;         ip[0] = (v4u){(unsigned)bv[0] | ((unsigned)bv[1] << 16), (unsigned)bv[2] | ((unsigned)bv[3] << 16), (unsigned)bv[4] | ((unsigned)bv[5] << 16), (unsigned)bv[6] | ((unsigned)bv[7] << 16)};
;         gp[0] = (f4v){e[0] * inv, e[1] * inv, e[2] * inv, e[3] * inv}; gp[1] = (f4v){e[4] * inv, e[5] * inv, e[6] * inv, e[7] * inv};
;     }
	v_and_b32_e32 v21, 0x7f80, v21
	v_lshrrev_b32_e32 v22, v22, v53
	v_and_or_b32 v21, v20, s3, v21
	v_lshlrev_b32_e32 v20, 3, v40
	v_lshlrev_b32_e32 v22, 7, v22
	v_lshrrev_b32_e32 v20, v20, v54
	v_and_b32_e32 v22, 0x7f80, v22
	v_and_or_b32 v20, v20, s3, v22
	v_lshlrev_b32_e32 v22, 3, v39
	v_lshrrev_b32_e32 v22, v22, v52
	v_and_b32_e32 v23, 0x7f80, v23
	v_and_or_b32 v39, v22, s3, v23
	v_lshrrev_b32_e32 v23, 1, v36
	v_and_b32_e32 v23, 24, v23
	v_lshrrev_b32_e32 v23, v23, v49
	v_lshlrev_b32_e32 v22, 3, v36
	v_lshlrev_b32_e32 v23, 7, v23
	v_lshrrev_b32_e32 v22, v22, v50
	v_and_b32_e32 v23, 0x7f80, v23
	v_and_or_b32 v36, v22, s3, v23
	v_lshrrev_b32_e32 v23, 1, v38
	v_and_b32_e32 v23, 24, v23
	v_lshrrev_b32_e32 v23, v23, v47
	v_lshlrev_b32_e32 v22, 3, v38
	v_lshlrev_b32_e32 v23, 7, v23
	v_lshrrev_b32_e32 v22, v22, v48
	v_and_b32_e32 v23, 0x7f80, v23
	v_and_or_b32 v38, v22, s3, v23
	v_lshrrev_b32_e32 v23, 1, v35
	v_and_b32_e32 v23, 24, v23
	v_lshrrev_b32_e32 v23, v23, v45
	v_lshlrev_b32_e32 v22, 3, v35
	v_lshlrev_b32_e32 v23, 7, v23
	v_lshrrev_b32_e32 v22, v22, v46
	v_and_b32_e32 v23, 0x7f80, v23
	v_and_or_b32 v35, v22, s3, v23
	v_lshrrev_b32_e32 v23, 1, v29
	v_and_b32_e32 v23, 24, v23
	v_lshrrev_b32_e32 v23, v23, v26
	v_lshlrev_b32_e32 v22, 3, v29
	v_lshlrev_b32_e32 v23, 7, v23
	v_lshrrev_b32_e32 v22, v22, v44
	v_and_b32_e32 v23, 0x7f80, v23
	v_and_or_b32 v40, v22, s3, v23
	v_sub_f32_e32 v22, v27, v32
	v_mul_f32_e32 v22, 0x3fb8aa3b, v22
	v_sub_f32_e32 v23, v34, v32
	v_exp_f32_e32 v22, v22
	v_mul_f32_e32 v23, 0x3fb8aa3b, v23
	v_sub_f32_e32 v24, v37, v32
	v_exp_f32_e32 v23, v23
	v_mul_f32_e32 v24, 0x3fb8aa3b, v24
	v_exp_f32_e32 v24, v24
	v_exp_f32_e32 v25, v25
	v_add_f32_e32 v26, 0, v22
	v_add_f32_e32 v26, v23, v26
	v_add_f32_e32 v26, v24, v26
	v_add_f32_e32 v31, v25, v26
	v_sub_f32_e32 v26, v33, v32
	v_mul_f32_e32 v26, 0x3fb8aa3b, v26
	v_sub_f32_e32 v27, v28, v32
	v_exp_f32_e32 v26, v26
	v_mul_f32_e32 v27, 0x3fb8aa3b, v27
	v_sub_f32_e32 v28, v41, v32
	v_exp_f32_e32 v27, v27
	v_mul_f32_e32 v28, 0x3fb8aa3b, v28
	v_sub_f32_e32 v29, v30, v32
	v_exp_f32_e32 v28, v28
	v_mul_f32_e32 v29, 0x3fb8aa3b, v29
	v_exp_f32_e32 v29, v29
	v_add_f32_e32 v30, v26, v31
	v_add_f32_e32 v30, v27, v30
	v_add_f32_e32 v30, v28, v30
	v_add_f32_e32 v30, v29, v30
	ds_bpermute_b32 v31, v123, v30
	v_lshrrev_b32_e32 v42, 1, v43
	v_and_b32_e32 v32, 24, v42
	v_lshrrev_b32_e32 v19, v32, v19
	v_lshlrev_b32_e32 v19, 7, v19
	s_waitcnt lgkmcnt(0)
	v_add_f32_e32 v30, v30, v31
	v_div_scale_f32 v31, s[12:13], v30, v30, 1.0
	v_rcp_f32_e32 v32, v31
	v_lshlrev_b32_e32 v33, 3, v43
	v_and_b32_e32 v19, 0x7f80, v19
	v_lshrrev_b32_e32 v18, v33, v18
	v_and_or_b32 v33, v18, s3, v19
	v_fma_f32 v18, -v31, v32, 1.0
	v_fmac_f32_e32 v32, v18, v32
	v_div_scale_f32 v18, vcc, 1.0, v30, 1.0
	v_mul_f32_e32 v19, v18, v32
	v_fma_f32 v34, -v31, v19, v18
	v_fmac_f32_e32 v19, v34, v32
	v_fma_f32 v18, -v31, v19, v18
	v_div_fmas_f32 v18, v18, v32, v19
	v_div_fixup_f32 v30, v18, v30, 1.0
	v_mov_b32_e32 v18, v1
	v_lshl_or_b32 v20, v20, 16, v39
	v_lshrrev_b32_e32 v19, 3, v18
	v_and_or_b32 v19, v19, 3, s57
	v_lshlrev_b32_e32 v31, 4, v18
	v_ashrrev_i32_e32 v18, 2, v18
	v_lshlrev_b32_e32 v19, 7, v19
	v_and_b32_e32 v31, 0x70, v31
	v_and_b32_e32 v18, -8, v18
	v_add3_u32 v18, v18, v31, v19
	v_lshl_add_u32 v31, v18, 1, s11
	v_lshl_add_u32 v32, v18, 2, s69
	v_lshl_or_b32 v18, v35, 16, v40
	v_lshl_or_b32 v19, v36, 16, v38
	v_lshl_or_b32 v21, v33, 16, v21
	ds_write_b128 v31, v[18:21]
	v_pk_mul_f32 v[20:21], v[24:25], v[30:31] op_sel_hi:[1,0]
	v_pk_mul_f32 v[18:19], v[22:23], v[30:31] op_sel_hi:[1,0]
	ds_write_b128 v32, v[18:21]
	v_pk_mul_f32 v[20:21], v[28:29], v[30:31] op_sel_hi:[1,0]
	v_pk_mul_f32 v[18:19], v[26:27], v[30:31] op_sel_hi:[1,0]
	ds_write_b128 v32, v[18:21] offset:16
	v_xor_b32_e32 v18, 4, v112
	v_cmp_lt_i32_e32 vcc, v18, v122
	s_waitcnt lgkmcnt(0)
	s_barrier
	v_cndmask_b32_e32 v18, v112, v18, vcc
	v_lshlrev_b32_e32 v30, 2, v18
	v_xor_b32_e32 v18, 2, v112
	v_cmp_lt_i32_e32 vcc, v18, v122
	s_nop 1
	v_cndmask_b32_e32 v18, v112, v18, vcc
	v_lshlrev_b32_e32 v31, 2, v18
	v_xor_b32_e32 v18, 1, v112
	v_cmp_lt_i32_e32 vcc, v18, v122
	s_nop 1
	v_cndmask_b32_e32 v18, v112, v18, vcc
	v_lshlrev_b32_e32 v32, 2, v18
	s_nop 0
	s_nop 0
	v_lshlrev_b32_e32 v56, 4, v1
	v_and_b32_e32 v56, 0x70, v56
	v_lshrrev_b32_e32 v59, 3, v1
	v_lshlrev_b32_e32 v59, 5, v59
	v_add_u32_e32 v59, s66, v59
	v_add_u32_e32 v59, -16, v59
	v_lshl_add_u32 v60, v1, 3, s64
	v_and_b32_e32 v38, 4, v1
	v_cmp_ne_u32_e64 s[10:11], 0, v38
	v_and_b32_e32 v38, 2, v1
	v_cmp_ne_u32_e64 s[12:13], 0, v38
	v_and_b32_e32 v38, 1, v1
	v_cmp_ne_u32_e64 s[14:15], 0, v38
	s_movk_i32 s94, 0x80
	s_mov_b32 s42, 0
	s_mov_b32 s43, 0
	s_mov_b32 s44, 1
	s_mov_b32 s45, 0
	s_lshl_b32 s32, s42, 11
	v_add_u32_e32 v39, s32, v59
	ds_read_b128 v[202:205], v39
	ds_read_b128 v[206:209], v39 offset:16
	s_lshl_b32 s46, s42, 3
	s_add_i32 s46, s46, s40
	s_lshl_b32 s46, s46, 9
	s_lshl_b32 s32, s43, 7
	s_add_i32 s46, s46, s32
	v_add_u32_e32 v57, s46, v56
	global_load_dwordx4 v[186:189], v57, s[34:35]
	global_load_dwordx4 v[190:193], v57, s[36:37]
	v_mov_b32_e32 v58, v56
	s_waitcnt lgkmcnt(0)
	v_and_b32_e32 v38, 0xffff, v202
	v_lshl_add_u32 v38, v38, 7, v58
	global_load_dwordx4 v[122:125], v38, s[96:97]
	v_lshrrev_b32_e32 v38, 16, v202
	v_lshl_add_u32 v38, v38, 7, v58
	global_load_dwordx4 v[126:129], v38, s[96:97]
	v_and_b32_e32 v38, 0xffff, v203
	v_lshl_add_u32 v38, v38, 7, v58
	global_load_dwordx4 v[130:133], v38, s[96:97]
	v_lshrrev_b32_e32 v38, 16, v203
	v_lshl_add_u32 v38, v38, 7, v58
	global_load_dwordx4 v[134:137], v38, s[96:97]
	v_and_b32_e32 v38, 0xffff, v204
	v_lshl_add_u32 v38, v38, 7, v58
	global_load_dwordx4 v[138:141], v38, s[96:97]
	v_lshrrev_b32_e32 v38, 16, v204
	v_lshl_add_u32 v38, v38, 7, v58
	global_load_dwordx4 v[142:145], v38, s[96:97]
	v_and_b32_e32 v38, 0xffff, v205
	v_lshl_add_u32 v38, v38, 7, v58
	global_load_dwordx4 v[146:149], v38, s[96:97]
	v_lshrrev_b32_e32 v38, 16, v205
	v_lshl_add_u32 v38, v38, 7, v58
	global_load_dwordx4 v[150:153], v38, s[96:97]
	v_and_b32_e32 v38, 0xffff, v206
	v_lshl_add_u32 v38, v38, 7, v58
	global_load_dwordx4 v[154:157], v38, s[96:97]
	v_lshrrev_b32_e32 v38, 16, v206
	v_lshl_add_u32 v38, v38, 7, v58
	global_load_dwordx4 v[158:161], v38, s[96:97]
	v_and_b32_e32 v38, 0xffff, v207
	v_lshl_add_u32 v38, v38, 7, v58
	global_load_dwordx4 v[162:165], v38, s[96:97]
	v_lshrrev_b32_e32 v38, 16, v207
	v_lshl_add_u32 v38, v38, 7, v58
	global_load_dwordx4 v[166:169], v38, s[96:97]
	v_and_b32_e32 v38, 0xffff, v208
	v_lshl_add_u32 v38, v38, 7, v58
	global_load_dwordx4 v[170:173], v38, s[96:97]
	v_lshrrev_b32_e32 v38, 16, v208
	v_lshl_add_u32 v38, v38, 7, v58
	global_load_dwordx4 v[174:177], v38, s[96:97]
	v_and_b32_e32 v38, 0xffff, v209
	v_lshl_add_u32 v38, v38, 7, v58
	global_load_dwordx4 v[178:181], v38, s[96:97]
	v_lshrrev_b32_e32 v38, 16, v209
	v_lshl_add_u32 v38, v38, 7, v58
	global_load_dwordx4 v[182:185], v38, s[96:97]
	s_mov_b32 s47, 15

; #define LAS __attribute__((address_space(3)))
; __global__ void __launch_bounds__(NTHR, 2) k_main(Args a) {
;     ...
;             for (int it = 0; it < 8; ++it) {
;                 const int tl = it * 8 + wave, t = j * 64 + tl;
;                 const unsigned ew = *(const LAS unsigned*)(EL + tl * 128 + 2 * lane); const int e0 = (int)(ew & 0xffffu), e1 = (int)(ew >> 16);
;                 typedef int i2v __attribute__((ext_vector_type(2))); const i2v si = *(const LAS i2v*)(ACC + tl * 128 + 2 * lane);
;                 typedef float f2v __attribute__((ext_vector_type(2))); const f2v gt = *(const LAS f2v*)(GL + tl * 128 + 2 * lane); const float xs = XS[t];
;                 const int sx = ((const int*)(XS + T))[t];
;                 const float z0 = (float)(2 * si.x + sx) * SU[e0] * xs, z1 = (float)(2 * si.y + sx) * SU[e1] * xs;
;                 const float a0 = gt.x * gelu_as(z0) * SV[e0], a1 = gt.y * gelu_as(z1) * SV[e1];
;                 const float mx = wave_max_dpp(fmaxf(fabsf(a0), fabsf(a1)));
;                 const float sc = mx > 0.f ? mx * (1.f / 119.f) : 1.f, inv = 1.f / sc;
;                 const int q0 = (int)rintf(a0 * inv), q1 = (int)rintf(a1 * inv);
;                 *(LAS unsigned short*)(AL + tl * 128 + 2 * lane) = (unsigned short)((q0 & 255) | ((q1 & 255) << 8));
;                 const int qs = wave_sum_dpp_i(q0 + q1);
;                 if (lane == 0) { ASC[tl] = sc; SAL[tl] = qs; }
.LBB0_674:
	s_nop 0
	s_nop 0
	s_nop 0
	s_nop 0
	s_nop 0
	s_nop 0
	s_nop 0
	s_nop 0
	s_nop 0
	s_nop 0
	s_nop 0
	s_nop 0
	s_nop 0
	s_nop 0
	s_ashr_i32 s41, s40, 31
	s_lshl_b64 s[10:11], s[40:41], 2
	s_add_u32 s14, s90, s10
	s_addc_u32 s15, s91, s11
	v_readlane_b32 s42, v235, 36
	v_readlane_b32 s43, v235, 37
	global_load_dword v78, v83, s[38:39] sc1
	v_add_u32_e32 v74, 0x16000, v91
	v_mov_b32_e32 v77, 3
	ds_read_b32 v18, v92
	ds_read_b32 v19, v92 offset:2048
	ds_read_b32 v20, v92 offset:4096
	ds_read_b32 v21, v92 offset:6144
	ds_read_b32 v22, v92 offset:8192
	ds_read_b32 v23, v92 offset:10240
	ds_read_b32 v24, v92 offset:12288
	ds_read_b32 v25, v92 offset:14336
	ds_read_b64 v[26:27], v91
	ds_read_b64 v[42:43], v74
	ds_read_b64 v[28:29], v91 offset:4096
	ds_read_b64 v[44:45], v74 offset:4096
	ds_read_b64 v[30:31], v91 offset:8192
	ds_read_b64 v[46:47], v74 offset:8192
	ds_read_b64 v[32:33], v91 offset:12288
	ds_read_b64 v[48:49], v74 offset:12288
	ds_read_b64 v[34:35], v91 offset:16384
	ds_read_b64 v[50:51], v74 offset:16384
	ds_read_b64 v[36:37], v91 offset:20480
	ds_read_b64 v[52:53], v74 offset:20480
	ds_read_b64 v[38:39], v91 offset:24576
	ds_read_b64 v[54:55], v74 offset:24576
	ds_read_b64 v[40:41], v91 offset:28672
	ds_read_b64 v[56:57], v74 offset:28672
	global_load_dword v58, v109, s[14:15]
	global_load_dword v66, v108, s[14:15]
	global_load_dword v59, v109, s[14:15] offset:32
	global_load_dword v67, v108, s[14:15] offset:32
	global_load_dword v60, v109, s[14:15] offset:64
	global_load_dword v68, v108, s[14:15] offset:64
	global_load_dword v61, v109, s[14:15] offset:96
	global_load_dword v69, v108, s[14:15] offset:96
	global_load_dword v62, v109, s[14:15] offset:128
	global_load_dword v70, v108, s[14:15] offset:128
	global_load_dword v63, v109, s[14:15] offset:160
	global_load_dword v71, v108, s[14:15] offset:160
	global_load_dword v64, v109, s[14:15] offset:192
	global_load_dword v72, v108, s[14:15] offset:192
	global_load_dword v65, v109, s[14:15] offset:224
	global_load_dword v73, v108, s[14:15] offset:224
	s_waitcnt lgkmcnt(0)
	v_lshlrev_b32_sdwa v75, v77, v18 dst_sel:DWORD dst_unused:UNUSED_PAD src0_sel:DWORD src1_sel:WORD_0
	v_lshlrev_b32_sdwa v76, v77, v18 dst_sel:DWORD dst_unused:UNUSED_PAD src0_sel:DWORD src1_sel:WORD_1
	s_nop 1
	global_load_dwordx2 v[122:123], v75, s[42:43]
	global_load_dwordx2 v[138:139], v76, s[42:43]
	v_lshlrev_b32_sdwa v75, v77, v19 dst_sel:DWORD dst_unused:UNUSED_PAD src0_sel:DWORD src1_sel:WORD_0
	v_lshlrev_b32_sdwa v76, v77, v19 dst_sel:DWORD dst_unused:UNUSED_PAD src0_sel:DWORD src1_sel:WORD_1
	s_nop 1
	global_load_dwordx2 v[124:125], v75, s[42:43]
	global_load_dwordx2 v[140:141], v76, s[42:43]
	v_lshlrev_b32_sdwa v75, v77, v20 dst_sel:DWORD dst_unused:UNUSED_PAD src0_sel:DWORD src1_sel:WORD_0
	v_lshlrev_b32_sdwa v76, v77, v20 dst_sel:DWORD dst_unused:UNUSED_PAD src0_sel:DWORD src1_sel:WORD_1
	s_nop 1
	global_load_dwordx2 v[126:127], v75, s[42:43]
	global_load_dwordx2 v[142:143], v76, s[42:43]
	v_lshlrev_b32_sdwa v75, v77, v21 dst_sel:DWORD dst_unused:UNUSED_PAD src0_sel:DWORD src1_sel:WORD_0
	v_lshlrev_b32_sdwa v76, v77, v21 dst_sel:DWORD dst_unused:UNUSED_PAD src0_sel:DWORD src1_sel:WORD_1
	s_nop 1
	global_load_dwordx2 v[128:129], v75, s[42:43]
	global_load_dwordx2 v[144:145], v76, s[42:43]
	v_lshlrev_b32_sdwa v75, v77, v22 dst_sel:DWORD dst_unused:UNUSED_PAD src0_sel:DWORD src1_sel:WORD_0
	v_lshlrev_b32_sdwa v76, v77, v22 dst_sel:DWORD dst_unused:UNUSED_PAD src0_sel:DWORD src1_sel:WORD_1
	s_nop 1
	global_load_dwordx2 v[130:131], v75, s[42:43]
	global_load_dwordx2 v[146:147], v76, s[42:43]
	v_lshlrev_b32_sdwa v75, v77, v23 dst_sel:DWORD dst_unused:UNUSED_PAD src0_sel:DWORD src1_sel:WORD_0
	v_lshlrev_b32_sdwa v76, v77, v23 dst_sel:DWORD dst_unused:UNUSED_PAD src0_sel:DWORD src1_sel:WORD_1
	s_nop 1
	global_load_dwordx2 v[132:133], v75, s[42:43]
	global_load_dwordx2 v[148:149], v76, s[42:43]
	v_lshlrev_b32_sdwa v75, v77, v24 dst_sel:DWORD dst_unused:UNUSED_PAD src0_sel:DWORD src1_sel:WORD_0
	v_lshlrev_b32_sdwa v76, v77, v24 dst_sel:DWORD dst_unused:UNUSED_PAD src0_sel:DWORD src1_sel:WORD_1
	s_nop 1
	global_load_dwordx2 v[134:135], v75, s[42:43]
	global_load_dwordx2 v[150:151], v76, s[42:43]
	v_lshlrev_b32_sdwa v75, v77, v25 dst_sel:DWORD dst_unused:UNUSED_PAD src0_sel:DWORD src1_sel:WORD_0
	v_lshlrev_b32_sdwa v76, v77, v25 dst_sel:DWORD dst_unused:UNUSED_PAD src0_sel:DWORD src1_sel:WORD_1
	s_nop 1
	global_load_dwordx2 v[136:137], v75, s[42:43]
	global_load_dwordx2 v[152:153], v76, s[42:43]
	s_waitcnt vmcnt(14)
; #define LAS __attribute__((address_space(3)))
; __device__ __forceinline__ float gelu_as(float z) {
;     const float ax = fabsf(z) * 0.70710678118654752f, t = __builtin_amdgcn_rcpf(1.f + 0.3275911f * ax);
;     const float poly = t * (0.254829592f + t * (-0.284496736f + t * (1.421413741f + t * (-1.453152027f + t * 1.061405429f))));
;     const float er = 1.f - poly * __expf(-ax * ax);
;     return 0.5f * z * (1.f + copysignf(er, z));
; }
; __global__ void __launch_bounds__(NTHR, 2) k_main(Args a) {
;     ...
;                 typedef float f2v __attribute__((ext_vector_type(2))); const f2v gt = *(const LAS f2v*)(GL + tl * 128 + 2 * lane); const float xs = XS[t];
;                 const int sx = ((const int*)(XS + T))[t];
;                 const float z0 = (float)(2 * si.x + sx) * SU[e0] * xs, z1 = (float)(2 * si.y + sx) * SU[e1] * xs;
;                 const float a0 = gt.x * gelu_as(z0) * SV[e0], a1 = gt.y * gelu_as(z1) * SV[e1];
;                 const float mx = wave_max_dpp(fmaxf(fabsf(a0), fabsf(a1)));
;                 const float sc = mx > 0.f ? mx * (1.f / 119.f) : 1.f, inv = 1.f / sc;
;                 const int q0 = (int)rintf(a0 * inv), q1 = (int)rintf(a1 * inv);
;                 *(LAS unsigned short*)(AL + tl * 128 + 2 * lane) = (unsigned short)((q0 & 255) | ((q1 & 255) << 8));
;                 const int qs = wave_sum_dpp_i(q0 + q1);
;                 if (lane == 0) { ASC[tl] = sc; SAL[tl] = qs; }
	v_lshl_add_u32 v154, v26, 1, v58
	v_lshl_add_u32 v155, v27, 1, v58
	v_cvt_f32_i32_e32 v154, v154
	v_cvt_f32_i32_e32 v155, v155
	v_mul_f32_e32 v154, v122, v154
	v_mul_f32_e32 v155, v138, v155
	v_mul_f32_e32 v154, v66, v154
	v_mul_f32_e32 v155, v66, v155
	v_mul_f32_e64 v156, |v154|, s82
	v_mul_f32_e64 v157, |v155|, s82
	v_fma_f32 v158, v156, s83, 1.0
	v_fma_f32 v159, v157, s83, 1.0
	v_rcp_f32_e32 v158, v158
	v_rcp_f32_e32 v159, v159
	v_mul_f32_e64 v156, v156, -v156
	v_mul_f32_e64 v157, v157, -v157
	v_mul_f32_e32 v156, 0x3fb8aa3b, v156
	v_mul_f32_e32 v157, 0x3fb8aa3b, v157
	v_fmamk_f32 v160, v158, 0x3f87dc22, v110
	v_fmamk_f32 v161, v159, 0x3f87dc22, v110
	v_exp_f32_e32 v156, v156
	v_exp_f32_e32 v157, v157
	v_fmaak_f32 v160, v158, v160, 0x3fb5f0e3
	v_fmaak_f32 v161, v159, v161, 0x3fb5f0e3
	v_fmaak_f32 v160, v158, v160, 0xbe91a98e
	v_fmaak_f32 v161, v159, v161, 0xbe91a98e
	v_fmaak_f32 v160, v158, v160, 0x3e827906
	v_fmaak_f32 v161, v159, v161, 0x3e827906
	v_mul_f32_e32 v158, v158, v160
	v_mul_f32_e32 v159, v159, v161
	v_fma_f32 v156, -v156, v158, 1.0
	v_fma_f32 v157, -v157, v159, 1.0
	v_mul_f32_e32 v162, 0.5, v154
	v_mul_f32_e32 v163, 0.5, v155
	v_bfi_b32 v154, s84, v156, v154
	v_bfi_b32 v155, s84, v157, v155
	v_add_f32_e32 v154, 1.0, v154
	v_add_f32_e32 v155, 1.0, v155
	v_mul_f32_e32 v154, v162, v154
	v_mul_f32_e32 v155, v163, v155
	v_mul_f32_e32 v154, v42, v154
	v_mul_f32_e32 v155, v43, v155
	v_mul_f32_e32 v154, v123, v154
	v_mul_f32_e32 v155, v139, v155
	v_max_f32_e64 v164, |v154|, |v155|
	s_nop 1
	v_max_f32_dpp v164, v164, v164 quad_perm:[1,0,3,2] row_mask:0xf bank_mask:0xf
	s_nop 1
	v_max_f32_dpp v164, v164, v164 quad_perm:[2,3,0,1] row_mask:0xf bank_mask:0xf
	s_nop 1
	v_max_f32_dpp v164, v164, v164 row_half_mirror row_mask:0xf bank_mask:0xf
	s_nop 1
	v_max_f32_dpp v164, v164, v164 row_mirror row_mask:0xf bank_mask:0xf
	s_nop 1
	v_readlane_b32 s46, v164, 32
	v_readlane_b32 s47, v164, 48
	v_readlane_b32 s12, v164, 0
	v_readlane_b32 s13, v164, 16
	s_nop 1
	v_mov_b32_e32 v164, s47
	v_max_f32_e32 v164, s46, v164
	v_mov_b32_e32 v165, s13
	v_max3_f32 v164, s12, v165, v164
	v_mul_f32_e32 v165, 0x3c09ae41, v164
	v_cmp_lt_f32_e32 vcc, 0, v164
	s_nop 1
	v_cndmask_b32_e32 v164, 1.0, v165, vcc
	v_div_scale_f32 v166, s[12:13], v164, v164, 1.0
	v_rcp_f32_e32 v167, v166
	v_div_scale_f32 v168, vcc, 1.0, v164, 1.0
	v_fma_f32 v169, -v166, v167, 1.0
	v_fmac_f32_e32 v167, v169, v167
	v_mul_f32_e32 v169, v168, v167
	v_fma_f32 v170, -v166, v169, v168
	v_fmac_f32_e32 v169, v170, v167
	v_fma_f32 v166, -v166, v169, v168
	v_div_fmas_f32 v166, v166, v167, v169
	v_div_fixup_f32 v166, v166, v164, 1.0
	v_mul_f32_e32 v154, v166, v154
	v_mul_f32_e32 v155, v166, v155
	v_rndne_f32_e32 v154, v154
	v_rndne_f32_e32 v155, v155
	v_cvt_i32_f32_e32 v154, v154
	v_cvt_i32_f32_e32 v155, v155
	v_perm_b32 v167, v155, v154, s85
	v_add_u32_e32 v154, v154, v155
	ds_write_b16 v90, v167
	s_nop 1
	v_add_u32_dpp v154, v154, v154 quad_perm:[1,0,3,2] row_mask:0xf bank_mask:0xf bound_ctrl:1
	s_nop 1
	v_add_u32_dpp v154, v154, v154 quad_perm:[2,3,0,1] row_mask:0xf bank_mask:0xf bound_ctrl:1
	s_nop 1
	v_add_u32_dpp v154, v154, v154 row_half_mirror row_mask:0xf bank_mask:0xf bound_ctrl:1
	s_nop 1
	v_add_u32_dpp v154, v154, v154 row_mirror row_mask:0xf bank_mask:0xf bound_ctrl:1
	s_nop 1
	v_readlane_b32 s46, v154, 0
	v_readlane_b32 s47, v154, 16
	v_readlane_b32 s12, v154, 32
	v_readlane_b32 s13, v154, 48
	s_nop 1
	s_add_i32 s46, s47, s46
	s_add_i32 s46, s46, s12
	s_add_i32 s46, s46, s13
	s_mov_b32 s47, s67
	s_and_saveexec_b64 s[12:13], s[8:9]
	v_mov_b32_e32 v154, s47
	v_mov_b32_e32 v155, s46
	ds_write2st64_b32 v154, v164, v155 offset1:1
	s_or_b64 exec, exec, s[12:13]
	s_waitcnt vmcnt(12)
	v_lshl_add_u32 v154, v28, 1, v59
	v_lshl_add_u32 v155, v29, 1, v59
	v_cvt_f32_i32_e32 v154, v154
	v_cvt_f32_i32_e32 v155, v155
	v_mul_f32_e32 v154, v124, v154
	v_mul_f32_e32 v155, v140, v155
	v_mul_f32_e32 v154, v67, v154
	v_mul_f32_e32 v155, v67, v155
	v_mul_f32_e64 v156, |v154|, s82
	v_mul_f32_e64 v157, |v155|, s82
	v_fma_f32 v158, v156, s83, 1.0
	v_fma_f32 v159, v157, s83, 1.0
	v_rcp_f32_e32 v158, v158
	v_rcp_f32_e32 v159, v159
	v_mul_f32_e64 v156, v156, -v156
	v_mul_f32_e64 v157, v157, -v157
	v_mul_f32_e32 v156, 0x3fb8aa3b, v156
	v_mul_f32_e32 v157, 0x3fb8aa3b, v157
	v_fmamk_f32 v160, v158, 0x3f87dc22, v110
	v_fmamk_f32 v161, v159, 0x3f87dc22, v110
	v_exp_f32_e32 v156, v156
	v_exp_f32_e32 v157, v157
	v_fmaak_f32 v160, v158, v160, 0x3fb5f0e3
	v_fmaak_f32 v161, v159, v161, 0x3fb5f0e3
	v_fmaak_f32 v160, v158, v160, 0xbe91a98e
	v_fmaak_f32 v161, v159, v161, 0xbe91a98e
	v_fmaak_f32 v160, v158, v160, 0x3e827906
	v_fmaak_f32 v161, v159, v161, 0x3e827906
	v_mul_f32_e32 v158, v158, v160
	v_mul_f32_e32 v159, v159, v161
	v_fma_f32 v156, -v156, v158, 1.0
	v_fma_f32 v157, -v157, v159, 1.0
	v_mul_f32_e32 v162, 0.5, v154
	v_mul_f32_e32 v163, 0.5, v155
	v_bfi_b32 v154, s84, v156, v154
	v_bfi_b32 v155, s84, v157, v155
	v_add_f32_e32 v154, 1.0, v154
	v_add_f32_e32 v155, 1.0, v155
	v_mul_f32_e32 v154, v162, v154
	v_mul_f32_e32 v155, v163, v155
	v_mul_f32_e32 v154, v44, v154
	v_mul_f32_e32 v155, v45, v155
	v_mul_f32_e32 v154, v125, v154
	v_mul_f32_e32 v155, v141, v155
	v_max_f32_e64 v164, |v154|, |v155|
	s_nop 1
	v_max_f32_dpp v164, v164, v164 quad_perm:[1,0,3,2] row_mask:0xf bank_mask:0xf
	s_nop 1
	v_max_f32_dpp v164, v164, v164 quad_perm:[2,3,0,1] row_mask:0xf bank_mask:0xf
	s_nop 1
	v_max_f32_dpp v164, v164, v164 row_half_mirror row_mask:0xf bank_mask:0xf
	s_nop 1
	v_max_f32_dpp v164, v164, v164 row_mirror row_mask:0xf bank_mask:0xf
	s_nop 1
	v_readlane_b32 s46, v164, 32
	v_readlane_b32 s47, v164, 48
	v_readlane_b32 s12, v164, 0
; #define LAS __attribute__((address_space(3)))
; __device__ __forceinline__ float gelu_as(float z) {
;     const float ax = fabsf(z) * 0.70710678118654752f, t = __builtin_amdgcn_rcpf(1.f + 0.3275911f * ax);
;     const float poly = t * (0.254829592f + t * (-0.284496736f + t * (1.421413741f + t * (-1.453152027f + t * 1.061405429f))));
;     const float er = 1.f - poly * __expf(-ax * ax);
;     return 0.5f * z * (1.f + copysignf(er, z));
; }
; __global__ void __launch_bounds__(NTHR, 2) k_main(Args a) {
;     ...
;                 typedef float f2v __attribute__((ext_vector_type(2))); const f2v gt = *(const LAS f2v*)(GL + tl * 128 + 2 * lane); const float xs = XS[t];
;                 const int sx = ((const int*)(XS + T))[t];
;                 const float z0 = (float)(2 * si.x + sx) * SU[e0] * xs, z1 = (float)(2 * si.y + sx) * SU[e1] * xs;
;                 const float a0 = gt.x * gelu_as(z0) * SV[e0], a1 = gt.y * gelu_as(z1) * SV[e1];
;                 const float mx = wave_max_dpp(fmaxf(fabsf(a0), fabsf(a1)));
;                 const float sc = mx > 0.f ? mx * (1.f / 119.f) : 1.f, inv = 1.f / sc;
;                 const int q0 = (int)rintf(a0 * inv), q1 = (int)rintf(a1 * inv);
;                 *(LAS unsigned short*)(AL + tl * 128 + 2 * lane) = (unsigned short)((q0 & 255) | ((q1 & 255) << 8));
;                 const int qs = wave_sum_dpp_i(q0 + q1);
;                 if (lane == 0) { ASC[tl] = sc; SAL[tl] = qs; }
	v_readlane_b32 s13, v164, 16
	s_nop 1
	v_mov_b32_e32 v164, s47
	v_max_f32_e32 v164, s46, v164
	v_mov_b32_e32 v165, s13
	v_max3_f32 v164, s12, v165, v164
	v_mul_f32_e32 v165, 0x3c09ae41, v164
	v_cmp_lt_f32_e32 vcc, 0, v164
	s_nop 1
	v_cndmask_b32_e32 v164, 1.0, v165, vcc
	v_div_scale_f32 v166, s[12:13], v164, v164, 1.0
	v_rcp_f32_e32 v167, v166
	v_div_scale_f32 v168, vcc, 1.0, v164, 1.0
	v_fma_f32 v169, -v166, v167, 1.0
	v_fmac_f32_e32 v167, v169, v167
	v_mul_f32_e32 v169, v168, v167
	v_fma_f32 v170, -v166, v169, v168
	v_fmac_f32_e32 v169, v170, v167
	v_fma_f32 v166, -v166, v169, v168
	v_div_fmas_f32 v166, v166, v167, v169
	v_div_fixup_f32 v166, v166, v164, 1.0
	v_mul_f32_e32 v154, v166, v154
	v_mul_f32_e32 v155, v166, v155
	v_rndne_f32_e32 v154, v154
	v_rndne_f32_e32 v155, v155
	v_cvt_i32_f32_e32 v154, v154
	v_cvt_i32_f32_e32 v155, v155
	v_perm_b32 v167, v155, v154, s85
	v_add_u32_e32 v154, v154, v155
	ds_write_b16 v90, v167 offset:1024
	s_nop 1
	v_add_u32_dpp v154, v154, v154 quad_perm:[1,0,3,2] row_mask:0xf bank_mask:0xf bound_ctrl:1
	s_nop 1
	v_add_u32_dpp v154, v154, v154 quad_perm:[2,3,0,1] row_mask:0xf bank_mask:0xf bound_ctrl:1
	s_nop 1
	v_add_u32_dpp v154, v154, v154 row_half_mirror row_mask:0xf bank_mask:0xf bound_ctrl:1
	s_nop 1
	v_add_u32_dpp v154, v154, v154 row_mirror row_mask:0xf bank_mask:0xf bound_ctrl:1
	s_nop 1
	v_readlane_b32 s46, v154, 0
	v_readlane_b32 s47, v154, 16
	v_readlane_b32 s12, v154, 32
	v_readlane_b32 s13, v154, 48
	s_nop 1
	s_add_i32 s46, s47, s46
	s_add_i32 s46, s46, s12
	s_add_i32 s46, s46, s13
	s_add_i32 s47, s67, 32
	s_and_saveexec_b64 s[12:13], s[8:9]
	v_mov_b32_e32 v154, s47
	v_mov_b32_e32 v155, s46
	ds_write2st64_b32 v154, v164, v155 offset1:1
	s_or_b64 exec, exec, s[12:13]
	s_waitcnt vmcnt(10)
	v_lshl_add_u32 v154, v30, 1, v60
	v_lshl_add_u32 v155, v31, 1, v60
	v_cvt_f32_i32_e32 v154, v154
	v_cvt_f32_i32_e32 v155, v155
	v_mul_f32_e32 v154, v126, v154
	v_mul_f32_e32 v155, v142, v155
	v_mul_f32_e32 v154, v68, v154
	v_mul_f32_e32 v155, v68, v155
	v_mul_f32_e64 v156, |v154|, s82
	v_mul_f32_e64 v157, |v155|, s82
	v_fma_f32 v158, v156, s83, 1.0
	v_fma_f32 v159, v157, s83, 1.0
	v_rcp_f32_e32 v158, v158
	v_rcp_f32_e32 v159, v159
	v_mul_f32_e64 v156, v156, -v156
	v_mul_f32_e64 v157, v157, -v157
	v_mul_f32_e32 v156, 0x3fb8aa3b, v156
	v_mul_f32_e32 v157, 0x3fb8aa3b, v157
	v_fmamk_f32 v160, v158, 0x3f87dc22, v110
	v_fmamk_f32 v161, v159, 0x3f87dc22, v110
	v_exp_f32_e32 v156, v156
	v_exp_f32_e32 v157, v157
	v_fmaak_f32 v160, v158, v160, 0x3fb5f0e3
	v_fmaak_f32 v161, v159, v161, 0x3fb5f0e3
	v_fmaak_f32 v160, v158, v160, 0xbe91a98e
	v_fmaak_f32 v161, v159, v161, 0xbe91a98e
	v_fmaak_f32 v160, v158, v160, 0x3e827906
	v_fmaak_f32 v161, v159, v161, 0x3e827906
	v_mul_f32_e32 v158, v158, v160
	v_mul_f32_e32 v159, v159, v161
	v_fma_f32 v156, -v156, v158, 1.0
	v_fma_f32 v157, -v157, v159, 1.0
	v_mul_f32_e32 v162, 0.5, v154
	v_mul_f32_e32 v163, 0.5, v155
	v_bfi_b32 v154, s84, v156, v154
	v_bfi_b32 v155, s84, v157, v155
	v_add_f32_e32 v154, 1.0, v154
	v_add_f32_e32 v155, 1.0, v155
	v_mul_f32_e32 v154, v162, v154
	v_mul_f32_e32 v155, v163, v155
	v_mul_f32_e32 v154, v46, v154
	v_mul_f32_e32 v155, v47, v155
	v_mul_f32_e32 v154, v127, v154
	v_mul_f32_e32 v155, v143, v155
	v_max_f32_e64 v164, |v154|, |v155|
	s_nop 1
	v_max_f32_dpp v164, v164, v164 quad_perm:[1,0,3,2] row_mask:0xf bank_mask:0xf
	s_nop 1
	v_max_f32_dpp v164, v164, v164 quad_perm:[2,3,0,1] row_mask:0xf bank_mask:0xf
	s_nop 1
	v_max_f32_dpp v164, v164, v164 row_half_mirror row_mask:0xf bank_mask:0xf
	s_nop 1
	v_max_f32_dpp v164, v164, v164 row_mirror row_mask:0xf bank_mask:0xf
	s_nop 1
	v_readlane_b32 s46, v164, 32
	v_readlane_b32 s47, v164, 48
	v_readlane_b32 s12, v164, 0
	v_readlane_b32 s13, v164, 16
	s_nop 1
	v_mov_b32_e32 v164, s47
	v_max_f32_e32 v164, s46, v164
	v_mov_b32_e32 v165, s13
	v_max3_f32 v164, s12, v165, v164
	v_mul_f32_e32 v165, 0x3c09ae41, v164
	v_cmp_lt_f32_e32 vcc, 0, v164
	s_nop 1
	v_cndmask_b32_e32 v164, 1.0, v165, vcc
	v_div_scale_f32 v166, s[12:13], v164, v164, 1.0
	v_rcp_f32_e32 v167, v166
	v_div_scale_f32 v168, vcc, 1.0, v164, 1.0
	v_fma_f32 v169, -v166, v167, 1.0
	v_fmac_f32_e32 v167, v169, v167
	v_mul_f32_e32 v169, v168, v167
	v_fma_f32 v170, -v166, v169, v168
	v_fmac_f32_e32 v169, v170, v167
	v_fma_f32 v166, -v166, v169, v168
	v_div_fmas_f32 v166, v166, v167, v169
	v_div_fixup_f32 v166, v166, v164, 1.0
	v_mul_f32_e32 v154, v166, v154
	v_mul_f32_e32 v155, v166, v155
	v_rndne_f32_e32 v154, v154
	v_rndne_f32_e32 v155, v155
	v_cvt_i32_f32_e32 v154, v154
	v_cvt_i32_f32_e32 v155, v155
	v_perm_b32 v167, v155, v154, s85
	v_add_u32_e32 v154, v154, v155
	ds_write_b16 v90, v167 offset:2048
	s_nop 1
	v_add_u32_dpp v154, v154, v154 quad_perm:[1,0,3,2] row_mask:0xf bank_mask:0xf bound_ctrl:1
	s_nop 1
	v_add_u32_dpp v154, v154, v154 quad_perm:[2,3,0,1] row_mask:0xf bank_mask:0xf bound_ctrl:1
	s_nop 1
	v_add_u32_dpp v154, v154, v154 row_half_mirror row_mask:0xf bank_mask:0xf bound_ctrl:1
	s_nop 1
	v_add_u32_dpp v154, v154, v154 row_mirror row_mask:0xf bank_mask:0xf bound_ctrl:1
	s_nop 1
	v_readlane_b32 s46, v154, 0
	v_readlane_b32 s47, v154, 16
	v_readlane_b32 s12, v154, 32
	v_readlane_b32 s13, v154, 48
	s_nop 1
	s_add_i32 s46, s47, s46
	s_add_i32 s46, s46, s12
	s_add_i32 s46, s46, s13
	s_add_i32 s47, s67, 64
	s_and_saveexec_b64 s[12:13], s[8:9]
	v_mov_b32_e32 v154, s47
	v_mov_b32_e32 v155, s46
	ds_write2st64_b32 v154, v164, v155 offset1:1
	s_or_b64 exec, exec, s[12:13]
	s_waitcnt vmcnt(8)
; #define LAS __attribute__((address_space(3)))
; __device__ __forceinline__ float gelu_as(float z) {
;     const float ax = fabsf(z) * 0.70710678118654752f, t = __builtin_amdgcn_rcpf(1.f + 0.3275911f * ax);
;     const float poly = t * (0.254829592f + t * (-0.284496736f + t * (1.421413741f + t * (-1.453152027f + t * 1.061405429f))));
;     const float er = 1.f - poly * __expf(-ax * ax);
;     return 0.5f * z * (1.f + copysignf(er, z));
; }
; __global__ void __launch_bounds__(NTHR, 2) k_main(Args a) {
;     ...
;                 const unsigned ew = *(const LAS unsigned*)(EL + tl * 128 + 2 * lane); const int e0 = (int)(ew & 0xffffu), e1 = (int)(ew >> 16);
;                 typedef int i2v __attribute__((ext_vector_type(2))); const i2v si = *(const LAS i2v*)(ACC + tl * 128 + 2 * lane);
;                 typedef float f2v __attribute__((ext_vector_type(2))); const f2v gt = *(const LAS f2v*)(GL + tl * 128 + 2 * lane); const float xs = XS[t];
;                 const int sx = ((const int*)(XS + T))[t];
;                 const float z0 = (float)(2 * si.x + sx) * SU[e0] * xs, z1 = (float)(2 * si.y + sx) * SU[e1] * xs;
;                 const float a0 = gt.x * gelu_as(z0) * SV[e0], a1 = gt.y * gelu_as(z1) * SV[e1];
;                 const float mx = wave_max_dpp(fmaxf(fabsf(a0), fabsf(a1)));
;                 const float sc = mx > 0.f ? mx * (1.f / 119.f) : 1.f, inv = 1.f / sc;
;                 const int q0 = (int)rintf(a0 * inv), q1 = (int)rintf(a1 * inv);
;                 *(LAS unsigned short*)(AL + tl * 128 + 2 * lane) = (unsigned short)((q0 & 255) | ((q1 & 255) << 8));
;                 const int qs = wave_sum_dpp_i(q0 + q1);
;                 if (lane == 0) { ASC[tl] = sc; SAL[tl] = qs; }
	v_lshl_add_u32 v154, v32, 1, v61
	v_lshl_add_u32 v155, v33, 1, v61
	v_cvt_f32_i32_e32 v154, v154
	v_cvt_f32_i32_e32 v155, v155
	v_mul_f32_e32 v154, v128, v154
	v_mul_f32_e32 v155, v144, v155
	v_mul_f32_e32 v154, v69, v154
	v_mul_f32_e32 v155, v69, v155
	v_mul_f32_e64 v156, |v154|, s82
	v_mul_f32_e64 v157, |v155|, s82
	v_fma_f32 v158, v156, s83, 1.0
	v_fma_f32 v159, v157, s83, 1.0
	v_rcp_f32_e32 v158, v158
	v_rcp_f32_e32 v159, v159
	v_mul_f32_e64 v156, v156, -v156
	v_mul_f32_e64 v157, v157, -v157
	v_mul_f32_e32 v156, 0x3fb8aa3b, v156
	v_mul_f32_e32 v157, 0x3fb8aa3b, v157
	v_fmamk_f32 v160, v158, 0x3f87dc22, v110
	v_fmamk_f32 v161, v159, 0x3f87dc22, v110
	v_exp_f32_e32 v156, v156
	v_exp_f32_e32 v157, v157
	v_fmaak_f32 v160, v158, v160, 0x3fb5f0e3
	v_fmaak_f32 v161, v159, v161, 0x3fb5f0e3
	v_fmaak_f32 v160, v158, v160, 0xbe91a98e
	v_fmaak_f32 v161, v159, v161, 0xbe91a98e
	v_fmaak_f32 v160, v158, v160, 0x3e827906
	v_fmaak_f32 v161, v159, v161, 0x3e827906
	v_mul_f32_e32 v158, v158, v160
	v_mul_f32_e32 v159, v159, v161
	v_fma_f32 v156, -v156, v158, 1.0
	v_fma_f32 v157, -v157, v159, 1.0
	v_mul_f32_e32 v162, 0.5, v154
	v_mul_f32_e32 v163, 0.5, v155
	v_bfi_b32 v154, s84, v156, v154
	v_bfi_b32 v155, s84, v157, v155
	v_add_f32_e32 v154, 1.0, v154
	v_add_f32_e32 v155, 1.0, v155
	v_mul_f32_e32 v154, v162, v154
	v_mul_f32_e32 v155, v163, v155
	v_mul_f32_e32 v154, v48, v154
	v_mul_f32_e32 v155, v49, v155
	v_mul_f32_e32 v154, v129, v154
	v_mul_f32_e32 v155, v145, v155
	v_max_f32_e64 v164, |v154|, |v155|
	s_nop 1
	v_max_f32_dpp v164, v164, v164 quad_perm:[1,0,3,2] row_mask:0xf bank_mask:0xf
	s_nop 1
	v_max_f32_dpp v164, v164, v164 quad_perm:[2,3,0,1] row_mask:0xf bank_mask:0xf
	s_nop 1
	v_max_f32_dpp v164, v164, v164 row_half_mirror row_mask:0xf bank_mask:0xf
	s_nop 1
	v_max_f32_dpp v164, v164, v164 row_mirror row_mask:0xf bank_mask:0xf
	s_nop 1
	v_readlane_b32 s46, v164, 32
	v_readlane_b32 s47, v164, 48
	v_readlane_b32 s12, v164, 0
	v_readlane_b32 s13, v164, 16
	s_nop 1
	v_mov_b32_e32 v164, s47
	v_max_f32_e32 v164, s46, v164
	v_mov_b32_e32 v165, s13
	v_max3_f32 v164, s12, v165, v164
	v_mul_f32_e32 v165, 0x3c09ae41, v164
	v_cmp_lt_f32_e32 vcc, 0, v164
	s_nop 1
	v_cndmask_b32_e32 v164, 1.0, v165, vcc
	v_div_scale_f32 v166, s[12:13], v164, v164, 1.0
	v_rcp_f32_e32 v167, v166
	v_div_scale_f32 v168, vcc, 1.0, v164, 1.0
	v_fma_f32 v169, -v166, v167, 1.0
	v_fmac_f32_e32 v167, v169, v167
	v_mul_f32_e32 v169, v168, v167
	v_fma_f32 v170, -v166, v169, v168
	v_fmac_f32_e32 v169, v170, v167
	v_fma_f32 v166, -v166, v169, v168
	v_div_fmas_f32 v166, v166, v167, v169
	v_div_fixup_f32 v166, v166, v164, 1.0
	v_mul_f32_e32 v154, v166, v154
	v_mul_f32_e32 v155, v166, v155
	v_rndne_f32_e32 v154, v154
	v_rndne_f32_e32 v155, v155
	v_cvt_i32_f32_e32 v154, v154
	v_cvt_i32_f32_e32 v155, v155
	v_perm_b32 v167, v155, v154, s85
	v_add_u32_e32 v154, v154, v155
	ds_write_b16 v90, v167 offset:3072
	s_nop 1
	v_add_u32_dpp v154, v154, v154 quad_perm:[1,0,3,2] row_mask:0xf bank_mask:0xf bound_ctrl:1
	s_nop 1
	v_add_u32_dpp v154, v154, v154 quad_perm:[2,3,0,1] row_mask:0xf bank_mask:0xf bound_ctrl:1
	s_nop 1
	v_add_u32_dpp v154, v154, v154 row_half_mirror row_mask:0xf bank_mask:0xf bound_ctrl:1
	s_nop 1
	v_add_u32_dpp v154, v154, v154 row_mirror row_mask:0xf bank_mask:0xf bound_ctrl:1
	s_nop 1
	v_readlane_b32 s46, v154, 0
	v_readlane_b32 s47, v154, 16
	v_readlane_b32 s12, v154, 32
	v_readlane_b32 s13, v154, 48
	s_nop 1
	s_add_i32 s46, s47, s46
	s_add_i32 s46, s46, s12
	s_add_i32 s46, s46, s13
	s_add_i32 s47, s67, 96
	s_and_saveexec_b64 s[12:13], s[8:9]
	v_mov_b32_e32 v154, s47
	v_mov_b32_e32 v155, s46
	ds_write2st64_b32 v154, v164, v155 offset1:1
	s_or_b64 exec, exec, s[12:13]
	s_waitcnt vmcnt(6)
	v_lshl_add_u32 v154, v34, 1, v62
	v_lshl_add_u32 v155, v35, 1, v62
	v_cvt_f32_i32_e32 v154, v154
	v_cvt_f32_i32_e32 v155, v155
	v_mul_f32_e32 v154, v130, v154
	v_mul_f32_e32 v155, v146, v155
	v_mul_f32_e32 v154, v70, v154
	v_mul_f32_e32 v155, v70, v155
	v_mul_f32_e64 v156, |v154|, s82
	v_mul_f32_e64 v157, |v155|, s82
	v_fma_f32 v158, v156, s83, 1.0
	v_fma_f32 v159, v157, s83, 1.0
	v_rcp_f32_e32 v158, v158
	v_rcp_f32_e32 v159, v159
	v_mul_f32_e64 v156, v156, -v156
	v_mul_f32_e64 v157, v157, -v157
	v_mul_f32_e32 v156, 0x3fb8aa3b, v156
	v_mul_f32_e32 v157, 0x3fb8aa3b, v157
	v_fmamk_f32 v160, v158, 0x3f87dc22, v110
	v_fmamk_f32 v161, v159, 0x3f87dc22, v110
	v_exp_f32_e32 v156, v156
	v_exp_f32_e32 v157, v157
	v_fmaak_f32 v160, v158, v160, 0x3fb5f0e3
	v_fmaak_f32 v161, v159, v161, 0x3fb5f0e3
	v_fmaak_f32 v160, v158, v160, 0xbe91a98e
	v_fmaak_f32 v161, v159, v161, 0xbe91a98e
	v_fmaak_f32 v160, v158, v160, 0x3e827906
	v_fmaak_f32 v161, v159, v161, 0x3e827906
	v_mul_f32_e32 v158, v158, v160
	v_mul_f32_e32 v159, v159, v161
	v_fma_f32 v156, -v156, v158, 1.0
	v_fma_f32 v157, -v157, v159, 1.0
	v_mul_f32_e32 v162, 0.5, v154
	v_mul_f32_e32 v163, 0.5, v155
	v_bfi_b32 v154, s84, v156, v154
	v_bfi_b32 v155, s84, v157, v155
	v_add_f32_e32 v154, 1.0, v154
	v_add_f32_e32 v155, 1.0, v155
	v_mul_f32_e32 v154, v162, v154
	v_mul_f32_e32 v155, v163, v155
	v_mul_f32_e32 v154, v50, v154
	v_mul_f32_e32 v155, v51, v155
	v_mul_f32_e32 v154, v131, v154
	v_mul_f32_e32 v155, v147, v155
	v_max_f32_e64 v164, |v154|, |v155|
	s_nop 1
	v_max_f32_dpp v164, v164, v164 quad_perm:[1,0,3,2] row_mask:0xf bank_mask:0xf
	s_nop 1
	v_max_f32_dpp v164, v164, v164 quad_perm:[2,3,0,1] row_mask:0xf bank_mask:0xf
	s_nop 1
	v_max_f32_dpp v164, v164, v164 row_half_mirror row_mask:0xf bank_mask:0xf
	s_nop 1
	v_max_f32_dpp v164, v164, v164 row_mirror row_mask:0xf bank_mask:0xf
	s_nop 1
	v_readlane_b32 s46, v164, 32
	v_readlane_b32 s47, v164, 48
; #define LAS __attribute__((address_space(3)))
; __device__ __forceinline__ float gelu_as(float z) {
;     const float ax = fabsf(z) * 0.70710678118654752f, t = __builtin_amdgcn_rcpf(1.f + 0.3275911f * ax);
;     const float poly = t * (0.254829592f + t * (-0.284496736f + t * (1.421413741f + t * (-1.453152027f + t * 1.061405429f))));
;     const float er = 1.f - poly * __expf(-ax * ax);
;     return 0.5f * z * (1.f + copysignf(er, z));
; }
; __global__ void __launch_bounds__(NTHR, 2) k_main(Args a) {
;     ...
;                 const unsigned ew = *(const LAS unsigned*)(EL + tl * 128 + 2 * lane); const int e0 = (int)(ew & 0xffffu), e1 = (int)(ew >> 16);
;                 typedef int i2v __attribute__((ext_vector_type(2))); const i2v si = *(const LAS i2v*)(ACC + tl * 128 + 2 * lane);
;                 typedef float f2v __attribute__((ext_vector_type(2))); const f2v gt = *(const LAS f2v*)(GL + tl * 128 + 2 * lane); const float xs = XS[t];
;                 const int sx = ((const int*)(XS + T))[t];
;                 const float z0 = (float)(2 * si.x + sx) * SU[e0] * xs, z1 = (float)(2 * si.y + sx) * SU[e1] * xs;
;                 const float a0 = gt.x * gelu_as(z0) * SV[e0], a1 = gt.y * gelu_as(z1) * SV[e1];
;                 const float mx = wave_max_dpp(fmaxf(fabsf(a0), fabsf(a1)));
;                 const float sc = mx > 0.f ? mx * (1.f / 119.f) : 1.f, inv = 1.f / sc;
;                 const int q0 = (int)rintf(a0 * inv), q1 = (int)rintf(a1 * inv);
;                 *(LAS unsigned short*)(AL + tl * 128 + 2 * lane) = (unsigned short)((q0 & 255) | ((q1 & 255) << 8));
;                 const int qs = wave_sum_dpp_i(q0 + q1);
;                 if (lane == 0) { ASC[tl] = sc; SAL[tl] = qs; }
	v_readlane_b32 s12, v164, 0
	v_readlane_b32 s13, v164, 16
	s_nop 1
	v_mov_b32_e32 v164, s47
	v_max_f32_e32 v164, s46, v164
	v_mov_b32_e32 v165, s13
	v_max3_f32 v164, s12, v165, v164
	v_mul_f32_e32 v165, 0x3c09ae41, v164
	v_cmp_lt_f32_e32 vcc, 0, v164
	s_nop 1
	v_cndmask_b32_e32 v164, 1.0, v165, vcc
	v_div_scale_f32 v166, s[12:13], v164, v164, 1.0
	v_rcp_f32_e32 v167, v166
	v_div_scale_f32 v168, vcc, 1.0, v164, 1.0
	v_fma_f32 v169, -v166, v167, 1.0
	v_fmac_f32_e32 v167, v169, v167
	v_mul_f32_e32 v169, v168, v167
	v_fma_f32 v170, -v166, v169, v168
	v_fmac_f32_e32 v169, v170, v167
	v_fma_f32 v166, -v166, v169, v168
	v_div_fmas_f32 v166, v166, v167, v169
	v_div_fixup_f32 v166, v166, v164, 1.0
	v_mul_f32_e32 v154, v166, v154
	v_mul_f32_e32 v155, v166, v155
	v_rndne_f32_e32 v154, v154
	v_rndne_f32_e32 v155, v155
	v_cvt_i32_f32_e32 v154, v154
	v_cvt_i32_f32_e32 v155, v155
	v_perm_b32 v167, v155, v154, s85
	v_add_u32_e32 v154, v154, v155
	ds_write_b16 v90, v167 offset:4096
	s_nop 1
	v_add_u32_dpp v154, v154, v154 quad_perm:[1,0,3,2] row_mask:0xf bank_mask:0xf bound_ctrl:1
	s_nop 1
	v_add_u32_dpp v154, v154, v154 quad_perm:[2,3,0,1] row_mask:0xf bank_mask:0xf bound_ctrl:1
	s_nop 1
	v_add_u32_dpp v154, v154, v154 row_half_mirror row_mask:0xf bank_mask:0xf bound_ctrl:1
	s_nop 1
	v_add_u32_dpp v154, v154, v154 row_mirror row_mask:0xf bank_mask:0xf bound_ctrl:1
	s_nop 1
	v_readlane_b32 s46, v154, 0
	v_readlane_b32 s47, v154, 16
	v_readlane_b32 s12, v154, 32
	v_readlane_b32 s13, v154, 48
	s_nop 1
	s_add_i32 s46, s47, s46
	s_add_i32 s46, s46, s12
	s_add_i32 s46, s46, s13
	s_add_i32 s47, s67, 128
	s_and_saveexec_b64 s[12:13], s[8:9]
	v_mov_b32_e32 v154, s47
	v_mov_b32_e32 v155, s46
	ds_write2st64_b32 v154, v164, v155 offset1:1
	s_or_b64 exec, exec, s[12:13]
	s_waitcnt vmcnt(4)
	v_lshl_add_u32 v154, v36, 1, v63
	v_lshl_add_u32 v155, v37, 1, v63
	v_cvt_f32_i32_e32 v154, v154
	v_cvt_f32_i32_e32 v155, v155
	v_mul_f32_e32 v154, v132, v154
	v_mul_f32_e32 v155, v148, v155
	v_mul_f32_e32 v154, v71, v154
	v_mul_f32_e32 v155, v71, v155
	v_mul_f32_e64 v156, |v154|, s82
	v_mul_f32_e64 v157, |v155|, s82
	v_fma_f32 v158, v156, s83, 1.0
	v_fma_f32 v159, v157, s83, 1.0
	v_rcp_f32_e32 v158, v158
	v_rcp_f32_e32 v159, v159
	v_mul_f32_e64 v156, v156, -v156
	v_mul_f32_e64 v157, v157, -v157
	v_mul_f32_e32 v156, 0x3fb8aa3b, v156
	v_mul_f32_e32 v157, 0x3fb8aa3b, v157
	v_fmamk_f32 v160, v158, 0x3f87dc22, v110
	v_fmamk_f32 v161, v159, 0x3f87dc22, v110
	v_exp_f32_e32 v156, v156
	v_exp_f32_e32 v157, v157
	v_fmaak_f32 v160, v158, v160, 0x3fb5f0e3
	v_fmaak_f32 v161, v159, v161, 0x3fb5f0e3
	v_fmaak_f32 v160, v158, v160, 0xbe91a98e
	v_fmaak_f32 v161, v159, v161, 0xbe91a98e
	v_fmaak_f32 v160, v158, v160, 0x3e827906
	v_fmaak_f32 v161, v159, v161, 0x3e827906
	v_mul_f32_e32 v158, v158, v160
	v_mul_f32_e32 v159, v159, v161
	v_fma_f32 v156, -v156, v158, 1.0
	v_fma_f32 v157, -v157, v159, 1.0
	v_mul_f32_e32 v162, 0.5, v154
	v_mul_f32_e32 v163, 0.5, v155
	v_bfi_b32 v154, s84, v156, v154
	v_bfi_b32 v155, s84, v157, v155
	v_add_f32_e32 v154, 1.0, v154
	v_add_f32_e32 v155, 1.0, v155
	v_mul_f32_e32 v154, v162, v154
	v_mul_f32_e32 v155, v163, v155
	v_mul_f32_e32 v154, v52, v154
	v_mul_f32_e32 v155, v53, v155
	v_mul_f32_e32 v154, v133, v154
	v_mul_f32_e32 v155, v149, v155
	v_max_f32_e64 v164, |v154|, |v155|
	s_nop 1
	v_max_f32_dpp v164, v164, v164 quad_perm:[1,0,3,2] row_mask:0xf bank_mask:0xf
	s_nop 1
	v_max_f32_dpp v164, v164, v164 quad_perm:[2,3,0,1] row_mask:0xf bank_mask:0xf
	s_nop 1
	v_max_f32_dpp v164, v164, v164 row_half_mirror row_mask:0xf bank_mask:0xf
	s_nop 1
	v_max_f32_dpp v164, v164, v164 row_mirror row_mask:0xf bank_mask:0xf
	s_nop 1
	v_readlane_b32 s46, v164, 32
	v_readlane_b32 s47, v164, 48
	v_readlane_b32 s12, v164, 0
	v_readlane_b32 s13, v164, 16
	s_nop 1
	v_mov_b32_e32 v164, s47
	v_max_f32_e32 v164, s46, v164
	v_mov_b32_e32 v165, s13
	v_max3_f32 v164, s12, v165, v164
	v_mul_f32_e32 v165, 0x3c09ae41, v164
	v_cmp_lt_f32_e32 vcc, 0, v164
	s_nop 1
	v_cndmask_b32_e32 v164, 1.0, v165, vcc
	v_div_scale_f32 v166, s[12:13], v164, v164, 1.0
	v_rcp_f32_e32 v167, v166
	v_div_scale_f32 v168, vcc, 1.0, v164, 1.0
	v_fma_f32 v169, -v166, v167, 1.0
	v_fmac_f32_e32 v167, v169, v167
	v_mul_f32_e32 v169, v168, v167
	v_fma_f32 v170, -v166, v169, v168
	v_fmac_f32_e32 v169, v170, v167
	v_fma_f32 v166, -v166, v169, v168
	v_div_fmas_f32 v166, v166, v167, v169
	v_div_fixup_f32 v166, v166, v164, 1.0
	v_mul_f32_e32 v154, v166, v154
	v_mul_f32_e32 v155, v166, v155
	v_rndne_f32_e32 v154, v154
	v_rndne_f32_e32 v155, v155
	v_cvt_i32_f32_e32 v154, v154
	v_cvt_i32_f32_e32 v155, v155
	v_perm_b32 v167, v155, v154, s85
	v_add_u32_e32 v154, v154, v155
	ds_write_b16 v90, v167 offset:5120
	s_nop 1
	v_add_u32_dpp v154, v154, v154 quad_perm:[1,0,3,2] row_mask:0xf bank_mask:0xf bound_ctrl:1
	s_nop 1
	v_add_u32_dpp v154, v154, v154 quad_perm:[2,3,0,1] row_mask:0xf bank_mask:0xf bound_ctrl:1
	s_nop 1
	v_add_u32_dpp v154, v154, v154 row_half_mirror row_mask:0xf bank_mask:0xf bound_ctrl:1
	s_nop 1
	v_add_u32_dpp v154, v154, v154 row_mirror row_mask:0xf bank_mask:0xf bound_ctrl:1
	s_nop 1
	v_readlane_b32 s46, v154, 0
	v_readlane_b32 s47, v154, 16
	v_readlane_b32 s12, v154, 32
	v_readlane_b32 s13, v154, 48
	s_nop 1
	s_add_i32 s46, s47, s46
	s_add_i32 s46, s46, s12
	s_add_i32 s46, s46, s13
	s_add_i32 s47, s67, 160
	s_and_saveexec_b64 s[12:13], s[8:9]
	v_mov_b32_e32 v154, s47
	v_mov_b32_e32 v155, s46
	ds_write2st64_b32 v154, v164, v155 offset1:1
	s_or_b64 exec, exec, s[12:13]
	s_waitcnt vmcnt(2)
; #define LAS __attribute__((address_space(3)))
; __device__ __forceinline__ float gelu_as(float z) {
;     const float ax = fabsf(z) * 0.70710678118654752f, t = __builtin_amdgcn_rcpf(1.f + 0.3275911f * ax);
;     const float poly = t * (0.254829592f + t * (-0.284496736f + t * (1.421413741f + t * (-1.453152027f + t * 1.061405429f))));
;     const float er = 1.f - poly * __expf(-ax * ax);
;     return 0.5f * z * (1.f + copysignf(er, z));
; }
; __global__ void __launch_bounds__(NTHR, 2) k_main(Args a) {
;     ...
;                 const unsigned ew = *(const LAS unsigned*)(EL + tl * 128 + 2 * lane); const int e0 = (int)(ew & 0xffffu), e1 = (int)(ew >> 16);
;                 typedef int i2v __attribute__((ext_vector_type(2))); const i2v si = *(const LAS i2v*)(ACC + tl * 128 + 2 * lane);
;                 typedef float f2v __attribute__((ext_vector_type(2))); const f2v gt = *(const LAS f2v*)(GL + tl * 128 + 2 * lane); const float xs = XS[t];
;                 const int sx = ((const int*)(XS + T))[t];
;                 const float z0 = (float)(2 * si.x + sx) * SU[e0] * xs, z1 = (float)(2 * si.y + sx) * SU[e1] * xs;
;                 const float a0 = gt.x * gelu_as(z0) * SV[e0], a1 = gt.y * gelu_as(z1) * SV[e1];
;                 const float mx = wave_max_dpp(fmaxf(fabsf(a0), fabsf(a1)));
;                 const float sc = mx > 0.f ? mx * (1.f / 119.f) : 1.f, inv = 1.f / sc;
;                 const int q0 = (int)rintf(a0 * inv), q1 = (int)rintf(a1 * inv);
;                 *(LAS unsigned short*)(AL + tl * 128 + 2 * lane) = (unsigned short)((q0 & 255) | ((q1 & 255) << 8));
;                 const int qs = wave_sum_dpp_i(q0 + q1);
;                 if (lane == 0) { ASC[tl] = sc; SAL[tl] = qs; }
	v_lshl_add_u32 v154, v38, 1, v64
	v_lshl_add_u32 v155, v39, 1, v64
	v_cvt_f32_i32_e32 v154, v154
	v_cvt_f32_i32_e32 v155, v155
	v_mul_f32_e32 v154, v134, v154
	v_mul_f32_e32 v155, v150, v155
	v_mul_f32_e32 v154, v72, v154
	v_mul_f32_e32 v155, v72, v155
	v_mul_f32_e64 v156, |v154|, s82
	v_mul_f32_e64 v157, |v155|, s82
	v_fma_f32 v158, v156, s83, 1.0
	v_fma_f32 v159, v157, s83, 1.0
	v_rcp_f32_e32 v158, v158
	v_rcp_f32_e32 v159, v159
	v_mul_f32_e64 v156, v156, -v156
	v_mul_f32_e64 v157, v157, -v157
	v_mul_f32_e32 v156, 0x3fb8aa3b, v156
	v_mul_f32_e32 v157, 0x3fb8aa3b, v157
	v_fmamk_f32 v160, v158, 0x3f87dc22, v110
	v_fmamk_f32 v161, v159, 0x3f87dc22, v110
	v_exp_f32_e32 v156, v156
	v_exp_f32_e32 v157, v157
	v_fmaak_f32 v160, v158, v160, 0x3fb5f0e3
	v_fmaak_f32 v161, v159, v161, 0x3fb5f0e3
	v_fmaak_f32 v160, v158, v160, 0xbe91a98e
	v_fmaak_f32 v161, v159, v161, 0xbe91a98e
	v_fmaak_f32 v160, v158, v160, 0x3e827906
	v_fmaak_f32 v161, v159, v161, 0x3e827906
	v_mul_f32_e32 v158, v158, v160
	v_mul_f32_e32 v159, v159, v161
	v_fma_f32 v156, -v156, v158, 1.0
	v_fma_f32 v157, -v157, v159, 1.0
	v_mul_f32_e32 v162, 0.5, v154
	v_mul_f32_e32 v163, 0.5, v155
	v_bfi_b32 v154, s84, v156, v154
	v_bfi_b32 v155, s84, v157, v155
	v_add_f32_e32 v154, 1.0, v154
	v_add_f32_e32 v155, 1.0, v155
	v_mul_f32_e32 v154, v162, v154
	v_mul_f32_e32 v155, v163, v155
	v_mul_f32_e32 v154, v54, v154
	v_mul_f32_e32 v155, v55, v155
	v_mul_f32_e32 v154, v135, v154
	v_mul_f32_e32 v155, v151, v155
	v_max_f32_e64 v164, |v154|, |v155|
	s_nop 1
	v_max_f32_dpp v164, v164, v164 quad_perm:[1,0,3,2] row_mask:0xf bank_mask:0xf
	s_nop 1
	v_max_f32_dpp v164, v164, v164 quad_perm:[2,3,0,1] row_mask:0xf bank_mask:0xf
	s_nop 1
	v_max_f32_dpp v164, v164, v164 row_half_mirror row_mask:0xf bank_mask:0xf
	s_nop 1
	v_max_f32_dpp v164, v164, v164 row_mirror row_mask:0xf bank_mask:0xf
	s_nop 1
	v_readlane_b32 s46, v164, 32
	v_readlane_b32 s47, v164, 48
	v_readlane_b32 s12, v164, 0
	v_readlane_b32 s13, v164, 16
	s_nop 1
	v_mov_b32_e32 v164, s47
	v_max_f32_e32 v164, s46, v164
	v_mov_b32_e32 v165, s13
	v_max3_f32 v164, s12, v165, v164
	v_mul_f32_e32 v165, 0x3c09ae41, v164
	v_cmp_lt_f32_e32 vcc, 0, v164
	s_nop 1
	v_cndmask_b32_e32 v164, 1.0, v165, vcc
	v_div_scale_f32 v166, s[12:13], v164, v164, 1.0
	v_rcp_f32_e32 v167, v166
	v_div_scale_f32 v168, vcc, 1.0, v164, 1.0
	v_fma_f32 v169, -v166, v167, 1.0
	v_fmac_f32_e32 v167, v169, v167
	v_mul_f32_e32 v169, v168, v167
	v_fma_f32 v170, -v166, v169, v168
	v_fmac_f32_e32 v169, v170, v167
	v_fma_f32 v166, -v166, v169, v168
	v_div_fmas_f32 v166, v166, v167, v169
	v_div_fixup_f32 v166, v166, v164, 1.0
	v_mul_f32_e32 v154, v166, v154
	v_mul_f32_e32 v155, v166, v155
	v_rndne_f32_e32 v154, v154
	v_rndne_f32_e32 v155, v155
	v_cvt_i32_f32_e32 v154, v154
	v_cvt_i32_f32_e32 v155, v155
	v_perm_b32 v167, v155, v154, s85
	v_add_u32_e32 v154, v154, v155
	ds_write_b16 v90, v167 offset:6144
	s_nop 1
	v_add_u32_dpp v154, v154, v154 quad_perm:[1,0,3,2] row_mask:0xf bank_mask:0xf bound_ctrl:1
	s_nop 1
	v_add_u32_dpp v154, v154, v154 quad_perm:[2,3,0,1] row_mask:0xf bank_mask:0xf bound_ctrl:1
	s_nop 1
	v_add_u32_dpp v154, v154, v154 row_half_mirror row_mask:0xf bank_mask:0xf bound_ctrl:1
	s_nop 1
	v_add_u32_dpp v154, v154, v154 row_mirror row_mask:0xf bank_mask:0xf bound_ctrl:1
	s_nop 1
	v_readlane_b32 s46, v154, 0
	v_readlane_b32 s47, v154, 16
	v_readlane_b32 s12, v154, 32
	v_readlane_b32 s13, v154, 48
	s_nop 1
	s_add_i32 s46, s47, s46
	s_add_i32 s46, s46, s12
	s_add_i32 s46, s46, s13
	s_add_i32 s47, s67, 192
	s_and_saveexec_b64 s[12:13], s[8:9]
	v_mov_b32_e32 v154, s47
	v_mov_b32_e32 v155, s46
	ds_write2st64_b32 v154, v164, v155 offset1:1
	s_or_b64 exec, exec, s[12:13]
	s_waitcnt vmcnt(0)
; #define LAS __attribute__((address_space(3)))
; __device__ __forceinline__ float gelu_as(float z) {
;     const float ax = fabsf(z) * 0.70710678118654752f, t = __builtin_amdgcn_rcpf(1.f + 0.3275911f * ax);
;     const float poly = t * (0.254829592f + t * (-0.284496736f + t * (1.421413741f + t * (-1.453152027f + t * 1.061405429f))));
;     const float er = 1.f - poly * __expf(-ax * ax);
;     return 0.5f * z * (1.f + copysignf(er, z));
; }
; __global__ void __launch_bounds__(NTHR, 2) k_main(Args a) {
;     ...
;                 const unsigned ew = *(const LAS unsigned*)(EL + tl * 128 + 2 * lane); const int e0 = (int)(ew & 0xffffu), e1 = (int)(ew >> 16);
;                 typedef int i2v __attribute__((ext_vector_type(2))); const i2v si = *(const LAS i2v*)(ACC + tl * 128 + 2 * lane);
;                 typedef float f2v __attribute__((ext_vector_type(2))); const f2v gt = *(const LAS f2v*)(GL + tl * 128 + 2 * lane); const float xs = XS[t];
;                 const int sx = ((const int*)(XS + T))[t];
;                 const float z0 = (float)(2 * si.x + sx) * SU[e0] * xs, z1 = (float)(2 * si.y + sx) * SU[e1] * xs;
;                 const float a0 = gt.x * gelu_as(z0) * SV[e0], a1 = gt.y * gelu_as(z1) * SV[e1];
;                 const float mx = wave_max_dpp(fmaxf(fabsf(a0), fabsf(a1)));
;                 const float sc = mx > 0.f ? mx * (1.f / 119.f) : 1.f, inv = 1.f / sc;
;                 const int q0 = (int)rintf(a0 * inv), q1 = (int)rintf(a1 * inv);
;                 *(LAS unsigned short*)(AL + tl * 128 + 2 * lane) = (unsigned short)((q0 & 255) | ((q1 & 255) << 8));
;                 const int qs = wave_sum_dpp_i(q0 + q1);
;                 if (lane == 0) { ASC[tl] = sc; SAL[tl] = qs; }
	v_lshl_add_u32 v154, v40, 1, v65
	v_lshl_add_u32 v155, v41, 1, v65
	v_cvt_f32_i32_e32 v154, v154
	v_cvt_f32_i32_e32 v155, v155
	v_mul_f32_e32 v154, v136, v154
	v_mul_f32_e32 v155, v152, v155
	v_mul_f32_e32 v154, v73, v154
	v_mul_f32_e32 v155, v73, v155
	v_mul_f32_e64 v156, |v154|, s82
	v_mul_f32_e64 v157, |v155|, s82
	v_fma_f32 v158, v156, s83, 1.0
	v_fma_f32 v159, v157, s83, 1.0
	v_rcp_f32_e32 v158, v158
	v_rcp_f32_e32 v159, v159
	v_mul_f32_e64 v156, v156, -v156
	v_mul_f32_e64 v157, v157, -v157
	v_mul_f32_e32 v156, 0x3fb8aa3b, v156
	v_mul_f32_e32 v157, 0x3fb8aa3b, v157
	v_fmamk_f32 v160, v158, 0x3f87dc22, v110
	v_fmamk_f32 v161, v159, 0x3f87dc22, v110
	v_exp_f32_e32 v156, v156
	v_exp_f32_e32 v157, v157
	v_fmaak_f32 v160, v158, v160, 0x3fb5f0e3
	v_fmaak_f32 v161, v159, v161, 0x3fb5f0e3
	v_fmaak_f32 v160, v158, v160, 0xbe91a98e
	v_fmaak_f32 v161, v159, v161, 0xbe91a98e
	v_fmaak_f32 v160, v158, v160, 0x3e827906
	v_fmaak_f32 v161, v159, v161, 0x3e827906
	v_mul_f32_e32 v158, v158, v160
	v_mul_f32_e32 v159, v159, v161
	v_fma_f32 v156, -v156, v158, 1.0
	v_fma_f32 v157, -v157, v159, 1.0
	v_mul_f32_e32 v162, 0.5, v154
	v_mul_f32_e32 v163, 0.5, v155
	v_bfi_b32 v154, s84, v156, v154
	v_bfi_b32 v155, s84, v157, v155
	v_add_f32_e32 v154, 1.0, v154
	v_add_f32_e32 v155, 1.0, v155
	v_mul_f32_e32 v154, v162, v154
	v_mul_f32_e32 v155, v163, v155
	v_mul_f32_e32 v154, v56, v154
	v_mul_f32_e32 v155, v57, v155
	v_mul_f32_e32 v154, v137, v154
	v_mul_f32_e32 v155, v153, v155
	v_max_f32_e64 v164, |v154|, |v155|
	s_nop 1
	v_max_f32_dpp v164, v164, v164 quad_perm:[1,0,3,2] row_mask:0xf bank_mask:0xf
	s_nop 1
	v_max_f32_dpp v164, v164, v164 quad_perm:[2,3,0,1] row_mask:0xf bank_mask:0xf
	s_nop 1
	v_max_f32_dpp v164, v164, v164 row_half_mirror row_mask:0xf bank_mask:0xf
	s_nop 1
	v_max_f32_dpp v164, v164, v164 row_mirror row_mask:0xf bank_mask:0xf
	s_nop 1
	v_readlane_b32 s46, v164, 32
	v_readlane_b32 s47, v164, 48
	v_readlane_b32 s12, v164, 0
	v_readlane_b32 s13, v164, 16
	s_nop 1
	v_mov_b32_e32 v164, s47
	v_max_f32_e32 v164, s46, v164
	v_mov_b32_e32 v165, s13
	v_max3_f32 v164, s12, v165, v164
	v_mul_f32_e32 v165, 0x3c09ae41, v164
	v_cmp_lt_f32_e32 vcc, 0, v164
	s_nop 1
	v_cndmask_b32_e32 v164, 1.0, v165, vcc
	v_div_scale_f32 v166, s[12:13], v164, v164, 1.0
	v_rcp_f32_e32 v167, v166
	v_div_scale_f32 v168, vcc, 1.0, v164, 1.0
	v_fma_f32 v169, -v166, v167, 1.0
	v_fmac_f32_e32 v167, v169, v167
	v_mul_f32_e32 v169, v168, v167
	v_fma_f32 v170, -v166, v169, v168
	v_fmac_f32_e32 v169, v170, v167
	v_fma_f32 v166, -v166, v169, v168
	v_div_fmas_f32 v166, v166, v167, v169
	v_div_fixup_f32 v166, v166, v164, 1.0
	v_mul_f32_e32 v154, v166, v154
	v_mul_f32_e32 v155, v166, v155
	v_rndne_f32_e32 v154, v154
	v_rndne_f32_e32 v155, v155
	v_cvt_i32_f32_e32 v154, v154
	v_cvt_i32_f32_e32 v155, v155
	v_perm_b32 v167, v155, v154, s85
	v_add_u32_e32 v154, v154, v155
	ds_write_b16 v90, v167 offset:7168
	s_nop 1
	v_add_u32_dpp v154, v154, v154 quad_perm:[1,0,3,2] row_mask:0xf bank_mask:0xf bound_ctrl:1
	s_nop 1
	v_add_u32_dpp v154, v154, v154 quad_perm:[2,3,0,1] row_mask:0xf bank_mask:0xf bound_ctrl:1
	s_nop 1
	v_add_u32_dpp v154, v154, v154 row_half_mirror row_mask:0xf bank_mask:0xf bound_ctrl:1
	s_nop 1
	v_add_u32_dpp v154, v154, v154 row_mirror row_mask:0xf bank_mask:0xf bound_ctrl:1
	s_nop 1
	v_readlane_b32 s46, v154, 0
	v_readlane_b32 s47, v154, 16
	v_readlane_b32 s12, v154, 32
	v_readlane_b32 s13, v154, 48
	s_nop 1
	s_add_i32 s46, s47, s46
	s_add_i32 s46, s46, s12
	s_add_i32 s46, s46, s13
	s_add_i32 s47, s67, 224
	s_and_saveexec_b64 s[12:13], s[8:9]
	v_mov_b32_e32 v154, s47
	v_mov_b32_e32 v155, s46
	ds_write2st64_b32 v154, v164, v155 offset1:1
	s_or_b64 exec, exec, s[12:13]
